# permlane-swap reductions also for the paired LayerNorm-statistics sums of the gelu epilogue
# baseline (speedup 1.0000x reference)
.LBB0_265:
	v_lshl_add_u32 v164, v159, 2, s55
	ds_read2_b32 v[172:173], v164 offset1:16
	ds_read2_b32 v[170:171], v164 offset0:32 offset1:48
	ds_read2_b32 v[168:169], v164 offset0:128 offset1:144
	ds_read2_b32 v[164:165], v164 offset0:160 offset1:176
	v_mov_b64_e32 v[194:195], s[34:35]
	s_waitcnt vmcnt(0) lgkmcnt(0)
	v_pk_fma_f32 v[142:143], v[142:143], v[172:173], v[54:55] op_sel_hi:[1,0,1]
	v_pk_fma_f32 v[136:137], v[136:137], v[172:173], v[48:49] op_sel_hi:[1,0,1]
	v_and_b32_e32 v201, 0x7fffffff, v143
	v_and_b32_e32 v200, 0x7fffffff, v142
	v_pk_fma_f32 v[200:201], v[200:201], s[20:21], 1.0 op_sel_hi:[1,0,0]
	v_pk_fma_f32 v[140:141], v[140:141], v[172:173], v[52:53] op_sel_hi:[1,0,1]
	v_rcp_f32_e32 v200, v200
	v_rcp_f32_e32 v201, v201
	v_and_b32_e32 v183, 0x7fffffff, v141
	v_and_b32_e32 v182, 0x7fffffff, v140
	v_pk_fma_f32 v[182:183], v[182:183], s[20:21], 1.0 op_sel_hi:[1,0,0]
	v_pk_fma_f32 v[202:203], v[200:201], s[22:23], v[194:195] op_sel_hi:[1,0,0]
	v_rcp_f32_e32 v182, v182
	v_pk_fma_f32 v[202:203], v[200:201], v[202:203], s[36:37] op_sel_hi:[1,1,0]
	v_rcp_f32_e32 v183, v183
	v_pk_fma_f32 v[202:203], v[200:201], v[202:203], s[38:39] op_sel_hi:[1,1,0]
	v_pk_fma_f32 v[138:139], v[138:139], v[172:173], v[50:51] op_sel_hi:[1,0,1]
	v_pk_fma_f32 v[202:203], v[200:201], v[202:203], s[40:41] op_sel_hi:[1,1,0]
	v_and_b32_e32 v209, 0x7fffffff, v139
	v_pk_mul_f32 v[200:201], v[200:201], v[202:203]
	v_and_b32_e32 v203, 0x7fffffff, v137
	v_and_b32_e32 v202, 0x7fffffff, v136
	v_pk_fma_f32 v[202:203], v[202:203], s[20:21], 1.0 op_sel_hi:[1,0,0]
	v_and_b32_e32 v208, 0x7fffffff, v138
	v_rcp_f32_e32 v202, v202
	v_rcp_f32_e32 v203, v203
	v_pk_fma_f32 v[208:209], v[208:209], s[20:21], 1.0 op_sel_hi:[1,0,0]
	v_pk_fma_f32 v[196:197], v[182:183], s[22:23], v[194:195] op_sel_hi:[1,0,0]
	v_rcp_f32_e32 v208, v208
	v_pk_fma_f32 v[204:205], v[202:203], s[22:23], v[194:195] op_sel_hi:[1,0,0]
	v_rcp_f32_e32 v209, v209
	v_pk_fma_f32 v[204:205], v[202:203], v[204:205], s[36:37] op_sel_hi:[1,1,0]
	v_pk_fma_f32 v[196:197], v[182:183], v[196:197], s[36:37] op_sel_hi:[1,1,0]
	v_pk_fma_f32 v[204:205], v[202:203], v[204:205], s[38:39] op_sel_hi:[1,1,0]
	v_pk_fma_f32 v[196:197], v[182:183], v[196:197], s[38:39] op_sel_hi:[1,1,0]
	v_pk_fma_f32 v[204:205], v[202:203], v[204:205], s[40:41] op_sel_hi:[1,1,0]
	v_pk_fma_f32 v[196:197], v[182:183], v[196:197], s[40:41] op_sel_hi:[1,1,0]
	v_pk_mul_f32 v[202:203], v[202:203], v[204:205]
	v_pk_mul_f32 v[204:205], v[138:139], v[138:139]
	v_pk_mul_f32 v[182:183], v[182:183], v[196:197]
	v_pk_mul_f32 v[196:197], v[142:143], v[142:143]
	v_pk_fma_f32 v[210:211], v[208:209], s[22:23], v[194:195] op_sel_hi:[1,0,0]
	v_pk_mul_f32 v[204:205], v[204:205], s[42:43] op_sel_hi:[1,0]
	v_pk_mul_f32 v[198:199], v[140:141], v[140:141]
	v_pk_mul_f32 v[196:197], v[196:197], s[42:43] op_sel_hi:[1,0]
	v_pk_fma_f32 v[210:211], v[208:209], v[210:211], s[36:37] op_sel_hi:[1,1,0]
	v_exp_f32_e32 v204, v204
	v_exp_f32_e32 v205, v205
	v_pk_mul_f32 v[198:199], v[198:199], s[42:43] op_sel_hi:[1,0]
	v_exp_f32_e32 v196, v196
	v_exp_f32_e32 v197, v197
	v_pk_fma_f32 v[210:211], v[208:209], v[210:211], s[38:39] op_sel_hi:[1,1,0]
	v_exp_f32_e32 v198, v198
	v_exp_f32_e32 v199, v199
	v_pk_fma_f32 v[210:211], v[208:209], v[210:211], s[40:41] op_sel_hi:[1,1,0]
	v_pk_mul_f32 v[196:197], v[196:197], v[200:201]
	v_pk_mul_f32 v[208:209], v[208:209], v[210:211]
	v_cmp_gt_f32_e64 s[2:3], 0, v139
	v_pk_mul_f32 v[204:205], v[204:205], v[208:209]
	v_pk_mul_f32 v[182:183], v[198:199], v[182:183]
	v_pk_mul_f32 v[208:209], v[138:139], v[204:205]
	v_pk_fma_f32 v[204:205], v[138:139], v[204:205], v[138:139] neg_lo:[1,0,0] neg_hi:[1,0,0]
	v_pk_mul_f32 v[200:201], v[142:143], v[196:197]
	v_pk_fma_f32 v[196:197], v[142:143], v[196:197], v[142:143] neg_lo:[1,0,0] neg_hi:[1,0,0]
	v_cndmask_b32_e64 v210, v205, v209, s[2:3]
	v_cmp_gt_f32_e64 s[2:3], 0, v142
	v_pk_mul_f32 v[198:199], v[140:141], v[182:183]
	v_pk_fma_f32 v[182:183], v[140:141], v[182:183], v[140:141] neg_lo:[1,0,0] neg_hi:[1,0,0]
	v_cndmask_b32_e64 v213, v196, v200, s[2:3]
	v_cmp_gt_f32_e64 s[2:3], 0, v140
	v_pk_fma_f32 v[134:135], v[134:135], v[172:173], v[46:47] op_sel_hi:[1,0,1]
	v_pk_fma_f32 v[132:133], v[132:133], v[172:173], v[44:45] op_sel_hi:[1,0,1]
	v_cndmask_b32_e64 v212, v182, v198, s[2:3]
	v_cmp_gt_f32_e64 s[2:3], 0, v143
	v_pk_fma_f32 v[128:129], v[128:129], v[172:173], v[40:41] op_sel_hi:[1,0,1]
	v_pk_fma_f32 v[130:131], v[130:131], v[172:173], v[42:43] op_sel_hi:[1,0,1]
	v_cndmask_b32_e64 v143, v197, v201, s[2:3]
	v_cmp_gt_f32_e64 s[2:3], 0, v141
	v_and_b32_e32 v221, 0x7fffffff, v131
	v_and_b32_e32 v220, 0x7fffffff, v130
	v_cndmask_b32_e64 v142, v183, v199, s[2:3]
	v_pk_add_f32 v[140:141], v[212:213], v[142:143]
	v_pk_mul_f32 v[200:201], v[132:133], v[132:133]
	v_pk_add_f32 v[182:183], v[140:141], v[140:141] op_sel:[0,1] op_sel_hi:[1,0]
	v_pk_mul_f32 v[140:141], v[142:143], v[142:143]
	v_pk_fma_f32 v[220:221], v[220:221], s[20:21], 1.0 op_sel_hi:[1,0,0]
	v_pk_fma_f32 v[140:141], v[212:213], v[212:213], v[140:141]
	v_pk_mul_f32 v[200:201], v[200:201], s[42:43] op_sel_hi:[1,0]
	v_pk_add_f32 v[196:197], v[140:141], v[140:141] op_sel_hi:[0,1]
	v_cvt_pk_bf16_f32 v140, v212, v142
	v_cvt_pk_bf16_f32 v141, v213, v143
	v_and_b32_e32 v213, 0x7fffffff, v135
	v_and_b32_e32 v212, 0x7fffffff, v134
	v_pk_fma_f32 v[212:213], v[212:213], s[20:21], 1.0 op_sel_hi:[1,0,0]
	v_and_b32_e32 v143, 0x7fffffff, v133
	v_rcp_f32_e32 v212, v212
	v_rcp_f32_e32 v213, v213
	v_and_b32_e32 v142, 0x7fffffff, v132
	v_pk_fma_f32 v[142:143], v[142:143], s[20:21], 1.0 op_sel_hi:[1,0,0]
	v_rcp_f32_e32 v220, v220
	v_pk_fma_f32 v[214:215], v[212:213], s[22:23], v[194:195] op_sel_hi:[1,0,0]
	v_rcp_f32_e32 v142, v142
	v_pk_fma_f32 v[214:215], v[212:213], v[214:215], s[36:37] op_sel_hi:[1,1,0]
	v_rcp_f32_e32 v143, v143
	v_pk_fma_f32 v[214:215], v[212:213], v[214:215], s[38:39] op_sel_hi:[1,1,0]
	v_rcp_f32_e32 v221, v221
	v_pk_fma_f32 v[214:215], v[212:213], v[214:215], s[40:41] op_sel_hi:[1,1,0]
	v_pk_fma_f32 v[198:199], v[142:143], s[22:23], v[194:195] op_sel_hi:[1,0,0]
	v_pk_mul_f32 v[212:213], v[212:213], v[214:215]
	v_and_b32_e32 v215, 0x7fffffff, v129
	v_and_b32_e32 v214, 0x7fffffff, v128
	v_pk_fma_f32 v[214:215], v[214:215], s[20:21], 1.0 op_sel_hi:[1,0,0]
	v_pk_fma_f32 v[198:199], v[142:143], v[198:199], s[36:37] op_sel_hi:[1,1,0]
	v_rcp_f32_e32 v214, v214
	v_rcp_f32_e32 v215, v215
	v_pk_fma_f32 v[198:199], v[142:143], v[198:199], s[38:39] op_sel_hi:[1,1,0]
	v_exp_f32_e32 v200, v200
	v_pk_fma_f32 v[198:199], v[142:143], v[198:199], s[40:41] op_sel_hi:[1,1,0]
	v_pk_fma_f32 v[216:217], v[214:215], s[22:23], v[194:195] op_sel_hi:[1,0,0]
	v_pk_mul_f32 v[142:143], v[142:143], v[198:199]
	v_pk_fma_f32 v[216:217], v[214:215], v[216:217], s[36:37] op_sel_hi:[1,1,0]
	v_pk_mul_f32 v[198:199], v[134:135], v[134:135]
	v_exp_f32_e32 v201, v201
	v_pk_fma_f32 v[216:217], v[214:215], v[216:217], s[38:39] op_sel_hi:[1,1,0]
	v_pk_mul_f32 v[198:199], v[198:199], s[42:43] op_sel_hi:[1,0]
	v_pk_fma_f32 v[216:217], v[214:215], v[216:217], s[40:41] op_sel_hi:[1,1,0]
	v_exp_f32_e32 v198, v198
	v_exp_f32_e32 v199, v199
	v_pk_mul_f32 v[214:215], v[214:215], v[216:217]
	v_pk_mul_f32 v[216:217], v[130:131], v[130:131]
	v_pk_fma_f32 v[194:195], v[220:221], s[22:23], v[194:195] op_sel_hi:[1,0,0]
	v_pk_mul_f32 v[216:217], v[216:217], s[42:43] op_sel_hi:[1,0]
	v_pk_mul_f32 v[206:207], v[136:137], v[136:137]
	v_pk_mul_f32 v[142:143], v[200:201], v[142:143]
	v_pk_fma_f32 v[194:195], v[220:221], v[194:195], s[36:37] op_sel_hi:[1,1,0]
	v_exp_f32_e32 v216, v216
	v_exp_f32_e32 v217, v217
	v_pk_mul_f32 v[206:207], v[206:207], s[42:43] op_sel_hi:[1,0]
	v_pk_mul_f32 v[200:201], v[132:133], v[142:143]
	v_pk_fma_f32 v[142:143], v[132:133], v[142:143], v[132:133] neg_lo:[1,0,0] neg_hi:[1,0,0]
	v_pk_mul_f32 v[218:219], v[128:129], v[128:129]
	v_pk_fma_f32 v[194:195], v[220:221], v[194:195], s[38:39] op_sel_hi:[1,1,0]
	v_cmp_gt_f32_e64 s[2:3], 0, v133
	v_exp_f32_e32 v206, v206
	v_exp_f32_e32 v207, v207
	v_pk_mul_f32 v[198:199], v[198:199], v[212:213]
	v_pk_mul_f32 v[218:219], v[218:219], s[42:43] op_sel_hi:[1,0]
	v_pk_fma_f32 v[194:195], v[220:221], v[194:195], s[40:41] op_sel_hi:[1,1,0]
	v_cndmask_b32_e64 v201, v143, v201, s[2:3]
	v_cmp_gt_f32_e64 s[2:3], 0, v132
	v_pk_mul_f32 v[212:213], v[134:135], v[198:199]
	v_pk_fma_f32 v[198:199], v[134:135], v[198:199], v[134:135] neg_lo:[1,0,0] neg_hi:[1,0,0]
	v_exp_f32_e32 v218, v218
	v_exp_f32_e32 v219, v219
	v_pk_mul_f32 v[194:195], v[220:221], v[194:195]
	v_cndmask_b32_e64 v200, v142, v200, s[2:3]
	v_cmp_gt_f32_e64 s[2:3], 0, v135
	v_pk_mul_f32 v[194:195], v[216:217], v[194:195]
	s_lshl_b32 s0, s0, 8
	v_cndmask_b32_e64 v199, v199, v213, s[2:3]
	v_cmp_gt_f32_e64 s[2:3], 0, v134
	v_pk_mul_f32 v[216:217], v[130:131], v[194:195]
	v_pk_fma_f32 v[194:195], v[130:131], v[194:195], v[130:131] neg_lo:[1,0,0] neg_hi:[1,0,0]
	v_cndmask_b32_e64 v198, v198, v212, s[2:3]
	v_cmp_gt_f32_e64 s[2:3], 0, v131
	v_pk_mul_f32 v[202:203], v[206:207], v[202:203]
	s_add_i32 s0, s0, s68
	v_cndmask_b32_e64 v131, v195, v217, s[2:3]
	v_cmp_gt_f32_e64 s[2:3], 0, v130
	v_pk_mul_f32 v[206:207], v[136:137], v[202:203]
	v_pk_fma_f32 v[202:203], v[136:137], v[202:203], v[136:137] neg_lo:[1,0,0] neg_hi:[1,0,0]
	v_pk_mul_f32 v[214:215], v[218:219], v[214:215]
	v_cndmask_b32_e64 v130, v194, v216, s[2:3]
	v_cmp_gt_f32_e64 s[2:3], 0, v136
	v_add_u32_e32 v166, s0, v159
	v_pk_mul_f32 v[218:219], v[128:129], v[214:215]
	v_pk_fma_f32 v[214:215], v[128:129], v[214:215], v[128:129] neg_lo:[1,0,0] neg_hi:[1,0,0]
	v_cndmask_b32_e64 v216, v202, v206, s[2:3]
	v_cmp_gt_f32_e64 s[2:3], 0, v128
	v_cmp_eq_u32_e32 vcc, 0, v167
	v_ashrrev_i32_e32 v167, 31, v166
	v_mul_f32_e32 v132, v200, v200
	v_cndmask_b32_e64 v217, v214, v218, s[2:3]
	v_cmp_gt_f32_e64 s[2:3], 0, v137
	v_lshlrev_b64 v[174:175], 13, v[166:167]
	v_pk_fma_f32 v[132:133], v[200:201], v[200:201], v[132:133] op_sel_hi:[1,1,0]
	v_mov_b32_e32 v134, v200
	v_mov_b32_e32 v135, v198
	v_mov_b32_e32 v142, v201
	v_mov_b32_e32 v143, v199
	v_cndmask_b32_e64 v136, v203, v207, s[2:3]
	v_cmp_gt_f32_e64 s[2:3], 0, v138
	v_lshl_add_u64 v[174:175], s[28:29], 0, v[174:175]
	v_pk_add_f32 v[134:135], v[134:135], v[142:143]
	v_mul_f32_e32 v132, v198, v198
	v_mov_b32_e32 v142, v216
	v_mov_b32_e32 v143, v136
	v_mul_f32_e32 v128, v216, v216
	v_cndmask_b32_e64 v139, v204, v208, s[2:3]
	v_cmp_gt_f32_e64 s[2:3], 0, v129
	v_lshl_add_u64 v[174:175], v[162:163], 1, v[174:175]
	v_pk_fma_f32 v[212:213], v[198:199], v[198:199], v[132:133] op_sel_hi:[1,1,0]
	v_mul_f32_e32 v132, v130, v130
	v_mov_b32_e32 v137, v217
	v_pk_fma_f32 v[202:203], v[142:143], v[142:143], v[128:129] op_sel_hi:[1,1,0]
	v_cvt_pk_bf16_f32 v142, v216, v136
	v_mov_b32_e32 v138, v217
	v_cndmask_b32_e64 v128, v215, v219, s[2:3]
	v_mov_b32_e32 v129, v139
	v_cvt_pk_bf16_f32 v143, v139, v210
	v_pk_fma_f32 v[194:195], v[130:131], v[130:131], v[132:133] op_sel_hi:[1,1,0]
	global_store_dwordx4 v[174:175], v[140:143], off
	v_mov_b32_e32 v132, v139
	v_mul_f32_e32 v159, v210, v210
	v_pk_add_f32 v[140:141], v[138:139], v[128:129]
	v_pk_mul_f32 v[142:143], v[138:139], v[128:129]
	v_pk_add_f32 v[138:139], v[216:217], v[136:137]
	v_pk_mul_f32 v[136:137], v[216:217], v[136:137]
	v_pk_add_f32 v[134:135], v[134:135], v[134:135] op_sel:[0,1] op_sel_hi:[1,0]
	v_mov_b32_e32 v139, v137
	v_pk_mul_f32 v[136:137], v[128:129], v[128:129]
	v_mov_b32_e32 v211, v213
	v_mov_b32_e32 v183, v136
	v_mov_b32_e32 v141, v143
	v_mov_b32_e32 v135, v159
	v_mov_b32_e32 v202, v130
	v_mov_b32_e32 v196, v131
	v_pk_add_f32 v[132:133], v[132:133], v[210:211]
	v_pk_add_f32 v[136:137], v[138:139], v[182:183]
	v_pk_add_f32 v[134:135], v[140:141], v[134:135]
	v_pk_add_f32 v[140:141], v[202:203], v[196:197]
	v_pk_add_f32 v[132:133], v[136:137], v[132:133]
	v_mov_b32_e32 v159, v195
	v_pk_add_f32 v[134:135], v[134:135], v[140:141]
	v_pk_add_f32 v[132:133], v[132:133], v[158:159]
	v_xor_b32_e32 v129, 16, v181
	v_pk_add_f32 v[138:139], v[134:135], v[132:133]
	v_and_b32_e32 v132, 64, v181
	v_add_u32_e32 v133, 64, v132
	v_cmp_lt_i32_e64 s[2:3], v129, v133
	v_cvt_pk_bf16_f32 v134, v200, v201
	v_cvt_pk_bf16_f32 v135, v198, v199
	v_cvt_pk_bf16_f32 v136, v217, v128
	v_cvt_pk_bf16_f32 v137, v130, v131
	v_xor_b32_e32 v130, 32, v181
	s_nop 0
	v_cndmask_b32_e64 v129, v181, v129, s[2:3]
	v_lshlrev_b32_e32 v132, 2, v129
	v_mov_b32_e32 v140, v138
	v_mov_b32_e32 v141, v139
	s_nop 1
	v_permlane16_swap_b32_e32 v140, v138
	v_permlane16_swap_b32_e32 v141, v139
	v_cmp_lt_i32_e64 s[2:3], v130, v133
	s_cmp_gt_i32 s60, 7
	s_cselect_b64 s[0:1], -1, 0
	v_cndmask_b32_e64 v130, v181, v130, s[2:3]
	s_waitcnt lgkmcnt(0)
	v_pk_add_f32 v[128:129], v[138:139], v[140:141]
	v_lshlrev_b32_e32 v133, 2, v130
	v_mov_b32_e32 v130, v128
	v_mov_b32_e32 v131, v129
	s_nop 1
	v_permlane32_swap_b32_e32 v130, v128
	v_permlane32_swap_b32_e32 v131, v129
	s_and_b64 s[2:3], s[0:1], vcc
	global_store_dwordx4 v[174:175], v[134:137], off offset:256
	s_and_saveexec_b64 s[0:1], s[2:3]
	s_cbranch_execz .LBB0_267
	s_lshl_b32 s46, s60, 3
	s_waitcnt lgkmcnt(0)
	v_pk_add_f32 v[128:129], v[128:129], v[130:131]
	v_lshlrev_b64 v[130:131], 8, v[166:167]
	s_add_i32 s46, s46, s53
	v_lshl_add_u64 v[130:131], s[26:27], 0, v[130:131]
	s_ashr_i32 s47, s46, 31
	v_lshl_add_u64 v[130:131], s[46:47], 2, v[130:131]
	global_store_dwordx2 v[130:131], v[128:129], off
.LBB0_267:
	s_or_b64 exec, exec, s[0:1]
	v_mov_b32_e32 v134, v173
	v_pk_fma_f32 v[126:127], v[126:127], v[134:135], v[54:55] op_sel_hi:[1,0,1]
	v_mov_b64_e32 v[138:139], s[34:35]
	v_and_b32_e32 v173, 0x7fffffff, v127
	v_and_b32_e32 v172, 0x7fffffff, v126
	v_pk_fma_f32 v[172:173], v[172:173], s[20:21], 1.0 op_sel_hi:[1,0,0]
	v_pk_fma_f32 v[120:121], v[120:121], v[134:135], v[48:49] op_sel_hi:[1,0,1]
	v_rcp_f32_e32 v172, v172
	v_rcp_f32_e32 v173, v173
	v_pk_fma_f32 v[124:125], v[124:125], v[134:135], v[52:53] op_sel_hi:[1,0,1]
	v_pk_fma_f32 v[122:123], v[122:123], v[134:135], v[50:51] op_sel_hi:[1,0,1]
	v_and_b32_e32 v137, 0x7fffffff, v125
	v_pk_fma_f32 v[174:175], v[172:173], s[22:23], v[138:139] op_sel_hi:[1,0,0]
	v_and_b32_e32 v136, 0x7fffffff, v124
	v_pk_fma_f32 v[174:175], v[172:173], v[174:175], s[36:37] op_sel_hi:[1,1,0]
	v_pk_fma_f32 v[136:137], v[136:137], s[20:21], 1.0 op_sel_hi:[1,0,0]
	v_pk_fma_f32 v[174:175], v[172:173], v[174:175], s[38:39] op_sel_hi:[1,1,0]
	v_rcp_f32_e32 v136, v136
	v_pk_fma_f32 v[174:175], v[172:173], v[174:175], s[40:41] op_sel_hi:[1,1,0]
	v_rcp_f32_e32 v137, v137
	v_pk_mul_f32 v[172:173], v[172:173], v[174:175]
	v_and_b32_e32 v175, 0x7fffffff, v121
	v_and_b32_e32 v174, 0x7fffffff, v120
	v_pk_fma_f32 v[174:175], v[174:175], s[20:21], 1.0 op_sel_hi:[1,0,0]
	v_and_b32_e32 v197, 0x7fffffff, v123
	v_rcp_f32_e32 v174, v174
	v_rcp_f32_e32 v175, v175
	v_and_b32_e32 v196, 0x7fffffff, v122
	v_pk_fma_f32 v[196:197], v[196:197], s[20:21], 1.0 op_sel_hi:[1,0,0]
	v_pk_fma_f32 v[140:141], v[136:137], s[22:23], v[138:139] op_sel_hi:[1,0,0]
	v_pk_fma_f32 v[182:183], v[174:175], s[22:23], v[138:139] op_sel_hi:[1,0,0]
	v_rcp_f32_e32 v196, v196
	v_pk_fma_f32 v[182:183], v[174:175], v[182:183], s[36:37] op_sel_hi:[1,1,0]
	v_rcp_f32_e32 v197, v197
	v_pk_fma_f32 v[140:141], v[136:137], v[140:141], s[36:37] op_sel_hi:[1,1,0]
	v_pk_fma_f32 v[182:183], v[174:175], v[182:183], s[38:39] op_sel_hi:[1,1,0]
	v_pk_fma_f32 v[140:141], v[136:137], v[140:141], s[38:39] op_sel_hi:[1,1,0]
	v_pk_fma_f32 v[182:183], v[174:175], v[182:183], s[40:41] op_sel_hi:[1,1,0]
	v_pk_fma_f32 v[140:141], v[136:137], v[140:141], s[40:41] op_sel_hi:[1,1,0]
	v_pk_mul_f32 v[174:175], v[174:175], v[182:183]
	v_pk_mul_f32 v[182:183], v[122:123], v[122:123]
	v_pk_mul_f32 v[136:137], v[136:137], v[140:141]
	v_pk_mul_f32 v[140:141], v[126:127], v[126:127]
	v_pk_fma_f32 v[198:199], v[196:197], s[22:23], v[138:139] op_sel_hi:[1,0,0]
	v_pk_mul_f32 v[182:183], v[182:183], s[42:43] op_sel_hi:[1,0]
	v_pk_mul_f32 v[142:143], v[124:125], v[124:125]
	v_pk_mul_f32 v[140:141], v[140:141], s[42:43] op_sel_hi:[1,0]
	v_pk_fma_f32 v[198:199], v[196:197], v[198:199], s[36:37] op_sel_hi:[1,1,0]
	v_exp_f32_e32 v182, v182
	v_exp_f32_e32 v183, v183
	v_pk_mul_f32 v[142:143], v[142:143], s[42:43] op_sel_hi:[1,0]
	v_exp_f32_e32 v140, v140
	v_exp_f32_e32 v141, v141
	v_pk_fma_f32 v[198:199], v[196:197], v[198:199], s[38:39] op_sel_hi:[1,1,0]
	v_exp_f32_e32 v142, v142
	v_exp_f32_e32 v143, v143
	v_pk_fma_f32 v[198:199], v[196:197], v[198:199], s[40:41] op_sel_hi:[1,1,0]
	v_pk_mul_f32 v[140:141], v[140:141], v[172:173]
	v_pk_mul_f32 v[196:197], v[196:197], v[198:199]
	v_cmp_gt_f32_e32 vcc, 0, v123
	v_pk_mul_f32 v[182:183], v[182:183], v[196:197]
	v_pk_mul_f32 v[136:137], v[142:143], v[136:137]
	v_pk_mul_f32 v[196:197], v[122:123], v[182:183]
	v_pk_fma_f32 v[182:183], v[122:123], v[182:183], v[122:123] neg_lo:[1,0,0] neg_hi:[1,0,0]
	v_pk_mul_f32 v[172:173], v[126:127], v[140:141]
	v_pk_fma_f32 v[140:141], v[126:127], v[140:141], v[126:127] neg_lo:[1,0,0] neg_hi:[1,0,0]
	v_cndmask_b32_e32 v198, v183, v197, vcc
	v_cmp_gt_f32_e32 vcc, 0, v126
	v_pk_mul_f32 v[142:143], v[124:125], v[136:137]
	v_pk_fma_f32 v[136:137], v[124:125], v[136:137], v[124:125] neg_lo:[1,0,0] neg_hi:[1,0,0]
	v_cndmask_b32_e32 v201, v140, v172, vcc
	v_cmp_gt_f32_e32 vcc, 0, v124
	v_pk_fma_f32 v[118:119], v[118:119], v[134:135], v[46:47] op_sel_hi:[1,0,1]
	v_pk_fma_f32 v[116:117], v[116:117], v[134:135], v[44:45] op_sel_hi:[1,0,1]
	v_cndmask_b32_e32 v200, v136, v142, vcc
	v_cmp_gt_f32_e32 vcc, 0, v127
	v_and_b32_e32 v172, 0x7fffffff, v118
	v_pk_fma_f32 v[112:113], v[112:113], v[134:135], v[40:41] op_sel_hi:[1,0,1]
	v_cndmask_b32_e32 v127, v141, v173, vcc
	v_and_b32_e32 v173, 0x7fffffff, v119
	v_cmp_gt_f32_e32 vcc, 0, v125
	v_pk_fma_f32 v[172:173], v[172:173], s[20:21], 1.0 op_sel_hi:[1,0,0]
	v_pk_fma_f32 v[114:115], v[114:115], v[134:135], v[42:43] op_sel_hi:[1,0,1]
	v_cndmask_b32_e32 v126, v137, v143, vcc
	v_rcp_f32_e32 v172, v172
	v_rcp_f32_e32 v173, v173
	v_pk_add_f32 v[124:125], v[200:201], v[126:127]
	v_and_b32_e32 v207, 0x7fffffff, v115
	v_pk_add_f32 v[136:137], v[124:125], v[124:125] op_sel:[0,1] op_sel_hi:[1,0]
	v_pk_mul_f32 v[124:125], v[126:127], v[126:127]
	v_and_b32_e32 v206, 0x7fffffff, v114
	v_pk_fma_f32 v[124:125], v[200:201], v[200:201], v[124:125]
	v_pk_mul_f32 v[142:143], v[116:117], v[116:117]
	v_pk_add_f32 v[140:141], v[124:125], v[124:125] op_sel_hi:[0,1]
	v_cvt_pk_bf16_f32 v124, v200, v126
	v_cvt_pk_bf16_f32 v125, v201, v127
	v_pk_fma_f32 v[200:201], v[172:173], s[22:23], v[138:139] op_sel_hi:[1,0,0]
	v_and_b32_e32 v127, 0x7fffffff, v117
	v_pk_fma_f32 v[200:201], v[172:173], v[200:201], s[36:37] op_sel_hi:[1,1,0]
	v_and_b32_e32 v126, 0x7fffffff, v116
	v_pk_fma_f32 v[200:201], v[172:173], v[200:201], s[38:39] op_sel_hi:[1,1,0]
	v_pk_fma_f32 v[126:127], v[126:127], s[20:21], 1.0 op_sel_hi:[1,0,0]
	v_pk_fma_f32 v[200:201], v[172:173], v[200:201], s[40:41] op_sel_hi:[1,1,0]
	v_rcp_f32_e32 v126, v126
	v_rcp_f32_e32 v127, v127
	v_pk_mul_f32 v[172:173], v[172:173], v[200:201]
	v_and_b32_e32 v201, 0x7fffffff, v113
	v_and_b32_e32 v200, 0x7fffffff, v112
	v_pk_fma_f32 v[200:201], v[200:201], s[20:21], 1.0 op_sel_hi:[1,0,0]
	v_pk_fma_f32 v[134:135], v[126:127], s[22:23], v[138:139] op_sel_hi:[1,0,0]
	v_rcp_f32_e32 v200, v200
	v_rcp_f32_e32 v201, v201
	v_pk_fma_f32 v[134:135], v[126:127], v[134:135], s[36:37] op_sel_hi:[1,1,0]
	v_pk_fma_f32 v[206:207], v[206:207], s[20:21], 1.0 op_sel_hi:[1,0,0]
	v_pk_fma_f32 v[134:135], v[126:127], v[134:135], s[38:39] op_sel_hi:[1,1,0]
	v_pk_fma_f32 v[202:203], v[200:201], s[22:23], v[138:139] op_sel_hi:[1,0,0]
	v_pk_fma_f32 v[134:135], v[126:127], v[134:135], s[40:41] op_sel_hi:[1,1,0]
	v_pk_mul_f32 v[142:143], v[142:143], s[42:43] op_sel_hi:[1,0]
	v_pk_fma_f32 v[202:203], v[200:201], v[202:203], s[36:37] op_sel_hi:[1,1,0]
	v_rcp_f32_e32 v206, v206
	v_rcp_f32_e32 v207, v207
	v_pk_mul_f32 v[126:127], v[126:127], v[134:135]
	v_pk_mul_f32 v[134:135], v[118:119], v[118:119]
	v_exp_f32_e32 v142, v142
	v_exp_f32_e32 v143, v143
	v_pk_fma_f32 v[202:203], v[200:201], v[202:203], s[38:39] op_sel_hi:[1,1,0]
	v_pk_mul_f32 v[134:135], v[134:135], s[42:43] op_sel_hi:[1,0]
	v_pk_fma_f32 v[202:203], v[200:201], v[202:203], s[40:41] op_sel_hi:[1,1,0]
	v_exp_f32_e32 v134, v134
	v_exp_f32_e32 v135, v135
	v_pk_mul_f32 v[200:201], v[200:201], v[202:203]
	v_pk_mul_f32 v[202:203], v[114:115], v[114:115]
	v_pk_fma_f32 v[138:139], v[206:207], s[22:23], v[138:139] op_sel_hi:[1,0,0]
	v_pk_mul_f32 v[202:203], v[202:203], s[42:43] op_sel_hi:[1,0]
	v_pk_mul_f32 v[194:195], v[120:121], v[120:121]
	v_pk_mul_f32 v[126:127], v[142:143], v[126:127]
	v_pk_fma_f32 v[138:139], v[206:207], v[138:139], s[36:37] op_sel_hi:[1,1,0]
	v_exp_f32_e32 v202, v202
	v_exp_f32_e32 v203, v203
	v_pk_mul_f32 v[194:195], v[194:195], s[42:43] op_sel_hi:[1,0]
	v_pk_mul_f32 v[142:143], v[116:117], v[126:127]
	v_pk_fma_f32 v[126:127], v[116:117], v[126:127], v[116:117] neg_lo:[1,0,0] neg_hi:[1,0,0]
	v_pk_mul_f32 v[204:205], v[112:113], v[112:113]
	v_pk_fma_f32 v[138:139], v[206:207], v[138:139], s[38:39] op_sel_hi:[1,1,0]
	v_cmp_gt_f32_e32 vcc, 0, v117
	v_exp_f32_e32 v194, v194
	v_exp_f32_e32 v195, v195
	v_pk_mul_f32 v[134:135], v[134:135], v[172:173]
	v_pk_mul_f32 v[204:205], v[204:205], s[42:43] op_sel_hi:[1,0]
	v_pk_fma_f32 v[138:139], v[206:207], v[138:139], s[40:41] op_sel_hi:[1,1,0]
	v_cndmask_b32_e32 v117, v127, v143, vcc
	v_cmp_gt_f32_e32 vcc, 0, v116
	v_pk_mul_f32 v[172:173], v[118:119], v[134:135]
	v_pk_fma_f32 v[134:135], v[118:119], v[134:135], v[118:119] neg_lo:[1,0,0] neg_hi:[1,0,0]
	v_exp_f32_e32 v204, v204
	v_exp_f32_e32 v205, v205
	v_pk_mul_f32 v[138:139], v[206:207], v[138:139]
	v_cndmask_b32_e32 v116, v126, v142, vcc
	v_cmp_gt_f32_e32 vcc, 0, v119
	v_pk_mul_f32 v[138:139], v[202:203], v[138:139]
	v_pk_mul_f32 v[174:175], v[194:195], v[174:175]
	v_cndmask_b32_e32 v119, v135, v173, vcc
	v_cmp_gt_f32_e32 vcc, 0, v118
	v_pk_mul_f32 v[202:203], v[114:115], v[138:139]
	v_pk_fma_f32 v[138:139], v[114:115], v[138:139], v[114:115] neg_lo:[1,0,0] neg_hi:[1,0,0]
	v_cndmask_b32_e32 v118, v134, v172, vcc
	v_cmp_gt_f32_e32 vcc, 0, v115
	v_pk_mul_f32 v[194:195], v[120:121], v[174:175]
	v_pk_fma_f32 v[174:175], v[120:121], v[174:175], v[120:121] neg_lo:[1,0,0] neg_hi:[1,0,0]
	v_cndmask_b32_e32 v139, v139, v203, vcc
	v_cmp_gt_f32_e32 vcc, 0, v114
	v_pk_mul_f32 v[200:201], v[204:205], v[200:201]
	v_mov_b32_e32 v134, v116
	v_cndmask_b32_e32 v138, v138, v202, vcc
	v_cmp_gt_f32_e32 vcc, 0, v120
	v_pk_mul_f32 v[204:205], v[112:113], v[200:201]
	v_pk_fma_f32 v[200:201], v[112:113], v[200:201], v[112:113] neg_lo:[1,0,0] neg_hi:[1,0,0]
	v_cndmask_b32_e32 v172, v174, v194, vcc
	v_cmp_gt_f32_e32 vcc, 0, v112
	v_mov_b32_e32 v135, v118
	v_mov_b32_e32 v142, v117
	v_cndmask_b32_e32 v173, v200, v204, vcc
	v_cmp_gt_f32_e32 vcc, 0, v121
	v_mov_b32_e32 v143, v119
	v_pk_add_f32 v[134:135], v[134:135], v[142:143]
	v_cndmask_b32_e32 v120, v175, v195, vcc
	v_cmp_gt_f32_e32 vcc, 0, v122
	v_mov_b32_e32 v174, v172
	v_mov_b32_e32 v175, v120
	v_cndmask_b32_e32 v123, v182, v196, vcc
	v_cmp_gt_f32_e32 vcc, 0, v113
	v_mul_f32_e32 v112, v172, v172
	v_mov_b32_e32 v122, v173
	v_cndmask_b32_e32 v182, v201, v205, vcc
	v_mov_b32_e32 v183, v123
	v_mul_f32_e32 v137, v198, v198
	v_pk_fma_f32 v[174:175], v[174:175], v[174:175], v[112:113] op_sel_hi:[1,1,0]
	v_pk_add_f32 v[112:113], v[122:123], v[182:183]
	v_pk_mul_f32 v[194:195], v[122:123], v[182:183]
	v_pk_add_f32 v[134:135], v[134:135], v[134:135] op_sel:[0,1] op_sel_hi:[1,0]
	v_mul_f32_e32 v126, v116, v116
	v_mov_b32_e32 v113, v195
	v_mov_b32_e32 v135, v137
	v_mov_b32_e32 v174, v138
	v_mov_b32_e32 v140, v139
	v_pk_fma_f32 v[126:127], v[116:117], v[116:117], v[126:127] op_sel_hi:[1,1,0]
	v_mov_b32_e32 v121, v173
	v_pk_add_f32 v[112:113], v[112:113], v[134:135]
	v_pk_add_f32 v[134:135], v[174:175], v[140:141]
	v_mul_f32_e32 v126, v118, v118
	v_pk_add_f32 v[112:113], v[112:113], v[134:135]
	v_pk_add_f32 v[134:135], v[172:173], v[120:121]
	v_pk_mul_f32 v[140:141], v[172:173], v[120:121]
	v_pk_fma_f32 v[142:143], v[118:119], v[118:119], v[126:127] op_sel_hi:[1,1,0]
	v_mov_b32_e32 v135, v141
	v_pk_mul_f32 v[140:141], v[182:183], v[182:183]
	v_mul_f32_e32 v114, v138, v138
	v_mov_b32_e32 v126, v123
	v_mov_b32_e32 v199, v143
	v_mov_b32_e32 v137, v140
	v_pk_fma_f32 v[114:115], v[138:139], v[138:139], v[114:115] op_sel_hi:[1,1,0]
	v_pk_add_f32 v[126:127], v[126:127], v[198:199]
	v_pk_add_f32 v[134:135], v[134:135], v[136:137]
	v_mov_b32_e32 v159, v115
	v_pk_add_f32 v[126:127], v[134:135], v[126:127]
	v_add_u32_e32 v128, 16, v166
	v_pk_add_f32 v[114:115], v[126:127], v[158:159]
	v_ashrrev_i32_e32 v129, 31, v128
	v_pk_add_f32 v[112:113], v[112:113], v[114:115]
	v_mov_b32_e32 v114, v112
	v_mov_b32_e32 v115, v113
	s_nop 1
	v_permlane16_swap_b32_e32 v114, v112
	v_permlane16_swap_b32_e32 v115, v113
	s_waitcnt lgkmcnt(2)
	v_lshlrev_b64 v[130:131], 13, v[128:129]
	v_lshl_add_u64 v[130:131], s[28:29], 0, v[130:131]
	v_lshl_add_u64 v[130:131], v[162:163], 1, v[130:131]
	v_cvt_pk_bf16_f32 v126, v172, v120
	s_waitcnt lgkmcnt(0)
	v_pk_add_f32 v[112:113], v[112:113], v[114:115]
	v_mov_b32_e32 v114, v112
	v_mov_b32_e32 v115, v113
	s_nop 1
	v_permlane32_swap_b32_e32 v114, v112
	v_permlane32_swap_b32_e32 v115, v113
	v_cvt_pk_bf16_f32 v127, v123, v198
	global_store_dwordx4 v[130:131], v[124:127], off
	v_cvt_pk_bf16_f32 v116, v116, v117
	v_cvt_pk_bf16_f32 v117, v118, v119
	v_cvt_pk_bf16_f32 v118, v173, v182
	v_cvt_pk_bf16_f32 v119, v138, v139
	global_store_dwordx4 v[130:131], v[116:119], off offset:256
	s_and_saveexec_b64 s[0:1], s[2:3]
	s_cbranch_execz .LBB0_269
	s_lshl_b32 s46, s60, 3
	s_waitcnt lgkmcnt(0)
	v_pk_add_f32 v[112:113], v[112:113], v[114:115]
	v_lshlrev_b64 v[114:115], 8, v[128:129]
	s_add_i32 s46, s46, s53
	v_lshl_add_u64 v[114:115], s[26:27], 0, v[114:115]
	s_ashr_i32 s47, s46, 31
	v_lshl_add_u64 v[114:115], s[46:47], 2, v[114:115]
	global_store_dwordx2 v[114:115], v[112:113], off
.LBB0_269:
	s_or_b64 exec, exec, s[0:1]
	v_pk_fma_f32 v[116:117], v[108:109], v[170:171], v[52:53] op_sel_hi:[1,0,1]
	v_pk_fma_f32 v[110:111], v[110:111], v[170:171], v[54:55] op_sel_hi:[1,0,1]
	v_and_b32_e32 v109, 0x7fffffff, v117
	v_and_b32_e32 v108, 0x7fffffff, v116
	v_pk_fma_f32 v[108:109], v[108:109], s[20:21], 1.0 op_sel_hi:[1,0,0]
	v_mov_b64_e32 v[118:119], s[34:35]
	v_rcp_f32_e32 v108, v108
	v_rcp_f32_e32 v109, v109
	v_pk_mul_f32 v[122:123], v[116:117], v[116:117]
	v_and_b32_e32 v125, 0x7fffffff, v111
	v_pk_mul_f32 v[122:123], v[122:123], s[42:43] op_sel_hi:[1,0]
	v_pk_fma_f32 v[120:121], v[108:109], s[22:23], v[118:119] op_sel_hi:[1,0,0]
	v_and_b32_e32 v124, 0x7fffffff, v110
	v_pk_fma_f32 v[120:121], v[108:109], v[120:121], s[36:37] op_sel_hi:[1,1,0]
	v_exp_f32_e32 v122, v122
	v_exp_f32_e32 v123, v123
	v_pk_fma_f32 v[124:125], v[124:125], s[20:21], 1.0 op_sel_hi:[1,0,0]
	v_pk_fma_f32 v[120:121], v[108:109], v[120:121], s[38:39] op_sel_hi:[1,1,0]
	v_rcp_f32_e32 v124, v124
	v_rcp_f32_e32 v125, v125
	v_pk_fma_f32 v[120:121], v[108:109], v[120:121], s[40:41] op_sel_hi:[1,1,0]
	v_pk_fma_f32 v[104:105], v[104:105], v[170:171], v[48:49] op_sel_hi:[1,0,1]
	v_pk_mul_f32 v[108:109], v[108:109], v[120:121]
	v_pk_mul_f32 v[120:121], v[110:111], v[110:111]
	v_pk_mul_f32 v[108:109], v[122:123], v[108:109]
	v_pk_mul_f32 v[120:121], v[120:121], s[42:43] op_sel_hi:[1,0]
	v_pk_mul_f32 v[122:123], v[116:117], v[108:109]
	v_pk_fma_f32 v[126:127], v[116:117], v[108:109], v[116:117] neg_lo:[1,0,0] neg_hi:[1,0,0]
	v_pk_fma_f32 v[108:109], v[124:125], s[22:23], v[118:119] op_sel_hi:[1,0,0]
	v_exp_f32_e32 v120, v120
	v_pk_fma_f32 v[108:109], v[124:125], v[108:109], s[36:37] op_sel_hi:[1,1,0]
	v_exp_f32_e32 v121, v121
	v_pk_fma_f32 v[108:109], v[124:125], v[108:109], s[38:39] op_sel_hi:[1,1,0]
	v_pk_fma_f32 v[106:107], v[106:107], v[170:171], v[50:51] op_sel_hi:[1,0,1]
	v_pk_fma_f32 v[108:109], v[124:125], v[108:109], s[40:41] op_sel_hi:[1,1,0]
	v_pk_mul_f32 v[130:131], v[104:105], v[104:105]
	v_pk_mul_f32 v[108:109], v[124:125], v[108:109]
	v_and_b32_e32 v125, 0x7fffffff, v105
	v_and_b32_e32 v124, 0x7fffffff, v104
	v_pk_fma_f32 v[124:125], v[124:125], s[20:21], 1.0 op_sel_hi:[1,0,0]
	v_pk_mul_f32 v[108:109], v[120:121], v[108:109]
	v_rcp_f32_e32 v124, v124
	v_rcp_f32_e32 v125, v125
	v_pk_mul_f32 v[120:121], v[110:111], v[108:109]
	v_pk_fma_f32 v[128:129], v[110:111], v[108:109], v[110:111] neg_lo:[1,0,0] neg_hi:[1,0,0]
	v_pk_mul_f32 v[130:131], v[130:131], s[42:43] op_sel_hi:[1,0]
	v_pk_fma_f32 v[108:109], v[124:125], s[22:23], v[118:119] op_sel_hi:[1,0,0]
	v_and_b32_e32 v135, 0x7fffffff, v107
	v_and_b32_e32 v134, 0x7fffffff, v106
	v_pk_fma_f32 v[108:109], v[124:125], v[108:109], s[36:37] op_sel_hi:[1,1,0]
	v_exp_f32_e32 v130, v130
	v_exp_f32_e32 v131, v131
	v_pk_fma_f32 v[134:135], v[134:135], s[20:21], 1.0 op_sel_hi:[1,0,0]
	v_pk_fma_f32 v[108:109], v[124:125], v[108:109], s[38:39] op_sel_hi:[1,1,0]
	v_rcp_f32_e32 v134, v134
	v_rcp_f32_e32 v135, v135
	v_pk_fma_f32 v[108:109], v[124:125], v[108:109], s[40:41] op_sel_hi:[1,1,0]
	v_cmp_gt_f32_e32 vcc, 0, v107
	v_pk_mul_f32 v[108:109], v[124:125], v[108:109]
	v_pk_mul_f32 v[124:125], v[106:107], v[106:107]
	v_pk_mul_f32 v[108:109], v[130:131], v[108:109]
	v_pk_mul_f32 v[124:125], v[124:125], s[42:43] op_sel_hi:[1,0]
	v_pk_mul_f32 v[130:131], v[104:105], v[108:109]
	v_pk_fma_f32 v[136:137], v[104:105], v[108:109], v[104:105] neg_lo:[1,0,0] neg_hi:[1,0,0]
	v_pk_fma_f32 v[108:109], v[134:135], s[22:23], v[118:119] op_sel_hi:[1,0,0]
	v_exp_f32_e32 v124, v124
	v_pk_fma_f32 v[108:109], v[134:135], v[108:109], s[36:37] op_sel_hi:[1,1,0]
	v_exp_f32_e32 v125, v125
	v_pk_fma_f32 v[108:109], v[134:135], v[108:109], s[38:39] op_sel_hi:[1,1,0]
	v_pk_fma_f32 v[102:103], v[102:103], v[170:171], v[46:47] op_sel_hi:[1,0,1]
	v_pk_fma_f32 v[108:109], v[134:135], v[108:109], s[40:41] op_sel_hi:[1,1,0]
	v_pk_fma_f32 v[100:101], v[100:101], v[170:171], v[44:45] op_sel_hi:[1,0,1]
	v_pk_mul_f32 v[108:109], v[134:135], v[108:109]
	v_pk_fma_f32 v[96:97], v[96:97], v[170:171], v[40:41] op_sel_hi:[1,0,1]
	v_pk_mul_f32 v[108:109], v[124:125], v[108:109]
	v_pk_fma_f32 v[98:99], v[98:99], v[170:171], v[42:43] op_sel_hi:[1,0,1]
	v_pk_mul_f32 v[124:125], v[106:107], v[108:109]
	v_pk_fma_f32 v[134:135], v[106:107], v[108:109], v[106:107] neg_lo:[1,0,0] neg_hi:[1,0,0]
	v_and_b32_e32 v175, 0x7fffffff, v99
	v_cndmask_b32_e32 v108, v135, v125, vcc
	v_cmp_gt_f32_e32 vcc, 0, v110
	v_and_b32_e32 v174, 0x7fffffff, v98
	v_pk_fma_f32 v[174:175], v[174:175], s[20:21], 1.0 op_sel_hi:[1,0,0]
	v_cndmask_b32_e32 v139, v128, v120, vcc
	v_cmp_gt_f32_e32 vcc, 0, v116
	v_rcp_f32_e32 v174, v174
	v_rcp_f32_e32 v175, v175
	v_cndmask_b32_e32 v138, v126, v122, vcc
	v_cmp_gt_f32_e32 vcc, 0, v111
	v_pk_mul_f32 v[172:173], v[96:97], v[96:97]
	v_mul_f32_e32 v109, v108, v108
	v_cndmask_b32_e32 v111, v129, v121, vcc
	v_cmp_gt_f32_e32 vcc, 0, v117
	v_pk_mul_f32 v[128:129], v[100:101], v[100:101]
	v_pk_mul_f32 v[172:173], v[172:173], s[42:43] op_sel_hi:[1,0]
	v_cndmask_b32_e32 v110, v127, v123, vcc
	v_pk_add_f32 v[116:117], v[138:139], v[110:111]
	v_pk_mul_f32 v[128:129], v[128:129], s[42:43] op_sel_hi:[1,0]
	v_pk_add_f32 v[120:121], v[116:117], v[116:117] op_sel:[0,1] op_sel_hi:[1,0]
	v_pk_mul_f32 v[116:117], v[110:111], v[110:111]
	v_exp_f32_e32 v128, v128
	v_pk_fma_f32 v[116:117], v[138:139], v[138:139], v[116:117]
	v_exp_f32_e32 v129, v129
	v_pk_add_f32 v[122:123], v[116:117], v[116:117] op_sel_hi:[0,1]
	v_cvt_pk_bf16_f32 v116, v138, v110
	v_cvt_pk_bf16_f32 v117, v139, v111
	v_and_b32_e32 v139, 0x7fffffff, v103
	v_and_b32_e32 v138, 0x7fffffff, v102
	v_pk_fma_f32 v[138:139], v[138:139], s[20:21], 1.0 op_sel_hi:[1,0,0]
	v_and_b32_e32 v111, 0x7fffffff, v101
	v_rcp_f32_e32 v138, v138
	v_rcp_f32_e32 v139, v139
	v_and_b32_e32 v110, 0x7fffffff, v100
	v_pk_fma_f32 v[110:111], v[110:111], s[20:21], 1.0 op_sel_hi:[1,0,0]
	v_cmp_gt_f32_e32 vcc, 0, v101
	v_pk_fma_f32 v[140:141], v[138:139], s[22:23], v[118:119] op_sel_hi:[1,0,0]
	v_rcp_f32_e32 v110, v110
	v_pk_fma_f32 v[140:141], v[138:139], v[140:141], s[36:37] op_sel_hi:[1,1,0]
	v_rcp_f32_e32 v111, v111
	v_pk_fma_f32 v[140:141], v[138:139], v[140:141], s[38:39] op_sel_hi:[1,1,0]
	v_exp_f32_e32 v172, v172
	v_pk_fma_f32 v[140:141], v[138:139], v[140:141], s[40:41] op_sel_hi:[1,1,0]
	v_pk_fma_f32 v[126:127], v[110:111], s[22:23], v[118:119] op_sel_hi:[1,0,0]
	v_pk_mul_f32 v[138:139], v[138:139], v[140:141]
	v_and_b32_e32 v141, 0x7fffffff, v97
	v_and_b32_e32 v140, 0x7fffffff, v96
	v_pk_fma_f32 v[140:141], v[140:141], s[20:21], 1.0 op_sel_hi:[1,0,0]
	v_pk_fma_f32 v[126:127], v[110:111], v[126:127], s[36:37] op_sel_hi:[1,1,0]
	v_rcp_f32_e32 v140, v140
	v_rcp_f32_e32 v141, v141
	v_pk_fma_f32 v[126:127], v[110:111], v[126:127], s[38:39] op_sel_hi:[1,1,0]
	v_exp_f32_e32 v173, v173
	v_pk_fma_f32 v[126:127], v[110:111], v[126:127], s[40:41] op_sel_hi:[1,1,0]
	v_pk_fma_f32 v[142:143], v[140:141], s[22:23], v[118:119] op_sel_hi:[1,0,0]
	v_pk_mul_f32 v[110:111], v[110:111], v[126:127]
	v_pk_fma_f32 v[142:143], v[140:141], v[142:143], s[36:37] op_sel_hi:[1,1,0]
	v_pk_mul_f32 v[126:127], v[102:103], v[102:103]
	v_pk_fma_f32 v[142:143], v[140:141], v[142:143], s[38:39] op_sel_hi:[1,1,0]
	v_pk_mul_f32 v[126:127], v[126:127], s[42:43] op_sel_hi:[1,0]
	v_pk_fma_f32 v[142:143], v[140:141], v[142:143], s[40:41] op_sel_hi:[1,1,0]
	v_exp_f32_e32 v126, v126
	v_exp_f32_e32 v127, v127
	v_pk_mul_f32 v[140:141], v[140:141], v[142:143]
	v_pk_mul_f32 v[142:143], v[98:99], v[98:99]
	v_pk_fma_f32 v[118:119], v[174:175], s[22:23], v[118:119] op_sel_hi:[1,0,0]
	v_pk_mul_f32 v[142:143], v[142:143], s[42:43] op_sel_hi:[1,0]
	v_pk_mul_f32 v[110:111], v[128:129], v[110:111]
	v_pk_fma_f32 v[118:119], v[174:175], v[118:119], s[36:37] op_sel_hi:[1,1,0]
	v_exp_f32_e32 v142, v142
	v_exp_f32_e32 v143, v143
	v_pk_mul_f32 v[128:129], v[100:101], v[110:111]
	v_pk_fma_f32 v[110:111], v[100:101], v[110:111], v[100:101] neg_lo:[1,0,0] neg_hi:[1,0,0]
	v_pk_fma_f32 v[118:119], v[174:175], v[118:119], s[38:39] op_sel_hi:[1,1,0]
	v_pk_mul_f32 v[126:127], v[126:127], v[138:139]
	v_pk_fma_f32 v[118:119], v[174:175], v[118:119], s[40:41] op_sel_hi:[1,1,0]
	v_cndmask_b32_e32 v101, v111, v129, vcc
	v_cmp_gt_f32_e32 vcc, 0, v100
	v_pk_mul_f32 v[138:139], v[102:103], v[126:127]
	v_pk_fma_f32 v[126:127], v[102:103], v[126:127], v[102:103] neg_lo:[1,0,0] neg_hi:[1,0,0]
	v_pk_mul_f32 v[118:119], v[174:175], v[118:119]
	v_cndmask_b32_e32 v100, v110, v128, vcc
	v_cmp_gt_f32_e32 vcc, 0, v103
	v_pk_mul_f32 v[118:119], v[142:143], v[118:119]
	v_pk_mul_f32 v[140:141], v[172:173], v[140:141]
	v_cndmask_b32_e32 v103, v127, v139, vcc
	v_cmp_gt_f32_e32 vcc, 0, v102
	v_pk_mul_f32 v[142:143], v[98:99], v[118:119]
	v_pk_fma_f32 v[118:119], v[98:99], v[118:119], v[98:99] neg_lo:[1,0,0] neg_hi:[1,0,0]
	v_cndmask_b32_e32 v102, v126, v138, vcc
	v_cmp_gt_f32_e32 vcc, 0, v99
	v_pk_mul_f32 v[172:173], v[96:97], v[140:141]
	v_pk_fma_f32 v[140:141], v[96:97], v[140:141], v[96:97] neg_lo:[1,0,0] neg_hi:[1,0,0]
	v_cndmask_b32_e32 v139, v119, v143, vcc
	v_cmp_gt_f32_e32 vcc, 0, v98
	v_mov_b32_e32 v126, v100
	v_mov_b32_e32 v127, v102
	v_cndmask_b32_e32 v138, v118, v142, vcc
	v_cmp_gt_f32_e32 vcc, 0, v104
	v_mov_b32_e32 v128, v101
	v_mov_b32_e32 v129, v103
	v_cndmask_b32_e32 v142, v136, v130, vcc
	v_cmp_gt_f32_e32 vcc, 0, v96
	v_pk_add_f32 v[126:127], v[126:127], v[128:129]
	v_mov_b32_e32 v118, v142
	v_cndmask_b32_e32 v143, v140, v172, vcc
	v_cmp_gt_f32_e32 vcc, 0, v105
	v_mul_f32_e32 v96, v142, v142
	v_pk_add_f32 v[126:127], v[126:127], v[126:127] op_sel:[0,1] op_sel_hi:[1,0]
	v_cndmask_b32_e32 v104, v137, v131, vcc
	v_cmp_gt_f32_e32 vcc, 0, v106
	v_mov_b32_e32 v119, v104
	v_mov_b32_e32 v106, v143
	v_cndmask_b32_e32 v107, v134, v124, vcc
	v_cmp_gt_f32_e32 vcc, 0, v97
	v_mov_b32_e32 v125, v107
	v_pk_fma_f32 v[118:119], v[118:119], v[118:119], v[96:97] op_sel_hi:[1,1,0]
	v_cndmask_b32_e32 v124, v141, v173, vcc
	v_pk_add_f32 v[96:97], v[106:107], v[124:125]
	v_pk_mul_f32 v[130:131], v[106:107], v[124:125]
	v_mul_f32_e32 v110, v100, v100
	v_mov_b32_e32 v97, v131
	v_mov_b32_e32 v127, v109
	v_mov_b32_e32 v118, v138
	v_mov_b32_e32 v122, v139
	v_pk_fma_f32 v[110:111], v[100:101], v[100:101], v[110:111] op_sel_hi:[1,1,0]
	v_mov_b32_e32 v105, v143
	v_pk_add_f32 v[96:97], v[96:97], v[126:127]
	v_pk_add_f32 v[118:119], v[118:119], v[122:123]
	v_mul_f32_e32 v110, v102, v102
	v_pk_add_f32 v[96:97], v[96:97], v[118:119]
	v_pk_add_f32 v[118:119], v[142:143], v[104:105]
	v_pk_mul_f32 v[122:123], v[142:143], v[104:105]
	v_pk_fma_f32 v[128:129], v[102:103], v[102:103], v[110:111] op_sel_hi:[1,1,0]
	v_mov_b32_e32 v119, v123
	v_pk_mul_f32 v[122:123], v[124:125], v[124:125]
	v_mul_f32_e32 v98, v138, v138
	v_mov_b32_e32 v110, v107
	v_mov_b32_e32 v109, v129
	v_mov_b32_e32 v121, v122
	v_pk_fma_f32 v[98:99], v[138:139], v[138:139], v[98:99] op_sel_hi:[1,1,0]
	v_pk_add_f32 v[110:111], v[110:111], v[108:109]
	v_pk_add_f32 v[118:119], v[118:119], v[120:121]
	v_mov_b32_e32 v159, v99
	v_pk_add_f32 v[110:111], v[118:119], v[110:111]
	v_add_u32_e32 v112, 32, v166
	v_pk_add_f32 v[98:99], v[110:111], v[158:159]
	v_ashrrev_i32_e32 v113, 31, v112
	v_pk_add_f32 v[96:97], v[96:97], v[98:99]
	v_mov_b32_e32 v98, v96
	v_mov_b32_e32 v99, v97
	s_nop 1
	v_permlane16_swap_b32_e32 v98, v96
	v_permlane16_swap_b32_e32 v99, v97
	s_waitcnt lgkmcnt(2)
	v_lshlrev_b64 v[114:115], 13, v[112:113]
	v_lshl_add_u64 v[114:115], s[28:29], 0, v[114:115]
	v_lshl_add_u64 v[114:115], v[162:163], 1, v[114:115]
	v_cvt_pk_bf16_f32 v118, v142, v104
	s_waitcnt lgkmcnt(0)
	v_pk_add_f32 v[96:97], v[96:97], v[98:99]
	v_mov_b32_e32 v98, v96
	v_mov_b32_e32 v99, v97
	s_nop 1
	v_permlane32_swap_b32_e32 v98, v96
	v_permlane32_swap_b32_e32 v99, v97
	v_cvt_pk_bf16_f32 v119, v107, v108
	global_store_dwordx4 v[114:115], v[116:119], off
	v_cvt_pk_bf16_f32 v100, v100, v101
	v_cvt_pk_bf16_f32 v101, v102, v103
	v_cvt_pk_bf16_f32 v102, v143, v124
	v_cvt_pk_bf16_f32 v103, v138, v139
	global_store_dwordx4 v[114:115], v[100:103], off offset:256
	s_and_saveexec_b64 s[0:1], s[2:3]
	s_cbranch_execz .LBB0_271
	s_lshl_b32 s46, s60, 3
	s_waitcnt lgkmcnt(0)
	v_pk_add_f32 v[96:97], v[96:97], v[98:99]
	v_lshlrev_b64 v[98:99], 8, v[112:113]
	s_add_i32 s46, s46, s53
	v_lshl_add_u64 v[98:99], s[26:27], 0, v[98:99]
	s_ashr_i32 s47, s46, 31
	v_lshl_add_u64 v[98:99], s[46:47], 2, v[98:99]
	global_store_dwordx2 v[98:99], v[96:97], off
.LBB0_271:
	s_or_b64 exec, exec, s[0:1]
	v_mov_b32_e32 v100, v171
	v_pk_fma_f32 v[94:95], v[94:95], v[100:101], v[54:55] op_sel_hi:[1,0,1]
	v_mov_b64_e32 v[104:105], s[34:35]
	v_and_b32_e32 v111, 0x7fffffff, v95
	v_and_b32_e32 v110, 0x7fffffff, v94
	v_pk_fma_f32 v[110:111], v[110:111], s[20:21], 1.0 op_sel_hi:[1,0,0]
	v_pk_fma_f32 v[88:89], v[88:89], v[100:101], v[48:49] op_sel_hi:[1,0,1]
	v_rcp_f32_e32 v110, v110
	v_rcp_f32_e32 v111, v111
	v_pk_fma_f32 v[92:93], v[92:93], v[100:101], v[52:53] op_sel_hi:[1,0,1]
	v_pk_fma_f32 v[90:91], v[90:91], v[100:101], v[50:51] op_sel_hi:[1,0,1]
	v_and_b32_e32 v103, 0x7fffffff, v93
	v_pk_fma_f32 v[112:113], v[110:111], s[22:23], v[104:105] op_sel_hi:[1,0,0]
	v_and_b32_e32 v102, 0x7fffffff, v92
	v_pk_fma_f32 v[112:113], v[110:111], v[112:113], s[36:37] op_sel_hi:[1,1,0]
	v_pk_fma_f32 v[102:103], v[102:103], s[20:21], 1.0 op_sel_hi:[1,0,0]
	v_pk_fma_f32 v[112:113], v[110:111], v[112:113], s[38:39] op_sel_hi:[1,1,0]
	v_rcp_f32_e32 v102, v102
	v_pk_fma_f32 v[112:113], v[110:111], v[112:113], s[40:41] op_sel_hi:[1,1,0]
	v_rcp_f32_e32 v103, v103
	v_pk_mul_f32 v[110:111], v[110:111], v[112:113]
	v_and_b32_e32 v113, 0x7fffffff, v89
	v_and_b32_e32 v112, 0x7fffffff, v88
	v_pk_fma_f32 v[112:113], v[112:113], s[20:21], 1.0 op_sel_hi:[1,0,0]
	v_and_b32_e32 v119, 0x7fffffff, v91
	v_rcp_f32_e32 v112, v112
	v_rcp_f32_e32 v113, v113
	v_and_b32_e32 v118, 0x7fffffff, v90
	v_pk_fma_f32 v[118:119], v[118:119], s[20:21], 1.0 op_sel_hi:[1,0,0]
	v_pk_fma_f32 v[106:107], v[102:103], s[22:23], v[104:105] op_sel_hi:[1,0,0]
	v_pk_fma_f32 v[114:115], v[112:113], s[22:23], v[104:105] op_sel_hi:[1,0,0]
	v_rcp_f32_e32 v118, v118
	v_pk_fma_f32 v[114:115], v[112:113], v[114:115], s[36:37] op_sel_hi:[1,1,0]
	v_rcp_f32_e32 v119, v119
	v_pk_fma_f32 v[106:107], v[102:103], v[106:107], s[36:37] op_sel_hi:[1,1,0]
	v_pk_fma_f32 v[114:115], v[112:113], v[114:115], s[38:39] op_sel_hi:[1,1,0]
	v_pk_fma_f32 v[106:107], v[102:103], v[106:107], s[38:39] op_sel_hi:[1,1,0]
	v_pk_fma_f32 v[114:115], v[112:113], v[114:115], s[40:41] op_sel_hi:[1,1,0]
	v_pk_fma_f32 v[106:107], v[102:103], v[106:107], s[40:41] op_sel_hi:[1,1,0]
	v_pk_mul_f32 v[112:113], v[112:113], v[114:115]
	v_pk_mul_f32 v[114:115], v[90:91], v[90:91]
	v_pk_mul_f32 v[102:103], v[102:103], v[106:107]
	v_pk_mul_f32 v[106:107], v[94:95], v[94:95]
	v_pk_fma_f32 v[120:121], v[118:119], s[22:23], v[104:105] op_sel_hi:[1,0,0]
	v_pk_mul_f32 v[114:115], v[114:115], s[42:43] op_sel_hi:[1,0]
	v_pk_mul_f32 v[108:109], v[92:93], v[92:93]
	v_pk_mul_f32 v[106:107], v[106:107], s[42:43] op_sel_hi:[1,0]
	v_pk_fma_f32 v[120:121], v[118:119], v[120:121], s[36:37] op_sel_hi:[1,1,0]
	v_exp_f32_e32 v114, v114
	v_exp_f32_e32 v115, v115
	v_pk_mul_f32 v[108:109], v[108:109], s[42:43] op_sel_hi:[1,0]
	v_exp_f32_e32 v106, v106
	v_exp_f32_e32 v107, v107
	v_pk_fma_f32 v[120:121], v[118:119], v[120:121], s[38:39] op_sel_hi:[1,1,0]
	v_exp_f32_e32 v108, v108
	v_exp_f32_e32 v109, v109
	v_pk_fma_f32 v[120:121], v[118:119], v[120:121], s[40:41] op_sel_hi:[1,1,0]
	v_pk_mul_f32 v[106:107], v[106:107], v[110:111]
	v_pk_mul_f32 v[118:119], v[118:119], v[120:121]
	v_cmp_gt_f32_e32 vcc, 0, v91
	v_pk_mul_f32 v[114:115], v[114:115], v[118:119]
	v_pk_mul_f32 v[102:103], v[108:109], v[102:103]
	v_pk_mul_f32 v[118:119], v[90:91], v[114:115]
	v_pk_fma_f32 v[114:115], v[90:91], v[114:115], v[90:91] neg_lo:[1,0,0] neg_hi:[1,0,0]
	v_pk_mul_f32 v[110:111], v[94:95], v[106:107]
	v_pk_fma_f32 v[106:107], v[94:95], v[106:107], v[94:95] neg_lo:[1,0,0] neg_hi:[1,0,0]
	v_cndmask_b32_e32 v120, v115, v119, vcc
	v_cmp_gt_f32_e32 vcc, 0, v94
	v_pk_mul_f32 v[108:109], v[92:93], v[102:103]
	v_pk_fma_f32 v[102:103], v[92:93], v[102:103], v[92:93] neg_lo:[1,0,0] neg_hi:[1,0,0]
	v_cndmask_b32_e32 v123, v106, v110, vcc
	v_cmp_gt_f32_e32 vcc, 0, v92
	v_pk_fma_f32 v[86:87], v[86:87], v[100:101], v[46:47] op_sel_hi:[1,0,1]
	v_pk_fma_f32 v[84:85], v[84:85], v[100:101], v[44:45] op_sel_hi:[1,0,1]
	v_cndmask_b32_e32 v122, v102, v108, vcc
	v_cmp_gt_f32_e32 vcc, 0, v95
	v_and_b32_e32 v110, 0x7fffffff, v86
	v_pk_fma_f32 v[80:81], v[80:81], v[100:101], v[40:41] op_sel_hi:[1,0,1]
	v_cndmask_b32_e32 v95, v107, v111, vcc
	v_and_b32_e32 v111, 0x7fffffff, v87
	v_cmp_gt_f32_e32 vcc, 0, v93
	v_pk_fma_f32 v[110:111], v[110:111], s[20:21], 1.0 op_sel_hi:[1,0,0]
	v_pk_fma_f32 v[82:83], v[82:83], v[100:101], v[42:43] op_sel_hi:[1,0,1]
	v_cndmask_b32_e32 v94, v103, v109, vcc
	v_rcp_f32_e32 v110, v110
	v_rcp_f32_e32 v111, v111
	v_pk_add_f32 v[92:93], v[122:123], v[94:95]
	v_and_b32_e32 v129, 0x7fffffff, v83
	v_pk_add_f32 v[102:103], v[92:93], v[92:93] op_sel:[0,1] op_sel_hi:[1,0]
	v_pk_mul_f32 v[92:93], v[94:95], v[94:95]
	v_and_b32_e32 v128, 0x7fffffff, v82
	v_pk_fma_f32 v[92:93], v[122:123], v[122:123], v[92:93]
	v_pk_mul_f32 v[108:109], v[84:85], v[84:85]
	v_pk_add_f32 v[106:107], v[92:93], v[92:93] op_sel_hi:[0,1]
	v_cvt_pk_bf16_f32 v92, v122, v94
	v_cvt_pk_bf16_f32 v93, v123, v95
	v_pk_fma_f32 v[122:123], v[110:111], s[22:23], v[104:105] op_sel_hi:[1,0,0]
	v_and_b32_e32 v95, 0x7fffffff, v85
	v_pk_fma_f32 v[122:123], v[110:111], v[122:123], s[36:37] op_sel_hi:[1,1,0]
	v_and_b32_e32 v94, 0x7fffffff, v84
	v_pk_fma_f32 v[122:123], v[110:111], v[122:123], s[38:39] op_sel_hi:[1,1,0]
	v_pk_fma_f32 v[94:95], v[94:95], s[20:21], 1.0 op_sel_hi:[1,0,0]
	v_pk_fma_f32 v[122:123], v[110:111], v[122:123], s[40:41] op_sel_hi:[1,1,0]
	v_rcp_f32_e32 v94, v94
	v_rcp_f32_e32 v95, v95
	v_pk_mul_f32 v[110:111], v[110:111], v[122:123]
	v_and_b32_e32 v123, 0x7fffffff, v81
	v_and_b32_e32 v122, 0x7fffffff, v80
	v_pk_fma_f32 v[122:123], v[122:123], s[20:21], 1.0 op_sel_hi:[1,0,0]
	v_pk_fma_f32 v[100:101], v[94:95], s[22:23], v[104:105] op_sel_hi:[1,0,0]
	v_rcp_f32_e32 v122, v122
	v_rcp_f32_e32 v123, v123
	v_pk_fma_f32 v[100:101], v[94:95], v[100:101], s[36:37] op_sel_hi:[1,1,0]
	v_pk_fma_f32 v[128:129], v[128:129], s[20:21], 1.0 op_sel_hi:[1,0,0]
	v_pk_fma_f32 v[100:101], v[94:95], v[100:101], s[38:39] op_sel_hi:[1,1,0]
	v_pk_fma_f32 v[124:125], v[122:123], s[22:23], v[104:105] op_sel_hi:[1,0,0]
	v_pk_fma_f32 v[100:101], v[94:95], v[100:101], s[40:41] op_sel_hi:[1,1,0]
	v_pk_mul_f32 v[108:109], v[108:109], s[42:43] op_sel_hi:[1,0]
	v_pk_fma_f32 v[124:125], v[122:123], v[124:125], s[36:37] op_sel_hi:[1,1,0]
	v_rcp_f32_e32 v128, v128
	v_rcp_f32_e32 v129, v129
	v_pk_mul_f32 v[94:95], v[94:95], v[100:101]
	v_pk_mul_f32 v[100:101], v[86:87], v[86:87]
	v_exp_f32_e32 v108, v108
	v_exp_f32_e32 v109, v109
	v_pk_fma_f32 v[124:125], v[122:123], v[124:125], s[38:39] op_sel_hi:[1,1,0]
	v_pk_mul_f32 v[100:101], v[100:101], s[42:43] op_sel_hi:[1,0]
	v_pk_fma_f32 v[124:125], v[122:123], v[124:125], s[40:41] op_sel_hi:[1,1,0]
	v_exp_f32_e32 v100, v100
	v_exp_f32_e32 v101, v101
	v_pk_mul_f32 v[122:123], v[122:123], v[124:125]
	v_pk_mul_f32 v[124:125], v[82:83], v[82:83]
	v_pk_fma_f32 v[104:105], v[128:129], s[22:23], v[104:105] op_sel_hi:[1,0,0]
	v_pk_mul_f32 v[124:125], v[124:125], s[42:43] op_sel_hi:[1,0]
	v_pk_mul_f32 v[116:117], v[88:89], v[88:89]
	v_pk_mul_f32 v[94:95], v[108:109], v[94:95]
	v_pk_fma_f32 v[104:105], v[128:129], v[104:105], s[36:37] op_sel_hi:[1,1,0]
	v_exp_f32_e32 v124, v124
	v_exp_f32_e32 v125, v125
	v_pk_mul_f32 v[116:117], v[116:117], s[42:43] op_sel_hi:[1,0]
	v_pk_mul_f32 v[108:109], v[84:85], v[94:95]
	v_pk_fma_f32 v[94:95], v[84:85], v[94:95], v[84:85] neg_lo:[1,0,0] neg_hi:[1,0,0]
	v_pk_mul_f32 v[126:127], v[80:81], v[80:81]
	v_pk_fma_f32 v[104:105], v[128:129], v[104:105], s[38:39] op_sel_hi:[1,1,0]
	v_cmp_gt_f32_e32 vcc, 0, v85
	v_exp_f32_e32 v116, v116
	v_exp_f32_e32 v117, v117
	v_pk_mul_f32 v[100:101], v[100:101], v[110:111]
	v_pk_mul_f32 v[126:127], v[126:127], s[42:43] op_sel_hi:[1,0]
	v_pk_fma_f32 v[104:105], v[128:129], v[104:105], s[40:41] op_sel_hi:[1,1,0]
	v_cndmask_b32_e32 v85, v95, v109, vcc
	v_cmp_gt_f32_e32 vcc, 0, v84
	v_pk_mul_f32 v[110:111], v[86:87], v[100:101]
	v_pk_fma_f32 v[100:101], v[86:87], v[100:101], v[86:87] neg_lo:[1,0,0] neg_hi:[1,0,0]
	v_exp_f32_e32 v126, v126
	v_exp_f32_e32 v127, v127
	v_pk_mul_f32 v[104:105], v[128:129], v[104:105]
	v_cndmask_b32_e32 v84, v94, v108, vcc
	v_cmp_gt_f32_e32 vcc, 0, v87
	v_pk_mul_f32 v[104:105], v[124:125], v[104:105]
	v_pk_mul_f32 v[112:113], v[116:117], v[112:113]
	v_cndmask_b32_e32 v87, v101, v111, vcc
	v_cmp_gt_f32_e32 vcc, 0, v86
	v_pk_mul_f32 v[124:125], v[82:83], v[104:105]
	v_pk_fma_f32 v[104:105], v[82:83], v[104:105], v[82:83] neg_lo:[1,0,0] neg_hi:[1,0,0]
	v_cndmask_b32_e32 v86, v100, v110, vcc
	v_cmp_gt_f32_e32 vcc, 0, v83
	v_pk_mul_f32 v[116:117], v[88:89], v[112:113]
	v_pk_fma_f32 v[112:113], v[88:89], v[112:113], v[88:89] neg_lo:[1,0,0] neg_hi:[1,0,0]
	v_cndmask_b32_e32 v105, v105, v125, vcc
	v_cmp_gt_f32_e32 vcc, 0, v82
	v_pk_mul_f32 v[122:123], v[126:127], v[122:123]
	v_mov_b32_e32 v100, v84
	v_cndmask_b32_e32 v104, v104, v124, vcc
	v_cmp_gt_f32_e32 vcc, 0, v88
	v_pk_mul_f32 v[126:127], v[80:81], v[122:123]
	v_pk_fma_f32 v[122:123], v[80:81], v[122:123], v[80:81] neg_lo:[1,0,0] neg_hi:[1,0,0]
	v_cndmask_b32_e32 v110, v112, v116, vcc
	v_cmp_gt_f32_e32 vcc, 0, v80
	v_mov_b32_e32 v101, v86
	v_mov_b32_e32 v108, v85
	v_cndmask_b32_e32 v111, v122, v126, vcc
	v_cmp_gt_f32_e32 vcc, 0, v89
	v_mov_b32_e32 v109, v87
	v_pk_add_f32 v[100:101], v[100:101], v[108:109]
	v_cndmask_b32_e32 v88, v113, v117, vcc
	v_cmp_gt_f32_e32 vcc, 0, v90
	v_mov_b32_e32 v112, v110
	v_mov_b32_e32 v113, v88
	v_cndmask_b32_e32 v91, v114, v118, vcc
	v_cmp_gt_f32_e32 vcc, 0, v81
	v_mul_f32_e32 v80, v110, v110
	v_mov_b32_e32 v90, v111
	v_cndmask_b32_e32 v114, v123, v127, vcc
	v_mov_b32_e32 v115, v91
	v_mul_f32_e32 v103, v120, v120
	v_pk_fma_f32 v[112:113], v[112:113], v[112:113], v[80:81] op_sel_hi:[1,1,0]
	v_pk_add_f32 v[80:81], v[90:91], v[114:115]
	v_pk_mul_f32 v[116:117], v[90:91], v[114:115]
	v_pk_add_f32 v[100:101], v[100:101], v[100:101] op_sel:[0,1] op_sel_hi:[1,0]
	v_mul_f32_e32 v94, v84, v84
	v_mov_b32_e32 v81, v117
	v_mov_b32_e32 v101, v103
	v_mov_b32_e32 v112, v104
	v_mov_b32_e32 v106, v105
	v_pk_fma_f32 v[94:95], v[84:85], v[84:85], v[94:95] op_sel_hi:[1,1,0]
	v_mov_b32_e32 v89, v111
	v_pk_add_f32 v[80:81], v[80:81], v[100:101]
	v_pk_add_f32 v[100:101], v[112:113], v[106:107]
	v_mul_f32_e32 v94, v86, v86
	v_pk_add_f32 v[80:81], v[80:81], v[100:101]
	v_pk_add_f32 v[100:101], v[110:111], v[88:89]
	v_pk_mul_f32 v[106:107], v[110:111], v[88:89]
	v_pk_fma_f32 v[108:109], v[86:87], v[86:87], v[94:95] op_sel_hi:[1,1,0]
	v_mov_b32_e32 v101, v107
	v_pk_mul_f32 v[106:107], v[114:115], v[114:115]
	v_mul_f32_e32 v82, v104, v104
	v_mov_b32_e32 v94, v91
	v_mov_b32_e32 v121, v109
	v_mov_b32_e32 v103, v106
	v_pk_fma_f32 v[82:83], v[104:105], v[104:105], v[82:83] op_sel_hi:[1,1,0]
	v_pk_add_f32 v[94:95], v[94:95], v[120:121]
	v_pk_add_f32 v[100:101], v[100:101], v[102:103]
	v_mov_b32_e32 v159, v83
	v_pk_add_f32 v[94:95], v[100:101], v[94:95]
	v_add_u32_e32 v96, 48, v166
	v_pk_add_f32 v[82:83], v[94:95], v[158:159]
	v_ashrrev_i32_e32 v97, 31, v96
	v_pk_add_f32 v[80:81], v[80:81], v[82:83]
	v_mov_b32_e32 v82, v80
	v_mov_b32_e32 v83, v81
	s_nop 1
	v_permlane16_swap_b32_e32 v82, v80
	v_permlane16_swap_b32_e32 v83, v81
	s_waitcnt lgkmcnt(2)
	v_lshlrev_b64 v[98:99], 13, v[96:97]
	v_lshl_add_u64 v[98:99], s[28:29], 0, v[98:99]
	v_lshl_add_u64 v[98:99], v[162:163], 1, v[98:99]
	v_cvt_pk_bf16_f32 v94, v110, v88
	s_waitcnt lgkmcnt(0)
	v_pk_add_f32 v[80:81], v[80:81], v[82:83]
	v_mov_b32_e32 v82, v80
	v_mov_b32_e32 v83, v81
	s_nop 1
	v_permlane32_swap_b32_e32 v82, v80
	v_permlane32_swap_b32_e32 v83, v81
	v_cvt_pk_bf16_f32 v95, v91, v120
	global_store_dwordx4 v[98:99], v[92:95], off
	v_cvt_pk_bf16_f32 v84, v84, v85
	v_cvt_pk_bf16_f32 v85, v86, v87
	v_cvt_pk_bf16_f32 v86, v111, v114
	v_cvt_pk_bf16_f32 v87, v104, v105
	global_store_dwordx4 v[98:99], v[84:87], off offset:256
	s_and_saveexec_b64 s[0:1], s[2:3]
	s_cbranch_execz .LBB0_273
	s_lshl_b32 s46, s60, 3
	s_waitcnt lgkmcnt(0)
	v_pk_add_f32 v[80:81], v[80:81], v[82:83]
	v_lshlrev_b64 v[82:83], 8, v[96:97]
	s_add_i32 s46, s46, s53
	v_lshl_add_u64 v[82:83], s[26:27], 0, v[82:83]
	s_ashr_i32 s47, s46, 31
	v_lshl_add_u64 v[82:83], s[46:47], 2, v[82:83]
	global_store_dwordx2 v[82:83], v[80:81], off
.LBB0_273:
	s_or_b64 exec, exec, s[0:1]
	v_pk_fma_f32 v[84:85], v[76:77], v[168:169], v[52:53] op_sel_hi:[1,0,1]
	v_pk_fma_f32 v[78:79], v[78:79], v[168:169], v[54:55] op_sel_hi:[1,0,1]
	v_and_b32_e32 v77, 0x7fffffff, v85
	v_and_b32_e32 v76, 0x7fffffff, v84
	v_pk_fma_f32 v[76:77], v[76:77], s[20:21], 1.0 op_sel_hi:[1,0,0]
	v_mov_b64_e32 v[86:87], s[34:35]
	v_rcp_f32_e32 v76, v76
	v_rcp_f32_e32 v77, v77
	v_pk_mul_f32 v[90:91], v[84:85], v[84:85]
	v_and_b32_e32 v93, 0x7fffffff, v79
	v_pk_mul_f32 v[90:91], v[90:91], s[42:43] op_sel_hi:[1,0]
	v_pk_fma_f32 v[88:89], v[76:77], s[22:23], v[86:87] op_sel_hi:[1,0,0]
	v_and_b32_e32 v92, 0x7fffffff, v78
	v_pk_fma_f32 v[88:89], v[76:77], v[88:89], s[36:37] op_sel_hi:[1,1,0]
	v_exp_f32_e32 v90, v90
	v_exp_f32_e32 v91, v91
	v_pk_fma_f32 v[92:93], v[92:93], s[20:21], 1.0 op_sel_hi:[1,0,0]
	v_pk_fma_f32 v[88:89], v[76:77], v[88:89], s[38:39] op_sel_hi:[1,1,0]
	v_rcp_f32_e32 v92, v92
	v_rcp_f32_e32 v93, v93
	v_pk_fma_f32 v[88:89], v[76:77], v[88:89], s[40:41] op_sel_hi:[1,1,0]
	v_pk_fma_f32 v[72:73], v[72:73], v[168:169], v[48:49] op_sel_hi:[1,0,1]
	v_pk_mul_f32 v[76:77], v[76:77], v[88:89]
	v_pk_mul_f32 v[88:89], v[78:79], v[78:79]
	v_pk_mul_f32 v[76:77], v[90:91], v[76:77]
	v_pk_mul_f32 v[88:89], v[88:89], s[42:43] op_sel_hi:[1,0]
	v_pk_mul_f32 v[90:91], v[84:85], v[76:77]
	v_pk_fma_f32 v[94:95], v[84:85], v[76:77], v[84:85] neg_lo:[1,0,0] neg_hi:[1,0,0]
	v_pk_fma_f32 v[76:77], v[92:93], s[22:23], v[86:87] op_sel_hi:[1,0,0]
	v_exp_f32_e32 v88, v88
	v_pk_fma_f32 v[76:77], v[92:93], v[76:77], s[36:37] op_sel_hi:[1,1,0]
	v_exp_f32_e32 v89, v89
	v_pk_fma_f32 v[76:77], v[92:93], v[76:77], s[38:39] op_sel_hi:[1,1,0]
	v_pk_fma_f32 v[74:75], v[74:75], v[168:169], v[50:51] op_sel_hi:[1,0,1]
	v_pk_fma_f32 v[76:77], v[92:93], v[76:77], s[40:41] op_sel_hi:[1,1,0]
	v_pk_mul_f32 v[98:99], v[72:73], v[72:73]
	v_pk_mul_f32 v[76:77], v[92:93], v[76:77]
	v_and_b32_e32 v93, 0x7fffffff, v73
	v_and_b32_e32 v92, 0x7fffffff, v72
	v_pk_fma_f32 v[92:93], v[92:93], s[20:21], 1.0 op_sel_hi:[1,0,0]
	v_pk_mul_f32 v[76:77], v[88:89], v[76:77]
	v_rcp_f32_e32 v92, v92
	v_rcp_f32_e32 v93, v93
	v_pk_mul_f32 v[88:89], v[78:79], v[76:77]
	v_pk_fma_f32 v[96:97], v[78:79], v[76:77], v[78:79] neg_lo:[1,0,0] neg_hi:[1,0,0]
	v_pk_mul_f32 v[98:99], v[98:99], s[42:43] op_sel_hi:[1,0]
	v_pk_fma_f32 v[76:77], v[92:93], s[22:23], v[86:87] op_sel_hi:[1,0,0]
	v_and_b32_e32 v101, 0x7fffffff, v75
	v_and_b32_e32 v100, 0x7fffffff, v74
	v_pk_fma_f32 v[76:77], v[92:93], v[76:77], s[36:37] op_sel_hi:[1,1,0]
	v_exp_f32_e32 v98, v98
	v_exp_f32_e32 v99, v99
	v_pk_fma_f32 v[100:101], v[100:101], s[20:21], 1.0 op_sel_hi:[1,0,0]
	v_pk_fma_f32 v[76:77], v[92:93], v[76:77], s[38:39] op_sel_hi:[1,1,0]
	v_rcp_f32_e32 v100, v100
	v_rcp_f32_e32 v101, v101
	v_pk_fma_f32 v[76:77], v[92:93], v[76:77], s[40:41] op_sel_hi:[1,1,0]
	v_cmp_gt_f32_e32 vcc, 0, v75
	v_pk_mul_f32 v[76:77], v[92:93], v[76:77]
	v_pk_mul_f32 v[92:93], v[74:75], v[74:75]
	v_pk_mul_f32 v[76:77], v[98:99], v[76:77]
	v_pk_mul_f32 v[92:93], v[92:93], s[42:43] op_sel_hi:[1,0]
	v_pk_mul_f32 v[98:99], v[72:73], v[76:77]
	v_pk_fma_f32 v[102:103], v[72:73], v[76:77], v[72:73] neg_lo:[1,0,0] neg_hi:[1,0,0]
	v_pk_fma_f32 v[76:77], v[100:101], s[22:23], v[86:87] op_sel_hi:[1,0,0]
	v_exp_f32_e32 v92, v92
	v_pk_fma_f32 v[76:77], v[100:101], v[76:77], s[36:37] op_sel_hi:[1,1,0]
	v_exp_f32_e32 v93, v93
	v_pk_fma_f32 v[76:77], v[100:101], v[76:77], s[38:39] op_sel_hi:[1,1,0]
	v_pk_fma_f32 v[70:71], v[70:71], v[168:169], v[46:47] op_sel_hi:[1,0,1]
	v_pk_fma_f32 v[76:77], v[100:101], v[76:77], s[40:41] op_sel_hi:[1,1,0]
	v_pk_fma_f32 v[68:69], v[68:69], v[168:169], v[44:45] op_sel_hi:[1,0,1]
	v_pk_mul_f32 v[76:77], v[100:101], v[76:77]
	v_pk_fma_f32 v[64:65], v[64:65], v[168:169], v[40:41] op_sel_hi:[1,0,1]
	v_pk_mul_f32 v[76:77], v[92:93], v[76:77]
	v_pk_fma_f32 v[66:67], v[66:67], v[168:169], v[42:43] op_sel_hi:[1,0,1]
	v_pk_mul_f32 v[92:93], v[74:75], v[76:77]
	v_pk_fma_f32 v[100:101], v[74:75], v[76:77], v[74:75] neg_lo:[1,0,0] neg_hi:[1,0,0]
	v_and_b32_e32 v113, 0x7fffffff, v67
	v_cndmask_b32_e32 v76, v101, v93, vcc
	v_cmp_gt_f32_e32 vcc, 0, v78
	v_and_b32_e32 v112, 0x7fffffff, v66
	v_pk_fma_f32 v[112:113], v[112:113], s[20:21], 1.0 op_sel_hi:[1,0,0]
	v_cndmask_b32_e32 v105, v96, v88, vcc
	v_cmp_gt_f32_e32 vcc, 0, v84
	v_rcp_f32_e32 v112, v112
	v_rcp_f32_e32 v113, v113
	v_cndmask_b32_e32 v104, v94, v90, vcc
	v_cmp_gt_f32_e32 vcc, 0, v79
	v_pk_mul_f32 v[110:111], v[64:65], v[64:65]
	v_mul_f32_e32 v77, v76, v76
	v_cndmask_b32_e32 v79, v97, v89, vcc
	v_cmp_gt_f32_e32 vcc, 0, v85
	v_pk_mul_f32 v[96:97], v[68:69], v[68:69]
	v_pk_mul_f32 v[110:111], v[110:111], s[42:43] op_sel_hi:[1,0]
	v_cndmask_b32_e32 v78, v95, v91, vcc
	v_pk_add_f32 v[84:85], v[104:105], v[78:79]
	v_pk_mul_f32 v[96:97], v[96:97], s[42:43] op_sel_hi:[1,0]
	v_pk_add_f32 v[88:89], v[84:85], v[84:85] op_sel:[0,1] op_sel_hi:[1,0]
	v_pk_mul_f32 v[84:85], v[78:79], v[78:79]
	v_exp_f32_e32 v96, v96
	v_pk_fma_f32 v[84:85], v[104:105], v[104:105], v[84:85]
	v_exp_f32_e32 v97, v97
	v_pk_add_f32 v[90:91], v[84:85], v[84:85] op_sel_hi:[0,1]
	v_cvt_pk_bf16_f32 v84, v104, v78
	v_cvt_pk_bf16_f32 v85, v105, v79
	v_and_b32_e32 v105, 0x7fffffff, v71
	v_and_b32_e32 v104, 0x7fffffff, v70
	v_pk_fma_f32 v[104:105], v[104:105], s[20:21], 1.0 op_sel_hi:[1,0,0]
	v_and_b32_e32 v79, 0x7fffffff, v69
	v_rcp_f32_e32 v104, v104
	v_rcp_f32_e32 v105, v105
	v_and_b32_e32 v78, 0x7fffffff, v68
	v_pk_fma_f32 v[78:79], v[78:79], s[20:21], 1.0 op_sel_hi:[1,0,0]
	v_cmp_gt_f32_e32 vcc, 0, v69
	v_pk_fma_f32 v[106:107], v[104:105], s[22:23], v[86:87] op_sel_hi:[1,0,0]
	v_rcp_f32_e32 v78, v78
	v_pk_fma_f32 v[106:107], v[104:105], v[106:107], s[36:37] op_sel_hi:[1,1,0]
	v_rcp_f32_e32 v79, v79
	v_pk_fma_f32 v[106:107], v[104:105], v[106:107], s[38:39] op_sel_hi:[1,1,0]
	v_exp_f32_e32 v110, v110
	v_pk_fma_f32 v[106:107], v[104:105], v[106:107], s[40:41] op_sel_hi:[1,1,0]
	v_pk_fma_f32 v[94:95], v[78:79], s[22:23], v[86:87] op_sel_hi:[1,0,0]
	v_pk_mul_f32 v[104:105], v[104:105], v[106:107]
	v_and_b32_e32 v107, 0x7fffffff, v65
	v_and_b32_e32 v106, 0x7fffffff, v64
	v_pk_fma_f32 v[106:107], v[106:107], s[20:21], 1.0 op_sel_hi:[1,0,0]
	v_pk_fma_f32 v[94:95], v[78:79], v[94:95], s[36:37] op_sel_hi:[1,1,0]
	v_rcp_f32_e32 v106, v106
	v_rcp_f32_e32 v107, v107
	v_pk_fma_f32 v[94:95], v[78:79], v[94:95], s[38:39] op_sel_hi:[1,1,0]
	v_exp_f32_e32 v111, v111
	v_pk_fma_f32 v[94:95], v[78:79], v[94:95], s[40:41] op_sel_hi:[1,1,0]
	v_pk_fma_f32 v[108:109], v[106:107], s[22:23], v[86:87] op_sel_hi:[1,0,0]
	v_pk_mul_f32 v[78:79], v[78:79], v[94:95]
	v_pk_fma_f32 v[108:109], v[106:107], v[108:109], s[36:37] op_sel_hi:[1,1,0]
	v_pk_mul_f32 v[94:95], v[70:71], v[70:71]
	v_pk_fma_f32 v[108:109], v[106:107], v[108:109], s[38:39] op_sel_hi:[1,1,0]
	v_pk_mul_f32 v[94:95], v[94:95], s[42:43] op_sel_hi:[1,0]
	v_pk_fma_f32 v[108:109], v[106:107], v[108:109], s[40:41] op_sel_hi:[1,1,0]
	v_exp_f32_e32 v94, v94
	v_exp_f32_e32 v95, v95
	v_pk_mul_f32 v[106:107], v[106:107], v[108:109]
	v_pk_mul_f32 v[108:109], v[66:67], v[66:67]
	v_pk_fma_f32 v[86:87], v[112:113], s[22:23], v[86:87] op_sel_hi:[1,0,0]
	v_pk_mul_f32 v[108:109], v[108:109], s[42:43] op_sel_hi:[1,0]
	v_pk_mul_f32 v[78:79], v[96:97], v[78:79]
	v_pk_fma_f32 v[86:87], v[112:113], v[86:87], s[36:37] op_sel_hi:[1,1,0]
	v_exp_f32_e32 v108, v108
	v_exp_f32_e32 v109, v109
	v_pk_mul_f32 v[96:97], v[68:69], v[78:79]
	v_pk_fma_f32 v[78:79], v[68:69], v[78:79], v[68:69] neg_lo:[1,0,0] neg_hi:[1,0,0]
	v_pk_fma_f32 v[86:87], v[112:113], v[86:87], s[38:39] op_sel_hi:[1,1,0]
	v_pk_mul_f32 v[94:95], v[94:95], v[104:105]
	v_pk_fma_f32 v[86:87], v[112:113], v[86:87], s[40:41] op_sel_hi:[1,1,0]
	v_cndmask_b32_e32 v69, v79, v97, vcc
	v_cmp_gt_f32_e32 vcc, 0, v68
	v_pk_mul_f32 v[104:105], v[70:71], v[94:95]
	v_pk_fma_f32 v[94:95], v[70:71], v[94:95], v[70:71] neg_lo:[1,0,0] neg_hi:[1,0,0]
	v_pk_mul_f32 v[86:87], v[112:113], v[86:87]
	v_cndmask_b32_e32 v68, v78, v96, vcc
	v_cmp_gt_f32_e32 vcc, 0, v71
	v_pk_mul_f32 v[86:87], v[108:109], v[86:87]
	v_pk_mul_f32 v[106:107], v[110:111], v[106:107]
	v_cndmask_b32_e32 v71, v95, v105, vcc
	v_cmp_gt_f32_e32 vcc, 0, v70
	v_pk_mul_f32 v[108:109], v[66:67], v[86:87]
	v_pk_fma_f32 v[86:87], v[66:67], v[86:87], v[66:67] neg_lo:[1,0,0] neg_hi:[1,0,0]
	v_cndmask_b32_e32 v70, v94, v104, vcc
	v_cmp_gt_f32_e32 vcc, 0, v67
	v_pk_mul_f32 v[110:111], v[64:65], v[106:107]
	v_pk_fma_f32 v[106:107], v[64:65], v[106:107], v[64:65] neg_lo:[1,0,0] neg_hi:[1,0,0]
	v_cndmask_b32_e32 v105, v87, v109, vcc
	v_cmp_gt_f32_e32 vcc, 0, v66
	v_mov_b32_e32 v94, v68
	v_mov_b32_e32 v95, v70
	v_cndmask_b32_e32 v104, v86, v108, vcc
	v_cmp_gt_f32_e32 vcc, 0, v72
	v_mov_b32_e32 v96, v69
	v_mov_b32_e32 v97, v71
	v_cndmask_b32_e32 v108, v102, v98, vcc
	v_cmp_gt_f32_e32 vcc, 0, v64
	v_pk_add_f32 v[94:95], v[94:95], v[96:97]
	v_mov_b32_e32 v86, v108
	v_cndmask_b32_e32 v109, v106, v110, vcc
	v_cmp_gt_f32_e32 vcc, 0, v73
	v_mul_f32_e32 v64, v108, v108
	v_pk_add_f32 v[94:95], v[94:95], v[94:95] op_sel:[0,1] op_sel_hi:[1,0]
	v_cndmask_b32_e32 v72, v103, v99, vcc
	v_cmp_gt_f32_e32 vcc, 0, v74
	v_mov_b32_e32 v87, v72
	v_mov_b32_e32 v74, v109
	v_cndmask_b32_e32 v75, v100, v92, vcc
	v_cmp_gt_f32_e32 vcc, 0, v65
	v_mov_b32_e32 v93, v75
	v_pk_fma_f32 v[86:87], v[86:87], v[86:87], v[64:65] op_sel_hi:[1,1,0]
	v_cndmask_b32_e32 v92, v107, v111, vcc
	v_pk_add_f32 v[64:65], v[74:75], v[92:93]
	v_pk_mul_f32 v[98:99], v[74:75], v[92:93]
	v_mul_f32_e32 v78, v68, v68
	v_mov_b32_e32 v65, v99
	v_mov_b32_e32 v95, v77
	v_mov_b32_e32 v86, v104
	v_mov_b32_e32 v90, v105
	v_pk_fma_f32 v[78:79], v[68:69], v[68:69], v[78:79] op_sel_hi:[1,1,0]
	v_mov_b32_e32 v73, v109
	v_pk_add_f32 v[64:65], v[64:65], v[94:95]
	v_pk_add_f32 v[86:87], v[86:87], v[90:91]
	v_mul_f32_e32 v78, v70, v70
	v_pk_add_f32 v[64:65], v[64:65], v[86:87]
	v_pk_add_f32 v[86:87], v[108:109], v[72:73]
	v_pk_mul_f32 v[90:91], v[108:109], v[72:73]
	v_pk_fma_f32 v[96:97], v[70:71], v[70:71], v[78:79] op_sel_hi:[1,1,0]
	v_mov_b32_e32 v87, v91
	v_pk_mul_f32 v[90:91], v[92:93], v[92:93]
	v_mul_f32_e32 v66, v104, v104
	v_mov_b32_e32 v78, v75
	v_mov_b32_e32 v77, v97
	v_mov_b32_e32 v89, v90
	v_pk_fma_f32 v[66:67], v[104:105], v[104:105], v[66:67] op_sel_hi:[1,1,0]
	v_pk_add_f32 v[78:79], v[78:79], v[76:77]
	v_pk_add_f32 v[86:87], v[86:87], v[88:89]
	v_mov_b32_e32 v159, v67
	v_pk_add_f32 v[78:79], v[86:87], v[78:79]
	v_add_u32_e32 v80, 0x80, v166
	v_pk_add_f32 v[66:67], v[78:79], v[158:159]
	v_ashrrev_i32_e32 v81, 31, v80
	v_pk_add_f32 v[64:65], v[64:65], v[66:67]
	v_mov_b32_e32 v66, v64
	v_mov_b32_e32 v67, v65
	s_nop 1
	v_permlane16_swap_b32_e32 v66, v64
	v_permlane16_swap_b32_e32 v67, v65
	s_waitcnt lgkmcnt(2)
	v_lshlrev_b64 v[82:83], 13, v[80:81]
	v_lshl_add_u64 v[82:83], s[28:29], 0, v[82:83]
	v_lshl_add_u64 v[82:83], v[162:163], 1, v[82:83]
	v_cvt_pk_bf16_f32 v86, v108, v72
	s_waitcnt lgkmcnt(0)
	v_pk_add_f32 v[64:65], v[64:65], v[66:67]
	v_mov_b32_e32 v66, v64
	v_mov_b32_e32 v67, v65
	s_nop 1
	v_permlane32_swap_b32_e32 v66, v64
	v_permlane32_swap_b32_e32 v67, v65
	v_cvt_pk_bf16_f32 v87, v75, v76
	global_store_dwordx4 v[82:83], v[84:87], off
	v_cvt_pk_bf16_f32 v68, v68, v69
	v_cvt_pk_bf16_f32 v69, v70, v71
	v_cvt_pk_bf16_f32 v70, v109, v92
	v_cvt_pk_bf16_f32 v71, v104, v105
	global_store_dwordx4 v[82:83], v[68:71], off offset:256
	s_and_saveexec_b64 s[0:1], s[2:3]
	s_cbranch_execz .LBB0_275
	s_lshl_b32 s46, s60, 3
	s_waitcnt lgkmcnt(0)
	v_pk_add_f32 v[64:65], v[64:65], v[66:67]
	v_lshlrev_b64 v[66:67], 8, v[80:81]
	s_add_i32 s46, s46, s53
	v_lshl_add_u64 v[66:67], s[26:27], 0, v[66:67]
	s_ashr_i32 s47, s46, 31
	v_lshl_add_u64 v[66:67], s[46:47], 2, v[66:67]
	global_store_dwordx2 v[66:67], v[64:65], off
.LBB0_275:
	s_or_b64 exec, exec, s[0:1]
	v_mov_b32_e32 v68, v169
	v_pk_fma_f32 v[62:63], v[62:63], v[68:69], v[54:55] op_sel_hi:[1,0,1]
	v_mov_b64_e32 v[72:73], s[34:35]
	v_and_b32_e32 v79, 0x7fffffff, v63
	v_and_b32_e32 v78, 0x7fffffff, v62
	v_pk_fma_f32 v[78:79], v[78:79], s[20:21], 1.0 op_sel_hi:[1,0,0]
	v_pk_fma_f32 v[56:57], v[56:57], v[68:69], v[48:49] op_sel_hi:[1,0,1]
	v_rcp_f32_e32 v78, v78
	v_rcp_f32_e32 v79, v79
	v_pk_fma_f32 v[60:61], v[60:61], v[68:69], v[52:53] op_sel_hi:[1,0,1]
	v_pk_fma_f32 v[58:59], v[58:59], v[68:69], v[50:51] op_sel_hi:[1,0,1]
	v_and_b32_e32 v71, 0x7fffffff, v61
	v_pk_fma_f32 v[80:81], v[78:79], s[22:23], v[72:73] op_sel_hi:[1,0,0]
	v_and_b32_e32 v70, 0x7fffffff, v60
	v_pk_fma_f32 v[80:81], v[78:79], v[80:81], s[36:37] op_sel_hi:[1,1,0]
	v_pk_fma_f32 v[70:71], v[70:71], s[20:21], 1.0 op_sel_hi:[1,0,0]
	v_pk_fma_f32 v[80:81], v[78:79], v[80:81], s[38:39] op_sel_hi:[1,1,0]
	v_rcp_f32_e32 v70, v70
	v_pk_fma_f32 v[80:81], v[78:79], v[80:81], s[40:41] op_sel_hi:[1,1,0]
	v_rcp_f32_e32 v71, v71
	v_pk_mul_f32 v[78:79], v[78:79], v[80:81]
	v_and_b32_e32 v81, 0x7fffffff, v57
	v_and_b32_e32 v80, 0x7fffffff, v56
	v_pk_fma_f32 v[80:81], v[80:81], s[20:21], 1.0 op_sel_hi:[1,0,0]
	v_and_b32_e32 v87, 0x7fffffff, v59
	v_rcp_f32_e32 v80, v80
	v_rcp_f32_e32 v81, v81
	v_and_b32_e32 v86, 0x7fffffff, v58
	v_pk_fma_f32 v[86:87], v[86:87], s[20:21], 1.0 op_sel_hi:[1,0,0]
	v_pk_fma_f32 v[74:75], v[70:71], s[22:23], v[72:73] op_sel_hi:[1,0,0]
	v_pk_fma_f32 v[82:83], v[80:81], s[22:23], v[72:73] op_sel_hi:[1,0,0]
	v_rcp_f32_e32 v86, v86
	v_pk_fma_f32 v[82:83], v[80:81], v[82:83], s[36:37] op_sel_hi:[1,1,0]
	v_rcp_f32_e32 v87, v87
	v_pk_fma_f32 v[74:75], v[70:71], v[74:75], s[36:37] op_sel_hi:[1,1,0]
	v_pk_fma_f32 v[82:83], v[80:81], v[82:83], s[38:39] op_sel_hi:[1,1,0]
	v_pk_fma_f32 v[74:75], v[70:71], v[74:75], s[38:39] op_sel_hi:[1,1,0]
	v_pk_fma_f32 v[82:83], v[80:81], v[82:83], s[40:41] op_sel_hi:[1,1,0]
	v_pk_fma_f32 v[74:75], v[70:71], v[74:75], s[40:41] op_sel_hi:[1,1,0]
	v_pk_mul_f32 v[80:81], v[80:81], v[82:83]
	v_pk_mul_f32 v[82:83], v[58:59], v[58:59]
	v_pk_mul_f32 v[70:71], v[70:71], v[74:75]
	v_pk_mul_f32 v[74:75], v[62:63], v[62:63]
	v_pk_fma_f32 v[88:89], v[86:87], s[22:23], v[72:73] op_sel_hi:[1,0,0]
	v_pk_mul_f32 v[82:83], v[82:83], s[42:43] op_sel_hi:[1,0]
	v_pk_mul_f32 v[76:77], v[60:61], v[60:61]
	v_pk_mul_f32 v[74:75], v[74:75], s[42:43] op_sel_hi:[1,0]
	v_pk_fma_f32 v[88:89], v[86:87], v[88:89], s[36:37] op_sel_hi:[1,1,0]
	v_exp_f32_e32 v82, v82
	v_exp_f32_e32 v83, v83
	v_pk_mul_f32 v[76:77], v[76:77], s[42:43] op_sel_hi:[1,0]
	v_exp_f32_e32 v74, v74
	v_exp_f32_e32 v75, v75
	v_pk_fma_f32 v[88:89], v[86:87], v[88:89], s[38:39] op_sel_hi:[1,1,0]
	v_exp_f32_e32 v76, v76
	v_exp_f32_e32 v77, v77
	v_pk_fma_f32 v[88:89], v[86:87], v[88:89], s[40:41] op_sel_hi:[1,1,0]
	v_pk_mul_f32 v[74:75], v[74:75], v[78:79]
	v_pk_mul_f32 v[86:87], v[86:87], v[88:89]
	v_cmp_gt_f32_e32 vcc, 0, v59
	v_pk_mul_f32 v[82:83], v[82:83], v[86:87]
	v_pk_mul_f32 v[70:71], v[76:77], v[70:71]
	v_pk_mul_f32 v[86:87], v[58:59], v[82:83]
	v_pk_fma_f32 v[82:83], v[58:59], v[82:83], v[58:59] neg_lo:[1,0,0] neg_hi:[1,0,0]
	v_pk_mul_f32 v[78:79], v[62:63], v[74:75]
	v_pk_fma_f32 v[74:75], v[62:63], v[74:75], v[62:63] neg_lo:[1,0,0] neg_hi:[1,0,0]
	v_cndmask_b32_e32 v88, v83, v87, vcc
	v_cmp_gt_f32_e32 vcc, 0, v62
	v_pk_mul_f32 v[76:77], v[60:61], v[70:71]
	v_pk_fma_f32 v[70:71], v[60:61], v[70:71], v[60:61] neg_lo:[1,0,0] neg_hi:[1,0,0]
	v_cndmask_b32_e32 v91, v74, v78, vcc
	v_cmp_gt_f32_e32 vcc, 0, v60
	v_pk_fma_f32 v[38:39], v[38:39], v[68:69], v[46:47] op_sel_hi:[1,0,1]
	v_pk_fma_f32 v[36:37], v[36:37], v[68:69], v[44:45] op_sel_hi:[1,0,1]
	v_cndmask_b32_e32 v90, v70, v76, vcc
	v_cmp_gt_f32_e32 vcc, 0, v63
	v_and_b32_e32 v78, 0x7fffffff, v38
	v_pk_fma_f32 v[32:33], v[32:33], v[68:69], v[40:41] op_sel_hi:[1,0,1]
	v_cndmask_b32_e32 v63, v75, v79, vcc
	v_and_b32_e32 v79, 0x7fffffff, v39
	v_cmp_gt_f32_e32 vcc, 0, v61
	v_pk_fma_f32 v[78:79], v[78:79], s[20:21], 1.0 op_sel_hi:[1,0,0]
	v_pk_fma_f32 v[34:35], v[34:35], v[68:69], v[42:43] op_sel_hi:[1,0,1]
	v_cndmask_b32_e32 v62, v71, v77, vcc
	v_rcp_f32_e32 v78, v78
	v_rcp_f32_e32 v79, v79
	v_pk_add_f32 v[60:61], v[90:91], v[62:63]
	v_and_b32_e32 v97, 0x7fffffff, v35
	v_pk_add_f32 v[70:71], v[60:61], v[60:61] op_sel:[0,1] op_sel_hi:[1,0]
	v_pk_mul_f32 v[60:61], v[62:63], v[62:63]
	v_and_b32_e32 v96, 0x7fffffff, v34
	v_pk_fma_f32 v[60:61], v[90:91], v[90:91], v[60:61]
	v_pk_mul_f32 v[76:77], v[36:37], v[36:37]
	v_pk_add_f32 v[74:75], v[60:61], v[60:61] op_sel_hi:[0,1]
	v_cvt_pk_bf16_f32 v60, v90, v62
	v_cvt_pk_bf16_f32 v61, v91, v63
	v_pk_fma_f32 v[90:91], v[78:79], s[22:23], v[72:73] op_sel_hi:[1,0,0]
	v_and_b32_e32 v63, 0x7fffffff, v37
	v_pk_fma_f32 v[90:91], v[78:79], v[90:91], s[36:37] op_sel_hi:[1,1,0]
	v_and_b32_e32 v62, 0x7fffffff, v36
	v_pk_fma_f32 v[90:91], v[78:79], v[90:91], s[38:39] op_sel_hi:[1,1,0]
	v_pk_fma_f32 v[62:63], v[62:63], s[20:21], 1.0 op_sel_hi:[1,0,0]
	v_pk_fma_f32 v[90:91], v[78:79], v[90:91], s[40:41] op_sel_hi:[1,1,0]
	v_rcp_f32_e32 v62, v62
	v_rcp_f32_e32 v63, v63
	v_pk_mul_f32 v[78:79], v[78:79], v[90:91]
	v_and_b32_e32 v91, 0x7fffffff, v33
	v_and_b32_e32 v90, 0x7fffffff, v32
	v_pk_fma_f32 v[90:91], v[90:91], s[20:21], 1.0 op_sel_hi:[1,0,0]
	v_pk_fma_f32 v[68:69], v[62:63], s[22:23], v[72:73] op_sel_hi:[1,0,0]
	v_rcp_f32_e32 v90, v90
	v_rcp_f32_e32 v91, v91
	v_pk_fma_f32 v[68:69], v[62:63], v[68:69], s[36:37] op_sel_hi:[1,1,0]
	v_pk_fma_f32 v[96:97], v[96:97], s[20:21], 1.0 op_sel_hi:[1,0,0]
	v_pk_fma_f32 v[68:69], v[62:63], v[68:69], s[38:39] op_sel_hi:[1,1,0]
	v_pk_fma_f32 v[92:93], v[90:91], s[22:23], v[72:73] op_sel_hi:[1,0,0]
	v_pk_fma_f32 v[68:69], v[62:63], v[68:69], s[40:41] op_sel_hi:[1,1,0]
	v_pk_mul_f32 v[76:77], v[76:77], s[42:43] op_sel_hi:[1,0]
	v_pk_fma_f32 v[92:93], v[90:91], v[92:93], s[36:37] op_sel_hi:[1,1,0]
	v_rcp_f32_e32 v96, v96
	v_rcp_f32_e32 v97, v97
	v_pk_mul_f32 v[62:63], v[62:63], v[68:69]
	v_pk_mul_f32 v[68:69], v[38:39], v[38:39]
	v_exp_f32_e32 v76, v76
	v_exp_f32_e32 v77, v77
	v_pk_fma_f32 v[92:93], v[90:91], v[92:93], s[38:39] op_sel_hi:[1,1,0]
	v_pk_mul_f32 v[68:69], v[68:69], s[42:43] op_sel_hi:[1,0]
	v_pk_fma_f32 v[92:93], v[90:91], v[92:93], s[40:41] op_sel_hi:[1,1,0]
	v_exp_f32_e32 v68, v68
	v_exp_f32_e32 v69, v69
	v_pk_mul_f32 v[90:91], v[90:91], v[92:93]
	v_pk_mul_f32 v[92:93], v[34:35], v[34:35]
	v_pk_fma_f32 v[72:73], v[96:97], s[22:23], v[72:73] op_sel_hi:[1,0,0]
	v_pk_mul_f32 v[92:93], v[92:93], s[42:43] op_sel_hi:[1,0]
	v_pk_mul_f32 v[84:85], v[56:57], v[56:57]
	v_pk_mul_f32 v[62:63], v[76:77], v[62:63]
	v_pk_fma_f32 v[72:73], v[96:97], v[72:73], s[36:37] op_sel_hi:[1,1,0]
	v_exp_f32_e32 v92, v92
	v_exp_f32_e32 v93, v93
	v_pk_mul_f32 v[84:85], v[84:85], s[42:43] op_sel_hi:[1,0]
	v_pk_mul_f32 v[76:77], v[36:37], v[62:63]
	v_pk_fma_f32 v[62:63], v[36:37], v[62:63], v[36:37] neg_lo:[1,0,0] neg_hi:[1,0,0]
	v_pk_mul_f32 v[94:95], v[32:33], v[32:33]
	v_pk_fma_f32 v[72:73], v[96:97], v[72:73], s[38:39] op_sel_hi:[1,1,0]
	v_cmp_gt_f32_e32 vcc, 0, v37
	v_exp_f32_e32 v84, v84
	v_exp_f32_e32 v85, v85
	v_pk_mul_f32 v[68:69], v[68:69], v[78:79]
	v_pk_mul_f32 v[94:95], v[94:95], s[42:43] op_sel_hi:[1,0]
	v_pk_fma_f32 v[72:73], v[96:97], v[72:73], s[40:41] op_sel_hi:[1,1,0]
	v_cndmask_b32_e32 v37, v63, v77, vcc
	v_cmp_gt_f32_e32 vcc, 0, v36
	v_pk_mul_f32 v[78:79], v[38:39], v[68:69]
	v_pk_fma_f32 v[68:69], v[38:39], v[68:69], v[38:39] neg_lo:[1,0,0] neg_hi:[1,0,0]
	v_exp_f32_e32 v94, v94
	v_exp_f32_e32 v95, v95
	v_pk_mul_f32 v[72:73], v[96:97], v[72:73]
	v_cndmask_b32_e32 v36, v62, v76, vcc
	v_cmp_gt_f32_e32 vcc, 0, v39
	v_pk_mul_f32 v[72:73], v[92:93], v[72:73]
	v_pk_mul_f32 v[80:81], v[84:85], v[80:81]
	v_cndmask_b32_e32 v39, v69, v79, vcc
	v_cmp_gt_f32_e32 vcc, 0, v38
	v_pk_mul_f32 v[92:93], v[34:35], v[72:73]
	v_pk_fma_f32 v[72:73], v[34:35], v[72:73], v[34:35] neg_lo:[1,0,0] neg_hi:[1,0,0]
	v_cndmask_b32_e32 v38, v68, v78, vcc
	v_cmp_gt_f32_e32 vcc, 0, v35
	v_pk_mul_f32 v[84:85], v[56:57], v[80:81]
	v_pk_fma_f32 v[80:81], v[56:57], v[80:81], v[56:57] neg_lo:[1,0,0] neg_hi:[1,0,0]
	v_cndmask_b32_e32 v73, v73, v93, vcc
	v_cmp_gt_f32_e32 vcc, 0, v34
	v_pk_mul_f32 v[90:91], v[94:95], v[90:91]
	v_mov_b32_e32 v68, v36
	v_cndmask_b32_e32 v72, v72, v92, vcc
	v_cmp_gt_f32_e32 vcc, 0, v56
	v_pk_mul_f32 v[94:95], v[32:33], v[90:91]
	v_pk_fma_f32 v[90:91], v[32:33], v[90:91], v[32:33] neg_lo:[1,0,0] neg_hi:[1,0,0]
	v_cndmask_b32_e32 v78, v80, v84, vcc
	v_cmp_gt_f32_e32 vcc, 0, v32
	v_mov_b32_e32 v69, v38
	v_mov_b32_e32 v76, v37
	v_cndmask_b32_e32 v79, v90, v94, vcc
	v_cmp_gt_f32_e32 vcc, 0, v57
	v_mov_b32_e32 v77, v39
	v_pk_add_f32 v[68:69], v[68:69], v[76:77]
	v_cndmask_b32_e32 v56, v81, v85, vcc
	v_cmp_gt_f32_e32 vcc, 0, v58
	v_mov_b32_e32 v80, v78
	v_mov_b32_e32 v81, v56
	v_cndmask_b32_e32 v59, v82, v86, vcc
	v_cmp_gt_f32_e32 vcc, 0, v33
	v_mul_f32_e32 v32, v78, v78
	v_mov_b32_e32 v58, v79
	v_cndmask_b32_e32 v82, v91, v95, vcc
	v_mov_b32_e32 v83, v59
	v_mul_f32_e32 v71, v88, v88
	v_pk_fma_f32 v[80:81], v[80:81], v[80:81], v[32:33] op_sel_hi:[1,1,0]
	v_pk_add_f32 v[32:33], v[58:59], v[82:83]
	v_pk_mul_f32 v[84:85], v[58:59], v[82:83]
	v_pk_add_f32 v[68:69], v[68:69], v[68:69] op_sel:[0,1] op_sel_hi:[1,0]
	v_mul_f32_e32 v62, v36, v36
	v_mov_b32_e32 v33, v85
	v_mov_b32_e32 v69, v71
	v_mov_b32_e32 v80, v72
	v_mov_b32_e32 v74, v73
	v_pk_fma_f32 v[62:63], v[36:37], v[36:37], v[62:63] op_sel_hi:[1,1,0]
	v_mov_b32_e32 v57, v79
	v_pk_add_f32 v[32:33], v[32:33], v[68:69]
	v_pk_add_f32 v[68:69], v[80:81], v[74:75]
	v_mul_f32_e32 v62, v38, v38
	v_pk_add_f32 v[32:33], v[32:33], v[68:69]
	v_pk_add_f32 v[68:69], v[78:79], v[56:57]
	v_pk_mul_f32 v[74:75], v[78:79], v[56:57]
	v_pk_fma_f32 v[76:77], v[38:39], v[38:39], v[62:63] op_sel_hi:[1,1,0]
	v_mov_b32_e32 v69, v75
	v_pk_mul_f32 v[74:75], v[82:83], v[82:83]
	v_mul_f32_e32 v34, v72, v72
	v_mov_b32_e32 v62, v59
	v_mov_b32_e32 v89, v77
	v_mov_b32_e32 v71, v74
	v_pk_fma_f32 v[34:35], v[72:73], v[72:73], v[34:35] op_sel_hi:[1,1,0]
	v_pk_add_f32 v[62:63], v[62:63], v[88:89]
	v_pk_add_f32 v[68:69], v[68:69], v[70:71]
	v_mov_b32_e32 v159, v35
	v_pk_add_f32 v[62:63], v[68:69], v[62:63]
	v_add_u32_e32 v64, 0x90, v166
	v_pk_add_f32 v[34:35], v[62:63], v[158:159]
	v_ashrrev_i32_e32 v65, 31, v64
	v_pk_add_f32 v[32:33], v[32:33], v[34:35]
	v_mov_b32_e32 v34, v32
	v_mov_b32_e32 v35, v33
	s_nop 1
	v_permlane16_swap_b32_e32 v34, v32
	v_permlane16_swap_b32_e32 v35, v33
	s_waitcnt lgkmcnt(2)
	v_lshlrev_b64 v[66:67], 13, v[64:65]
	v_lshl_add_u64 v[66:67], s[28:29], 0, v[66:67]
	v_lshl_add_u64 v[66:67], v[162:163], 1, v[66:67]
	v_cvt_pk_bf16_f32 v62, v78, v56
	s_waitcnt lgkmcnt(0)
	v_pk_add_f32 v[32:33], v[32:33], v[34:35]
	v_mov_b32_e32 v34, v32
	v_mov_b32_e32 v35, v33
	s_nop 1
	v_permlane32_swap_b32_e32 v34, v32
	v_permlane32_swap_b32_e32 v35, v33
	v_cvt_pk_bf16_f32 v63, v59, v88
	global_store_dwordx4 v[66:67], v[60:63], off
	v_cvt_pk_bf16_f32 v36, v36, v37
	v_cvt_pk_bf16_f32 v37, v38, v39
	v_cvt_pk_bf16_f32 v38, v79, v82
	v_cvt_pk_bf16_f32 v39, v72, v73
	global_store_dwordx4 v[66:67], v[36:39], off offset:256
	s_and_saveexec_b64 s[0:1], s[2:3]
	s_cbranch_execz .LBB0_277
	s_lshl_b32 s46, s60, 3
	s_waitcnt lgkmcnt(0)
	v_pk_add_f32 v[32:33], v[32:33], v[34:35]
	v_lshlrev_b64 v[34:35], 8, v[64:65]
	s_add_i32 s46, s46, s53
	v_lshl_add_u64 v[34:35], s[26:27], 0, v[34:35]
	s_ashr_i32 s47, s46, 31
	v_lshl_add_u64 v[34:35], s[46:47], 2, v[34:35]
	global_store_dwordx2 v[34:35], v[32:33], off
.LBB0_277:
	s_or_b64 exec, exec, s[0:1]
	v_pk_fma_f32 v[36:37], v[28:29], v[164:165], v[52:53] op_sel_hi:[1,0,1]
	v_pk_fma_f32 v[30:31], v[30:31], v[164:165], v[54:55] op_sel_hi:[1,0,1]
	v_and_b32_e32 v29, 0x7fffffff, v37
	v_and_b32_e32 v28, 0x7fffffff, v36
	v_pk_fma_f32 v[28:29], v[28:29], s[20:21], 1.0 op_sel_hi:[1,0,0]
	v_mov_b64_e32 v[38:39], s[34:35]
	v_rcp_f32_e32 v28, v28
	v_rcp_f32_e32 v29, v29
	v_pk_mul_f32 v[58:59], v[36:37], v[36:37]
	v_and_b32_e32 v61, 0x7fffffff, v31
	v_pk_mul_f32 v[58:59], v[58:59], s[42:43] op_sel_hi:[1,0]
	v_pk_fma_f32 v[56:57], v[28:29], s[22:23], v[38:39] op_sel_hi:[1,0,0]
	v_and_b32_e32 v60, 0x7fffffff, v30
	v_pk_fma_f32 v[56:57], v[28:29], v[56:57], s[36:37] op_sel_hi:[1,1,0]
	v_exp_f32_e32 v58, v58
	v_exp_f32_e32 v59, v59
	v_pk_fma_f32 v[60:61], v[60:61], s[20:21], 1.0 op_sel_hi:[1,0,0]
	v_pk_fma_f32 v[56:57], v[28:29], v[56:57], s[38:39] op_sel_hi:[1,1,0]
	v_rcp_f32_e32 v60, v60
	v_rcp_f32_e32 v61, v61
	v_pk_fma_f32 v[56:57], v[28:29], v[56:57], s[40:41] op_sel_hi:[1,1,0]
	v_pk_fma_f32 v[24:25], v[24:25], v[164:165], v[48:49] op_sel_hi:[1,0,1]
	v_pk_mul_f32 v[28:29], v[28:29], v[56:57]
	v_pk_mul_f32 v[56:57], v[30:31], v[30:31]
	v_pk_mul_f32 v[28:29], v[58:59], v[28:29]
	v_pk_mul_f32 v[56:57], v[56:57], s[42:43] op_sel_hi:[1,0]
	v_pk_mul_f32 v[58:59], v[36:37], v[28:29]
	v_pk_fma_f32 v[62:63], v[36:37], v[28:29], v[36:37] neg_lo:[1,0,0] neg_hi:[1,0,0]
	v_pk_fma_f32 v[28:29], v[60:61], s[22:23], v[38:39] op_sel_hi:[1,0,0]
	v_exp_f32_e32 v56, v56
	v_pk_fma_f32 v[28:29], v[60:61], v[28:29], s[36:37] op_sel_hi:[1,1,0]
	v_exp_f32_e32 v57, v57
	v_pk_fma_f32 v[28:29], v[60:61], v[28:29], s[38:39] op_sel_hi:[1,1,0]
	v_pk_fma_f32 v[26:27], v[26:27], v[164:165], v[50:51] op_sel_hi:[1,0,1]
	v_pk_fma_f32 v[28:29], v[60:61], v[28:29], s[40:41] op_sel_hi:[1,1,0]
	v_pk_mul_f32 v[66:67], v[24:25], v[24:25]
	v_pk_mul_f32 v[28:29], v[60:61], v[28:29]
	v_and_b32_e32 v61, 0x7fffffff, v25
	v_and_b32_e32 v60, 0x7fffffff, v24
	v_pk_fma_f32 v[60:61], v[60:61], s[20:21], 1.0 op_sel_hi:[1,0,0]
	v_pk_mul_f32 v[28:29], v[56:57], v[28:29]
	v_rcp_f32_e32 v60, v60
	v_rcp_f32_e32 v61, v61
	v_pk_mul_f32 v[56:57], v[30:31], v[28:29]
	v_pk_fma_f32 v[64:65], v[30:31], v[28:29], v[30:31] neg_lo:[1,0,0] neg_hi:[1,0,0]
	v_pk_mul_f32 v[66:67], v[66:67], s[42:43] op_sel_hi:[1,0]
	v_pk_fma_f32 v[28:29], v[60:61], s[22:23], v[38:39] op_sel_hi:[1,0,0]
	v_and_b32_e32 v69, 0x7fffffff, v27
	v_and_b32_e32 v68, 0x7fffffff, v26
	v_pk_fma_f32 v[28:29], v[60:61], v[28:29], s[36:37] op_sel_hi:[1,1,0]
	v_exp_f32_e32 v66, v66
	v_exp_f32_e32 v67, v67
	v_pk_fma_f32 v[68:69], v[68:69], s[20:21], 1.0 op_sel_hi:[1,0,0]
	v_pk_fma_f32 v[28:29], v[60:61], v[28:29], s[38:39] op_sel_hi:[1,1,0]
	v_rcp_f32_e32 v68, v68
	v_rcp_f32_e32 v69, v69
	v_pk_fma_f32 v[28:29], v[60:61], v[28:29], s[40:41] op_sel_hi:[1,1,0]
	v_cmp_gt_f32_e32 vcc, 0, v27
	v_pk_mul_f32 v[28:29], v[60:61], v[28:29]
	v_pk_mul_f32 v[60:61], v[26:27], v[26:27]
	v_pk_mul_f32 v[28:29], v[66:67], v[28:29]
	v_pk_mul_f32 v[60:61], v[60:61], s[42:43] op_sel_hi:[1,0]
	v_pk_mul_f32 v[66:67], v[24:25], v[28:29]
	v_pk_fma_f32 v[70:71], v[24:25], v[28:29], v[24:25] neg_lo:[1,0,0] neg_hi:[1,0,0]
	v_pk_fma_f32 v[28:29], v[68:69], s[22:23], v[38:39] op_sel_hi:[1,0,0]
	v_exp_f32_e32 v60, v60
	v_pk_fma_f32 v[28:29], v[68:69], v[28:29], s[36:37] op_sel_hi:[1,1,0]
	v_exp_f32_e32 v61, v61
	v_pk_fma_f32 v[28:29], v[68:69], v[28:29], s[38:39] op_sel_hi:[1,1,0]
	v_pk_fma_f32 v[22:23], v[22:23], v[164:165], v[46:47] op_sel_hi:[1,0,1]
	v_pk_fma_f32 v[28:29], v[68:69], v[28:29], s[40:41] op_sel_hi:[1,1,0]
	v_pk_fma_f32 v[20:21], v[20:21], v[164:165], v[44:45] op_sel_hi:[1,0,1]
	v_pk_mul_f32 v[28:29], v[68:69], v[28:29]
	v_pk_fma_f32 v[16:17], v[16:17], v[164:165], v[40:41] op_sel_hi:[1,0,1]
	v_pk_mul_f32 v[28:29], v[60:61], v[28:29]
	v_pk_fma_f32 v[18:19], v[18:19], v[164:165], v[42:43] op_sel_hi:[1,0,1]
	v_pk_mul_f32 v[60:61], v[26:27], v[28:29]
	v_pk_fma_f32 v[68:69], v[26:27], v[28:29], v[26:27] neg_lo:[1,0,0] neg_hi:[1,0,0]
	v_and_b32_e32 v81, 0x7fffffff, v19
	v_cndmask_b32_e32 v28, v69, v61, vcc
	v_cmp_gt_f32_e32 vcc, 0, v30
	v_and_b32_e32 v80, 0x7fffffff, v18
	v_pk_fma_f32 v[80:81], v[80:81], s[20:21], 1.0 op_sel_hi:[1,0,0]
	v_cndmask_b32_e32 v73, v64, v56, vcc
	v_cmp_gt_f32_e32 vcc, 0, v36
	v_rcp_f32_e32 v80, v80
	v_rcp_f32_e32 v81, v81
	v_cndmask_b32_e32 v72, v62, v58, vcc
	v_cmp_gt_f32_e32 vcc, 0, v31
	v_pk_mul_f32 v[78:79], v[16:17], v[16:17]
	v_mul_f32_e32 v29, v28, v28
	v_cndmask_b32_e32 v31, v65, v57, vcc
	v_cmp_gt_f32_e32 vcc, 0, v37
	v_pk_mul_f32 v[64:65], v[20:21], v[20:21]
	v_pk_mul_f32 v[78:79], v[78:79], s[42:43] op_sel_hi:[1,0]
	v_cndmask_b32_e32 v30, v63, v59, vcc
	v_pk_add_f32 v[36:37], v[72:73], v[30:31]
	v_pk_mul_f32 v[64:65], v[64:65], s[42:43] op_sel_hi:[1,0]
	v_pk_add_f32 v[56:57], v[36:37], v[36:37] op_sel:[0,1] op_sel_hi:[1,0]
	v_pk_mul_f32 v[36:37], v[30:31], v[30:31]
	v_exp_f32_e32 v64, v64
	v_pk_fma_f32 v[36:37], v[72:73], v[72:73], v[36:37]
	v_exp_f32_e32 v65, v65
	v_pk_add_f32 v[58:59], v[36:37], v[36:37] op_sel_hi:[0,1]
	v_cvt_pk_bf16_f32 v36, v72, v30
	v_cvt_pk_bf16_f32 v37, v73, v31
	v_and_b32_e32 v73, 0x7fffffff, v23
	v_and_b32_e32 v72, 0x7fffffff, v22
	v_pk_fma_f32 v[72:73], v[72:73], s[20:21], 1.0 op_sel_hi:[1,0,0]
	v_and_b32_e32 v31, 0x7fffffff, v21
	v_rcp_f32_e32 v72, v72
	v_rcp_f32_e32 v73, v73
	v_and_b32_e32 v30, 0x7fffffff, v20
	v_pk_fma_f32 v[30:31], v[30:31], s[20:21], 1.0 op_sel_hi:[1,0,0]
	v_cmp_gt_f32_e32 vcc, 0, v21
	v_pk_fma_f32 v[74:75], v[72:73], s[22:23], v[38:39] op_sel_hi:[1,0,0]
	v_rcp_f32_e32 v30, v30
	v_pk_fma_f32 v[74:75], v[72:73], v[74:75], s[36:37] op_sel_hi:[1,1,0]
	v_rcp_f32_e32 v31, v31
	v_pk_fma_f32 v[74:75], v[72:73], v[74:75], s[38:39] op_sel_hi:[1,1,0]
	v_exp_f32_e32 v78, v78
	v_pk_fma_f32 v[74:75], v[72:73], v[74:75], s[40:41] op_sel_hi:[1,1,0]
	v_pk_fma_f32 v[62:63], v[30:31], s[22:23], v[38:39] op_sel_hi:[1,0,0]
	v_pk_mul_f32 v[72:73], v[72:73], v[74:75]
	v_and_b32_e32 v75, 0x7fffffff, v17
	v_and_b32_e32 v74, 0x7fffffff, v16
	v_pk_fma_f32 v[74:75], v[74:75], s[20:21], 1.0 op_sel_hi:[1,0,0]
	v_pk_fma_f32 v[62:63], v[30:31], v[62:63], s[36:37] op_sel_hi:[1,1,0]
	v_rcp_f32_e32 v74, v74
	v_rcp_f32_e32 v75, v75
	v_pk_fma_f32 v[62:63], v[30:31], v[62:63], s[38:39] op_sel_hi:[1,1,0]
	v_exp_f32_e32 v79, v79
	v_pk_fma_f32 v[62:63], v[30:31], v[62:63], s[40:41] op_sel_hi:[1,1,0]
	v_pk_fma_f32 v[76:77], v[74:75], s[22:23], v[38:39] op_sel_hi:[1,0,0]
	v_pk_mul_f32 v[30:31], v[30:31], v[62:63]
	v_pk_fma_f32 v[76:77], v[74:75], v[76:77], s[36:37] op_sel_hi:[1,1,0]
	v_pk_mul_f32 v[62:63], v[22:23], v[22:23]
	v_pk_fma_f32 v[76:77], v[74:75], v[76:77], s[38:39] op_sel_hi:[1,1,0]
	v_pk_mul_f32 v[62:63], v[62:63], s[42:43] op_sel_hi:[1,0]
	v_pk_fma_f32 v[76:77], v[74:75], v[76:77], s[40:41] op_sel_hi:[1,1,0]
	v_exp_f32_e32 v62, v62
	v_exp_f32_e32 v63, v63
	v_pk_mul_f32 v[74:75], v[74:75], v[76:77]
	v_pk_mul_f32 v[76:77], v[18:19], v[18:19]
	v_pk_fma_f32 v[38:39], v[80:81], s[22:23], v[38:39] op_sel_hi:[1,0,0]
	v_pk_mul_f32 v[76:77], v[76:77], s[42:43] op_sel_hi:[1,0]
	v_pk_mul_f32 v[30:31], v[64:65], v[30:31]
	v_pk_fma_f32 v[38:39], v[80:81], v[38:39], s[36:37] op_sel_hi:[1,1,0]
	v_exp_f32_e32 v76, v76
	v_exp_f32_e32 v77, v77
	v_pk_mul_f32 v[64:65], v[20:21], v[30:31]
	v_pk_fma_f32 v[30:31], v[20:21], v[30:31], v[20:21] neg_lo:[1,0,0] neg_hi:[1,0,0]
	v_pk_fma_f32 v[38:39], v[80:81], v[38:39], s[38:39] op_sel_hi:[1,1,0]
	v_pk_mul_f32 v[62:63], v[62:63], v[72:73]
	v_pk_fma_f32 v[38:39], v[80:81], v[38:39], s[40:41] op_sel_hi:[1,1,0]
	v_cndmask_b32_e32 v21, v31, v65, vcc
	v_cmp_gt_f32_e32 vcc, 0, v20
	v_pk_mul_f32 v[72:73], v[22:23], v[62:63]
	v_pk_fma_f32 v[62:63], v[22:23], v[62:63], v[22:23] neg_lo:[1,0,0] neg_hi:[1,0,0]
	v_pk_mul_f32 v[38:39], v[80:81], v[38:39]
	v_cndmask_b32_e32 v20, v30, v64, vcc
	v_cmp_gt_f32_e32 vcc, 0, v23
	v_pk_mul_f32 v[38:39], v[76:77], v[38:39]
	v_pk_mul_f32 v[74:75], v[78:79], v[74:75]
	v_cndmask_b32_e32 v23, v63, v73, vcc
	v_cmp_gt_f32_e32 vcc, 0, v22
	v_pk_mul_f32 v[76:77], v[18:19], v[38:39]
	v_pk_fma_f32 v[38:39], v[18:19], v[38:39], v[18:19] neg_lo:[1,0,0] neg_hi:[1,0,0]
	v_cndmask_b32_e32 v22, v62, v72, vcc
	v_cmp_gt_f32_e32 vcc, 0, v19
	v_pk_mul_f32 v[78:79], v[16:17], v[74:75]
	v_pk_fma_f32 v[74:75], v[16:17], v[74:75], v[16:17] neg_lo:[1,0,0] neg_hi:[1,0,0]
	v_cndmask_b32_e32 v73, v39, v77, vcc
	v_cmp_gt_f32_e32 vcc, 0, v18
	v_mov_b32_e32 v62, v20
	v_mov_b32_e32 v63, v22
	v_cndmask_b32_e32 v72, v38, v76, vcc
	v_cmp_gt_f32_e32 vcc, 0, v24
	v_mov_b32_e32 v64, v21
	v_mov_b32_e32 v65, v23
	v_cndmask_b32_e32 v76, v70, v66, vcc
	v_cmp_gt_f32_e32 vcc, 0, v16
	v_pk_add_f32 v[62:63], v[62:63], v[64:65]
	v_mov_b32_e32 v38, v76
	v_cndmask_b32_e32 v77, v74, v78, vcc
	v_cmp_gt_f32_e32 vcc, 0, v25
	v_mul_f32_e32 v16, v76, v76
	v_pk_add_f32 v[62:63], v[62:63], v[62:63] op_sel:[0,1] op_sel_hi:[1,0]
	v_cndmask_b32_e32 v24, v71, v67, vcc
	v_cmp_gt_f32_e32 vcc, 0, v26
	v_mov_b32_e32 v39, v24
	v_mov_b32_e32 v26, v77
	v_cndmask_b32_e32 v27, v68, v60, vcc
	v_cmp_gt_f32_e32 vcc, 0, v17
	v_mov_b32_e32 v61, v27
	v_pk_fma_f32 v[38:39], v[38:39], v[38:39], v[16:17] op_sel_hi:[1,1,0]
	v_cndmask_b32_e32 v60, v75, v79, vcc
	v_pk_add_f32 v[16:17], v[26:27], v[60:61]
	v_pk_mul_f32 v[66:67], v[26:27], v[60:61]
	v_mul_f32_e32 v30, v20, v20
	v_mov_b32_e32 v17, v67
	v_mov_b32_e32 v63, v29
	v_mov_b32_e32 v38, v72
	v_mov_b32_e32 v58, v73
	v_pk_fma_f32 v[30:31], v[20:21], v[20:21], v[30:31] op_sel_hi:[1,1,0]
	v_mov_b32_e32 v25, v77
	v_pk_add_f32 v[16:17], v[16:17], v[62:63]
	v_pk_add_f32 v[38:39], v[38:39], v[58:59]
	v_mul_f32_e32 v30, v22, v22
	v_pk_add_f32 v[16:17], v[16:17], v[38:39]
	v_pk_add_f32 v[38:39], v[76:77], v[24:25]
	v_pk_mul_f32 v[58:59], v[76:77], v[24:25]
	v_pk_fma_f32 v[64:65], v[22:23], v[22:23], v[30:31] op_sel_hi:[1,1,0]
	v_mov_b32_e32 v39, v59
	v_pk_mul_f32 v[58:59], v[60:61], v[60:61]
	v_mul_f32_e32 v18, v72, v72
	v_mov_b32_e32 v30, v27
	v_mov_b32_e32 v29, v65
	v_mov_b32_e32 v57, v58
	v_pk_fma_f32 v[18:19], v[72:73], v[72:73], v[18:19] op_sel_hi:[1,1,0]
	v_pk_add_f32 v[30:31], v[30:31], v[28:29]
	v_pk_add_f32 v[38:39], v[38:39], v[56:57]
	v_mov_b32_e32 v159, v19
	v_pk_add_f32 v[30:31], v[38:39], v[30:31]
	v_add_u32_e32 v32, 0xa0, v166
	v_pk_add_f32 v[18:19], v[30:31], v[158:159]
	v_ashrrev_i32_e32 v33, 31, v32
	v_pk_add_f32 v[16:17], v[16:17], v[18:19]
	v_mov_b32_e32 v18, v16
	v_mov_b32_e32 v19, v17
	s_nop 1
	v_permlane16_swap_b32_e32 v18, v16
	v_permlane16_swap_b32_e32 v19, v17
	s_waitcnt lgkmcnt(2)
	v_lshlrev_b64 v[34:35], 13, v[32:33]
	v_lshl_add_u64 v[34:35], s[28:29], 0, v[34:35]
	v_lshl_add_u64 v[34:35], v[162:163], 1, v[34:35]
	v_cvt_pk_bf16_f32 v38, v76, v24
	s_waitcnt lgkmcnt(0)
	v_pk_add_f32 v[16:17], v[16:17], v[18:19]
	v_mov_b32_e32 v18, v16
	v_mov_b32_e32 v19, v17
	s_nop 1
	v_permlane32_swap_b32_e32 v18, v16
	v_permlane32_swap_b32_e32 v19, v17
	v_cvt_pk_bf16_f32 v39, v27, v28
	global_store_dwordx4 v[34:35], v[36:39], off
	v_cvt_pk_bf16_f32 v20, v20, v21
	v_cvt_pk_bf16_f32 v21, v22, v23
	v_cvt_pk_bf16_f32 v22, v77, v60
	v_cvt_pk_bf16_f32 v23, v72, v73
	global_store_dwordx4 v[34:35], v[20:23], off offset:256
	s_and_saveexec_b64 s[0:1], s[2:3]
	s_cbranch_execz .LBB0_279
	s_lshl_b32 s46, s60, 3
	s_waitcnt lgkmcnt(0)
	v_pk_add_f32 v[16:17], v[16:17], v[18:19]
	v_lshlrev_b64 v[18:19], 8, v[32:33]
	s_add_i32 s46, s46, s53
	v_lshl_add_u64 v[18:19], s[26:27], 0, v[18:19]
	s_ashr_i32 s47, s46, 31
	v_lshl_add_u64 v[18:19], s[46:47], 2, v[18:19]
	global_store_dwordx2 v[18:19], v[16:17], off
.LBB0_279:
	s_or_b64 exec, exec, s[0:1]
	v_mov_b32_e32 v20, v165
	v_pk_fma_f32 v[14:15], v[14:15], v[20:21], v[54:55] op_sel_hi:[1,0,1]
	v_mov_b64_e32 v[24:25], s[34:35]
	v_and_b32_e32 v31, 0x7fffffff, v15
	v_and_b32_e32 v30, 0x7fffffff, v14
	v_pk_fma_f32 v[30:31], v[30:31], s[20:21], 1.0 op_sel_hi:[1,0,0]
	v_pk_fma_f32 v[8:9], v[8:9], v[20:21], v[48:49] op_sel_hi:[1,0,1]
	v_rcp_f32_e32 v30, v30
	v_rcp_f32_e32 v31, v31
	v_pk_fma_f32 v[12:13], v[12:13], v[20:21], v[52:53] op_sel_hi:[1,0,1]
	v_pk_fma_f32 v[10:11], v[10:11], v[20:21], v[50:51] op_sel_hi:[1,0,1]
	v_and_b32_e32 v23, 0x7fffffff, v13
	v_pk_fma_f32 v[32:33], v[30:31], s[22:23], v[24:25] op_sel_hi:[1,0,0]
	v_and_b32_e32 v22, 0x7fffffff, v12
	v_pk_fma_f32 v[32:33], v[30:31], v[32:33], s[36:37] op_sel_hi:[1,1,0]
	v_pk_fma_f32 v[22:23], v[22:23], s[20:21], 1.0 op_sel_hi:[1,0,0]
	v_pk_fma_f32 v[32:33], v[30:31], v[32:33], s[38:39] op_sel_hi:[1,1,0]
	v_rcp_f32_e32 v22, v22
	v_pk_fma_f32 v[32:33], v[30:31], v[32:33], s[40:41] op_sel_hi:[1,1,0]
	v_rcp_f32_e32 v23, v23
	v_pk_mul_f32 v[30:31], v[30:31], v[32:33]
	v_and_b32_e32 v33, 0x7fffffff, v9
	v_and_b32_e32 v32, 0x7fffffff, v8
	v_pk_fma_f32 v[32:33], v[32:33], s[20:21], 1.0 op_sel_hi:[1,0,0]
	v_and_b32_e32 v39, 0x7fffffff, v11
	v_rcp_f32_e32 v32, v32
	v_rcp_f32_e32 v33, v33
	v_and_b32_e32 v38, 0x7fffffff, v10
	v_pk_fma_f32 v[38:39], v[38:39], s[20:21], 1.0 op_sel_hi:[1,0,0]
	v_pk_fma_f32 v[26:27], v[22:23], s[22:23], v[24:25] op_sel_hi:[1,0,0]
	v_pk_fma_f32 v[34:35], v[32:33], s[22:23], v[24:25] op_sel_hi:[1,0,0]
	v_rcp_f32_e32 v38, v38
	v_pk_fma_f32 v[34:35], v[32:33], v[34:35], s[36:37] op_sel_hi:[1,1,0]
	v_rcp_f32_e32 v39, v39
	v_pk_fma_f32 v[26:27], v[22:23], v[26:27], s[36:37] op_sel_hi:[1,1,0]
	v_pk_fma_f32 v[34:35], v[32:33], v[34:35], s[38:39] op_sel_hi:[1,1,0]
	v_pk_fma_f32 v[26:27], v[22:23], v[26:27], s[38:39] op_sel_hi:[1,1,0]
	v_pk_fma_f32 v[34:35], v[32:33], v[34:35], s[40:41] op_sel_hi:[1,1,0]
	v_pk_fma_f32 v[26:27], v[22:23], v[26:27], s[40:41] op_sel_hi:[1,1,0]
	v_pk_mul_f32 v[32:33], v[32:33], v[34:35]
	v_pk_mul_f32 v[34:35], v[10:11], v[10:11]
	v_pk_mul_f32 v[22:23], v[22:23], v[26:27]
	v_pk_mul_f32 v[26:27], v[14:15], v[14:15]
	v_pk_fma_f32 v[48:49], v[38:39], s[22:23], v[24:25] op_sel_hi:[1,0,0]
	v_pk_mul_f32 v[34:35], v[34:35], s[42:43] op_sel_hi:[1,0]
	v_pk_mul_f32 v[28:29], v[12:13], v[12:13]
	v_pk_mul_f32 v[26:27], v[26:27], s[42:43] op_sel_hi:[1,0]
	v_pk_fma_f32 v[48:49], v[38:39], v[48:49], s[36:37] op_sel_hi:[1,1,0]
	v_exp_f32_e32 v34, v34
	v_exp_f32_e32 v35, v35
	v_pk_mul_f32 v[28:29], v[28:29], s[42:43] op_sel_hi:[1,0]
	v_exp_f32_e32 v26, v26
	v_exp_f32_e32 v27, v27
	v_pk_fma_f32 v[48:49], v[38:39], v[48:49], s[38:39] op_sel_hi:[1,1,0]
	v_exp_f32_e32 v28, v28
	v_exp_f32_e32 v29, v29
	v_pk_fma_f32 v[48:49], v[38:39], v[48:49], s[40:41] op_sel_hi:[1,1,0]
	v_pk_mul_f32 v[26:27], v[26:27], v[30:31]
	v_pk_mul_f32 v[38:39], v[38:39], v[48:49]
	v_cmp_gt_f32_e32 vcc, 0, v11
	v_pk_mul_f32 v[34:35], v[34:35], v[38:39]
	v_pk_mul_f32 v[22:23], v[28:29], v[22:23]
	v_pk_mul_f32 v[38:39], v[10:11], v[34:35]
	v_pk_fma_f32 v[34:35], v[10:11], v[34:35], v[10:11] neg_lo:[1,0,0] neg_hi:[1,0,0]
	v_pk_mul_f32 v[30:31], v[14:15], v[26:27]
	v_pk_fma_f32 v[26:27], v[14:15], v[26:27], v[14:15] neg_lo:[1,0,0] neg_hi:[1,0,0]
	v_cndmask_b32_e32 v48, v35, v39, vcc
	v_cmp_gt_f32_e32 vcc, 0, v14
	v_pk_mul_f32 v[28:29], v[12:13], v[22:23]
	v_pk_fma_f32 v[22:23], v[12:13], v[22:23], v[12:13] neg_lo:[1,0,0] neg_hi:[1,0,0]
	v_cndmask_b32_e32 v51, v26, v30, vcc
	v_cmp_gt_f32_e32 vcc, 0, v12
	v_pk_fma_f32 v[6:7], v[6:7], v[20:21], v[46:47] op_sel_hi:[1,0,1]
	v_pk_fma_f32 v[0:1], v[0:1], v[20:21], v[40:41] op_sel_hi:[1,0,1]
	v_cndmask_b32_e32 v50, v22, v28, vcc
	v_cmp_gt_f32_e32 vcc, 0, v15
	v_and_b32_e32 v30, 0x7fffffff, v6
	v_pk_fma_f32 v[4:5], v[4:5], v[20:21], v[44:45] op_sel_hi:[1,0,1]
	v_cndmask_b32_e32 v15, v27, v31, vcc
	v_and_b32_e32 v31, 0x7fffffff, v7
	v_pk_fma_f32 v[30:31], v[30:31], s[20:21], 1.0 op_sel_hi:[1,0,0]
	v_cmp_gt_f32_e32 vcc, 0, v13
	v_rcp_f32_e32 v30, v30
	v_rcp_f32_e32 v31, v31
	v_cndmask_b32_e32 v14, v23, v29, vcc
	v_pk_add_f32 v[12:13], v[50:51], v[14:15]
	v_pk_fma_f32 v[2:3], v[2:3], v[20:21], v[42:43] op_sel_hi:[1,0,1]
	v_pk_add_f32 v[22:23], v[12:13], v[12:13] op_sel:[0,1] op_sel_hi:[1,0]
	v_pk_mul_f32 v[12:13], v[14:15], v[14:15]
	v_pk_fma_f32 v[40:41], v[30:31], s[22:23], v[24:25] op_sel_hi:[1,0,0]
	v_pk_fma_f32 v[12:13], v[50:51], v[50:51], v[12:13]
	v_pk_fma_f32 v[40:41], v[30:31], v[40:41], s[36:37] op_sel_hi:[1,1,0]
	v_pk_add_f32 v[26:27], v[12:13], v[12:13] op_sel_hi:[0,1]
	v_cvt_pk_bf16_f32 v12, v50, v14
	v_cvt_pk_bf16_f32 v13, v51, v15
	v_and_b32_e32 v15, 0x7fffffff, v5
	v_and_b32_e32 v14, 0x7fffffff, v4
	v_pk_fma_f32 v[40:41], v[30:31], v[40:41], s[38:39] op_sel_hi:[1,1,0]
	v_pk_fma_f32 v[14:15], v[14:15], s[20:21], 1.0 op_sel_hi:[1,0,0]
	v_pk_fma_f32 v[40:41], v[30:31], v[40:41], s[40:41] op_sel_hi:[1,1,0]
	v_rcp_f32_e32 v14, v14
	v_rcp_f32_e32 v15, v15
	v_pk_mul_f32 v[30:31], v[30:31], v[40:41]
	v_and_b32_e32 v41, 0x7fffffff, v1
	v_and_b32_e32 v40, 0x7fffffff, v0
	v_pk_fma_f32 v[40:41], v[40:41], s[20:21], 1.0 op_sel_hi:[1,0,0]
	v_pk_fma_f32 v[20:21], v[14:15], s[22:23], v[24:25] op_sel_hi:[1,0,0]
	v_rcp_f32_e32 v40, v40
	v_rcp_f32_e32 v41, v41
	v_pk_fma_f32 v[20:21], v[14:15], v[20:21], s[36:37] op_sel_hi:[1,1,0]
	v_and_b32_e32 v47, 0x7fffffff, v3
	v_and_b32_e32 v46, 0x7fffffff, v2
	v_pk_fma_f32 v[20:21], v[14:15], v[20:21], s[38:39] op_sel_hi:[1,1,0]
	v_pk_mul_f32 v[28:29], v[4:5], v[4:5]
	v_pk_fma_f32 v[42:43], v[40:41], s[22:23], v[24:25] op_sel_hi:[1,0,0]
	v_pk_fma_f32 v[46:47], v[46:47], s[20:21], 1.0 op_sel_hi:[1,0,0]
	v_pk_fma_f32 v[20:21], v[14:15], v[20:21], s[40:41] op_sel_hi:[1,1,0]
	v_pk_mul_f32 v[28:29], v[28:29], s[42:43] op_sel_hi:[1,0]
	v_pk_fma_f32 v[42:43], v[40:41], v[42:43], s[36:37] op_sel_hi:[1,1,0]
	v_rcp_f32_e32 v46, v46
	v_rcp_f32_e32 v47, v47
	v_pk_mul_f32 v[14:15], v[14:15], v[20:21]
	v_pk_mul_f32 v[20:21], v[6:7], v[6:7]
	v_exp_f32_e32 v28, v28
	v_exp_f32_e32 v29, v29
	v_pk_fma_f32 v[42:43], v[40:41], v[42:43], s[38:39] op_sel_hi:[1,1,0]
	v_pk_mul_f32 v[20:21], v[20:21], s[42:43] op_sel_hi:[1,0]
	v_pk_fma_f32 v[42:43], v[40:41], v[42:43], s[40:41] op_sel_hi:[1,1,0]
	v_exp_f32_e32 v20, v20
	v_exp_f32_e32 v21, v21
	v_pk_mul_f32 v[40:41], v[40:41], v[42:43]
	v_pk_mul_f32 v[42:43], v[2:3], v[2:3]
	v_pk_fma_f32 v[24:25], v[46:47], s[22:23], v[24:25] op_sel_hi:[1,0,0]
	v_pk_mul_f32 v[42:43], v[42:43], s[42:43] op_sel_hi:[1,0]
	v_pk_mul_f32 v[36:37], v[8:9], v[8:9]
	v_pk_mul_f32 v[14:15], v[28:29], v[14:15]
	v_pk_fma_f32 v[24:25], v[46:47], v[24:25], s[36:37] op_sel_hi:[1,1,0]
	v_exp_f32_e32 v42, v42
	v_exp_f32_e32 v43, v43
	v_pk_mul_f32 v[36:37], v[36:37], s[42:43] op_sel_hi:[1,0]
	v_pk_mul_f32 v[28:29], v[4:5], v[14:15]
	v_pk_fma_f32 v[14:15], v[4:5], v[14:15], v[4:5] neg_lo:[1,0,0] neg_hi:[1,0,0]
	v_pk_mul_f32 v[44:45], v[0:1], v[0:1]
	v_pk_fma_f32 v[24:25], v[46:47], v[24:25], s[38:39] op_sel_hi:[1,1,0]
	v_cmp_gt_f32_e32 vcc, 0, v5
	v_exp_f32_e32 v36, v36
	v_exp_f32_e32 v37, v37
	v_pk_mul_f32 v[20:21], v[20:21], v[30:31]
	v_pk_mul_f32 v[44:45], v[44:45], s[42:43] op_sel_hi:[1,0]
	v_pk_fma_f32 v[24:25], v[46:47], v[24:25], s[40:41] op_sel_hi:[1,1,0]
	v_cndmask_b32_e32 v5, v15, v29, vcc
	v_cmp_gt_f32_e32 vcc, 0, v4
	v_pk_mul_f32 v[30:31], v[6:7], v[20:21]
	v_pk_fma_f32 v[20:21], v[6:7], v[20:21], v[6:7] neg_lo:[1,0,0] neg_hi:[1,0,0]
	v_exp_f32_e32 v44, v44
	v_exp_f32_e32 v45, v45
	v_pk_mul_f32 v[24:25], v[46:47], v[24:25]
	v_cndmask_b32_e32 v4, v14, v28, vcc
	v_cmp_gt_f32_e32 vcc, 0, v7
	v_pk_mul_f32 v[24:25], v[42:43], v[24:25]
	v_pk_mul_f32 v[32:33], v[36:37], v[32:33]
	v_cndmask_b32_e32 v7, v21, v31, vcc
	v_cmp_gt_f32_e32 vcc, 0, v6
	v_pk_mul_f32 v[42:43], v[2:3], v[24:25]
	v_pk_fma_f32 v[24:25], v[2:3], v[24:25], v[2:3] neg_lo:[1,0,0] neg_hi:[1,0,0]
	v_cndmask_b32_e32 v6, v20, v30, vcc
	v_cmp_gt_f32_e32 vcc, 0, v3
	v_pk_mul_f32 v[36:37], v[8:9], v[32:33]
	v_pk_fma_f32 v[32:33], v[8:9], v[32:33], v[8:9] neg_lo:[1,0,0] neg_hi:[1,0,0]
	v_cndmask_b32_e32 v25, v25, v43, vcc
	v_cmp_gt_f32_e32 vcc, 0, v2
	v_pk_mul_f32 v[40:41], v[44:45], v[40:41]
	v_mov_b32_e32 v20, v4
	v_cndmask_b32_e32 v24, v24, v42, vcc
	v_cmp_gt_f32_e32 vcc, 0, v8
	v_pk_mul_f32 v[44:45], v[0:1], v[40:41]
	v_pk_fma_f32 v[40:41], v[0:1], v[40:41], v[0:1] neg_lo:[1,0,0] neg_hi:[1,0,0]
	v_cndmask_b32_e32 v30, v32, v36, vcc
	v_cmp_gt_f32_e32 vcc, 0, v0
	v_mov_b32_e32 v21, v6
	v_mov_b32_e32 v28, v5
	v_cndmask_b32_e32 v31, v40, v44, vcc
	v_cmp_gt_f32_e32 vcc, 0, v9
	v_mov_b32_e32 v29, v7
	v_pk_add_f32 v[20:21], v[20:21], v[28:29]
	v_cndmask_b32_e32 v8, v33, v37, vcc
	v_cmp_gt_f32_e32 vcc, 0, v10
	v_mov_b32_e32 v32, v30
	v_mov_b32_e32 v33, v8
	v_cndmask_b32_e32 v11, v34, v38, vcc
	v_cmp_gt_f32_e32 vcc, 0, v1
	v_mul_f32_e32 v0, v30, v30
	v_mov_b32_e32 v10, v31
	v_cndmask_b32_e32 v34, v41, v45, vcc
	v_mov_b32_e32 v35, v11
	v_mul_f32_e32 v23, v48, v48
	v_pk_fma_f32 v[32:33], v[32:33], v[32:33], v[0:1] op_sel_hi:[1,1,0]
	v_pk_add_f32 v[0:1], v[10:11], v[34:35]
	v_pk_mul_f32 v[36:37], v[10:11], v[34:35]
	v_pk_add_f32 v[20:21], v[20:21], v[20:21] op_sel:[0,1] op_sel_hi:[1,0]
	v_mul_f32_e32 v14, v4, v4
	v_mov_b32_e32 v1, v37
	v_mov_b32_e32 v21, v23
	v_mov_b32_e32 v32, v24
	v_mov_b32_e32 v26, v25
	v_pk_fma_f32 v[14:15], v[4:5], v[4:5], v[14:15] op_sel_hi:[1,1,0]
	v_mov_b32_e32 v9, v31
	v_pk_add_f32 v[0:1], v[0:1], v[20:21]
	v_pk_add_f32 v[20:21], v[32:33], v[26:27]
	v_mul_f32_e32 v14, v6, v6
	v_pk_add_f32 v[0:1], v[0:1], v[20:21]
	v_pk_add_f32 v[20:21], v[30:31], v[8:9]
	v_pk_mul_f32 v[26:27], v[30:31], v[8:9]
	v_pk_fma_f32 v[28:29], v[6:7], v[6:7], v[14:15] op_sel_hi:[1,1,0]
	v_mov_b32_e32 v21, v27
	v_pk_mul_f32 v[26:27], v[34:35], v[34:35]
	v_mul_f32_e32 v2, v24, v24
	v_mov_b32_e32 v14, v11
	v_mov_b32_e32 v49, v29
	v_mov_b32_e32 v23, v26
	v_pk_fma_f32 v[2:3], v[24:25], v[24:25], v[2:3] op_sel_hi:[1,1,0]
	v_pk_add_f32 v[14:15], v[14:15], v[48:49]
	v_pk_add_f32 v[20:21], v[20:21], v[22:23]
	v_mov_b32_e32 v159, v3
	v_pk_add_f32 v[14:15], v[20:21], v[14:15]
	v_add_u32_e32 v16, 0xb0, v166
	v_pk_add_f32 v[2:3], v[14:15], v[158:159]
	v_ashrrev_i32_e32 v17, 31, v16
	v_pk_add_f32 v[0:1], v[0:1], v[2:3]
	v_mov_b32_e32 v2, v0
	v_mov_b32_e32 v3, v1
	s_nop 1
	v_permlane16_swap_b32_e32 v2, v0
	v_permlane16_swap_b32_e32 v3, v1
	s_waitcnt lgkmcnt(2)
	v_lshlrev_b64 v[18:19], 13, v[16:17]
	v_lshl_add_u64 v[18:19], s[28:29], 0, v[18:19]
	v_lshl_add_u64 v[18:19], v[162:163], 1, v[18:19]
	v_cvt_pk_bf16_f32 v14, v30, v8
	s_waitcnt lgkmcnt(0)
	v_pk_add_f32 v[0:1], v[0:1], v[2:3]
	ds_bpermute_b32 v2, v133, v0
	ds_bpermute_b32 v3, v133, v1
	v_cvt_pk_bf16_f32 v15, v11, v48
	global_store_dwordx4 v[18:19], v[12:15], off
	v_cvt_pk_bf16_f32 v4, v4, v5
	v_cvt_pk_bf16_f32 v5, v6, v7
	v_cvt_pk_bf16_f32 v6, v31, v34
	v_cvt_pk_bf16_f32 v7, v24, v25
	global_store_dwordx4 v[18:19], v[4:7], off offset:256
	s_and_saveexec_b64 s[0:1], s[2:3]
	s_cbranch_execnz .LBB0_281
	s_or_b64 exec, exec, s[0:1]
	s_andn2_b64 vcc, exec, s[44:45]
	s_mov_b64 s[0:1], -1
	s_cbranch_vccnz .LBB0_252
	s_branch .LBB0_282

.LBB0_306:
	v_lshl_add_u32 v172, v174, 2, s74
	ds_read2_b32 v[180:181], v172 offset1:16
	ds_read2_b32 v[178:179], v172 offset0:32 offset1:48
	ds_read2_b32 v[176:177], v172 offset0:128 offset1:144
	ds_read2_b32 v[172:173], v172 offset0:160 offset1:176
	s_mov_b32 s6, 0x3e6d3388
	s_waitcnt vmcnt(0) lgkmcnt(0)
	v_pk_fma_f32 v[142:143], v[142:143], v[180:181], v[54:55] op_sel_hi:[1,0,1]
	s_lshl_b32 s0, s0, 8
	v_and_b32_e32 v205, 0x7fffffff, v143
	v_and_b32_e32 v204, 0x7fffffff, v142
	v_pk_fma_f32 v[204:205], v[204:205], s[6:7], 1.0 op_sel_hi:[1,0,0]
	s_add_i32 s0, s0, s68
	v_rcp_f32_e32 v204, v204
	v_rcp_f32_e32 v205, v205
	s_mov_b32 s16, 0xbf3a00e3
	v_add_u32_e32 v174, s0, v174
	s_mov_b32 s0, 0x3f07dc22
	v_mov_b64_e32 v[198:199], s[16:17]
	s_mov_b32 s12, 0x3f35f0e3
	v_pk_fma_f32 v[206:207], v[204:205], s[0:1], v[198:199] op_sel_hi:[1,0,0]
	s_mov_b32 s8, 0xbe11a98e
	v_pk_fma_f32 v[206:207], v[204:205], v[206:207], s[12:13] op_sel_hi:[1,1,0]
	s_mov_b32 s10, 0x3e027906
	v_pk_fma_f32 v[206:207], v[204:205], v[206:207], s[8:9] op_sel_hi:[1,1,0]
	v_pk_fma_f32 v[136:137], v[136:137], v[180:181], v[48:49] op_sel_hi:[1,0,1]
	v_pk_fma_f32 v[206:207], v[204:205], v[206:207], s[10:11] op_sel_hi:[1,1,0]
	v_pk_fma_f32 v[140:141], v[140:141], v[180:181], v[52:53] op_sel_hi:[1,0,1]
	v_pk_mul_f32 v[204:205], v[204:205], v[206:207]
	v_and_b32_e32 v207, 0x7fffffff, v137
	v_and_b32_e32 v206, 0x7fffffff, v136
	v_and_b32_e32 v197, 0x7fffffff, v141
	v_and_b32_e32 v196, 0x7fffffff, v140
	v_pk_fma_f32 v[206:207], v[206:207], s[6:7], 1.0 op_sel_hi:[1,0,0]
	v_pk_fma_f32 v[196:197], v[196:197], s[6:7], 1.0 op_sel_hi:[1,0,0]
	v_rcp_f32_e32 v206, v206
	v_rcp_f32_e32 v207, v207
	v_rcp_f32_e32 v196, v196
	v_rcp_f32_e32 v197, v197
	v_pk_fma_f32 v[138:139], v[138:139], v[180:181], v[50:51] op_sel_hi:[1,0,1]
	v_pk_fma_f32 v[208:209], v[206:207], s[0:1], v[198:199] op_sel_hi:[1,0,0]
	v_and_b32_e32 v213, 0x7fffffff, v139
	v_and_b32_e32 v212, 0x7fffffff, v138
	v_pk_fma_f32 v[212:213], v[212:213], s[6:7], 1.0 op_sel_hi:[1,0,0]
	v_pk_fma_f32 v[200:201], v[196:197], s[0:1], v[198:199] op_sel_hi:[1,0,0]
	v_pk_fma_f32 v[208:209], v[206:207], v[208:209], s[12:13] op_sel_hi:[1,1,0]
	v_rcp_f32_e32 v212, v212
	v_rcp_f32_e32 v213, v213
	v_pk_fma_f32 v[200:201], v[196:197], v[200:201], s[12:13] op_sel_hi:[1,1,0]
	v_pk_fma_f32 v[208:209], v[206:207], v[208:209], s[8:9] op_sel_hi:[1,1,0]
	v_pk_fma_f32 v[200:201], v[196:197], v[200:201], s[8:9] op_sel_hi:[1,1,0]
	v_pk_fma_f32 v[208:209], v[206:207], v[208:209], s[10:11] op_sel_hi:[1,1,0]
	v_pk_fma_f32 v[200:201], v[196:197], v[200:201], s[10:11] op_sel_hi:[1,1,0]
	s_mov_b32 s14, 0xbf38aa3b
	v_pk_mul_f32 v[206:207], v[206:207], v[208:209]
	v_pk_mul_f32 v[208:209], v[138:139], v[138:139]
	v_pk_mul_f32 v[196:197], v[196:197], v[200:201]
	v_pk_mul_f32 v[200:201], v[142:143], v[142:143]
	v_pk_fma_f32 v[214:215], v[212:213], s[0:1], v[198:199] op_sel_hi:[1,0,0]
	v_pk_mul_f32 v[208:209], v[208:209], s[14:15] op_sel_hi:[1,0]
	v_pk_mul_f32 v[202:203], v[140:141], v[140:141]
	v_pk_mul_f32 v[200:201], v[200:201], s[14:15] op_sel_hi:[1,0]
	v_pk_fma_f32 v[214:215], v[212:213], v[214:215], s[12:13] op_sel_hi:[1,1,0]
	v_exp_f32_e32 v208, v208
	v_exp_f32_e32 v209, v209
	v_pk_mul_f32 v[202:203], v[202:203], s[14:15] op_sel_hi:[1,0]
	v_exp_f32_e32 v200, v200
	v_exp_f32_e32 v201, v201
	v_pk_fma_f32 v[214:215], v[212:213], v[214:215], s[8:9] op_sel_hi:[1,1,0]
	v_exp_f32_e32 v202, v202
	v_exp_f32_e32 v203, v203
	v_pk_fma_f32 v[214:215], v[212:213], v[214:215], s[10:11] op_sel_hi:[1,1,0]
	v_pk_mul_f32 v[200:201], v[200:201], v[204:205]
	v_pk_mul_f32 v[212:213], v[212:213], v[214:215]
	v_cmp_gt_f32_e64 s[4:5], 0, v139
	v_pk_mul_f32 v[208:209], v[208:209], v[212:213]
	v_pk_mul_f32 v[196:197], v[202:203], v[196:197]
	v_pk_mul_f32 v[212:213], v[138:139], v[208:209]
	v_pk_fma_f32 v[208:209], v[138:139], v[208:209], v[138:139] neg_lo:[1,0,0] neg_hi:[1,0,0]
	v_pk_mul_f32 v[204:205], v[142:143], v[200:201]
	v_pk_fma_f32 v[200:201], v[142:143], v[200:201], v[142:143] neg_lo:[1,0,0] neg_hi:[1,0,0]
	v_cndmask_b32_e64 v214, v209, v213, s[4:5]
	v_cmp_gt_f32_e64 s[4:5], 0, v142
	v_pk_mul_f32 v[202:203], v[140:141], v[196:197]
	v_pk_fma_f32 v[196:197], v[140:141], v[196:197], v[140:141] neg_lo:[1,0,0] neg_hi:[1,0,0]
	v_cndmask_b32_e64 v217, v200, v204, s[4:5]
	v_cmp_gt_f32_e64 s[4:5], 0, v140
	v_pk_fma_f32 v[134:135], v[134:135], v[180:181], v[46:47] op_sel_hi:[1,0,1]
	v_pk_fma_f32 v[132:133], v[132:133], v[180:181], v[44:45] op_sel_hi:[1,0,1]
	v_cndmask_b32_e64 v216, v196, v202, s[4:5]
	v_cmp_gt_f32_e64 s[4:5], 0, v143
	v_pk_fma_f32 v[130:131], v[130:131], v[180:181], v[42:43] op_sel_hi:[1,0,1]
	v_pk_mul_f32 v[210:211], v[136:137], v[136:137]
	v_cndmask_b32_e64 v143, v201, v205, s[4:5]
	v_cmp_gt_f32_e64 s[4:5], 0, v141
	v_and_b32_e32 v225, 0x7fffffff, v131
	v_and_b32_e32 v224, 0x7fffffff, v130
	v_cndmask_b32_e64 v142, v197, v203, s[4:5]
	v_pk_add_f32 v[140:141], v[216:217], v[142:143]
	v_pk_fma_f32 v[202:203], v[128:129], v[180:181], v[40:41] op_sel_hi:[1,0,1]
	v_pk_add_f32 v[196:197], v[140:141], v[140:141] op_sel:[0,1] op_sel_hi:[1,0]
	v_pk_mul_f32 v[140:141], v[142:143], v[142:143]
	v_pk_mul_f32 v[204:205], v[132:133], v[132:133]
	v_pk_fma_f32 v[140:141], v[216:217], v[216:217], v[140:141]
	v_pk_fma_f32 v[224:225], v[224:225], s[6:7], 1.0 op_sel_hi:[1,0,0]
	v_pk_add_f32 v[200:201], v[140:141], v[140:141] op_sel_hi:[0,1]
	v_cvt_pk_bf16_f32 v140, v216, v142
	v_cvt_pk_bf16_f32 v141, v217, v143
	v_and_b32_e32 v217, 0x7fffffff, v135
	v_and_b32_e32 v216, 0x7fffffff, v134
	v_pk_fma_f32 v[216:217], v[216:217], s[6:7], 1.0 op_sel_hi:[1,0,0]
	v_and_b32_e32 v143, 0x7fffffff, v133
	v_rcp_f32_e32 v216, v216
	v_rcp_f32_e32 v217, v217
	v_and_b32_e32 v142, 0x7fffffff, v132
	v_pk_fma_f32 v[142:143], v[142:143], s[6:7], 1.0 op_sel_hi:[1,0,0]
	v_pk_mul_f32 v[204:205], v[204:205], s[14:15] op_sel_hi:[1,0]
	v_pk_fma_f32 v[218:219], v[216:217], s[0:1], v[198:199] op_sel_hi:[1,0,0]
	v_rcp_f32_e32 v142, v142
	v_pk_fma_f32 v[218:219], v[216:217], v[218:219], s[12:13] op_sel_hi:[1,1,0]
	v_rcp_f32_e32 v143, v143
	v_pk_fma_f32 v[218:219], v[216:217], v[218:219], s[8:9] op_sel_hi:[1,1,0]
	v_rcp_f32_e32 v224, v224
	v_pk_fma_f32 v[218:219], v[216:217], v[218:219], s[10:11] op_sel_hi:[1,1,0]
	v_pk_fma_f32 v[128:129], v[142:143], s[0:1], v[198:199] op_sel_hi:[1,0,0]
	v_pk_mul_f32 v[216:217], v[216:217], v[218:219]
	v_and_b32_e32 v219, 0x7fffffff, v203
	v_and_b32_e32 v218, 0x7fffffff, v202
	v_pk_fma_f32 v[218:219], v[218:219], s[6:7], 1.0 op_sel_hi:[1,0,0]
	v_pk_fma_f32 v[128:129], v[142:143], v[128:129], s[12:13] op_sel_hi:[1,1,0]
	v_rcp_f32_e32 v218, v218
	v_rcp_f32_e32 v219, v219
	v_pk_fma_f32 v[128:129], v[142:143], v[128:129], s[8:9] op_sel_hi:[1,1,0]
	v_rcp_f32_e32 v225, v225
	v_pk_fma_f32 v[128:129], v[142:143], v[128:129], s[10:11] op_sel_hi:[1,1,0]
	v_pk_fma_f32 v[220:221], v[218:219], s[0:1], v[198:199] op_sel_hi:[1,0,0]
	v_pk_mul_f32 v[128:129], v[142:143], v[128:129]
	v_pk_fma_f32 v[220:221], v[218:219], v[220:221], s[12:13] op_sel_hi:[1,1,0]
	v_pk_mul_f32 v[142:143], v[134:135], v[134:135]
	v_exp_f32_e32 v204, v204
	v_exp_f32_e32 v205, v205
	v_pk_fma_f32 v[220:221], v[218:219], v[220:221], s[8:9] op_sel_hi:[1,1,0]
	v_pk_mul_f32 v[142:143], v[142:143], s[14:15] op_sel_hi:[1,0]
	v_pk_fma_f32 v[220:221], v[218:219], v[220:221], s[10:11] op_sel_hi:[1,1,0]
	v_exp_f32_e32 v142, v142
	v_exp_f32_e32 v143, v143
	v_pk_mul_f32 v[218:219], v[218:219], v[220:221]
	v_pk_mul_f32 v[220:221], v[130:131], v[130:131]
	v_pk_fma_f32 v[198:199], v[224:225], s[0:1], v[198:199] op_sel_hi:[1,0,0]
	v_pk_mul_f32 v[220:221], v[220:221], s[14:15] op_sel_hi:[1,0]
	v_pk_mul_f32 v[128:129], v[204:205], v[128:129]
	v_pk_fma_f32 v[198:199], v[224:225], v[198:199], s[12:13] op_sel_hi:[1,1,0]
	v_exp_f32_e32 v220, v220
	v_exp_f32_e32 v221, v221
	v_pk_mul_f32 v[210:211], v[210:211], s[14:15] op_sel_hi:[1,0]
	v_pk_mul_f32 v[204:205], v[132:133], v[128:129]
	v_pk_fma_f32 v[128:129], v[132:133], v[128:129], v[132:133] neg_lo:[1,0,0] neg_hi:[1,0,0]
	v_pk_mul_f32 v[222:223], v[202:203], v[202:203]
	v_pk_fma_f32 v[198:199], v[224:225], v[198:199], s[8:9] op_sel_hi:[1,1,0]
	v_cmp_gt_f32_e64 s[4:5], 0, v133
	v_exp_f32_e32 v210, v210
	v_exp_f32_e32 v211, v211
	v_pk_mul_f32 v[142:143], v[142:143], v[216:217]
	v_pk_mul_f32 v[222:223], v[222:223], s[14:15] op_sel_hi:[1,0]
	v_pk_fma_f32 v[198:199], v[224:225], v[198:199], s[10:11] op_sel_hi:[1,1,0]
	v_cndmask_b32_e64 v133, v129, v205, s[4:5]
	v_cmp_gt_f32_e64 s[4:5], 0, v132
	v_pk_mul_f32 v[216:217], v[134:135], v[142:143]
	v_pk_fma_f32 v[142:143], v[134:135], v[142:143], v[134:135] neg_lo:[1,0,0] neg_hi:[1,0,0]
	v_exp_f32_e32 v222, v222
	v_exp_f32_e32 v223, v223
	v_pk_mul_f32 v[198:199], v[224:225], v[198:199]
	v_cndmask_b32_e64 v132, v128, v204, s[4:5]
	v_cmp_gt_f32_e64 s[4:5], 0, v135
	v_pk_mul_f32 v[198:199], v[220:221], v[198:199]
	v_pk_mul_f32 v[206:207], v[210:211], v[206:207]
	v_cndmask_b32_e64 v217, v143, v217, s[4:5]
	v_cmp_gt_f32_e64 s[4:5], 0, v134
	v_pk_mul_f32 v[220:221], v[130:131], v[198:199]
	v_pk_fma_f32 v[198:199], v[130:131], v[198:199], v[130:131] neg_lo:[1,0,0] neg_hi:[1,0,0]
	v_cndmask_b32_e64 v216, v142, v216, s[4:5]
	v_cmp_gt_f32_e64 s[4:5], 0, v131
	v_mul_f32_e32 v128, v132, v132
	v_pk_mul_f32 v[210:211], v[136:137], v[206:207]
	v_cndmask_b32_e64 v131, v199, v221, s[4:5]
	v_cmp_gt_f32_e64 s[4:5], 0, v130
	v_pk_fma_f32 v[206:207], v[136:137], v[206:207], v[136:137] neg_lo:[1,0,0] neg_hi:[1,0,0]
	v_pk_mul_f32 v[218:219], v[222:223], v[218:219]
	v_pk_fma_f32 v[204:205], v[132:133], v[132:133], v[128:129] op_sel_hi:[1,1,0]
	v_mov_b32_e32 v128, v132
	v_mov_b32_e32 v129, v216
	v_mov_b32_e32 v134, v133
	v_mov_b32_e32 v135, v217
	v_cndmask_b32_e64 v130, v198, v220, s[4:5]
	v_cmp_gt_f32_e64 s[4:5], 0, v136
	v_pk_mul_f32 v[222:223], v[202:203], v[218:219]
	v_pk_fma_f32 v[218:219], v[202:203], v[218:219], v[202:203] neg_lo:[1,0,0] neg_hi:[1,0,0]
	v_pk_add_f32 v[134:135], v[128:129], v[134:135]
	v_mul_f32_e32 v128, v216, v216
	v_cndmask_b32_e64 v198, v206, v210, s[4:5]
	v_cmp_gt_f32_e64 s[4:5], 0, v202
	v_cmp_eq_u32_e32 vcc, 0, v175
	v_ashrrev_i32_e32 v175, 31, v174
	v_pk_fma_f32 v[224:225], v[216:217], v[216:217], v[128:129] op_sel_hi:[1,1,0]
	v_mul_f32_e32 v128, v130, v130
	v_cndmask_b32_e64 v199, v218, v222, s[4:5]
	v_cmp_gt_f32_e64 s[4:5], 0, v137
	v_lshlrev_b64 v[182:183], 13, v[174:175]
	v_pk_fma_f32 v[128:129], v[130:131], v[130:131], v[128:129] op_sel_hi:[1,1,0]
	v_cndmask_b32_e64 v136, v207, v211, s[4:5]
	v_cmp_gt_f32_e64 s[4:5], 0, v138
	v_lshl_add_u64 v[182:183], s[28:29], 0, v[182:183]
	v_mov_b32_e32 v142, v198
	v_mov_b32_e32 v143, v136
	v_mul_f32_e32 v128, v198, v198
	v_cndmask_b32_e64 v139, v208, v212, s[4:5]
	v_cmp_gt_f32_e64 s[4:5], 0, v203
	v_lshl_add_u64 v[182:183], v[170:171], 1, v[182:183]
	v_pk_fma_f32 v[206:207], v[142:143], v[142:143], v[128:129] op_sel_hi:[1,1,0]
	v_cvt_pk_bf16_f32 v142, v198, v136
	v_mov_b32_e32 v138, v199
	v_cndmask_b32_e64 v202, v219, v223, s[4:5]
	v_mov_b32_e32 v203, v139
	v_cvt_pk_bf16_f32 v143, v139, v214
	v_mul_f32_e32 v195, v214, v214
	global_store_dwordx4 v[182:183], v[140:143], off
	v_pk_add_f32 v[134:135], v[134:135], v[134:135] op_sel:[0,1] op_sel_hi:[1,0]
	v_mov_b32_e32 v206, v130
	v_pk_add_f32 v[140:141], v[138:139], v[202:203]
	v_pk_mul_f32 v[142:143], v[138:139], v[202:203]
	v_mov_b32_e32 v135, v195
	v_mov_b32_e32 v141, v143
	v_mov_b32_e32 v200, v131
	v_mov_b32_e32 v137, v199
	v_pk_add_f32 v[134:135], v[140:141], v[134:135]
	v_pk_add_f32 v[140:141], v[206:207], v[200:201]
	v_mov_b32_e32 v204, v139
	v_pk_add_f32 v[134:135], v[134:135], v[140:141]
	v_pk_add_f32 v[140:141], v[198:199], v[136:137]
	v_pk_mul_f32 v[136:137], v[198:199], v[136:137]
	v_mov_b32_e32 v215, v225
	v_mov_b32_e32 v141, v137
	v_pk_mul_f32 v[136:137], v[202:203], v[202:203]
	v_pk_add_f32 v[138:139], v[204:205], v[214:215]
	v_mov_b32_e32 v197, v136
	v_pk_add_f32 v[136:137], v[140:141], v[196:197]
	v_mov_b32_e32 v128, 0
	v_pk_add_f32 v[136:137], v[136:137], v[138:139]
	s_cmp_gt_i32 s15, 7
	v_pk_add_f32 v[136:137], v[136:137], v[128:129]
	v_mbcnt_lo_u32_b32 v129, -1, 0
	v_mbcnt_hi_u32_b32 v129, -1, v129
	v_pk_add_f32 v[140:141], v[134:135], v[136:137]
	v_and_b32_e32 v135, 64, v129
	v_xor_b32_e32 v134, 16, v129
	v_add_u32_e32 v135, 64, v135
	v_cmp_lt_i32_e64 s[4:5], v134, v135
	v_cvt_pk_bf16_f32 v136, v132, v133
	v_xor_b32_e32 v132, 32, v129
	v_cvt_pk_bf16_f32 v137, v216, v217
	v_cvt_pk_bf16_f32 v138, v199, v202
	v_cvt_pk_bf16_f32 v139, v130, v131
	s_nop 0
	v_cndmask_b32_e64 v134, v129, v134, s[4:5]
	v_lshlrev_b32_e32 v134, 2, v134
	v_mov_b32_e32 v142, v140
	v_mov_b32_e32 v143, v141
	s_nop 1
	v_permlane16_swap_b32_e32 v142, v140
	v_permlane16_swap_b32_e32 v143, v141
	v_cmp_lt_i32_e64 s[4:5], v132, v135
	global_store_dwordx4 v[182:183], v[136:139], off offset:256
	s_waitcnt lgkmcnt(0)
	v_pk_add_f32 v[130:131], v[140:141], v[142:143]
	v_cndmask_b32_e64 v129, v129, v132, s[4:5]
	v_lshlrev_b32_e32 v135, 2, v129
	v_mov_b32_e32 v132, v130
	v_mov_b32_e32 v133, v131
	s_nop 1
	v_permlane32_swap_b32_e32 v132, v130
	v_permlane32_swap_b32_e32 v133, v131
	s_cselect_b64 s[4:5], -1, 0
	s_and_b64 s[4:5], s[4:5], vcc
	s_and_saveexec_b64 s[18:19], s[4:5]
	s_cbranch_execz .LBB0_308
	s_lshl_b32 s1, s15, 3
	s_waitcnt lgkmcnt(0)
	v_pk_add_f32 v[130:131], v[130:131], v[132:133]
	v_lshlrev_b64 v[132:133], 8, v[174:175]
	s_add_i32 s20, s1, s72
	v_lshl_add_u64 v[132:133], s[26:27], 0, v[132:133]
	s_ashr_i32 s21, s20, 31
	v_lshl_add_u64 v[132:133], s[20:21], 2, v[132:133]
	global_store_dwordx2 v[132:133], v[130:131], off
.LBB0_308:
	s_or_b64 exec, exec, s[18:19]
	v_mov_b32_e32 v136, v181
	v_pk_fma_f32 v[126:127], v[126:127], v[136:137], v[54:55] op_sel_hi:[1,0,1]
	v_mov_b64_e32 v[140:141], s[16:17]
	v_and_b32_e32 v183, 0x7fffffff, v127
	v_and_b32_e32 v182, 0x7fffffff, v126
	v_pk_fma_f32 v[182:183], v[182:183], s[6:7], 1.0 op_sel_hi:[1,0,0]
	v_pk_fma_f32 v[120:121], v[120:121], v[136:137], v[48:49] op_sel_hi:[1,0,1]
	v_rcp_f32_e32 v182, v182
	v_rcp_f32_e32 v183, v183
	v_pk_fma_f32 v[124:125], v[124:125], v[136:137], v[52:53] op_sel_hi:[1,0,1]
	v_pk_fma_f32 v[122:123], v[122:123], v[136:137], v[50:51] op_sel_hi:[1,0,1]
	v_and_b32_e32 v139, 0x7fffffff, v125
	v_pk_fma_f32 v[196:197], v[182:183], s[0:1], v[140:141] op_sel_hi:[1,0,0]
	v_and_b32_e32 v138, 0x7fffffff, v124
	v_pk_fma_f32 v[196:197], v[182:183], v[196:197], s[12:13] op_sel_hi:[1,1,0]
	v_pk_fma_f32 v[138:139], v[138:139], s[6:7], 1.0 op_sel_hi:[1,0,0]
	v_pk_fma_f32 v[196:197], v[182:183], v[196:197], s[8:9] op_sel_hi:[1,1,0]
	v_rcp_f32_e32 v138, v138
	v_pk_fma_f32 v[196:197], v[182:183], v[196:197], s[10:11] op_sel_hi:[1,1,0]
	v_rcp_f32_e32 v139, v139
	v_pk_mul_f32 v[182:183], v[182:183], v[196:197]
	v_and_b32_e32 v197, 0x7fffffff, v121
	v_and_b32_e32 v196, 0x7fffffff, v120
	v_pk_fma_f32 v[196:197], v[196:197], s[6:7], 1.0 op_sel_hi:[1,0,0]
	v_and_b32_e32 v203, 0x7fffffff, v123
	v_rcp_f32_e32 v196, v196
	v_rcp_f32_e32 v197, v197
	v_and_b32_e32 v202, 0x7fffffff, v122
	v_pk_fma_f32 v[202:203], v[202:203], s[6:7], 1.0 op_sel_hi:[1,0,0]
	v_pk_fma_f32 v[142:143], v[138:139], s[0:1], v[140:141] op_sel_hi:[1,0,0]
	v_pk_fma_f32 v[198:199], v[196:197], s[0:1], v[140:141] op_sel_hi:[1,0,0]
	v_rcp_f32_e32 v202, v202
	v_pk_fma_f32 v[198:199], v[196:197], v[198:199], s[12:13] op_sel_hi:[1,1,0]
	v_rcp_f32_e32 v203, v203
	v_pk_fma_f32 v[142:143], v[138:139], v[142:143], s[12:13] op_sel_hi:[1,1,0]
	v_pk_fma_f32 v[198:199], v[196:197], v[198:199], s[8:9] op_sel_hi:[1,1,0]
	v_pk_fma_f32 v[142:143], v[138:139], v[142:143], s[8:9] op_sel_hi:[1,1,0]
	v_pk_fma_f32 v[198:199], v[196:197], v[198:199], s[10:11] op_sel_hi:[1,1,0]
	v_pk_fma_f32 v[142:143], v[138:139], v[142:143], s[10:11] op_sel_hi:[1,1,0]
	v_pk_mul_f32 v[196:197], v[196:197], v[198:199]
	v_pk_mul_f32 v[198:199], v[122:123], v[122:123]
	v_pk_mul_f32 v[138:139], v[138:139], v[142:143]
	v_pk_mul_f32 v[142:143], v[126:127], v[126:127]
	v_pk_fma_f32 v[204:205], v[202:203], s[0:1], v[140:141] op_sel_hi:[1,0,0]
	v_pk_mul_f32 v[198:199], v[198:199], s[14:15] op_sel_hi:[1,0]
	v_pk_mul_f32 v[180:181], v[124:125], v[124:125]
	v_pk_mul_f32 v[142:143], v[142:143], s[14:15] op_sel_hi:[1,0]
	v_pk_fma_f32 v[204:205], v[202:203], v[204:205], s[12:13] op_sel_hi:[1,1,0]
	v_exp_f32_e32 v198, v198
	v_exp_f32_e32 v199, v199
	v_pk_mul_f32 v[180:181], v[180:181], s[14:15] op_sel_hi:[1,0]
	v_exp_f32_e32 v142, v142
	v_exp_f32_e32 v143, v143
	v_pk_fma_f32 v[204:205], v[202:203], v[204:205], s[8:9] op_sel_hi:[1,1,0]
	v_exp_f32_e32 v180, v180
	v_exp_f32_e32 v181, v181
	v_pk_fma_f32 v[204:205], v[202:203], v[204:205], s[10:11] op_sel_hi:[1,1,0]
	v_pk_mul_f32 v[142:143], v[142:143], v[182:183]
	v_pk_mul_f32 v[202:203], v[202:203], v[204:205]
	v_cmp_gt_f32_e32 vcc, 0, v123
	v_pk_mul_f32 v[198:199], v[198:199], v[202:203]
	v_pk_mul_f32 v[138:139], v[180:181], v[138:139]
	v_pk_mul_f32 v[202:203], v[122:123], v[198:199]
	v_pk_fma_f32 v[198:199], v[122:123], v[198:199], v[122:123] neg_lo:[1,0,0] neg_hi:[1,0,0]
	v_pk_mul_f32 v[182:183], v[126:127], v[142:143]
	v_pk_fma_f32 v[142:143], v[126:127], v[142:143], v[126:127] neg_lo:[1,0,0] neg_hi:[1,0,0]
	v_cndmask_b32_e32 v204, v199, v203, vcc
	v_cmp_gt_f32_e32 vcc, 0, v126
	v_pk_mul_f32 v[180:181], v[124:125], v[138:139]
	v_pk_fma_f32 v[138:139], v[124:125], v[138:139], v[124:125] neg_lo:[1,0,0] neg_hi:[1,0,0]
	v_cndmask_b32_e32 v207, v142, v182, vcc
	v_cmp_gt_f32_e32 vcc, 0, v124
	v_pk_fma_f32 v[118:119], v[118:119], v[136:137], v[46:47] op_sel_hi:[1,0,1]
	v_pk_fma_f32 v[116:117], v[116:117], v[136:137], v[44:45] op_sel_hi:[1,0,1]
	v_cndmask_b32_e32 v206, v138, v180, vcc
	v_cmp_gt_f32_e32 vcc, 0, v127
	v_and_b32_e32 v182, 0x7fffffff, v118
	v_pk_fma_f32 v[112:113], v[112:113], v[136:137], v[40:41] op_sel_hi:[1,0,1]
	v_cndmask_b32_e32 v127, v143, v183, vcc
	v_and_b32_e32 v183, 0x7fffffff, v119
	v_cmp_gt_f32_e32 vcc, 0, v125
	v_pk_fma_f32 v[182:183], v[182:183], s[6:7], 1.0 op_sel_hi:[1,0,0]
	v_pk_fma_f32 v[114:115], v[114:115], v[136:137], v[42:43] op_sel_hi:[1,0,1]
	v_cndmask_b32_e32 v126, v139, v181, vcc
	v_rcp_f32_e32 v182, v182
	v_rcp_f32_e32 v183, v183
	v_pk_add_f32 v[124:125], v[206:207], v[126:127]
	v_and_b32_e32 v213, 0x7fffffff, v115
	v_pk_add_f32 v[138:139], v[124:125], v[124:125] op_sel:[0,1] op_sel_hi:[1,0]
	v_pk_mul_f32 v[124:125], v[126:127], v[126:127]
	v_and_b32_e32 v212, 0x7fffffff, v114
	v_pk_fma_f32 v[124:125], v[206:207], v[206:207], v[124:125]
	v_pk_mul_f32 v[180:181], v[116:117], v[116:117]
	v_pk_add_f32 v[142:143], v[124:125], v[124:125] op_sel_hi:[0,1]
	v_cvt_pk_bf16_f32 v124, v206, v126
	v_cvt_pk_bf16_f32 v125, v207, v127
	v_pk_fma_f32 v[206:207], v[182:183], s[0:1], v[140:141] op_sel_hi:[1,0,0]
	v_and_b32_e32 v127, 0x7fffffff, v117
	v_pk_fma_f32 v[206:207], v[182:183], v[206:207], s[12:13] op_sel_hi:[1,1,0]
	v_and_b32_e32 v126, 0x7fffffff, v116
	v_pk_fma_f32 v[206:207], v[182:183], v[206:207], s[8:9] op_sel_hi:[1,1,0]
	v_pk_fma_f32 v[126:127], v[126:127], s[6:7], 1.0 op_sel_hi:[1,0,0]
	v_pk_fma_f32 v[206:207], v[182:183], v[206:207], s[10:11] op_sel_hi:[1,1,0]
	v_rcp_f32_e32 v126, v126
	v_rcp_f32_e32 v127, v127
	v_pk_mul_f32 v[182:183], v[182:183], v[206:207]
	v_and_b32_e32 v207, 0x7fffffff, v113
	v_and_b32_e32 v206, 0x7fffffff, v112
	v_pk_fma_f32 v[206:207], v[206:207], s[6:7], 1.0 op_sel_hi:[1,0,0]
	v_pk_fma_f32 v[136:137], v[126:127], s[0:1], v[140:141] op_sel_hi:[1,0,0]
	v_rcp_f32_e32 v206, v206
	v_rcp_f32_e32 v207, v207
	v_pk_fma_f32 v[136:137], v[126:127], v[136:137], s[12:13] op_sel_hi:[1,1,0]
	v_pk_fma_f32 v[212:213], v[212:213], s[6:7], 1.0 op_sel_hi:[1,0,0]
	v_pk_fma_f32 v[136:137], v[126:127], v[136:137], s[8:9] op_sel_hi:[1,1,0]
	v_pk_fma_f32 v[208:209], v[206:207], s[0:1], v[140:141] op_sel_hi:[1,0,0]
	v_pk_fma_f32 v[136:137], v[126:127], v[136:137], s[10:11] op_sel_hi:[1,1,0]
	v_pk_mul_f32 v[180:181], v[180:181], s[14:15] op_sel_hi:[1,0]
	v_pk_fma_f32 v[208:209], v[206:207], v[208:209], s[12:13] op_sel_hi:[1,1,0]
	v_rcp_f32_e32 v212, v212
	v_rcp_f32_e32 v213, v213
	v_pk_mul_f32 v[126:127], v[126:127], v[136:137]
	v_pk_mul_f32 v[136:137], v[118:119], v[118:119]
	v_exp_f32_e32 v180, v180
	v_exp_f32_e32 v181, v181
	v_pk_fma_f32 v[208:209], v[206:207], v[208:209], s[8:9] op_sel_hi:[1,1,0]
	v_pk_mul_f32 v[136:137], v[136:137], s[14:15] op_sel_hi:[1,0]
	v_pk_fma_f32 v[208:209], v[206:207], v[208:209], s[10:11] op_sel_hi:[1,1,0]
	v_exp_f32_e32 v136, v136
	v_exp_f32_e32 v137, v137
	v_pk_mul_f32 v[206:207], v[206:207], v[208:209]
	v_pk_mul_f32 v[208:209], v[114:115], v[114:115]
	v_pk_fma_f32 v[140:141], v[212:213], s[0:1], v[140:141] op_sel_hi:[1,0,0]
	v_pk_mul_f32 v[208:209], v[208:209], s[14:15] op_sel_hi:[1,0]
	v_pk_mul_f32 v[200:201], v[120:121], v[120:121]
	v_pk_mul_f32 v[126:127], v[180:181], v[126:127]
	v_pk_fma_f32 v[140:141], v[212:213], v[140:141], s[12:13] op_sel_hi:[1,1,0]
	v_exp_f32_e32 v208, v208
	v_exp_f32_e32 v209, v209
	v_pk_mul_f32 v[200:201], v[200:201], s[14:15] op_sel_hi:[1,0]
	v_pk_mul_f32 v[180:181], v[116:117], v[126:127]
	v_pk_fma_f32 v[126:127], v[116:117], v[126:127], v[116:117] neg_lo:[1,0,0] neg_hi:[1,0,0]
	v_pk_mul_f32 v[210:211], v[112:113], v[112:113]
	v_pk_fma_f32 v[140:141], v[212:213], v[140:141], s[8:9] op_sel_hi:[1,1,0]
	v_cmp_gt_f32_e32 vcc, 0, v117
	v_exp_f32_e32 v200, v200
	v_exp_f32_e32 v201, v201
	v_pk_mul_f32 v[136:137], v[136:137], v[182:183]
	v_pk_mul_f32 v[210:211], v[210:211], s[14:15] op_sel_hi:[1,0]
	v_pk_fma_f32 v[140:141], v[212:213], v[140:141], s[10:11] op_sel_hi:[1,1,0]
	v_cndmask_b32_e32 v117, v127, v181, vcc
	v_cmp_gt_f32_e32 vcc, 0, v116
	v_pk_mul_f32 v[182:183], v[118:119], v[136:137]
	v_pk_fma_f32 v[136:137], v[118:119], v[136:137], v[118:119] neg_lo:[1,0,0] neg_hi:[1,0,0]
	v_exp_f32_e32 v210, v210
	v_exp_f32_e32 v211, v211
	v_pk_mul_f32 v[140:141], v[212:213], v[140:141]
	v_cndmask_b32_e32 v116, v126, v180, vcc
	v_cmp_gt_f32_e32 vcc, 0, v119
	v_pk_mul_f32 v[140:141], v[208:209], v[140:141]
	v_pk_mul_f32 v[196:197], v[200:201], v[196:197]
	v_cndmask_b32_e32 v119, v137, v183, vcc
	v_cmp_gt_f32_e32 vcc, 0, v118
	v_pk_mul_f32 v[208:209], v[114:115], v[140:141]
	v_pk_fma_f32 v[140:141], v[114:115], v[140:141], v[114:115] neg_lo:[1,0,0] neg_hi:[1,0,0]
	v_cndmask_b32_e32 v118, v136, v182, vcc
	v_cmp_gt_f32_e32 vcc, 0, v115
	v_pk_mul_f32 v[200:201], v[120:121], v[196:197]
	v_pk_fma_f32 v[196:197], v[120:121], v[196:197], v[120:121] neg_lo:[1,0,0] neg_hi:[1,0,0]
	v_cndmask_b32_e32 v141, v141, v209, vcc
	v_cmp_gt_f32_e32 vcc, 0, v114
	v_pk_mul_f32 v[206:207], v[210:211], v[206:207]
	v_mov_b32_e32 v136, v116
	v_cndmask_b32_e32 v140, v140, v208, vcc
	v_cmp_gt_f32_e32 vcc, 0, v120
	v_pk_mul_f32 v[210:211], v[112:113], v[206:207]
	v_pk_fma_f32 v[206:207], v[112:113], v[206:207], v[112:113] neg_lo:[1,0,0] neg_hi:[1,0,0]
	v_cndmask_b32_e32 v182, v196, v200, vcc
	v_cmp_gt_f32_e32 vcc, 0, v112
	v_mov_b32_e32 v137, v118
	v_mov_b32_e32 v180, v117
	v_cndmask_b32_e32 v183, v206, v210, vcc
	v_cmp_gt_f32_e32 vcc, 0, v121
	v_mov_b32_e32 v181, v119
	v_pk_add_f32 v[136:137], v[136:137], v[180:181]
	v_cndmask_b32_e32 v120, v197, v201, vcc
	v_cmp_gt_f32_e32 vcc, 0, v122
	v_mov_b32_e32 v196, v182
	v_mov_b32_e32 v197, v120
	v_cndmask_b32_e32 v123, v198, v202, vcc
	v_cmp_gt_f32_e32 vcc, 0, v113
	v_mul_f32_e32 v112, v182, v182
	v_mov_b32_e32 v122, v183
	v_cndmask_b32_e32 v198, v207, v211, vcc
	v_mov_b32_e32 v199, v123
	v_mul_f32_e32 v129, v204, v204
	v_pk_fma_f32 v[196:197], v[196:197], v[196:197], v[112:113] op_sel_hi:[1,1,0]
	v_pk_add_f32 v[112:113], v[122:123], v[198:199]
	v_pk_mul_f32 v[200:201], v[122:123], v[198:199]
	v_pk_add_f32 v[136:137], v[136:137], v[136:137] op_sel:[0,1] op_sel_hi:[1,0]
	v_mul_f32_e32 v126, v116, v116
	v_mov_b32_e32 v113, v201
	v_mov_b32_e32 v137, v129
	v_mov_b32_e32 v196, v140
	v_mov_b32_e32 v142, v141
	v_pk_fma_f32 v[126:127], v[116:117], v[116:117], v[126:127] op_sel_hi:[1,1,0]
	v_mov_b32_e32 v121, v183
	v_pk_add_f32 v[112:113], v[112:113], v[136:137]
	v_pk_add_f32 v[136:137], v[196:197], v[142:143]
	v_mul_f32_e32 v126, v118, v118
	v_pk_add_f32 v[112:113], v[112:113], v[136:137]
	v_pk_add_f32 v[136:137], v[182:183], v[120:121]
	v_pk_mul_f32 v[142:143], v[182:183], v[120:121]
	v_pk_fma_f32 v[180:181], v[118:119], v[118:119], v[126:127] op_sel_hi:[1,1,0]
	v_mov_b32_e32 v137, v143
	v_pk_mul_f32 v[142:143], v[198:199], v[198:199]
	v_mul_f32_e32 v114, v140, v140
	v_mov_b32_e32 v126, v123
	v_mov_b32_e32 v205, v181
	v_mov_b32_e32 v139, v142
	v_pk_fma_f32 v[114:115], v[140:141], v[140:141], v[114:115] op_sel_hi:[1,1,0]
	v_pk_add_f32 v[126:127], v[126:127], v[204:205]
	v_pk_add_f32 v[136:137], v[136:137], v[138:139]
	v_mov_b32_e32 v129, v115
	v_pk_add_f32 v[126:127], v[136:137], v[126:127]
	v_add_u32_e32 v130, 16, v174
	v_pk_add_f32 v[114:115], v[126:127], v[128:129]
	v_ashrrev_i32_e32 v131, 31, v130
	v_pk_add_f32 v[112:113], v[112:113], v[114:115]
	v_mov_b32_e32 v114, v112
	v_mov_b32_e32 v115, v113
	s_nop 1
	v_permlane16_swap_b32_e32 v114, v112
	v_permlane16_swap_b32_e32 v115, v113
	s_waitcnt lgkmcnt(2)
	v_lshlrev_b64 v[132:133], 13, v[130:131]
	v_lshl_add_u64 v[132:133], s[28:29], 0, v[132:133]
	v_lshl_add_u64 v[132:133], v[170:171], 1, v[132:133]
	v_cvt_pk_bf16_f32 v126, v182, v120
	s_waitcnt lgkmcnt(0)
	v_pk_add_f32 v[112:113], v[112:113], v[114:115]
	v_mov_b32_e32 v114, v112
	v_mov_b32_e32 v115, v113
	s_nop 1
	v_permlane32_swap_b32_e32 v114, v112
	v_permlane32_swap_b32_e32 v115, v113
	v_cvt_pk_bf16_f32 v127, v123, v204
	global_store_dwordx4 v[132:133], v[124:127], off
	v_cvt_pk_bf16_f32 v116, v116, v117
	v_cvt_pk_bf16_f32 v117, v118, v119
	v_cvt_pk_bf16_f32 v118, v183, v198
	v_cvt_pk_bf16_f32 v119, v140, v141
	global_store_dwordx4 v[132:133], v[116:119], off offset:256
	s_and_saveexec_b64 s[0:1], s[4:5]
	s_cbranch_execz .LBB0_310
	s_lshl_b32 s6, s15, 3
	s_waitcnt lgkmcnt(0)
	v_pk_add_f32 v[112:113], v[112:113], v[114:115]
	v_lshlrev_b64 v[114:115], 8, v[130:131]
	s_add_i32 s6, s6, s72
	v_lshl_add_u64 v[114:115], s[26:27], 0, v[114:115]
	s_ashr_i32 s7, s6, 31
	v_lshl_add_u64 v[114:115], s[6:7], 2, v[114:115]
	global_store_dwordx2 v[114:115], v[112:113], off
.LBB0_310:
	s_or_b64 exec, exec, s[0:1]
	v_pk_fma_f32 v[116:117], v[108:109], v[178:179], v[52:53] op_sel_hi:[1,0,1]
	s_mov_b32 s6, 0x3e6d3388
	v_and_b32_e32 v109, 0x7fffffff, v117
	v_and_b32_e32 v108, 0x7fffffff, v116
	v_pk_fma_f32 v[108:109], v[108:109], s[6:7], 1.0 op_sel_hi:[1,0,0]
	v_pk_fma_f32 v[110:111], v[110:111], v[178:179], v[54:55] op_sel_hi:[1,0,1]
	v_rcp_f32_e32 v108, v108
	v_rcp_f32_e32 v109, v109
	s_mov_b32 s0, 0x3f07dc22
	v_mov_b64_e32 v[118:119], s[16:17]
	v_pk_mul_f32 v[122:123], v[116:117], v[116:117]
	v_pk_fma_f32 v[120:121], v[108:109], s[0:1], v[118:119] op_sel_hi:[1,0,0]
	v_pk_mul_f32 v[122:123], v[122:123], s[14:15] op_sel_hi:[1,0]
	v_and_b32_e32 v125, 0x7fffffff, v111
	v_and_b32_e32 v124, 0x7fffffff, v110
	v_pk_fma_f32 v[120:121], v[108:109], v[120:121], s[12:13] op_sel_hi:[1,1,0]
	v_exp_f32_e32 v122, v122
	v_exp_f32_e32 v123, v123
	v_pk_fma_f32 v[124:125], v[124:125], s[6:7], 1.0 op_sel_hi:[1,0,0]
	v_pk_fma_f32 v[120:121], v[108:109], v[120:121], s[8:9] op_sel_hi:[1,1,0]
	v_rcp_f32_e32 v124, v124
	v_rcp_f32_e32 v125, v125
	v_pk_fma_f32 v[120:121], v[108:109], v[120:121], s[10:11] op_sel_hi:[1,1,0]
	v_pk_fma_f32 v[104:105], v[104:105], v[178:179], v[48:49] op_sel_hi:[1,0,1]
	v_pk_mul_f32 v[108:109], v[108:109], v[120:121]
	v_pk_mul_f32 v[120:121], v[110:111], v[110:111]
	v_pk_mul_f32 v[108:109], v[122:123], v[108:109]
	v_pk_mul_f32 v[120:121], v[120:121], s[14:15] op_sel_hi:[1,0]
	v_pk_mul_f32 v[122:123], v[116:117], v[108:109]
	v_pk_fma_f32 v[126:127], v[116:117], v[108:109], v[116:117] neg_lo:[1,0,0] neg_hi:[1,0,0]
	v_pk_fma_f32 v[108:109], v[124:125], s[0:1], v[118:119] op_sel_hi:[1,0,0]
	v_exp_f32_e32 v120, v120
	v_pk_fma_f32 v[108:109], v[124:125], v[108:109], s[12:13] op_sel_hi:[1,1,0]
	v_exp_f32_e32 v121, v121
	v_pk_fma_f32 v[108:109], v[124:125], v[108:109], s[8:9] op_sel_hi:[1,1,0]
	v_pk_fma_f32 v[106:107], v[106:107], v[178:179], v[50:51] op_sel_hi:[1,0,1]
	v_pk_fma_f32 v[108:109], v[124:125], v[108:109], s[10:11] op_sel_hi:[1,1,0]
	v_pk_mul_f32 v[130:131], v[104:105], v[104:105]
	v_pk_mul_f32 v[108:109], v[124:125], v[108:109]
	v_and_b32_e32 v125, 0x7fffffff, v105
	v_and_b32_e32 v124, 0x7fffffff, v104
	v_pk_fma_f32 v[124:125], v[124:125], s[6:7], 1.0 op_sel_hi:[1,0,0]
	v_pk_mul_f32 v[108:109], v[120:121], v[108:109]
	v_rcp_f32_e32 v124, v124
	v_rcp_f32_e32 v125, v125
	v_pk_mul_f32 v[120:121], v[110:111], v[108:109]
	v_pk_fma_f32 v[128:129], v[110:111], v[108:109], v[110:111] neg_lo:[1,0,0] neg_hi:[1,0,0]
	v_pk_mul_f32 v[130:131], v[130:131], s[14:15] op_sel_hi:[1,0]
	v_pk_fma_f32 v[108:109], v[124:125], s[0:1], v[118:119] op_sel_hi:[1,0,0]
	v_and_b32_e32 v133, 0x7fffffff, v107
	v_and_b32_e32 v132, 0x7fffffff, v106
	v_pk_fma_f32 v[108:109], v[124:125], v[108:109], s[12:13] op_sel_hi:[1,1,0]
	v_exp_f32_e32 v130, v130
	v_exp_f32_e32 v131, v131
	v_pk_fma_f32 v[132:133], v[132:133], s[6:7], 1.0 op_sel_hi:[1,0,0]
	v_pk_fma_f32 v[108:109], v[124:125], v[108:109], s[8:9] op_sel_hi:[1,1,0]
	v_rcp_f32_e32 v132, v132
	v_rcp_f32_e32 v133, v133
	v_pk_fma_f32 v[108:109], v[124:125], v[108:109], s[10:11] op_sel_hi:[1,1,0]
	v_cmp_gt_f32_e32 vcc, 0, v107
	v_pk_mul_f32 v[108:109], v[124:125], v[108:109]
	v_pk_mul_f32 v[124:125], v[106:107], v[106:107]
	v_pk_mul_f32 v[108:109], v[130:131], v[108:109]
	v_pk_mul_f32 v[124:125], v[124:125], s[14:15] op_sel_hi:[1,0]
	v_pk_mul_f32 v[130:131], v[104:105], v[108:109]
	v_pk_fma_f32 v[136:137], v[104:105], v[108:109], v[104:105] neg_lo:[1,0,0] neg_hi:[1,0,0]
	v_pk_fma_f32 v[108:109], v[132:133], s[0:1], v[118:119] op_sel_hi:[1,0,0]
	v_exp_f32_e32 v124, v124
	v_pk_fma_f32 v[108:109], v[132:133], v[108:109], s[12:13] op_sel_hi:[1,1,0]
	v_exp_f32_e32 v125, v125
	v_pk_fma_f32 v[108:109], v[132:133], v[108:109], s[8:9] op_sel_hi:[1,1,0]
	v_pk_fma_f32 v[102:103], v[102:103], v[178:179], v[46:47] op_sel_hi:[1,0,1]
	v_pk_fma_f32 v[108:109], v[132:133], v[108:109], s[10:11] op_sel_hi:[1,1,0]
	v_pk_fma_f32 v[100:101], v[100:101], v[178:179], v[44:45] op_sel_hi:[1,0,1]
	v_pk_mul_f32 v[108:109], v[132:133], v[108:109]
	v_pk_fma_f32 v[98:99], v[98:99], v[178:179], v[42:43] op_sel_hi:[1,0,1]
	v_pk_mul_f32 v[108:109], v[124:125], v[108:109]
	v_and_b32_e32 v183, 0x7fffffff, v99
	v_pk_mul_f32 v[124:125], v[106:107], v[108:109]
	v_pk_fma_f32 v[132:133], v[106:107], v[108:109], v[106:107] neg_lo:[1,0,0] neg_hi:[1,0,0]
	v_and_b32_e32 v182, 0x7fffffff, v98
	v_cndmask_b32_e32 v108, v133, v125, vcc
	v_cmp_gt_f32_e32 vcc, 0, v110
	v_pk_fma_f32 v[182:183], v[182:183], s[6:7], 1.0 op_sel_hi:[1,0,0]
	v_mul_f32_e32 v109, v108, v108
	v_cndmask_b32_e32 v139, v128, v120, vcc
	v_cmp_gt_f32_e32 vcc, 0, v116
	v_rcp_f32_e32 v182, v182
	v_rcp_f32_e32 v183, v183
	v_cndmask_b32_e32 v138, v126, v122, vcc
	v_cmp_gt_f32_e32 vcc, 0, v111
	v_add_u32_e32 v112, 32, v174
	v_ashrrev_i32_e32 v113, 31, v112
	v_cndmask_b32_e32 v111, v129, v121, vcc
	v_cmp_gt_f32_e32 vcc, 0, v117
	v_pk_mul_f32 v[128:129], v[100:101], v[100:101]
	s_waitcnt lgkmcnt(0)
	v_lshlrev_b64 v[114:115], 13, v[112:113]
	v_cndmask_b32_e32 v110, v127, v123, vcc
	v_pk_add_f32 v[116:117], v[138:139], v[110:111]
	v_pk_fma_f32 v[126:127], v[96:97], v[178:179], v[40:41] op_sel_hi:[1,0,1]
	v_pk_add_f32 v[120:121], v[116:117], v[116:117] op_sel:[0,1] op_sel_hi:[1,0]
	v_pk_mul_f32 v[116:117], v[110:111], v[110:111]
	v_pk_mul_f32 v[128:129], v[128:129], s[14:15] op_sel_hi:[1,0]
	v_pk_fma_f32 v[116:117], v[138:139], v[138:139], v[116:117]
	v_exp_f32_e32 v128, v128
	v_pk_add_f32 v[122:123], v[116:117], v[116:117] op_sel_hi:[0,1]
	v_cvt_pk_bf16_f32 v116, v138, v110
	v_cvt_pk_bf16_f32 v117, v139, v111
	v_and_b32_e32 v139, 0x7fffffff, v103
	v_and_b32_e32 v138, 0x7fffffff, v102
	v_pk_fma_f32 v[138:139], v[138:139], s[6:7], 1.0 op_sel_hi:[1,0,0]
	v_and_b32_e32 v111, 0x7fffffff, v101
	v_rcp_f32_e32 v138, v138
	v_rcp_f32_e32 v139, v139
	v_and_b32_e32 v110, 0x7fffffff, v100
	v_pk_fma_f32 v[110:111], v[110:111], s[6:7], 1.0 op_sel_hi:[1,0,0]
	v_exp_f32_e32 v129, v129
	v_pk_fma_f32 v[140:141], v[138:139], s[0:1], v[118:119] op_sel_hi:[1,0,0]
	v_rcp_f32_e32 v110, v110
	v_pk_fma_f32 v[140:141], v[138:139], v[140:141], s[12:13] op_sel_hi:[1,1,0]
	v_rcp_f32_e32 v111, v111
	v_pk_fma_f32 v[140:141], v[138:139], v[140:141], s[8:9] op_sel_hi:[1,1,0]
	v_pk_mul_f32 v[180:181], v[126:127], v[126:127]
	v_pk_fma_f32 v[140:141], v[138:139], v[140:141], s[10:11] op_sel_hi:[1,1,0]
	v_pk_fma_f32 v[96:97], v[110:111], s[0:1], v[118:119] op_sel_hi:[1,0,0]
	v_pk_mul_f32 v[138:139], v[138:139], v[140:141]
	v_and_b32_e32 v141, 0x7fffffff, v127
	v_and_b32_e32 v140, 0x7fffffff, v126
	v_pk_fma_f32 v[140:141], v[140:141], s[6:7], 1.0 op_sel_hi:[1,0,0]
	v_pk_fma_f32 v[96:97], v[110:111], v[96:97], s[12:13] op_sel_hi:[1,1,0]
	v_rcp_f32_e32 v140, v140
	v_rcp_f32_e32 v141, v141
	v_pk_fma_f32 v[96:97], v[110:111], v[96:97], s[8:9] op_sel_hi:[1,1,0]
	v_cmp_gt_f32_e32 vcc, 0, v101
	v_pk_fma_f32 v[96:97], v[110:111], v[96:97], s[10:11] op_sel_hi:[1,1,0]
	v_pk_fma_f32 v[142:143], v[140:141], s[0:1], v[118:119] op_sel_hi:[1,0,0]
	v_pk_mul_f32 v[96:97], v[110:111], v[96:97]
	v_pk_fma_f32 v[142:143], v[140:141], v[142:143], s[12:13] op_sel_hi:[1,1,0]
	v_pk_mul_f32 v[110:111], v[102:103], v[102:103]
	v_pk_fma_f32 v[142:143], v[140:141], v[142:143], s[8:9] op_sel_hi:[1,1,0]
	v_pk_mul_f32 v[110:111], v[110:111], s[14:15] op_sel_hi:[1,0]
	v_pk_fma_f32 v[142:143], v[140:141], v[142:143], s[10:11] op_sel_hi:[1,1,0]
	v_exp_f32_e32 v110, v110
	v_exp_f32_e32 v111, v111
	v_pk_mul_f32 v[140:141], v[140:141], v[142:143]
	v_pk_mul_f32 v[142:143], v[98:99], v[98:99]
	v_pk_fma_f32 v[118:119], v[182:183], s[0:1], v[118:119] op_sel_hi:[1,0,0]
	v_pk_mul_f32 v[142:143], v[142:143], s[14:15] op_sel_hi:[1,0]
	v_pk_mul_f32 v[96:97], v[128:129], v[96:97]
	v_pk_fma_f32 v[118:119], v[182:183], v[118:119], s[12:13] op_sel_hi:[1,1,0]
	v_exp_f32_e32 v142, v142
	v_exp_f32_e32 v143, v143
	v_pk_mul_f32 v[128:129], v[100:101], v[96:97]
	v_pk_fma_f32 v[96:97], v[100:101], v[96:97], v[100:101] neg_lo:[1,0,0] neg_hi:[1,0,0]
	v_pk_fma_f32 v[118:119], v[182:183], v[118:119], s[8:9] op_sel_hi:[1,1,0]
	v_pk_mul_f32 v[110:111], v[110:111], v[138:139]
	v_pk_mul_f32 v[180:181], v[180:181], s[14:15] op_sel_hi:[1,0]
	v_pk_fma_f32 v[118:119], v[182:183], v[118:119], s[10:11] op_sel_hi:[1,1,0]
	v_cndmask_b32_e32 v101, v97, v129, vcc
	v_cmp_gt_f32_e32 vcc, 0, v100
	v_pk_mul_f32 v[138:139], v[102:103], v[110:111]
	v_pk_fma_f32 v[110:111], v[102:103], v[110:111], v[102:103] neg_lo:[1,0,0] neg_hi:[1,0,0]
	v_exp_f32_e32 v180, v180
	v_exp_f32_e32 v181, v181
	v_pk_mul_f32 v[118:119], v[182:183], v[118:119]
	v_cndmask_b32_e32 v100, v96, v128, vcc
	v_cmp_gt_f32_e32 vcc, 0, v103
	v_pk_mul_f32 v[118:119], v[142:143], v[118:119]
	v_pk_mul_f32 v[140:141], v[180:181], v[140:141]
	v_cndmask_b32_e32 v111, v111, v139, vcc
	v_cmp_gt_f32_e32 vcc, 0, v102
	v_pk_mul_f32 v[142:143], v[98:99], v[118:119]
	v_pk_fma_f32 v[118:119], v[98:99], v[118:119], v[98:99] neg_lo:[1,0,0] neg_hi:[1,0,0]
	v_cndmask_b32_e32 v110, v110, v138, vcc
	v_cmp_gt_f32_e32 vcc, 0, v99
	v_mul_f32_e32 v96, v100, v100
	v_pk_mul_f32 v[180:181], v[126:127], v[140:141]
	v_cndmask_b32_e32 v143, v119, v143, vcc
	v_cmp_gt_f32_e32 vcc, 0, v98
	v_pk_fma_f32 v[140:141], v[126:127], v[140:141], v[126:127] neg_lo:[1,0,0] neg_hi:[1,0,0]
	v_pk_fma_f32 v[128:129], v[100:101], v[100:101], v[96:97] op_sel_hi:[1,1,0]
	v_cndmask_b32_e32 v142, v118, v142, vcc
	v_cmp_gt_f32_e32 vcc, 0, v104
	v_mov_b32_e32 v96, v100
	v_mov_b32_e32 v97, v110
	v_mov_b32_e32 v102, v101
	v_mov_b32_e32 v103, v111
	v_cndmask_b32_e32 v182, v136, v130, vcc
	v_cmp_gt_f32_e32 vcc, 0, v126
	v_pk_add_f32 v[102:103], v[96:97], v[102:103]
	v_mul_f32_e32 v96, v110, v110
	v_cndmask_b32_e32 v183, v140, v180, vcc
	v_cmp_gt_f32_e32 vcc, 0, v105
	v_pk_fma_f32 v[138:139], v[110:111], v[110:111], v[96:97] op_sel_hi:[1,1,0]
	v_mul_f32_e32 v96, v142, v142
	v_cndmask_b32_e32 v98, v137, v131, vcc
	v_cmp_gt_f32_e32 vcc, 0, v106
	v_pk_fma_f32 v[96:97], v[142:143], v[142:143], v[96:97] op_sel_hi:[1,1,0]
	v_mov_b32_e32 v104, v182
	v_cndmask_b32_e32 v107, v132, v124, vcc
	v_cmp_gt_f32_e32 vcc, 0, v127
	v_mov_b32_e32 v105, v98
	v_mul_f32_e32 v96, v182, v182
	v_mov_b32_e32 v106, v183
	v_cndmask_b32_e32 v124, v141, v181, vcc
	v_mov_b32_e32 v125, v107
	v_pk_fma_f32 v[104:105], v[104:105], v[104:105], v[96:97] op_sel_hi:[1,1,0]
	v_pk_add_f32 v[118:119], v[106:107], v[124:125]
	v_pk_mul_f32 v[126:127], v[106:107], v[124:125]
	v_pk_add_f32 v[102:103], v[102:103], v[102:103] op_sel:[0,1] op_sel_hi:[1,0]
	v_mov_b32_e32 v99, v183
	v_mov_b32_e32 v119, v127
	v_mov_b32_e32 v103, v109
	v_mov_b32_e32 v104, v142
	v_mov_b32_e32 v122, v143
	v_pk_add_f32 v[102:103], v[118:119], v[102:103]
	v_pk_add_f32 v[104:105], v[104:105], v[122:123]
	v_pk_add_f32 v[118:119], v[182:183], v[98:99]
	v_pk_mul_f32 v[122:123], v[182:183], v[98:99]
	v_mov_b32_e32 v128, v107
	v_mov_b32_e32 v119, v123
	v_pk_mul_f32 v[122:123], v[124:125], v[124:125]
	v_mov_b32_e32 v109, v139
	v_mov_b32_e32 v121, v122
	v_pk_add_f32 v[102:103], v[102:103], v[104:105]
	v_pk_add_f32 v[104:105], v[128:129], v[108:109]
	v_pk_add_f32 v[118:119], v[118:119], v[120:121]
	v_mov_b32_e32 v96, 0
	v_pk_add_f32 v[104:105], v[118:119], v[104:105]
	v_lshl_add_u64 v[114:115], s[28:29], 0, v[114:115]
	v_pk_add_f32 v[104:105], v[104:105], v[96:97]
	v_lshl_add_u64 v[114:115], v[170:171], 1, v[114:115]
	v_pk_add_f32 v[104:105], v[102:103], v[104:105]
	v_mov_b32_e32 v120, v104
	v_mov_b32_e32 v121, v105
	s_nop 1
	v_permlane16_swap_b32_e32 v120, v104
	v_permlane16_swap_b32_e32 v121, v105
	v_cvt_pk_bf16_f32 v118, v182, v98
	v_cvt_pk_bf16_f32 v119, v107, v108
	global_store_dwordx4 v[114:115], v[116:119], off
	v_cvt_pk_bf16_f32 v102, v100, v101
	s_waitcnt lgkmcnt(0)
	v_pk_add_f32 v[98:99], v[104:105], v[120:121]
	v_mov_b32_e32 v100, v98
	v_mov_b32_e32 v101, v99
	s_nop 1
	v_permlane32_swap_b32_e32 v100, v98
	v_permlane32_swap_b32_e32 v101, v99
	v_cvt_pk_bf16_f32 v103, v110, v111
	v_cvt_pk_bf16_f32 v104, v183, v124
	v_cvt_pk_bf16_f32 v105, v142, v143
	global_store_dwordx4 v[114:115], v[102:105], off offset:256
	s_and_saveexec_b64 s[18:19], s[4:5]
	s_cbranch_execz .LBB0_312
	s_lshl_b32 s1, s15, 3
	s_waitcnt lgkmcnt(0)
	v_pk_add_f32 v[98:99], v[98:99], v[100:101]
	v_lshlrev_b64 v[100:101], 8, v[112:113]
	s_add_i32 s20, s1, s72
	v_lshl_add_u64 v[100:101], s[26:27], 0, v[100:101]
	s_ashr_i32 s21, s20, 31
	v_lshl_add_u64 v[100:101], s[20:21], 2, v[100:101]
	global_store_dwordx2 v[100:101], v[98:99], off
.LBB0_312:
	s_or_b64 exec, exec, s[18:19]
	v_mov_b32_e32 v102, v179
	v_pk_fma_f32 v[94:95], v[94:95], v[102:103], v[54:55] op_sel_hi:[1,0,1]
	v_mov_b64_e32 v[106:107], s[16:17]
	v_and_b32_e32 v113, 0x7fffffff, v95
	v_and_b32_e32 v112, 0x7fffffff, v94
	v_pk_fma_f32 v[112:113], v[112:113], s[6:7], 1.0 op_sel_hi:[1,0,0]
	v_pk_fma_f32 v[88:89], v[88:89], v[102:103], v[48:49] op_sel_hi:[1,0,1]
	v_rcp_f32_e32 v112, v112
	v_rcp_f32_e32 v113, v113
	v_pk_fma_f32 v[92:93], v[92:93], v[102:103], v[52:53] op_sel_hi:[1,0,1]
	v_pk_fma_f32 v[90:91], v[90:91], v[102:103], v[50:51] op_sel_hi:[1,0,1]
	v_and_b32_e32 v105, 0x7fffffff, v93
	v_pk_fma_f32 v[114:115], v[112:113], s[0:1], v[106:107] op_sel_hi:[1,0,0]
	v_and_b32_e32 v104, 0x7fffffff, v92
	v_pk_fma_f32 v[114:115], v[112:113], v[114:115], s[12:13] op_sel_hi:[1,1,0]
	v_pk_fma_f32 v[104:105], v[104:105], s[6:7], 1.0 op_sel_hi:[1,0,0]
	v_pk_fma_f32 v[114:115], v[112:113], v[114:115], s[8:9] op_sel_hi:[1,1,0]
	v_rcp_f32_e32 v104, v104
	v_pk_fma_f32 v[114:115], v[112:113], v[114:115], s[10:11] op_sel_hi:[1,1,0]
	v_rcp_f32_e32 v105, v105
	v_pk_mul_f32 v[112:113], v[112:113], v[114:115]
	v_and_b32_e32 v115, 0x7fffffff, v89
	v_and_b32_e32 v114, 0x7fffffff, v88
	v_pk_fma_f32 v[114:115], v[114:115], s[6:7], 1.0 op_sel_hi:[1,0,0]
	v_and_b32_e32 v121, 0x7fffffff, v91
	v_rcp_f32_e32 v114, v114
	v_rcp_f32_e32 v115, v115
	v_and_b32_e32 v120, 0x7fffffff, v90
	v_pk_fma_f32 v[120:121], v[120:121], s[6:7], 1.0 op_sel_hi:[1,0,0]
	v_pk_fma_f32 v[108:109], v[104:105], s[0:1], v[106:107] op_sel_hi:[1,0,0]
	v_pk_fma_f32 v[116:117], v[114:115], s[0:1], v[106:107] op_sel_hi:[1,0,0]
	v_rcp_f32_e32 v120, v120
	v_pk_fma_f32 v[116:117], v[114:115], v[116:117], s[12:13] op_sel_hi:[1,1,0]
	v_rcp_f32_e32 v121, v121
	v_pk_fma_f32 v[108:109], v[104:105], v[108:109], s[12:13] op_sel_hi:[1,1,0]
	v_pk_fma_f32 v[116:117], v[114:115], v[116:117], s[8:9] op_sel_hi:[1,1,0]
	v_pk_fma_f32 v[108:109], v[104:105], v[108:109], s[8:9] op_sel_hi:[1,1,0]
	v_pk_fma_f32 v[116:117], v[114:115], v[116:117], s[10:11] op_sel_hi:[1,1,0]
	v_pk_fma_f32 v[108:109], v[104:105], v[108:109], s[10:11] op_sel_hi:[1,1,0]
	v_pk_mul_f32 v[114:115], v[114:115], v[116:117]
	v_pk_mul_f32 v[116:117], v[90:91], v[90:91]
	v_pk_mul_f32 v[104:105], v[104:105], v[108:109]
	v_pk_mul_f32 v[108:109], v[94:95], v[94:95]
	v_pk_fma_f32 v[122:123], v[120:121], s[0:1], v[106:107] op_sel_hi:[1,0,0]
	v_pk_mul_f32 v[116:117], v[116:117], s[14:15] op_sel_hi:[1,0]
	v_pk_mul_f32 v[110:111], v[92:93], v[92:93]
	v_pk_mul_f32 v[108:109], v[108:109], s[14:15] op_sel_hi:[1,0]
	v_pk_fma_f32 v[122:123], v[120:121], v[122:123], s[12:13] op_sel_hi:[1,1,0]
	v_exp_f32_e32 v116, v116
	v_exp_f32_e32 v117, v117
	v_pk_mul_f32 v[110:111], v[110:111], s[14:15] op_sel_hi:[1,0]
	v_exp_f32_e32 v108, v108
	v_exp_f32_e32 v109, v109
	v_pk_fma_f32 v[122:123], v[120:121], v[122:123], s[8:9] op_sel_hi:[1,1,0]
	v_exp_f32_e32 v110, v110
	v_exp_f32_e32 v111, v111
	v_pk_fma_f32 v[122:123], v[120:121], v[122:123], s[10:11] op_sel_hi:[1,1,0]
	v_pk_mul_f32 v[108:109], v[108:109], v[112:113]
	v_pk_mul_f32 v[120:121], v[120:121], v[122:123]
	v_cmp_gt_f32_e32 vcc, 0, v91
	v_pk_mul_f32 v[116:117], v[116:117], v[120:121]
	v_pk_mul_f32 v[104:105], v[110:111], v[104:105]
	v_pk_mul_f32 v[120:121], v[90:91], v[116:117]
	v_pk_fma_f32 v[116:117], v[90:91], v[116:117], v[90:91] neg_lo:[1,0,0] neg_hi:[1,0,0]
	v_pk_mul_f32 v[112:113], v[94:95], v[108:109]
	v_pk_fma_f32 v[108:109], v[94:95], v[108:109], v[94:95] neg_lo:[1,0,0] neg_hi:[1,0,0]
	v_cndmask_b32_e32 v122, v117, v121, vcc
	v_cmp_gt_f32_e32 vcc, 0, v94
	v_pk_mul_f32 v[110:111], v[92:93], v[104:105]
	v_pk_fma_f32 v[104:105], v[92:93], v[104:105], v[92:93] neg_lo:[1,0,0] neg_hi:[1,0,0]
	v_cndmask_b32_e32 v125, v108, v112, vcc
	v_cmp_gt_f32_e32 vcc, 0, v92
	v_pk_fma_f32 v[86:87], v[86:87], v[102:103], v[46:47] op_sel_hi:[1,0,1]
	v_pk_fma_f32 v[84:85], v[84:85], v[102:103], v[44:45] op_sel_hi:[1,0,1]
	v_cndmask_b32_e32 v124, v104, v110, vcc
	v_cmp_gt_f32_e32 vcc, 0, v95
	v_and_b32_e32 v112, 0x7fffffff, v86
	v_pk_fma_f32 v[80:81], v[80:81], v[102:103], v[40:41] op_sel_hi:[1,0,1]
	v_cndmask_b32_e32 v95, v109, v113, vcc
	v_and_b32_e32 v113, 0x7fffffff, v87
	v_cmp_gt_f32_e32 vcc, 0, v93
	v_pk_fma_f32 v[112:113], v[112:113], s[6:7], 1.0 op_sel_hi:[1,0,0]
	v_pk_fma_f32 v[82:83], v[82:83], v[102:103], v[42:43] op_sel_hi:[1,0,1]
	v_cndmask_b32_e32 v94, v105, v111, vcc
	v_rcp_f32_e32 v112, v112
	v_rcp_f32_e32 v113, v113
	v_pk_add_f32 v[92:93], v[124:125], v[94:95]
	v_and_b32_e32 v131, 0x7fffffff, v83
	v_pk_add_f32 v[104:105], v[92:93], v[92:93] op_sel:[0,1] op_sel_hi:[1,0]
	v_pk_mul_f32 v[92:93], v[94:95], v[94:95]
	v_and_b32_e32 v130, 0x7fffffff, v82
	v_pk_fma_f32 v[92:93], v[124:125], v[124:125], v[92:93]
	v_pk_mul_f32 v[110:111], v[84:85], v[84:85]
	v_pk_add_f32 v[108:109], v[92:93], v[92:93] op_sel_hi:[0,1]
	v_cvt_pk_bf16_f32 v92, v124, v94
	v_cvt_pk_bf16_f32 v93, v125, v95
	v_pk_fma_f32 v[124:125], v[112:113], s[0:1], v[106:107] op_sel_hi:[1,0,0]
	v_and_b32_e32 v95, 0x7fffffff, v85
	v_pk_fma_f32 v[124:125], v[112:113], v[124:125], s[12:13] op_sel_hi:[1,1,0]
	v_and_b32_e32 v94, 0x7fffffff, v84
	v_pk_fma_f32 v[124:125], v[112:113], v[124:125], s[8:9] op_sel_hi:[1,1,0]
	v_pk_fma_f32 v[94:95], v[94:95], s[6:7], 1.0 op_sel_hi:[1,0,0]
	v_pk_fma_f32 v[124:125], v[112:113], v[124:125], s[10:11] op_sel_hi:[1,1,0]
	v_rcp_f32_e32 v94, v94
	v_rcp_f32_e32 v95, v95
	v_pk_mul_f32 v[112:113], v[112:113], v[124:125]
	v_and_b32_e32 v125, 0x7fffffff, v81
	v_and_b32_e32 v124, 0x7fffffff, v80
	v_pk_fma_f32 v[124:125], v[124:125], s[6:7], 1.0 op_sel_hi:[1,0,0]
	v_pk_fma_f32 v[102:103], v[94:95], s[0:1], v[106:107] op_sel_hi:[1,0,0]
	v_rcp_f32_e32 v124, v124
	v_rcp_f32_e32 v125, v125
	v_pk_fma_f32 v[102:103], v[94:95], v[102:103], s[12:13] op_sel_hi:[1,1,0]
	v_pk_fma_f32 v[130:131], v[130:131], s[6:7], 1.0 op_sel_hi:[1,0,0]
	v_pk_fma_f32 v[102:103], v[94:95], v[102:103], s[8:9] op_sel_hi:[1,1,0]
	v_pk_fma_f32 v[126:127], v[124:125], s[0:1], v[106:107] op_sel_hi:[1,0,0]
	v_pk_fma_f32 v[102:103], v[94:95], v[102:103], s[10:11] op_sel_hi:[1,1,0]
	v_pk_mul_f32 v[110:111], v[110:111], s[14:15] op_sel_hi:[1,0]
	v_pk_fma_f32 v[126:127], v[124:125], v[126:127], s[12:13] op_sel_hi:[1,1,0]
	v_rcp_f32_e32 v130, v130
	v_rcp_f32_e32 v131, v131
	v_pk_mul_f32 v[94:95], v[94:95], v[102:103]
	v_pk_mul_f32 v[102:103], v[86:87], v[86:87]
	v_exp_f32_e32 v110, v110
	v_exp_f32_e32 v111, v111
	v_pk_fma_f32 v[126:127], v[124:125], v[126:127], s[8:9] op_sel_hi:[1,1,0]
	v_pk_mul_f32 v[102:103], v[102:103], s[14:15] op_sel_hi:[1,0]
	v_pk_fma_f32 v[126:127], v[124:125], v[126:127], s[10:11] op_sel_hi:[1,1,0]
	v_exp_f32_e32 v102, v102
	v_exp_f32_e32 v103, v103
	v_pk_mul_f32 v[124:125], v[124:125], v[126:127]
	v_pk_mul_f32 v[126:127], v[82:83], v[82:83]
	v_pk_fma_f32 v[106:107], v[130:131], s[0:1], v[106:107] op_sel_hi:[1,0,0]
	v_pk_mul_f32 v[126:127], v[126:127], s[14:15] op_sel_hi:[1,0]
	v_pk_mul_f32 v[118:119], v[88:89], v[88:89]
	v_pk_mul_f32 v[94:95], v[110:111], v[94:95]
	v_pk_fma_f32 v[106:107], v[130:131], v[106:107], s[12:13] op_sel_hi:[1,1,0]
	v_exp_f32_e32 v126, v126
	v_exp_f32_e32 v127, v127
	v_pk_mul_f32 v[118:119], v[118:119], s[14:15] op_sel_hi:[1,0]
	v_pk_mul_f32 v[110:111], v[84:85], v[94:95]
	v_pk_fma_f32 v[94:95], v[84:85], v[94:95], v[84:85] neg_lo:[1,0,0] neg_hi:[1,0,0]
	v_pk_mul_f32 v[128:129], v[80:81], v[80:81]
	v_pk_fma_f32 v[106:107], v[130:131], v[106:107], s[8:9] op_sel_hi:[1,1,0]
	v_cmp_gt_f32_e32 vcc, 0, v85
	v_exp_f32_e32 v118, v118
	v_exp_f32_e32 v119, v119
	v_pk_mul_f32 v[102:103], v[102:103], v[112:113]
	v_pk_mul_f32 v[128:129], v[128:129], s[14:15] op_sel_hi:[1,0]
	v_pk_fma_f32 v[106:107], v[130:131], v[106:107], s[10:11] op_sel_hi:[1,1,0]
	v_cndmask_b32_e32 v85, v95, v111, vcc
	v_cmp_gt_f32_e32 vcc, 0, v84
	v_pk_mul_f32 v[112:113], v[86:87], v[102:103]
	v_pk_fma_f32 v[102:103], v[86:87], v[102:103], v[86:87] neg_lo:[1,0,0] neg_hi:[1,0,0]
	v_exp_f32_e32 v128, v128
	v_exp_f32_e32 v129, v129
	v_pk_mul_f32 v[106:107], v[130:131], v[106:107]
	v_cndmask_b32_e32 v84, v94, v110, vcc
	v_cmp_gt_f32_e32 vcc, 0, v87
	v_pk_mul_f32 v[106:107], v[126:127], v[106:107]
	v_pk_mul_f32 v[114:115], v[118:119], v[114:115]
	v_cndmask_b32_e32 v87, v103, v113, vcc
	v_cmp_gt_f32_e32 vcc, 0, v86
	v_pk_mul_f32 v[126:127], v[82:83], v[106:107]
	v_pk_fma_f32 v[106:107], v[82:83], v[106:107], v[82:83] neg_lo:[1,0,0] neg_hi:[1,0,0]
	v_cndmask_b32_e32 v86, v102, v112, vcc
	v_cmp_gt_f32_e32 vcc, 0, v83
	v_pk_mul_f32 v[118:119], v[88:89], v[114:115]
	v_pk_fma_f32 v[114:115], v[88:89], v[114:115], v[88:89] neg_lo:[1,0,0] neg_hi:[1,0,0]
	v_cndmask_b32_e32 v107, v107, v127, vcc
	v_cmp_gt_f32_e32 vcc, 0, v82
	v_pk_mul_f32 v[124:125], v[128:129], v[124:125]
	v_mov_b32_e32 v102, v84
	v_cndmask_b32_e32 v106, v106, v126, vcc
	v_cmp_gt_f32_e32 vcc, 0, v88
	v_pk_mul_f32 v[128:129], v[80:81], v[124:125]
	v_pk_fma_f32 v[124:125], v[80:81], v[124:125], v[80:81] neg_lo:[1,0,0] neg_hi:[1,0,0]
	v_cndmask_b32_e32 v112, v114, v118, vcc
	v_cmp_gt_f32_e32 vcc, 0, v80
	v_mov_b32_e32 v103, v86
	v_mov_b32_e32 v110, v85
	v_cndmask_b32_e32 v113, v124, v128, vcc
	v_cmp_gt_f32_e32 vcc, 0, v89
	v_mov_b32_e32 v111, v87
	v_pk_add_f32 v[102:103], v[102:103], v[110:111]
	v_cndmask_b32_e32 v88, v115, v119, vcc
	v_cmp_gt_f32_e32 vcc, 0, v90
	v_mov_b32_e32 v114, v112
	v_mov_b32_e32 v115, v88
	v_cndmask_b32_e32 v91, v116, v120, vcc
	v_cmp_gt_f32_e32 vcc, 0, v81
	v_mul_f32_e32 v80, v112, v112
	v_mov_b32_e32 v90, v113
	v_cndmask_b32_e32 v116, v125, v129, vcc
	v_mov_b32_e32 v117, v91
	v_mul_f32_e32 v97, v122, v122
	v_pk_fma_f32 v[114:115], v[114:115], v[114:115], v[80:81] op_sel_hi:[1,1,0]
	v_pk_add_f32 v[80:81], v[90:91], v[116:117]
	v_pk_mul_f32 v[118:119], v[90:91], v[116:117]
	v_pk_add_f32 v[102:103], v[102:103], v[102:103] op_sel:[0,1] op_sel_hi:[1,0]
	v_mul_f32_e32 v94, v84, v84
	v_mov_b32_e32 v81, v119
	v_mov_b32_e32 v103, v97
	v_mov_b32_e32 v114, v106
	v_mov_b32_e32 v108, v107
	v_pk_fma_f32 v[94:95], v[84:85], v[84:85], v[94:95] op_sel_hi:[1,1,0]
	v_mov_b32_e32 v89, v113
	v_pk_add_f32 v[80:81], v[80:81], v[102:103]
	v_pk_add_f32 v[102:103], v[114:115], v[108:109]
	v_mul_f32_e32 v94, v86, v86
	v_pk_add_f32 v[80:81], v[80:81], v[102:103]
	v_pk_add_f32 v[102:103], v[112:113], v[88:89]
	v_pk_mul_f32 v[108:109], v[112:113], v[88:89]
	v_pk_fma_f32 v[110:111], v[86:87], v[86:87], v[94:95] op_sel_hi:[1,1,0]
	v_mov_b32_e32 v103, v109
	v_pk_mul_f32 v[108:109], v[116:117], v[116:117]
	v_mul_f32_e32 v82, v106, v106
	v_mov_b32_e32 v94, v91
	v_mov_b32_e32 v123, v111
	v_mov_b32_e32 v105, v108
	v_pk_fma_f32 v[82:83], v[106:107], v[106:107], v[82:83] op_sel_hi:[1,1,0]
	v_pk_add_f32 v[94:95], v[94:95], v[122:123]
	v_pk_add_f32 v[102:103], v[102:103], v[104:105]
	v_mov_b32_e32 v97, v83
	v_pk_add_f32 v[94:95], v[102:103], v[94:95]
	v_add_u32_e32 v98, 48, v174
	v_pk_add_f32 v[82:83], v[94:95], v[96:97]
	v_ashrrev_i32_e32 v99, 31, v98
	v_pk_add_f32 v[80:81], v[80:81], v[82:83]
	v_mov_b32_e32 v82, v80
	v_mov_b32_e32 v83, v81
	s_nop 1
	v_permlane16_swap_b32_e32 v82, v80
	v_permlane16_swap_b32_e32 v83, v81
	s_waitcnt lgkmcnt(2)
	v_lshlrev_b64 v[100:101], 13, v[98:99]
	v_lshl_add_u64 v[100:101], s[28:29], 0, v[100:101]
	v_lshl_add_u64 v[100:101], v[170:171], 1, v[100:101]
	v_cvt_pk_bf16_f32 v94, v112, v88
	s_waitcnt lgkmcnt(0)
	v_pk_add_f32 v[80:81], v[80:81], v[82:83]
	v_mov_b32_e32 v82, v80
	v_mov_b32_e32 v83, v81
	s_nop 1
	v_permlane32_swap_b32_e32 v82, v80
	v_permlane32_swap_b32_e32 v83, v81
	v_cvt_pk_bf16_f32 v95, v91, v122
	global_store_dwordx4 v[100:101], v[92:95], off
	v_cvt_pk_bf16_f32 v84, v84, v85
	v_cvt_pk_bf16_f32 v85, v86, v87
	v_cvt_pk_bf16_f32 v86, v113, v116
	v_cvt_pk_bf16_f32 v87, v106, v107
	global_store_dwordx4 v[100:101], v[84:87], off offset:256
	s_and_saveexec_b64 s[0:1], s[4:5]
	s_cbranch_execz .LBB0_314
	s_lshl_b32 s6, s15, 3
	s_waitcnt lgkmcnt(0)
	v_pk_add_f32 v[80:81], v[80:81], v[82:83]
	v_lshlrev_b64 v[82:83], 8, v[98:99]
	s_add_i32 s6, s6, s72
	v_lshl_add_u64 v[82:83], s[26:27], 0, v[82:83]
	s_ashr_i32 s7, s6, 31
	v_lshl_add_u64 v[82:83], s[6:7], 2, v[82:83]
	global_store_dwordx2 v[82:83], v[80:81], off
.LBB0_314:
	s_or_b64 exec, exec, s[0:1]
	v_pk_fma_f32 v[84:85], v[76:77], v[176:177], v[52:53] op_sel_hi:[1,0,1]
	s_mov_b32 s6, 0x3e6d3388
	v_and_b32_e32 v77, 0x7fffffff, v85
	v_and_b32_e32 v76, 0x7fffffff, v84
	v_pk_fma_f32 v[76:77], v[76:77], s[6:7], 1.0 op_sel_hi:[1,0,0]
	v_pk_fma_f32 v[78:79], v[78:79], v[176:177], v[54:55] op_sel_hi:[1,0,1]
	v_rcp_f32_e32 v76, v76
	v_rcp_f32_e32 v77, v77
	s_mov_b32 s0, 0x3f07dc22
	v_mov_b64_e32 v[86:87], s[16:17]
	v_pk_mul_f32 v[90:91], v[84:85], v[84:85]
	v_pk_fma_f32 v[88:89], v[76:77], s[0:1], v[86:87] op_sel_hi:[1,0,0]
	v_pk_mul_f32 v[90:91], v[90:91], s[14:15] op_sel_hi:[1,0]
	v_and_b32_e32 v93, 0x7fffffff, v79
	v_and_b32_e32 v92, 0x7fffffff, v78
	v_pk_fma_f32 v[88:89], v[76:77], v[88:89], s[12:13] op_sel_hi:[1,1,0]
	v_exp_f32_e32 v90, v90
	v_exp_f32_e32 v91, v91
	v_pk_fma_f32 v[92:93], v[92:93], s[6:7], 1.0 op_sel_hi:[1,0,0]
	v_pk_fma_f32 v[88:89], v[76:77], v[88:89], s[8:9] op_sel_hi:[1,1,0]
	v_rcp_f32_e32 v92, v92
	v_rcp_f32_e32 v93, v93
	v_pk_fma_f32 v[88:89], v[76:77], v[88:89], s[10:11] op_sel_hi:[1,1,0]
	v_pk_fma_f32 v[72:73], v[72:73], v[176:177], v[48:49] op_sel_hi:[1,0,1]
	v_pk_mul_f32 v[76:77], v[76:77], v[88:89]
	v_pk_mul_f32 v[88:89], v[78:79], v[78:79]
	v_pk_mul_f32 v[76:77], v[90:91], v[76:77]
	v_pk_mul_f32 v[88:89], v[88:89], s[14:15] op_sel_hi:[1,0]
	v_pk_mul_f32 v[90:91], v[84:85], v[76:77]
	v_pk_fma_f32 v[94:95], v[84:85], v[76:77], v[84:85] neg_lo:[1,0,0] neg_hi:[1,0,0]
	v_pk_fma_f32 v[76:77], v[92:93], s[0:1], v[86:87] op_sel_hi:[1,0,0]
	v_exp_f32_e32 v88, v88
	v_pk_fma_f32 v[76:77], v[92:93], v[76:77], s[12:13] op_sel_hi:[1,1,0]
	v_exp_f32_e32 v89, v89
	v_pk_fma_f32 v[76:77], v[92:93], v[76:77], s[8:9] op_sel_hi:[1,1,0]
	v_pk_fma_f32 v[74:75], v[74:75], v[176:177], v[50:51] op_sel_hi:[1,0,1]
	v_pk_fma_f32 v[76:77], v[92:93], v[76:77], s[10:11] op_sel_hi:[1,1,0]
	v_pk_mul_f32 v[98:99], v[72:73], v[72:73]
	v_pk_mul_f32 v[76:77], v[92:93], v[76:77]
	v_and_b32_e32 v93, 0x7fffffff, v73
	v_and_b32_e32 v92, 0x7fffffff, v72
	v_pk_fma_f32 v[92:93], v[92:93], s[6:7], 1.0 op_sel_hi:[1,0,0]
	v_pk_mul_f32 v[76:77], v[88:89], v[76:77]
	v_rcp_f32_e32 v92, v92
	v_rcp_f32_e32 v93, v93
	v_pk_mul_f32 v[88:89], v[78:79], v[76:77]
	v_pk_fma_f32 v[96:97], v[78:79], v[76:77], v[78:79] neg_lo:[1,0,0] neg_hi:[1,0,0]
	v_pk_mul_f32 v[98:99], v[98:99], s[14:15] op_sel_hi:[1,0]
	v_pk_fma_f32 v[76:77], v[92:93], s[0:1], v[86:87] op_sel_hi:[1,0,0]
	v_and_b32_e32 v101, 0x7fffffff, v75
	v_and_b32_e32 v100, 0x7fffffff, v74
	v_pk_fma_f32 v[76:77], v[92:93], v[76:77], s[12:13] op_sel_hi:[1,1,0]
	v_exp_f32_e32 v98, v98
	v_exp_f32_e32 v99, v99
	v_pk_fma_f32 v[100:101], v[100:101], s[6:7], 1.0 op_sel_hi:[1,0,0]
	v_pk_fma_f32 v[76:77], v[92:93], v[76:77], s[8:9] op_sel_hi:[1,1,0]
	v_rcp_f32_e32 v100, v100
	v_rcp_f32_e32 v101, v101
	v_pk_fma_f32 v[76:77], v[92:93], v[76:77], s[10:11] op_sel_hi:[1,1,0]
	v_cmp_gt_f32_e32 vcc, 0, v75
	v_pk_mul_f32 v[76:77], v[92:93], v[76:77]
	v_pk_mul_f32 v[92:93], v[74:75], v[74:75]
	v_pk_mul_f32 v[76:77], v[98:99], v[76:77]
	v_pk_mul_f32 v[92:93], v[92:93], s[14:15] op_sel_hi:[1,0]
	v_pk_mul_f32 v[98:99], v[72:73], v[76:77]
	v_pk_fma_f32 v[102:103], v[72:73], v[76:77], v[72:73] neg_lo:[1,0,0] neg_hi:[1,0,0]
	v_pk_fma_f32 v[76:77], v[100:101], s[0:1], v[86:87] op_sel_hi:[1,0,0]
	v_exp_f32_e32 v92, v92
	v_pk_fma_f32 v[76:77], v[100:101], v[76:77], s[12:13] op_sel_hi:[1,1,0]
	v_exp_f32_e32 v93, v93
	v_pk_fma_f32 v[76:77], v[100:101], v[76:77], s[8:9] op_sel_hi:[1,1,0]
	v_pk_fma_f32 v[70:71], v[70:71], v[176:177], v[46:47] op_sel_hi:[1,0,1]
	v_pk_fma_f32 v[76:77], v[100:101], v[76:77], s[10:11] op_sel_hi:[1,1,0]
	v_pk_fma_f32 v[68:69], v[68:69], v[176:177], v[44:45] op_sel_hi:[1,0,1]
	v_pk_mul_f32 v[76:77], v[100:101], v[76:77]
	v_pk_fma_f32 v[66:67], v[66:67], v[176:177], v[42:43] op_sel_hi:[1,0,1]
	v_pk_mul_f32 v[76:77], v[92:93], v[76:77]
	v_and_b32_e32 v113, 0x7fffffff, v67
	v_pk_mul_f32 v[92:93], v[74:75], v[76:77]
	v_pk_fma_f32 v[100:101], v[74:75], v[76:77], v[74:75] neg_lo:[1,0,0] neg_hi:[1,0,0]
	v_and_b32_e32 v112, 0x7fffffff, v66
	v_cndmask_b32_e32 v76, v101, v93, vcc
	v_cmp_gt_f32_e32 vcc, 0, v78
	v_pk_fma_f32 v[112:113], v[112:113], s[6:7], 1.0 op_sel_hi:[1,0,0]
	v_mul_f32_e32 v77, v76, v76
	v_cndmask_b32_e32 v105, v96, v88, vcc
	v_cmp_gt_f32_e32 vcc, 0, v84
	v_rcp_f32_e32 v112, v112
	v_rcp_f32_e32 v113, v113
	v_cndmask_b32_e32 v104, v94, v90, vcc
	v_cmp_gt_f32_e32 vcc, 0, v79
	v_add_u32_e32 v80, 0x80, v174
	v_ashrrev_i32_e32 v81, 31, v80
	v_cndmask_b32_e32 v79, v97, v89, vcc
	v_cmp_gt_f32_e32 vcc, 0, v85
	v_pk_mul_f32 v[96:97], v[68:69], v[68:69]
	s_waitcnt lgkmcnt(0)
	v_lshlrev_b64 v[82:83], 13, v[80:81]
	v_cndmask_b32_e32 v78, v95, v91, vcc
	v_pk_add_f32 v[84:85], v[104:105], v[78:79]
	v_pk_fma_f32 v[94:95], v[64:65], v[176:177], v[40:41] op_sel_hi:[1,0,1]
	v_pk_add_f32 v[88:89], v[84:85], v[84:85] op_sel:[0,1] op_sel_hi:[1,0]
	v_pk_mul_f32 v[84:85], v[78:79], v[78:79]
	v_pk_mul_f32 v[96:97], v[96:97], s[14:15] op_sel_hi:[1,0]
	v_pk_fma_f32 v[84:85], v[104:105], v[104:105], v[84:85]
	v_exp_f32_e32 v96, v96
	v_pk_add_f32 v[90:91], v[84:85], v[84:85] op_sel_hi:[0,1]
	v_cvt_pk_bf16_f32 v84, v104, v78
	v_cvt_pk_bf16_f32 v85, v105, v79
	v_and_b32_e32 v105, 0x7fffffff, v71
	v_and_b32_e32 v104, 0x7fffffff, v70
	v_pk_fma_f32 v[104:105], v[104:105], s[6:7], 1.0 op_sel_hi:[1,0,0]
	v_and_b32_e32 v79, 0x7fffffff, v69
	v_rcp_f32_e32 v104, v104
	v_rcp_f32_e32 v105, v105
	v_and_b32_e32 v78, 0x7fffffff, v68
	v_pk_fma_f32 v[78:79], v[78:79], s[6:7], 1.0 op_sel_hi:[1,0,0]
	v_exp_f32_e32 v97, v97
	v_pk_fma_f32 v[106:107], v[104:105], s[0:1], v[86:87] op_sel_hi:[1,0,0]
	v_rcp_f32_e32 v78, v78
	v_pk_fma_f32 v[106:107], v[104:105], v[106:107], s[12:13] op_sel_hi:[1,1,0]
	v_rcp_f32_e32 v79, v79
	v_pk_fma_f32 v[106:107], v[104:105], v[106:107], s[8:9] op_sel_hi:[1,1,0]
	v_pk_mul_f32 v[110:111], v[94:95], v[94:95]
	v_pk_fma_f32 v[106:107], v[104:105], v[106:107], s[10:11] op_sel_hi:[1,1,0]
	v_pk_fma_f32 v[64:65], v[78:79], s[0:1], v[86:87] op_sel_hi:[1,0,0]
	v_pk_mul_f32 v[104:105], v[104:105], v[106:107]
	v_and_b32_e32 v107, 0x7fffffff, v95
	v_and_b32_e32 v106, 0x7fffffff, v94
	v_pk_fma_f32 v[106:107], v[106:107], s[6:7], 1.0 op_sel_hi:[1,0,0]
	v_pk_fma_f32 v[64:65], v[78:79], v[64:65], s[12:13] op_sel_hi:[1,1,0]
	v_rcp_f32_e32 v106, v106
	v_rcp_f32_e32 v107, v107
	v_pk_fma_f32 v[64:65], v[78:79], v[64:65], s[8:9] op_sel_hi:[1,1,0]
	v_cmp_gt_f32_e32 vcc, 0, v69
	v_pk_fma_f32 v[64:65], v[78:79], v[64:65], s[10:11] op_sel_hi:[1,1,0]
	v_pk_fma_f32 v[108:109], v[106:107], s[0:1], v[86:87] op_sel_hi:[1,0,0]
	v_pk_mul_f32 v[64:65], v[78:79], v[64:65]
	v_pk_fma_f32 v[108:109], v[106:107], v[108:109], s[12:13] op_sel_hi:[1,1,0]
	v_pk_mul_f32 v[78:79], v[70:71], v[70:71]
	v_pk_fma_f32 v[108:109], v[106:107], v[108:109], s[8:9] op_sel_hi:[1,1,0]
	v_pk_mul_f32 v[78:79], v[78:79], s[14:15] op_sel_hi:[1,0]
	v_pk_fma_f32 v[108:109], v[106:107], v[108:109], s[10:11] op_sel_hi:[1,1,0]
	v_exp_f32_e32 v78, v78
	v_exp_f32_e32 v79, v79
	v_pk_mul_f32 v[106:107], v[106:107], v[108:109]
	v_pk_mul_f32 v[108:109], v[66:67], v[66:67]
	v_pk_fma_f32 v[86:87], v[112:113], s[0:1], v[86:87] op_sel_hi:[1,0,0]
	v_pk_mul_f32 v[108:109], v[108:109], s[14:15] op_sel_hi:[1,0]
	v_pk_mul_f32 v[64:65], v[96:97], v[64:65]
	v_pk_fma_f32 v[86:87], v[112:113], v[86:87], s[12:13] op_sel_hi:[1,1,0]
	v_exp_f32_e32 v108, v108
	v_exp_f32_e32 v109, v109
	v_pk_mul_f32 v[96:97], v[68:69], v[64:65]
	v_pk_fma_f32 v[64:65], v[68:69], v[64:65], v[68:69] neg_lo:[1,0,0] neg_hi:[1,0,0]
	v_pk_fma_f32 v[86:87], v[112:113], v[86:87], s[8:9] op_sel_hi:[1,1,0]
	v_pk_mul_f32 v[78:79], v[78:79], v[104:105]
	v_pk_mul_f32 v[110:111], v[110:111], s[14:15] op_sel_hi:[1,0]
	v_pk_fma_f32 v[86:87], v[112:113], v[86:87], s[10:11] op_sel_hi:[1,1,0]
	v_cndmask_b32_e32 v69, v65, v97, vcc
	v_cmp_gt_f32_e32 vcc, 0, v68
	v_pk_mul_f32 v[104:105], v[70:71], v[78:79]
	v_pk_fma_f32 v[78:79], v[70:71], v[78:79], v[70:71] neg_lo:[1,0,0] neg_hi:[1,0,0]
	v_exp_f32_e32 v110, v110
	v_exp_f32_e32 v111, v111
	v_pk_mul_f32 v[86:87], v[112:113], v[86:87]
	v_cndmask_b32_e32 v68, v64, v96, vcc
	v_cmp_gt_f32_e32 vcc, 0, v71
	v_pk_mul_f32 v[86:87], v[108:109], v[86:87]
	v_pk_mul_f32 v[106:107], v[110:111], v[106:107]
	v_cndmask_b32_e32 v79, v79, v105, vcc
	v_cmp_gt_f32_e32 vcc, 0, v70
	v_pk_mul_f32 v[108:109], v[66:67], v[86:87]
	v_pk_fma_f32 v[86:87], v[66:67], v[86:87], v[66:67] neg_lo:[1,0,0] neg_hi:[1,0,0]
	v_cndmask_b32_e32 v78, v78, v104, vcc
	v_cmp_gt_f32_e32 vcc, 0, v67
	v_mul_f32_e32 v64, v68, v68
	v_pk_mul_f32 v[110:111], v[94:95], v[106:107]
	v_cndmask_b32_e32 v109, v87, v109, vcc
	v_cmp_gt_f32_e32 vcc, 0, v66
	v_pk_fma_f32 v[106:107], v[94:95], v[106:107], v[94:95] neg_lo:[1,0,0] neg_hi:[1,0,0]
	v_pk_fma_f32 v[96:97], v[68:69], v[68:69], v[64:65] op_sel_hi:[1,1,0]
	v_cndmask_b32_e32 v108, v86, v108, vcc
	v_cmp_gt_f32_e32 vcc, 0, v72
	v_mov_b32_e32 v64, v68
	v_mov_b32_e32 v65, v78
	v_mov_b32_e32 v70, v69
	v_mov_b32_e32 v71, v79
	v_cndmask_b32_e32 v112, v102, v98, vcc
	v_cmp_gt_f32_e32 vcc, 0, v94
	v_pk_add_f32 v[70:71], v[64:65], v[70:71]
	v_mul_f32_e32 v64, v78, v78
	v_cndmask_b32_e32 v113, v106, v110, vcc
	v_cmp_gt_f32_e32 vcc, 0, v73
	v_pk_fma_f32 v[104:105], v[78:79], v[78:79], v[64:65] op_sel_hi:[1,1,0]
	v_mul_f32_e32 v64, v108, v108
	v_cndmask_b32_e32 v66, v103, v99, vcc
	v_cmp_gt_f32_e32 vcc, 0, v74
	v_pk_fma_f32 v[64:65], v[108:109], v[108:109], v[64:65] op_sel_hi:[1,1,0]
	v_mov_b32_e32 v72, v112
	v_cndmask_b32_e32 v75, v100, v92, vcc
	v_cmp_gt_f32_e32 vcc, 0, v95
	v_mov_b32_e32 v73, v66
	v_mul_f32_e32 v64, v112, v112
	v_mov_b32_e32 v74, v113
	v_cndmask_b32_e32 v92, v107, v111, vcc
	v_mov_b32_e32 v93, v75
	v_pk_fma_f32 v[72:73], v[72:73], v[72:73], v[64:65] op_sel_hi:[1,1,0]
	v_pk_add_f32 v[86:87], v[74:75], v[92:93]
	v_pk_mul_f32 v[94:95], v[74:75], v[92:93]
	v_pk_add_f32 v[70:71], v[70:71], v[70:71] op_sel:[0,1] op_sel_hi:[1,0]
	v_mov_b32_e32 v67, v113
	v_mov_b32_e32 v87, v95
	v_mov_b32_e32 v71, v77
	v_mov_b32_e32 v72, v108
	v_mov_b32_e32 v90, v109
	v_pk_add_f32 v[70:71], v[86:87], v[70:71]
	v_pk_add_f32 v[72:73], v[72:73], v[90:91]
	v_pk_add_f32 v[86:87], v[112:113], v[66:67]
	v_pk_mul_f32 v[90:91], v[112:113], v[66:67]
	v_mov_b32_e32 v96, v75
	v_mov_b32_e32 v87, v91
	v_pk_mul_f32 v[90:91], v[92:93], v[92:93]
	v_mov_b32_e32 v77, v105
	v_mov_b32_e32 v89, v90
	v_pk_add_f32 v[70:71], v[70:71], v[72:73]
	v_pk_add_f32 v[72:73], v[96:97], v[76:77]
	v_pk_add_f32 v[86:87], v[86:87], v[88:89]
	v_mov_b32_e32 v64, 0
	v_pk_add_f32 v[72:73], v[86:87], v[72:73]
	v_lshl_add_u64 v[82:83], s[28:29], 0, v[82:83]
	v_pk_add_f32 v[72:73], v[72:73], v[64:65]
	v_lshl_add_u64 v[82:83], v[170:171], 1, v[82:83]
	v_pk_add_f32 v[72:73], v[70:71], v[72:73]
	v_mov_b32_e32 v88, v72
	v_mov_b32_e32 v89, v73
	s_nop 1
	v_permlane16_swap_b32_e32 v88, v72
	v_permlane16_swap_b32_e32 v89, v73
	v_cvt_pk_bf16_f32 v86, v112, v66
	v_cvt_pk_bf16_f32 v87, v75, v76
	global_store_dwordx4 v[82:83], v[84:87], off
	v_cvt_pk_bf16_f32 v70, v68, v69
	s_waitcnt lgkmcnt(0)
	v_pk_add_f32 v[66:67], v[72:73], v[88:89]
	v_mov_b32_e32 v68, v66
	v_mov_b32_e32 v69, v67
	s_nop 1
	v_permlane32_swap_b32_e32 v68, v66
	v_permlane32_swap_b32_e32 v69, v67
	v_cvt_pk_bf16_f32 v71, v78, v79
	v_cvt_pk_bf16_f32 v72, v113, v92
	v_cvt_pk_bf16_f32 v73, v108, v109
	global_store_dwordx4 v[82:83], v[70:73], off offset:256
	s_and_saveexec_b64 s[18:19], s[4:5]
	s_cbranch_execz .LBB0_316
	s_lshl_b32 s1, s15, 3
	s_waitcnt lgkmcnt(0)
	v_pk_add_f32 v[66:67], v[66:67], v[68:69]
	v_lshlrev_b64 v[68:69], 8, v[80:81]
	s_add_i32 s20, s1, s72
	v_lshl_add_u64 v[68:69], s[26:27], 0, v[68:69]
	s_ashr_i32 s21, s20, 31
	v_lshl_add_u64 v[68:69], s[20:21], 2, v[68:69]
	global_store_dwordx2 v[68:69], v[66:67], off
.LBB0_316:
	s_or_b64 exec, exec, s[18:19]
	v_mov_b32_e32 v70, v177
	v_pk_fma_f32 v[62:63], v[62:63], v[70:71], v[54:55] op_sel_hi:[1,0,1]
	v_mov_b64_e32 v[74:75], s[16:17]
	v_and_b32_e32 v81, 0x7fffffff, v63
	v_and_b32_e32 v80, 0x7fffffff, v62
	v_pk_fma_f32 v[80:81], v[80:81], s[6:7], 1.0 op_sel_hi:[1,0,0]
	v_pk_fma_f32 v[56:57], v[56:57], v[70:71], v[48:49] op_sel_hi:[1,0,1]
	v_rcp_f32_e32 v80, v80
	v_rcp_f32_e32 v81, v81
	v_pk_fma_f32 v[60:61], v[60:61], v[70:71], v[52:53] op_sel_hi:[1,0,1]
	v_pk_fma_f32 v[58:59], v[58:59], v[70:71], v[50:51] op_sel_hi:[1,0,1]
	v_and_b32_e32 v73, 0x7fffffff, v61
	v_pk_fma_f32 v[82:83], v[80:81], s[0:1], v[74:75] op_sel_hi:[1,0,0]
	v_and_b32_e32 v72, 0x7fffffff, v60
	v_pk_fma_f32 v[82:83], v[80:81], v[82:83], s[12:13] op_sel_hi:[1,1,0]
	v_pk_fma_f32 v[72:73], v[72:73], s[6:7], 1.0 op_sel_hi:[1,0,0]
	v_pk_fma_f32 v[82:83], v[80:81], v[82:83], s[8:9] op_sel_hi:[1,1,0]
	v_rcp_f32_e32 v72, v72
	v_pk_fma_f32 v[82:83], v[80:81], v[82:83], s[10:11] op_sel_hi:[1,1,0]
	v_rcp_f32_e32 v73, v73
	v_pk_mul_f32 v[80:81], v[80:81], v[82:83]
	v_and_b32_e32 v83, 0x7fffffff, v57
	v_and_b32_e32 v82, 0x7fffffff, v56
	v_pk_fma_f32 v[82:83], v[82:83], s[6:7], 1.0 op_sel_hi:[1,0,0]
	v_and_b32_e32 v89, 0x7fffffff, v59
	v_rcp_f32_e32 v82, v82
	v_rcp_f32_e32 v83, v83
	v_and_b32_e32 v88, 0x7fffffff, v58
	v_pk_fma_f32 v[88:89], v[88:89], s[6:7], 1.0 op_sel_hi:[1,0,0]
	v_pk_fma_f32 v[76:77], v[72:73], s[0:1], v[74:75] op_sel_hi:[1,0,0]
	v_pk_fma_f32 v[84:85], v[82:83], s[0:1], v[74:75] op_sel_hi:[1,0,0]
	v_rcp_f32_e32 v88, v88
	v_pk_fma_f32 v[84:85], v[82:83], v[84:85], s[12:13] op_sel_hi:[1,1,0]
	v_rcp_f32_e32 v89, v89
	v_pk_fma_f32 v[76:77], v[72:73], v[76:77], s[12:13] op_sel_hi:[1,1,0]
	v_pk_fma_f32 v[84:85], v[82:83], v[84:85], s[8:9] op_sel_hi:[1,1,0]
	v_pk_fma_f32 v[76:77], v[72:73], v[76:77], s[8:9] op_sel_hi:[1,1,0]
	v_pk_fma_f32 v[84:85], v[82:83], v[84:85], s[10:11] op_sel_hi:[1,1,0]
	v_pk_fma_f32 v[76:77], v[72:73], v[76:77], s[10:11] op_sel_hi:[1,1,0]
	v_pk_mul_f32 v[82:83], v[82:83], v[84:85]
	v_pk_mul_f32 v[84:85], v[58:59], v[58:59]
	v_pk_mul_f32 v[72:73], v[72:73], v[76:77]
	v_pk_mul_f32 v[76:77], v[62:63], v[62:63]
	v_pk_fma_f32 v[90:91], v[88:89], s[0:1], v[74:75] op_sel_hi:[1,0,0]
	v_pk_mul_f32 v[84:85], v[84:85], s[14:15] op_sel_hi:[1,0]
	v_pk_mul_f32 v[78:79], v[60:61], v[60:61]
	v_pk_mul_f32 v[76:77], v[76:77], s[14:15] op_sel_hi:[1,0]
	v_pk_fma_f32 v[90:91], v[88:89], v[90:91], s[12:13] op_sel_hi:[1,1,0]
	v_exp_f32_e32 v84, v84
	v_exp_f32_e32 v85, v85
	v_pk_mul_f32 v[78:79], v[78:79], s[14:15] op_sel_hi:[1,0]
	v_exp_f32_e32 v76, v76
	v_exp_f32_e32 v77, v77
	v_pk_fma_f32 v[90:91], v[88:89], v[90:91], s[8:9] op_sel_hi:[1,1,0]
	v_exp_f32_e32 v78, v78
	v_exp_f32_e32 v79, v79
	v_pk_fma_f32 v[90:91], v[88:89], v[90:91], s[10:11] op_sel_hi:[1,1,0]
	v_pk_mul_f32 v[76:77], v[76:77], v[80:81]
	v_pk_mul_f32 v[88:89], v[88:89], v[90:91]
	v_cmp_gt_f32_e32 vcc, 0, v59
	v_pk_mul_f32 v[84:85], v[84:85], v[88:89]
	v_pk_mul_f32 v[72:73], v[78:79], v[72:73]
	v_pk_mul_f32 v[88:89], v[58:59], v[84:85]
	v_pk_fma_f32 v[84:85], v[58:59], v[84:85], v[58:59] neg_lo:[1,0,0] neg_hi:[1,0,0]
	v_pk_mul_f32 v[80:81], v[62:63], v[76:77]
	v_pk_fma_f32 v[76:77], v[62:63], v[76:77], v[62:63] neg_lo:[1,0,0] neg_hi:[1,0,0]
	v_cndmask_b32_e32 v90, v85, v89, vcc
	v_cmp_gt_f32_e32 vcc, 0, v62
	v_pk_mul_f32 v[78:79], v[60:61], v[72:73]
	v_pk_fma_f32 v[72:73], v[60:61], v[72:73], v[60:61] neg_lo:[1,0,0] neg_hi:[1,0,0]
	v_cndmask_b32_e32 v93, v76, v80, vcc
	v_cmp_gt_f32_e32 vcc, 0, v60
	v_pk_fma_f32 v[38:39], v[38:39], v[70:71], v[46:47] op_sel_hi:[1,0,1]
	v_pk_fma_f32 v[36:37], v[36:37], v[70:71], v[44:45] op_sel_hi:[1,0,1]
	v_cndmask_b32_e32 v92, v72, v78, vcc
	v_cmp_gt_f32_e32 vcc, 0, v63
	v_and_b32_e32 v80, 0x7fffffff, v38
	v_pk_fma_f32 v[32:33], v[32:33], v[70:71], v[40:41] op_sel_hi:[1,0,1]
	v_cndmask_b32_e32 v63, v77, v81, vcc
	v_and_b32_e32 v81, 0x7fffffff, v39
	v_cmp_gt_f32_e32 vcc, 0, v61
	v_pk_fma_f32 v[80:81], v[80:81], s[6:7], 1.0 op_sel_hi:[1,0,0]
	v_pk_fma_f32 v[34:35], v[34:35], v[70:71], v[42:43] op_sel_hi:[1,0,1]
	v_cndmask_b32_e32 v62, v73, v79, vcc
	v_rcp_f32_e32 v80, v80
	v_rcp_f32_e32 v81, v81
	v_pk_add_f32 v[60:61], v[92:93], v[62:63]
	v_and_b32_e32 v99, 0x7fffffff, v35
	v_pk_add_f32 v[72:73], v[60:61], v[60:61] op_sel:[0,1] op_sel_hi:[1,0]
	v_pk_mul_f32 v[60:61], v[62:63], v[62:63]
	v_and_b32_e32 v98, 0x7fffffff, v34
	v_pk_fma_f32 v[60:61], v[92:93], v[92:93], v[60:61]
	v_pk_mul_f32 v[78:79], v[36:37], v[36:37]
	v_pk_add_f32 v[76:77], v[60:61], v[60:61] op_sel_hi:[0,1]
	v_cvt_pk_bf16_f32 v60, v92, v62
	v_cvt_pk_bf16_f32 v61, v93, v63
	v_pk_fma_f32 v[92:93], v[80:81], s[0:1], v[74:75] op_sel_hi:[1,0,0]
	v_and_b32_e32 v63, 0x7fffffff, v37
	v_pk_fma_f32 v[92:93], v[80:81], v[92:93], s[12:13] op_sel_hi:[1,1,0]
	v_and_b32_e32 v62, 0x7fffffff, v36
	v_pk_fma_f32 v[92:93], v[80:81], v[92:93], s[8:9] op_sel_hi:[1,1,0]
	v_pk_fma_f32 v[62:63], v[62:63], s[6:7], 1.0 op_sel_hi:[1,0,0]
	v_pk_fma_f32 v[92:93], v[80:81], v[92:93], s[10:11] op_sel_hi:[1,1,0]
	v_rcp_f32_e32 v62, v62
	v_rcp_f32_e32 v63, v63
	v_pk_mul_f32 v[80:81], v[80:81], v[92:93]
	v_and_b32_e32 v93, 0x7fffffff, v33
	v_and_b32_e32 v92, 0x7fffffff, v32
	v_pk_fma_f32 v[92:93], v[92:93], s[6:7], 1.0 op_sel_hi:[1,0,0]
	v_pk_fma_f32 v[70:71], v[62:63], s[0:1], v[74:75] op_sel_hi:[1,0,0]
	v_rcp_f32_e32 v92, v92
	v_rcp_f32_e32 v93, v93
	v_pk_fma_f32 v[70:71], v[62:63], v[70:71], s[12:13] op_sel_hi:[1,1,0]
	v_pk_fma_f32 v[98:99], v[98:99], s[6:7], 1.0 op_sel_hi:[1,0,0]
	v_pk_fma_f32 v[70:71], v[62:63], v[70:71], s[8:9] op_sel_hi:[1,1,0]
	v_pk_fma_f32 v[94:95], v[92:93], s[0:1], v[74:75] op_sel_hi:[1,0,0]
	v_pk_fma_f32 v[70:71], v[62:63], v[70:71], s[10:11] op_sel_hi:[1,1,0]
	v_pk_mul_f32 v[78:79], v[78:79], s[14:15] op_sel_hi:[1,0]
	v_pk_fma_f32 v[94:95], v[92:93], v[94:95], s[12:13] op_sel_hi:[1,1,0]
	v_rcp_f32_e32 v98, v98
	v_rcp_f32_e32 v99, v99
	v_pk_mul_f32 v[62:63], v[62:63], v[70:71]
	v_pk_mul_f32 v[70:71], v[38:39], v[38:39]
	v_exp_f32_e32 v78, v78
	v_exp_f32_e32 v79, v79
	v_pk_fma_f32 v[94:95], v[92:93], v[94:95], s[8:9] op_sel_hi:[1,1,0]
	v_pk_mul_f32 v[70:71], v[70:71], s[14:15] op_sel_hi:[1,0]
	v_pk_fma_f32 v[94:95], v[92:93], v[94:95], s[10:11] op_sel_hi:[1,1,0]
	v_exp_f32_e32 v70, v70
	v_exp_f32_e32 v71, v71
	v_pk_mul_f32 v[92:93], v[92:93], v[94:95]
	v_pk_mul_f32 v[94:95], v[34:35], v[34:35]
	v_pk_fma_f32 v[74:75], v[98:99], s[0:1], v[74:75] op_sel_hi:[1,0,0]
	v_pk_mul_f32 v[94:95], v[94:95], s[14:15] op_sel_hi:[1,0]
	v_pk_mul_f32 v[86:87], v[56:57], v[56:57]
	v_pk_mul_f32 v[62:63], v[78:79], v[62:63]
	v_pk_fma_f32 v[74:75], v[98:99], v[74:75], s[12:13] op_sel_hi:[1,1,0]
	v_exp_f32_e32 v94, v94
	v_exp_f32_e32 v95, v95
	v_pk_mul_f32 v[86:87], v[86:87], s[14:15] op_sel_hi:[1,0]
	v_pk_mul_f32 v[78:79], v[36:37], v[62:63]
	v_pk_fma_f32 v[62:63], v[36:37], v[62:63], v[36:37] neg_lo:[1,0,0] neg_hi:[1,0,0]
	v_pk_mul_f32 v[96:97], v[32:33], v[32:33]
	v_pk_fma_f32 v[74:75], v[98:99], v[74:75], s[8:9] op_sel_hi:[1,1,0]
	v_cmp_gt_f32_e32 vcc, 0, v37
	v_exp_f32_e32 v86, v86
	v_exp_f32_e32 v87, v87
	v_pk_mul_f32 v[70:71], v[70:71], v[80:81]
	v_pk_mul_f32 v[96:97], v[96:97], s[14:15] op_sel_hi:[1,0]
	v_pk_fma_f32 v[74:75], v[98:99], v[74:75], s[10:11] op_sel_hi:[1,1,0]
	v_cndmask_b32_e32 v37, v63, v79, vcc
	v_cmp_gt_f32_e32 vcc, 0, v36
	v_pk_mul_f32 v[80:81], v[38:39], v[70:71]
	v_pk_fma_f32 v[70:71], v[38:39], v[70:71], v[38:39] neg_lo:[1,0,0] neg_hi:[1,0,0]
	v_exp_f32_e32 v96, v96
	v_exp_f32_e32 v97, v97
	v_pk_mul_f32 v[74:75], v[98:99], v[74:75]
	v_cndmask_b32_e32 v36, v62, v78, vcc
	v_cmp_gt_f32_e32 vcc, 0, v39
	v_pk_mul_f32 v[74:75], v[94:95], v[74:75]
	v_pk_mul_f32 v[82:83], v[86:87], v[82:83]
	v_cndmask_b32_e32 v39, v71, v81, vcc
	v_cmp_gt_f32_e32 vcc, 0, v38
	v_pk_mul_f32 v[94:95], v[34:35], v[74:75]
	v_pk_fma_f32 v[74:75], v[34:35], v[74:75], v[34:35] neg_lo:[1,0,0] neg_hi:[1,0,0]
	v_cndmask_b32_e32 v38, v70, v80, vcc
	v_cmp_gt_f32_e32 vcc, 0, v35
	v_pk_mul_f32 v[86:87], v[56:57], v[82:83]
	v_pk_fma_f32 v[82:83], v[56:57], v[82:83], v[56:57] neg_lo:[1,0,0] neg_hi:[1,0,0]
	v_cndmask_b32_e32 v75, v75, v95, vcc
	v_cmp_gt_f32_e32 vcc, 0, v34
	v_pk_mul_f32 v[92:93], v[96:97], v[92:93]
	v_mov_b32_e32 v70, v36
	v_cndmask_b32_e32 v74, v74, v94, vcc
	v_cmp_gt_f32_e32 vcc, 0, v56
	v_pk_mul_f32 v[96:97], v[32:33], v[92:93]
	v_pk_fma_f32 v[92:93], v[32:33], v[92:93], v[32:33] neg_lo:[1,0,0] neg_hi:[1,0,0]
	v_cndmask_b32_e32 v80, v82, v86, vcc
	v_cmp_gt_f32_e32 vcc, 0, v32
	v_mov_b32_e32 v71, v38
	v_mov_b32_e32 v78, v37
	v_cndmask_b32_e32 v81, v92, v96, vcc
	v_cmp_gt_f32_e32 vcc, 0, v57
	v_mov_b32_e32 v79, v39
	v_pk_add_f32 v[70:71], v[70:71], v[78:79]
	v_cndmask_b32_e32 v56, v83, v87, vcc
	v_cmp_gt_f32_e32 vcc, 0, v58
	v_mov_b32_e32 v82, v80
	v_mov_b32_e32 v83, v56
	v_cndmask_b32_e32 v59, v84, v88, vcc
	v_cmp_gt_f32_e32 vcc, 0, v33
	v_mul_f32_e32 v32, v80, v80
	v_mov_b32_e32 v58, v81
	v_cndmask_b32_e32 v84, v93, v97, vcc
	v_mov_b32_e32 v85, v59
	v_mul_f32_e32 v65, v90, v90
	v_pk_fma_f32 v[82:83], v[82:83], v[82:83], v[32:33] op_sel_hi:[1,1,0]
	v_pk_add_f32 v[32:33], v[58:59], v[84:85]
	v_pk_mul_f32 v[86:87], v[58:59], v[84:85]
	v_pk_add_f32 v[70:71], v[70:71], v[70:71] op_sel:[0,1] op_sel_hi:[1,0]
	v_mul_f32_e32 v62, v36, v36
	v_mov_b32_e32 v33, v87
	v_mov_b32_e32 v71, v65
	v_mov_b32_e32 v82, v74
	v_mov_b32_e32 v76, v75
	v_pk_fma_f32 v[62:63], v[36:37], v[36:37], v[62:63] op_sel_hi:[1,1,0]
	v_mov_b32_e32 v57, v81
	v_pk_add_f32 v[32:33], v[32:33], v[70:71]
	v_pk_add_f32 v[70:71], v[82:83], v[76:77]
	v_mul_f32_e32 v62, v38, v38
	v_pk_add_f32 v[32:33], v[32:33], v[70:71]
	v_pk_add_f32 v[70:71], v[80:81], v[56:57]
	v_pk_mul_f32 v[76:77], v[80:81], v[56:57]
	v_pk_fma_f32 v[78:79], v[38:39], v[38:39], v[62:63] op_sel_hi:[1,1,0]
	v_mov_b32_e32 v71, v77
	v_pk_mul_f32 v[76:77], v[84:85], v[84:85]
	v_mul_f32_e32 v34, v74, v74
	v_mov_b32_e32 v62, v59
	v_mov_b32_e32 v91, v79
	v_mov_b32_e32 v73, v76
	v_pk_fma_f32 v[34:35], v[74:75], v[74:75], v[34:35] op_sel_hi:[1,1,0]
	v_pk_add_f32 v[62:63], v[62:63], v[90:91]
	v_pk_add_f32 v[70:71], v[70:71], v[72:73]
	v_mov_b32_e32 v65, v35
	v_pk_add_f32 v[62:63], v[70:71], v[62:63]
	v_add_u32_e32 v66, 0x90, v174
	v_pk_add_f32 v[34:35], v[62:63], v[64:65]
	v_ashrrev_i32_e32 v67, 31, v66
	v_pk_add_f32 v[32:33], v[32:33], v[34:35]
	v_mov_b32_e32 v34, v32
	v_mov_b32_e32 v35, v33
	s_nop 1
	v_permlane16_swap_b32_e32 v34, v32
	v_permlane16_swap_b32_e32 v35, v33
	s_waitcnt lgkmcnt(2)
	v_lshlrev_b64 v[68:69], 13, v[66:67]
	v_lshl_add_u64 v[68:69], s[28:29], 0, v[68:69]
	v_lshl_add_u64 v[68:69], v[170:171], 1, v[68:69]
	v_cvt_pk_bf16_f32 v62, v80, v56
	s_waitcnt lgkmcnt(0)
	v_pk_add_f32 v[32:33], v[32:33], v[34:35]
	v_mov_b32_e32 v34, v32
	v_mov_b32_e32 v35, v33
	s_nop 1
	v_permlane32_swap_b32_e32 v34, v32
	v_permlane32_swap_b32_e32 v35, v33
	v_cvt_pk_bf16_f32 v63, v59, v90
	global_store_dwordx4 v[68:69], v[60:63], off
	v_cvt_pk_bf16_f32 v36, v36, v37
	v_cvt_pk_bf16_f32 v37, v38, v39
	v_cvt_pk_bf16_f32 v38, v81, v84
	v_cvt_pk_bf16_f32 v39, v74, v75
	global_store_dwordx4 v[68:69], v[36:39], off offset:256
	s_and_saveexec_b64 s[0:1], s[4:5]
	s_cbranch_execz .LBB0_318
	s_lshl_b32 s6, s15, 3
	s_waitcnt lgkmcnt(0)
	v_pk_add_f32 v[32:33], v[32:33], v[34:35]
	v_lshlrev_b64 v[34:35], 8, v[66:67]
	s_add_i32 s6, s6, s72
	v_lshl_add_u64 v[34:35], s[26:27], 0, v[34:35]
	s_ashr_i32 s7, s6, 31
	v_lshl_add_u64 v[34:35], s[6:7], 2, v[34:35]
	global_store_dwordx2 v[34:35], v[32:33], off
.LBB0_318:
	s_or_b64 exec, exec, s[0:1]
	v_pk_fma_f32 v[36:37], v[28:29], v[172:173], v[52:53] op_sel_hi:[1,0,1]
	s_mov_b32 s6, 0x3e6d3388
	v_and_b32_e32 v29, 0x7fffffff, v37
	v_and_b32_e32 v28, 0x7fffffff, v36
	v_pk_fma_f32 v[28:29], v[28:29], s[6:7], 1.0 op_sel_hi:[1,0,0]
	v_pk_fma_f32 v[30:31], v[30:31], v[172:173], v[54:55] op_sel_hi:[1,0,1]
	v_rcp_f32_e32 v28, v28
	v_rcp_f32_e32 v29, v29
	s_mov_b32 s0, 0x3f07dc22
	v_mov_b64_e32 v[38:39], s[16:17]
	v_pk_mul_f32 v[58:59], v[36:37], v[36:37]
	v_pk_fma_f32 v[56:57], v[28:29], s[0:1], v[38:39] op_sel_hi:[1,0,0]
	v_pk_mul_f32 v[58:59], v[58:59], s[14:15] op_sel_hi:[1,0]
	v_and_b32_e32 v61, 0x7fffffff, v31
	v_and_b32_e32 v60, 0x7fffffff, v30
	v_pk_fma_f32 v[56:57], v[28:29], v[56:57], s[12:13] op_sel_hi:[1,1,0]
	v_exp_f32_e32 v58, v58
	v_exp_f32_e32 v59, v59
	v_pk_fma_f32 v[60:61], v[60:61], s[6:7], 1.0 op_sel_hi:[1,0,0]
	v_pk_fma_f32 v[56:57], v[28:29], v[56:57], s[8:9] op_sel_hi:[1,1,0]
	v_rcp_f32_e32 v60, v60
	v_rcp_f32_e32 v61, v61
	v_pk_fma_f32 v[56:57], v[28:29], v[56:57], s[10:11] op_sel_hi:[1,1,0]
	v_pk_fma_f32 v[24:25], v[24:25], v[172:173], v[48:49] op_sel_hi:[1,0,1]
	v_pk_mul_f32 v[28:29], v[28:29], v[56:57]
	v_pk_mul_f32 v[56:57], v[30:31], v[30:31]
	v_pk_mul_f32 v[28:29], v[58:59], v[28:29]
	v_pk_mul_f32 v[56:57], v[56:57], s[14:15] op_sel_hi:[1,0]
	v_pk_mul_f32 v[58:59], v[36:37], v[28:29]
	v_pk_fma_f32 v[62:63], v[36:37], v[28:29], v[36:37] neg_lo:[1,0,0] neg_hi:[1,0,0]
	v_pk_fma_f32 v[28:29], v[60:61], s[0:1], v[38:39] op_sel_hi:[1,0,0]
	v_exp_f32_e32 v56, v56
	v_pk_fma_f32 v[28:29], v[60:61], v[28:29], s[12:13] op_sel_hi:[1,1,0]
	v_exp_f32_e32 v57, v57
	v_pk_fma_f32 v[28:29], v[60:61], v[28:29], s[8:9] op_sel_hi:[1,1,0]
	v_pk_fma_f32 v[26:27], v[26:27], v[172:173], v[50:51] op_sel_hi:[1,0,1]
	v_pk_fma_f32 v[28:29], v[60:61], v[28:29], s[10:11] op_sel_hi:[1,1,0]
	v_pk_mul_f32 v[66:67], v[24:25], v[24:25]
	v_pk_mul_f32 v[28:29], v[60:61], v[28:29]
	v_and_b32_e32 v61, 0x7fffffff, v25
	v_and_b32_e32 v60, 0x7fffffff, v24
	v_pk_fma_f32 v[60:61], v[60:61], s[6:7], 1.0 op_sel_hi:[1,0,0]
	v_pk_mul_f32 v[28:29], v[56:57], v[28:29]
	v_rcp_f32_e32 v60, v60
	v_rcp_f32_e32 v61, v61
	v_pk_mul_f32 v[56:57], v[30:31], v[28:29]
	v_pk_fma_f32 v[64:65], v[30:31], v[28:29], v[30:31] neg_lo:[1,0,0] neg_hi:[1,0,0]
	v_pk_mul_f32 v[66:67], v[66:67], s[14:15] op_sel_hi:[1,0]
	v_pk_fma_f32 v[28:29], v[60:61], s[0:1], v[38:39] op_sel_hi:[1,0,0]
	v_and_b32_e32 v69, 0x7fffffff, v27
	v_and_b32_e32 v68, 0x7fffffff, v26
	v_pk_fma_f32 v[28:29], v[60:61], v[28:29], s[12:13] op_sel_hi:[1,1,0]
	v_exp_f32_e32 v66, v66
	v_exp_f32_e32 v67, v67
	v_pk_fma_f32 v[68:69], v[68:69], s[6:7], 1.0 op_sel_hi:[1,0,0]
	v_pk_fma_f32 v[28:29], v[60:61], v[28:29], s[8:9] op_sel_hi:[1,1,0]
	v_rcp_f32_e32 v68, v68
	v_rcp_f32_e32 v69, v69
	v_pk_fma_f32 v[28:29], v[60:61], v[28:29], s[10:11] op_sel_hi:[1,1,0]
	v_cmp_gt_f32_e32 vcc, 0, v27
	v_pk_mul_f32 v[28:29], v[60:61], v[28:29]
	v_pk_mul_f32 v[60:61], v[26:27], v[26:27]
	v_pk_mul_f32 v[28:29], v[66:67], v[28:29]
	v_pk_mul_f32 v[60:61], v[60:61], s[14:15] op_sel_hi:[1,0]
	v_pk_mul_f32 v[66:67], v[24:25], v[28:29]
	v_pk_fma_f32 v[70:71], v[24:25], v[28:29], v[24:25] neg_lo:[1,0,0] neg_hi:[1,0,0]
	v_pk_fma_f32 v[28:29], v[68:69], s[0:1], v[38:39] op_sel_hi:[1,0,0]
	v_exp_f32_e32 v60, v60
	v_pk_fma_f32 v[28:29], v[68:69], v[28:29], s[12:13] op_sel_hi:[1,1,0]
	v_exp_f32_e32 v61, v61
	v_pk_fma_f32 v[28:29], v[68:69], v[28:29], s[8:9] op_sel_hi:[1,1,0]
	v_pk_fma_f32 v[22:23], v[22:23], v[172:173], v[46:47] op_sel_hi:[1,0,1]
	v_pk_fma_f32 v[28:29], v[68:69], v[28:29], s[10:11] op_sel_hi:[1,1,0]
	v_pk_fma_f32 v[20:21], v[20:21], v[172:173], v[44:45] op_sel_hi:[1,0,1]
	v_pk_mul_f32 v[28:29], v[68:69], v[28:29]
	v_pk_fma_f32 v[18:19], v[18:19], v[172:173], v[42:43] op_sel_hi:[1,0,1]
	v_pk_mul_f32 v[28:29], v[60:61], v[28:29]
	v_and_b32_e32 v81, 0x7fffffff, v19
	v_pk_mul_f32 v[60:61], v[26:27], v[28:29]
	v_pk_fma_f32 v[68:69], v[26:27], v[28:29], v[26:27] neg_lo:[1,0,0] neg_hi:[1,0,0]
	v_and_b32_e32 v80, 0x7fffffff, v18
	v_cndmask_b32_e32 v28, v69, v61, vcc
	v_cmp_gt_f32_e32 vcc, 0, v30
	v_pk_fma_f32 v[80:81], v[80:81], s[6:7], 1.0 op_sel_hi:[1,0,0]
	v_mul_f32_e32 v29, v28, v28
	v_cndmask_b32_e32 v73, v64, v56, vcc
	v_cmp_gt_f32_e32 vcc, 0, v36
	v_rcp_f32_e32 v80, v80
	v_rcp_f32_e32 v81, v81
	v_cndmask_b32_e32 v72, v62, v58, vcc
	v_cmp_gt_f32_e32 vcc, 0, v31
	v_add_u32_e32 v32, 0xa0, v174
	v_ashrrev_i32_e32 v33, 31, v32
	v_cndmask_b32_e32 v31, v65, v57, vcc
	v_cmp_gt_f32_e32 vcc, 0, v37
	v_pk_mul_f32 v[64:65], v[20:21], v[20:21]
	s_waitcnt lgkmcnt(0)
	v_lshlrev_b64 v[34:35], 13, v[32:33]
	v_cndmask_b32_e32 v30, v63, v59, vcc
	v_pk_add_f32 v[36:37], v[72:73], v[30:31]
	v_pk_fma_f32 v[62:63], v[16:17], v[172:173], v[40:41] op_sel_hi:[1,0,1]
	v_pk_add_f32 v[56:57], v[36:37], v[36:37] op_sel:[0,1] op_sel_hi:[1,0]
	v_pk_mul_f32 v[36:37], v[30:31], v[30:31]
	v_pk_mul_f32 v[64:65], v[64:65], s[14:15] op_sel_hi:[1,0]
	v_pk_fma_f32 v[36:37], v[72:73], v[72:73], v[36:37]
	v_exp_f32_e32 v64, v64
	v_pk_add_f32 v[58:59], v[36:37], v[36:37] op_sel_hi:[0,1]
	v_cvt_pk_bf16_f32 v36, v72, v30
	v_cvt_pk_bf16_f32 v37, v73, v31
	v_and_b32_e32 v73, 0x7fffffff, v23
	v_and_b32_e32 v72, 0x7fffffff, v22
	v_pk_fma_f32 v[72:73], v[72:73], s[6:7], 1.0 op_sel_hi:[1,0,0]
	v_and_b32_e32 v31, 0x7fffffff, v21
	v_rcp_f32_e32 v72, v72
	v_rcp_f32_e32 v73, v73
	v_and_b32_e32 v30, 0x7fffffff, v20
	v_pk_fma_f32 v[30:31], v[30:31], s[6:7], 1.0 op_sel_hi:[1,0,0]
	v_exp_f32_e32 v65, v65
	v_pk_fma_f32 v[74:75], v[72:73], s[0:1], v[38:39] op_sel_hi:[1,0,0]
	v_rcp_f32_e32 v30, v30
	v_pk_fma_f32 v[74:75], v[72:73], v[74:75], s[12:13] op_sel_hi:[1,1,0]
	v_rcp_f32_e32 v31, v31
	v_pk_fma_f32 v[74:75], v[72:73], v[74:75], s[8:9] op_sel_hi:[1,1,0]
	v_pk_mul_f32 v[78:79], v[62:63], v[62:63]
	v_pk_fma_f32 v[74:75], v[72:73], v[74:75], s[10:11] op_sel_hi:[1,1,0]
	v_pk_fma_f32 v[16:17], v[30:31], s[0:1], v[38:39] op_sel_hi:[1,0,0]
	v_pk_mul_f32 v[72:73], v[72:73], v[74:75]
	v_and_b32_e32 v75, 0x7fffffff, v63
	v_and_b32_e32 v74, 0x7fffffff, v62
	v_pk_fma_f32 v[74:75], v[74:75], s[6:7], 1.0 op_sel_hi:[1,0,0]
	v_pk_fma_f32 v[16:17], v[30:31], v[16:17], s[12:13] op_sel_hi:[1,1,0]
	v_rcp_f32_e32 v74, v74
	v_rcp_f32_e32 v75, v75
	v_pk_fma_f32 v[16:17], v[30:31], v[16:17], s[8:9] op_sel_hi:[1,1,0]
	v_cmp_gt_f32_e32 vcc, 0, v21
	v_pk_fma_f32 v[16:17], v[30:31], v[16:17], s[10:11] op_sel_hi:[1,1,0]
	v_pk_fma_f32 v[76:77], v[74:75], s[0:1], v[38:39] op_sel_hi:[1,0,0]
	v_pk_mul_f32 v[16:17], v[30:31], v[16:17]
	v_pk_fma_f32 v[76:77], v[74:75], v[76:77], s[12:13] op_sel_hi:[1,1,0]
	v_pk_mul_f32 v[30:31], v[22:23], v[22:23]
	v_pk_fma_f32 v[76:77], v[74:75], v[76:77], s[8:9] op_sel_hi:[1,1,0]
	v_pk_mul_f32 v[30:31], v[30:31], s[14:15] op_sel_hi:[1,0]
	v_pk_fma_f32 v[76:77], v[74:75], v[76:77], s[10:11] op_sel_hi:[1,1,0]
	v_exp_f32_e32 v30, v30
	v_exp_f32_e32 v31, v31
	v_pk_mul_f32 v[74:75], v[74:75], v[76:77]
	v_pk_mul_f32 v[76:77], v[18:19], v[18:19]
	v_pk_fma_f32 v[38:39], v[80:81], s[0:1], v[38:39] op_sel_hi:[1,0,0]
	v_pk_mul_f32 v[76:77], v[76:77], s[14:15] op_sel_hi:[1,0]
	v_pk_mul_f32 v[16:17], v[64:65], v[16:17]
	v_pk_fma_f32 v[38:39], v[80:81], v[38:39], s[12:13] op_sel_hi:[1,1,0]
	v_exp_f32_e32 v76, v76
	v_exp_f32_e32 v77, v77
	v_pk_mul_f32 v[64:65], v[20:21], v[16:17]
	v_pk_fma_f32 v[16:17], v[20:21], v[16:17], v[20:21] neg_lo:[1,0,0] neg_hi:[1,0,0]
	v_pk_fma_f32 v[38:39], v[80:81], v[38:39], s[8:9] op_sel_hi:[1,1,0]
	v_pk_mul_f32 v[30:31], v[30:31], v[72:73]
	v_pk_mul_f32 v[78:79], v[78:79], s[14:15] op_sel_hi:[1,0]
	v_pk_fma_f32 v[38:39], v[80:81], v[38:39], s[10:11] op_sel_hi:[1,1,0]
	v_cndmask_b32_e32 v21, v17, v65, vcc
	v_cmp_gt_f32_e32 vcc, 0, v20
	v_pk_mul_f32 v[72:73], v[22:23], v[30:31]
	v_pk_fma_f32 v[30:31], v[22:23], v[30:31], v[22:23] neg_lo:[1,0,0] neg_hi:[1,0,0]
	v_exp_f32_e32 v78, v78
	v_exp_f32_e32 v79, v79
	v_pk_mul_f32 v[38:39], v[80:81], v[38:39]
	v_cndmask_b32_e32 v20, v16, v64, vcc
	v_cmp_gt_f32_e32 vcc, 0, v23
	v_pk_mul_f32 v[38:39], v[76:77], v[38:39]
	v_pk_mul_f32 v[74:75], v[78:79], v[74:75]
	v_cndmask_b32_e32 v31, v31, v73, vcc
	v_cmp_gt_f32_e32 vcc, 0, v22
	v_pk_mul_f32 v[76:77], v[18:19], v[38:39]
	v_pk_fma_f32 v[38:39], v[18:19], v[38:39], v[18:19] neg_lo:[1,0,0] neg_hi:[1,0,0]
	v_cndmask_b32_e32 v30, v30, v72, vcc
	v_cmp_gt_f32_e32 vcc, 0, v19
	v_mul_f32_e32 v16, v20, v20
	v_pk_mul_f32 v[78:79], v[62:63], v[74:75]
	v_cndmask_b32_e32 v77, v39, v77, vcc
	v_cmp_gt_f32_e32 vcc, 0, v18
	v_pk_fma_f32 v[74:75], v[62:63], v[74:75], v[62:63] neg_lo:[1,0,0] neg_hi:[1,0,0]
	v_pk_fma_f32 v[64:65], v[20:21], v[20:21], v[16:17] op_sel_hi:[1,1,0]
	v_cndmask_b32_e32 v76, v38, v76, vcc
	v_cmp_gt_f32_e32 vcc, 0, v24
	v_mov_b32_e32 v16, v20
	v_mov_b32_e32 v17, v30
	v_mov_b32_e32 v22, v21
	v_mov_b32_e32 v23, v31
	v_cndmask_b32_e32 v80, v70, v66, vcc
	v_cmp_gt_f32_e32 vcc, 0, v62
	v_pk_add_f32 v[22:23], v[16:17], v[22:23]
	v_mul_f32_e32 v16, v30, v30
	v_cndmask_b32_e32 v81, v74, v78, vcc
	v_cmp_gt_f32_e32 vcc, 0, v25
	v_pk_fma_f32 v[72:73], v[30:31], v[30:31], v[16:17] op_sel_hi:[1,1,0]
	v_mul_f32_e32 v16, v76, v76
	v_cndmask_b32_e32 v18, v71, v67, vcc
	v_cmp_gt_f32_e32 vcc, 0, v26
	v_pk_fma_f32 v[16:17], v[76:77], v[76:77], v[16:17] op_sel_hi:[1,1,0]
	v_mov_b32_e32 v24, v80
	v_cndmask_b32_e32 v27, v68, v60, vcc
	v_cmp_gt_f32_e32 vcc, 0, v63
	v_mov_b32_e32 v25, v18
	v_mul_f32_e32 v16, v80, v80
	v_mov_b32_e32 v26, v81
	v_cndmask_b32_e32 v60, v75, v79, vcc
	v_mov_b32_e32 v61, v27
	v_pk_fma_f32 v[24:25], v[24:25], v[24:25], v[16:17] op_sel_hi:[1,1,0]
	v_pk_add_f32 v[38:39], v[26:27], v[60:61]
	v_pk_mul_f32 v[62:63], v[26:27], v[60:61]
	v_pk_add_f32 v[22:23], v[22:23], v[22:23] op_sel:[0,1] op_sel_hi:[1,0]
	v_mov_b32_e32 v19, v81
	v_mov_b32_e32 v39, v63
	v_mov_b32_e32 v23, v29
	v_mov_b32_e32 v24, v76
	v_mov_b32_e32 v58, v77
	v_pk_add_f32 v[22:23], v[38:39], v[22:23]
	v_pk_add_f32 v[24:25], v[24:25], v[58:59]
	v_pk_add_f32 v[38:39], v[80:81], v[18:19]
	v_pk_mul_f32 v[58:59], v[80:81], v[18:19]
	v_mov_b32_e32 v64, v27
	v_mov_b32_e32 v39, v59
	v_pk_mul_f32 v[58:59], v[60:61], v[60:61]
	v_mov_b32_e32 v29, v73
	v_mov_b32_e32 v57, v58
	v_pk_add_f32 v[22:23], v[22:23], v[24:25]
	v_pk_add_f32 v[24:25], v[64:65], v[28:29]
	v_pk_add_f32 v[38:39], v[38:39], v[56:57]
	v_mov_b32_e32 v16, 0
	v_pk_add_f32 v[24:25], v[38:39], v[24:25]
	v_lshl_add_u64 v[34:35], s[28:29], 0, v[34:35]
	v_pk_add_f32 v[24:25], v[24:25], v[16:17]
	v_lshl_add_u64 v[34:35], v[170:171], 1, v[34:35]
	v_pk_add_f32 v[24:25], v[22:23], v[24:25]
	v_mov_b32_e32 v56, v24
	v_mov_b32_e32 v57, v25
	s_nop 1
	v_permlane16_swap_b32_e32 v56, v24
	v_permlane16_swap_b32_e32 v57, v25
	v_cvt_pk_bf16_f32 v38, v80, v18
	v_cvt_pk_bf16_f32 v39, v27, v28
	global_store_dwordx4 v[34:35], v[36:39], off
	v_cvt_pk_bf16_f32 v22, v20, v21
	s_waitcnt lgkmcnt(0)
	v_pk_add_f32 v[18:19], v[24:25], v[56:57]
	v_mov_b32_e32 v20, v18
	v_mov_b32_e32 v21, v19
	s_nop 1
	v_permlane32_swap_b32_e32 v20, v18
	v_permlane32_swap_b32_e32 v21, v19
	v_cvt_pk_bf16_f32 v23, v30, v31
	v_cvt_pk_bf16_f32 v24, v81, v60
	v_cvt_pk_bf16_f32 v25, v76, v77
	global_store_dwordx4 v[34:35], v[22:25], off offset:256
	s_and_saveexec_b64 s[18:19], s[4:5]
	s_cbranch_execz .LBB0_320
	s_lshl_b32 s1, s15, 3
	s_waitcnt lgkmcnt(0)
	v_pk_add_f32 v[18:19], v[18:19], v[20:21]
	v_lshlrev_b64 v[20:21], 8, v[32:33]
	s_add_i32 s20, s1, s72
	v_lshl_add_u64 v[20:21], s[26:27], 0, v[20:21]
	s_ashr_i32 s21, s20, 31
	v_lshl_add_u64 v[20:21], s[20:21], 2, v[20:21]
	global_store_dwordx2 v[20:21], v[18:19], off
.LBB0_320:
	s_or_b64 exec, exec, s[18:19]
	v_mov_b32_e32 v22, v173
	v_pk_fma_f32 v[14:15], v[14:15], v[22:23], v[54:55] op_sel_hi:[1,0,1]
	v_mov_b64_e32 v[26:27], s[16:17]
	v_and_b32_e32 v33, 0x7fffffff, v15
	v_and_b32_e32 v32, 0x7fffffff, v14
	v_pk_fma_f32 v[32:33], v[32:33], s[6:7], 1.0 op_sel_hi:[1,0,0]
	v_pk_fma_f32 v[8:9], v[8:9], v[22:23], v[48:49] op_sel_hi:[1,0,1]
	v_rcp_f32_e32 v32, v32
	v_rcp_f32_e32 v33, v33
	v_pk_fma_f32 v[12:13], v[12:13], v[22:23], v[52:53] op_sel_hi:[1,0,1]
	v_pk_fma_f32 v[10:11], v[10:11], v[22:23], v[50:51] op_sel_hi:[1,0,1]
	v_and_b32_e32 v25, 0x7fffffff, v13
	v_pk_fma_f32 v[34:35], v[32:33], s[0:1], v[26:27] op_sel_hi:[1,0,0]
	v_and_b32_e32 v24, 0x7fffffff, v12
	v_pk_fma_f32 v[34:35], v[32:33], v[34:35], s[12:13] op_sel_hi:[1,1,0]
	v_pk_fma_f32 v[24:25], v[24:25], s[6:7], 1.0 op_sel_hi:[1,0,0]
	v_pk_fma_f32 v[34:35], v[32:33], v[34:35], s[8:9] op_sel_hi:[1,1,0]
	v_rcp_f32_e32 v24, v24
	v_pk_fma_f32 v[34:35], v[32:33], v[34:35], s[10:11] op_sel_hi:[1,1,0]
	v_rcp_f32_e32 v25, v25
	v_pk_mul_f32 v[32:33], v[32:33], v[34:35]
	v_and_b32_e32 v35, 0x7fffffff, v9
	v_and_b32_e32 v34, 0x7fffffff, v8
	v_pk_fma_f32 v[34:35], v[34:35], s[6:7], 1.0 op_sel_hi:[1,0,0]
	v_and_b32_e32 v49, 0x7fffffff, v11
	v_rcp_f32_e32 v34, v34
	v_rcp_f32_e32 v35, v35
	v_and_b32_e32 v48, 0x7fffffff, v10
	v_pk_fma_f32 v[48:49], v[48:49], s[6:7], 1.0 op_sel_hi:[1,0,0]
	v_pk_fma_f32 v[28:29], v[24:25], s[0:1], v[26:27] op_sel_hi:[1,0,0]
	v_pk_fma_f32 v[36:37], v[34:35], s[0:1], v[26:27] op_sel_hi:[1,0,0]
	v_rcp_f32_e32 v48, v48
	v_pk_fma_f32 v[36:37], v[34:35], v[36:37], s[12:13] op_sel_hi:[1,1,0]
	v_rcp_f32_e32 v49, v49
	v_pk_fma_f32 v[28:29], v[24:25], v[28:29], s[12:13] op_sel_hi:[1,1,0]
	v_pk_fma_f32 v[36:37], v[34:35], v[36:37], s[8:9] op_sel_hi:[1,1,0]
	v_pk_fma_f32 v[28:29], v[24:25], v[28:29], s[8:9] op_sel_hi:[1,1,0]
	v_pk_fma_f32 v[36:37], v[34:35], v[36:37], s[10:11] op_sel_hi:[1,1,0]
	v_pk_fma_f32 v[28:29], v[24:25], v[28:29], s[10:11] op_sel_hi:[1,1,0]
	v_pk_mul_f32 v[34:35], v[34:35], v[36:37]
	v_pk_mul_f32 v[36:37], v[10:11], v[10:11]
	v_pk_mul_f32 v[24:25], v[24:25], v[28:29]
	v_pk_mul_f32 v[28:29], v[14:15], v[14:15]
	v_pk_fma_f32 v[50:51], v[48:49], s[0:1], v[26:27] op_sel_hi:[1,0,0]
	v_pk_mul_f32 v[36:37], v[36:37], s[14:15] op_sel_hi:[1,0]
	v_pk_mul_f32 v[30:31], v[12:13], v[12:13]
	v_pk_mul_f32 v[28:29], v[28:29], s[14:15] op_sel_hi:[1,0]
	v_pk_fma_f32 v[50:51], v[48:49], v[50:51], s[12:13] op_sel_hi:[1,1,0]
	v_exp_f32_e32 v36, v36
	v_exp_f32_e32 v37, v37
	v_pk_mul_f32 v[30:31], v[30:31], s[14:15] op_sel_hi:[1,0]
	v_exp_f32_e32 v28, v28
	v_exp_f32_e32 v29, v29
	v_pk_fma_f32 v[50:51], v[48:49], v[50:51], s[8:9] op_sel_hi:[1,1,0]
	v_exp_f32_e32 v30, v30
	v_exp_f32_e32 v31, v31
	v_pk_fma_f32 v[50:51], v[48:49], v[50:51], s[10:11] op_sel_hi:[1,1,0]
	v_pk_mul_f32 v[28:29], v[28:29], v[32:33]
	v_pk_mul_f32 v[48:49], v[48:49], v[50:51]
	v_cmp_gt_f32_e32 vcc, 0, v11
	v_pk_mul_f32 v[36:37], v[36:37], v[48:49]
	v_pk_mul_f32 v[24:25], v[30:31], v[24:25]
	v_pk_mul_f32 v[48:49], v[10:11], v[36:37]
	v_pk_fma_f32 v[36:37], v[10:11], v[36:37], v[10:11] neg_lo:[1,0,0] neg_hi:[1,0,0]
	v_pk_mul_f32 v[32:33], v[14:15], v[28:29]
	v_pk_fma_f32 v[28:29], v[14:15], v[28:29], v[14:15] neg_lo:[1,0,0] neg_hi:[1,0,0]
	v_cndmask_b32_e32 v50, v37, v49, vcc
	v_cmp_gt_f32_e32 vcc, 0, v14
	v_pk_mul_f32 v[30:31], v[12:13], v[24:25]
	v_pk_fma_f32 v[24:25], v[12:13], v[24:25], v[12:13] neg_lo:[1,0,0] neg_hi:[1,0,0]
	v_cndmask_b32_e32 v53, v28, v32, vcc
	v_cmp_gt_f32_e32 vcc, 0, v12
	v_pk_fma_f32 v[6:7], v[6:7], v[22:23], v[46:47] op_sel_hi:[1,0,1]
	v_pk_fma_f32 v[0:1], v[0:1], v[22:23], v[40:41] op_sel_hi:[1,0,1]
	v_cndmask_b32_e32 v52, v24, v30, vcc
	v_cmp_gt_f32_e32 vcc, 0, v15
	v_and_b32_e32 v32, 0x7fffffff, v6
	v_pk_fma_f32 v[4:5], v[4:5], v[22:23], v[44:45] op_sel_hi:[1,0,1]
	v_cndmask_b32_e32 v15, v29, v33, vcc
	v_and_b32_e32 v33, 0x7fffffff, v7
	v_pk_fma_f32 v[32:33], v[32:33], s[6:7], 1.0 op_sel_hi:[1,0,0]
	v_cmp_gt_f32_e32 vcc, 0, v13
	v_rcp_f32_e32 v32, v32
	v_rcp_f32_e32 v33, v33
	v_cndmask_b32_e32 v14, v25, v31, vcc
	v_pk_add_f32 v[12:13], v[52:53], v[14:15]
	v_pk_fma_f32 v[2:3], v[2:3], v[22:23], v[42:43] op_sel_hi:[1,0,1]
	v_pk_add_f32 v[24:25], v[12:13], v[12:13] op_sel:[0,1] op_sel_hi:[1,0]
	v_pk_mul_f32 v[12:13], v[14:15], v[14:15]
	v_pk_fma_f32 v[40:41], v[32:33], s[0:1], v[26:27] op_sel_hi:[1,0,0]
	v_pk_fma_f32 v[12:13], v[52:53], v[52:53], v[12:13]
	v_pk_fma_f32 v[40:41], v[32:33], v[40:41], s[12:13] op_sel_hi:[1,1,0]
	v_pk_add_f32 v[28:29], v[12:13], v[12:13] op_sel_hi:[0,1]
	v_cvt_pk_bf16_f32 v12, v52, v14
	v_cvt_pk_bf16_f32 v13, v53, v15
	v_and_b32_e32 v15, 0x7fffffff, v5
	v_and_b32_e32 v14, 0x7fffffff, v4
	v_pk_fma_f32 v[40:41], v[32:33], v[40:41], s[8:9] op_sel_hi:[1,1,0]
	v_pk_fma_f32 v[14:15], v[14:15], s[6:7], 1.0 op_sel_hi:[1,0,0]
	v_pk_fma_f32 v[40:41], v[32:33], v[40:41], s[10:11] op_sel_hi:[1,1,0]
	v_rcp_f32_e32 v14, v14
	v_rcp_f32_e32 v15, v15
	v_pk_mul_f32 v[32:33], v[32:33], v[40:41]
	v_and_b32_e32 v41, 0x7fffffff, v1
	v_and_b32_e32 v40, 0x7fffffff, v0
	v_pk_fma_f32 v[40:41], v[40:41], s[6:7], 1.0 op_sel_hi:[1,0,0]
	v_pk_fma_f32 v[22:23], v[14:15], s[0:1], v[26:27] op_sel_hi:[1,0,0]
	v_rcp_f32_e32 v40, v40
	v_rcp_f32_e32 v41, v41
	v_pk_fma_f32 v[22:23], v[14:15], v[22:23], s[12:13] op_sel_hi:[1,1,0]
	v_and_b32_e32 v47, 0x7fffffff, v3
	v_and_b32_e32 v46, 0x7fffffff, v2
	v_pk_fma_f32 v[22:23], v[14:15], v[22:23], s[8:9] op_sel_hi:[1,1,0]
	v_pk_mul_f32 v[30:31], v[4:5], v[4:5]
	v_pk_fma_f32 v[42:43], v[40:41], s[0:1], v[26:27] op_sel_hi:[1,0,0]
	v_pk_fma_f32 v[46:47], v[46:47], s[6:7], 1.0 op_sel_hi:[1,0,0]
	v_pk_fma_f32 v[22:23], v[14:15], v[22:23], s[10:11] op_sel_hi:[1,1,0]
	v_pk_mul_f32 v[30:31], v[30:31], s[14:15] op_sel_hi:[1,0]
	v_pk_fma_f32 v[42:43], v[40:41], v[42:43], s[12:13] op_sel_hi:[1,1,0]
	v_rcp_f32_e32 v46, v46
	v_rcp_f32_e32 v47, v47
	v_pk_mul_f32 v[14:15], v[14:15], v[22:23]
	v_pk_mul_f32 v[22:23], v[6:7], v[6:7]
	v_exp_f32_e32 v30, v30
	v_exp_f32_e32 v31, v31
	v_pk_fma_f32 v[42:43], v[40:41], v[42:43], s[8:9] op_sel_hi:[1,1,0]
	v_pk_mul_f32 v[22:23], v[22:23], s[14:15] op_sel_hi:[1,0]
	v_pk_fma_f32 v[42:43], v[40:41], v[42:43], s[10:11] op_sel_hi:[1,1,0]
	v_exp_f32_e32 v22, v22
	v_exp_f32_e32 v23, v23
	v_pk_mul_f32 v[40:41], v[40:41], v[42:43]
	v_pk_mul_f32 v[42:43], v[2:3], v[2:3]
	v_pk_fma_f32 v[26:27], v[46:47], s[0:1], v[26:27] op_sel_hi:[1,0,0]
	v_pk_mul_f32 v[42:43], v[42:43], s[14:15] op_sel_hi:[1,0]
	v_pk_mul_f32 v[38:39], v[8:9], v[8:9]
	v_pk_mul_f32 v[14:15], v[30:31], v[14:15]
	v_pk_fma_f32 v[26:27], v[46:47], v[26:27], s[12:13] op_sel_hi:[1,1,0]
	v_exp_f32_e32 v42, v42
	v_exp_f32_e32 v43, v43
	v_pk_mul_f32 v[38:39], v[38:39], s[14:15] op_sel_hi:[1,0]
	v_pk_mul_f32 v[30:31], v[4:5], v[14:15]
	v_pk_fma_f32 v[14:15], v[4:5], v[14:15], v[4:5] neg_lo:[1,0,0] neg_hi:[1,0,0]
	v_pk_mul_f32 v[44:45], v[0:1], v[0:1]
	v_pk_fma_f32 v[26:27], v[46:47], v[26:27], s[8:9] op_sel_hi:[1,1,0]
	v_cmp_gt_f32_e32 vcc, 0, v5
	v_exp_f32_e32 v38, v38
	v_exp_f32_e32 v39, v39
	v_pk_mul_f32 v[22:23], v[22:23], v[32:33]
	v_pk_mul_f32 v[44:45], v[44:45], s[14:15] op_sel_hi:[1,0]
	v_pk_fma_f32 v[26:27], v[46:47], v[26:27], s[10:11] op_sel_hi:[1,1,0]
	v_cndmask_b32_e32 v5, v15, v31, vcc
	v_cmp_gt_f32_e32 vcc, 0, v4
	v_pk_mul_f32 v[32:33], v[6:7], v[22:23]
	v_pk_fma_f32 v[22:23], v[6:7], v[22:23], v[6:7] neg_lo:[1,0,0] neg_hi:[1,0,0]
	v_exp_f32_e32 v44, v44
	v_exp_f32_e32 v45, v45
	v_pk_mul_f32 v[26:27], v[46:47], v[26:27]
	v_cndmask_b32_e32 v4, v14, v30, vcc
	v_cmp_gt_f32_e32 vcc, 0, v7
	v_pk_mul_f32 v[26:27], v[42:43], v[26:27]
	v_pk_mul_f32 v[34:35], v[38:39], v[34:35]
	v_cndmask_b32_e32 v7, v23, v33, vcc
	v_cmp_gt_f32_e32 vcc, 0, v6
	v_pk_mul_f32 v[42:43], v[2:3], v[26:27]
	v_pk_fma_f32 v[26:27], v[2:3], v[26:27], v[2:3] neg_lo:[1,0,0] neg_hi:[1,0,0]
	v_cndmask_b32_e32 v6, v22, v32, vcc
	v_cmp_gt_f32_e32 vcc, 0, v3
	v_pk_mul_f32 v[38:39], v[8:9], v[34:35]
	v_pk_fma_f32 v[34:35], v[8:9], v[34:35], v[8:9] neg_lo:[1,0,0] neg_hi:[1,0,0]
	v_cndmask_b32_e32 v27, v27, v43, vcc
	v_cmp_gt_f32_e32 vcc, 0, v2
	v_pk_mul_f32 v[40:41], v[44:45], v[40:41]
	v_mov_b32_e32 v22, v4
	v_cndmask_b32_e32 v26, v26, v42, vcc
	v_cmp_gt_f32_e32 vcc, 0, v8
	v_pk_mul_f32 v[44:45], v[0:1], v[40:41]
	v_pk_fma_f32 v[40:41], v[0:1], v[40:41], v[0:1] neg_lo:[1,0,0] neg_hi:[1,0,0]
	v_cndmask_b32_e32 v32, v34, v38, vcc
	v_cmp_gt_f32_e32 vcc, 0, v0
	v_mov_b32_e32 v23, v6
	v_mov_b32_e32 v30, v5
	v_cndmask_b32_e32 v33, v40, v44, vcc
	v_cmp_gt_f32_e32 vcc, 0, v9
	v_mov_b32_e32 v31, v7
	v_pk_add_f32 v[22:23], v[22:23], v[30:31]
	v_cndmask_b32_e32 v8, v35, v39, vcc
	v_cmp_gt_f32_e32 vcc, 0, v10
	v_mov_b32_e32 v34, v32
	v_mov_b32_e32 v35, v8
	v_cndmask_b32_e32 v11, v36, v48, vcc
	v_cmp_gt_f32_e32 vcc, 0, v1
	v_mul_f32_e32 v0, v32, v32
	v_mov_b32_e32 v10, v33
	v_cndmask_b32_e32 v36, v41, v45, vcc
	v_mov_b32_e32 v37, v11
	v_mul_f32_e32 v17, v50, v50
	v_pk_fma_f32 v[34:35], v[34:35], v[34:35], v[0:1] op_sel_hi:[1,1,0]
	v_pk_add_f32 v[0:1], v[10:11], v[36:37]
	v_pk_mul_f32 v[38:39], v[10:11], v[36:37]
	v_pk_add_f32 v[22:23], v[22:23], v[22:23] op_sel:[0,1] op_sel_hi:[1,0]
	v_mul_f32_e32 v14, v4, v4
	v_mov_b32_e32 v1, v39
	v_mov_b32_e32 v23, v17
	v_mov_b32_e32 v34, v26
	v_mov_b32_e32 v28, v27
	v_pk_fma_f32 v[14:15], v[4:5], v[4:5], v[14:15] op_sel_hi:[1,1,0]
	v_mov_b32_e32 v9, v33
	v_pk_add_f32 v[0:1], v[0:1], v[22:23]
	v_pk_add_f32 v[22:23], v[34:35], v[28:29]
	v_mul_f32_e32 v14, v6, v6
	v_pk_add_f32 v[0:1], v[0:1], v[22:23]
	v_pk_add_f32 v[22:23], v[32:33], v[8:9]
	v_pk_mul_f32 v[28:29], v[32:33], v[8:9]
	v_pk_fma_f32 v[30:31], v[6:7], v[6:7], v[14:15] op_sel_hi:[1,1,0]
	v_mov_b32_e32 v23, v29
	v_pk_mul_f32 v[28:29], v[36:37], v[36:37]
	v_mul_f32_e32 v2, v26, v26
	v_mov_b32_e32 v14, v11
	v_mov_b32_e32 v51, v31
	v_mov_b32_e32 v25, v28
	v_pk_fma_f32 v[2:3], v[26:27], v[26:27], v[2:3] op_sel_hi:[1,1,0]
	v_pk_add_f32 v[14:15], v[14:15], v[50:51]
	v_pk_add_f32 v[22:23], v[22:23], v[24:25]
	v_mov_b32_e32 v17, v3
	v_pk_add_f32 v[14:15], v[22:23], v[14:15]
	v_add_u32_e32 v18, 0xb0, v174
	v_pk_add_f32 v[2:3], v[14:15], v[16:17]
	v_ashrrev_i32_e32 v19, 31, v18
	v_pk_add_f32 v[0:1], v[0:1], v[2:3]
	v_mov_b32_e32 v2, v0
	v_mov_b32_e32 v3, v1
	s_nop 1
	v_permlane16_swap_b32_e32 v2, v0
	v_permlane16_swap_b32_e32 v3, v1
	s_waitcnt lgkmcnt(2)
	v_lshlrev_b64 v[20:21], 13, v[18:19]
	v_lshl_add_u64 v[20:21], s[28:29], 0, v[20:21]
	v_lshl_add_u64 v[20:21], v[170:171], 1, v[20:21]
	v_cvt_pk_bf16_f32 v14, v32, v8
	s_waitcnt lgkmcnt(0)
	v_pk_add_f32 v[0:1], v[0:1], v[2:3]
	v_mov_b32_e32 v2, v0
	v_mov_b32_e32 v3, v1
	s_nop 1
	v_permlane32_swap_b32_e32 v2, v0
	v_permlane32_swap_b32_e32 v3, v1
	v_cvt_pk_bf16_f32 v15, v11, v50
	global_store_dwordx4 v[20:21], v[12:15], off
	v_cvt_pk_bf16_f32 v4, v4, v5
	v_cvt_pk_bf16_f32 v5, v6, v7
	v_cvt_pk_bf16_f32 v6, v33, v36
	v_cvt_pk_bf16_f32 v7, v26, v27
	global_store_dwordx4 v[20:21], v[4:7], off offset:256
	s_and_saveexec_b64 s[0:1], s[4:5]
	s_cbranch_execz .LBB0_322
	s_lshl_b32 s4, s15, 3
	s_waitcnt lgkmcnt(0)
	v_pk_add_f32 v[0:1], v[0:1], v[2:3]
	v_lshlrev_b64 v[2:3], 8, v[18:19]
	s_add_i32 s4, s4, s72
	v_lshl_add_u64 v[2:3], s[26:27], 0, v[2:3]
	s_ashr_i32 s5, s4, 31
	v_lshl_add_u64 v[2:3], s[4:5], 2, v[2:3]
	global_store_dwordx2 v[2:3], v[0:1], off

.LBB0_349:
	v_lshl_add_u32 v150, v152, 2, s74
	ds_read2_b32 v[158:159], v150 offset1:16
	ds_read2_b32 v[156:157], v150 offset0:32 offset1:48
	ds_read2_b32 v[154:155], v150 offset0:128 offset1:144
	ds_read2_b32 v[150:151], v150 offset0:160 offset1:176
	s_mov_b32 s4, 0x3e6d3388
	s_waitcnt vmcnt(0) lgkmcnt(0)
	v_pk_fma_f32 v[142:143], v[142:143], v[158:159], v[54:55] op_sel_hi:[1,0,1]
	s_lshl_b32 s0, s73, 8
	v_and_b32_e32 v171, 0x7fffffff, v143
	v_and_b32_e32 v170, 0x7fffffff, v142
	v_pk_fma_f32 v[170:171], v[170:171], s[4:5], 1.0 op_sel_hi:[1,0,0]
	s_add_i32 s0, s0, s68
	v_rcp_f32_e32 v170, v170
	v_rcp_f32_e32 v171, v171
	s_mov_b32 s14, 0xbf3a00e3
	v_add_u32_e32 v152, s0, v152
	s_mov_b32 s0, 0x3f07dc22
	v_mov_b64_e32 v[164:165], s[14:15]
	s_mov_b32 s10, 0x3f35f0e3
	v_pk_fma_f32 v[172:173], v[170:171], s[0:1], v[164:165] op_sel_hi:[1,0,0]
	s_mov_b32 s6, 0xbe11a98e
	v_pk_fma_f32 v[172:173], v[170:171], v[172:173], s[10:11] op_sel_hi:[1,1,0]
	s_mov_b32 s8, 0x3e027906
	v_pk_fma_f32 v[172:173], v[170:171], v[172:173], s[6:7] op_sel_hi:[1,1,0]
	v_pk_fma_f32 v[136:137], v[136:137], v[158:159], v[48:49] op_sel_hi:[1,0,1]
	v_pk_fma_f32 v[172:173], v[170:171], v[172:173], s[8:9] op_sel_hi:[1,1,0]
	v_pk_fma_f32 v[140:141], v[140:141], v[158:159], v[52:53] op_sel_hi:[1,0,1]
	v_pk_mul_f32 v[170:171], v[170:171], v[172:173]
	v_and_b32_e32 v173, 0x7fffffff, v137
	v_and_b32_e32 v172, 0x7fffffff, v136
	v_and_b32_e32 v163, 0x7fffffff, v141
	v_and_b32_e32 v162, 0x7fffffff, v140
	v_pk_fma_f32 v[172:173], v[172:173], s[4:5], 1.0 op_sel_hi:[1,0,0]
	v_pk_fma_f32 v[162:163], v[162:163], s[4:5], 1.0 op_sel_hi:[1,0,0]
	v_rcp_f32_e32 v172, v172
	v_rcp_f32_e32 v173, v173
	v_rcp_f32_e32 v162, v162
	v_rcp_f32_e32 v163, v163
	v_pk_fma_f32 v[138:139], v[138:139], v[158:159], v[50:51] op_sel_hi:[1,0,1]
	v_pk_fma_f32 v[174:175], v[172:173], s[0:1], v[164:165] op_sel_hi:[1,0,0]
	v_and_b32_e32 v179, 0x7fffffff, v139
	v_and_b32_e32 v178, 0x7fffffff, v138
	v_pk_fma_f32 v[178:179], v[178:179], s[4:5], 1.0 op_sel_hi:[1,0,0]
	v_pk_fma_f32 v[166:167], v[162:163], s[0:1], v[164:165] op_sel_hi:[1,0,0]
	v_pk_fma_f32 v[174:175], v[172:173], v[174:175], s[10:11] op_sel_hi:[1,1,0]
	v_rcp_f32_e32 v178, v178
	v_rcp_f32_e32 v179, v179
	v_pk_fma_f32 v[166:167], v[162:163], v[166:167], s[10:11] op_sel_hi:[1,1,0]
	v_pk_fma_f32 v[174:175], v[172:173], v[174:175], s[6:7] op_sel_hi:[1,1,0]
	v_pk_fma_f32 v[166:167], v[162:163], v[166:167], s[6:7] op_sel_hi:[1,1,0]
	v_pk_fma_f32 v[174:175], v[172:173], v[174:175], s[8:9] op_sel_hi:[1,1,0]
	v_pk_fma_f32 v[166:167], v[162:163], v[166:167], s[8:9] op_sel_hi:[1,1,0]
	s_mov_b32 s12, 0xbf38aa3b
	v_pk_mul_f32 v[172:173], v[172:173], v[174:175]
	v_pk_mul_f32 v[174:175], v[138:139], v[138:139]
	v_pk_mul_f32 v[162:163], v[162:163], v[166:167]
	v_pk_mul_f32 v[166:167], v[142:143], v[142:143]
	v_pk_fma_f32 v[180:181], v[178:179], s[0:1], v[164:165] op_sel_hi:[1,0,0]
	v_pk_mul_f32 v[174:175], v[174:175], s[12:13] op_sel_hi:[1,0]
	v_pk_mul_f32 v[168:169], v[140:141], v[140:141]
	v_pk_mul_f32 v[166:167], v[166:167], s[12:13] op_sel_hi:[1,0]
	v_pk_fma_f32 v[180:181], v[178:179], v[180:181], s[10:11] op_sel_hi:[1,1,0]
	v_exp_f32_e32 v174, v174
	v_exp_f32_e32 v175, v175
	v_pk_mul_f32 v[168:169], v[168:169], s[12:13] op_sel_hi:[1,0]
	v_exp_f32_e32 v166, v166
	v_exp_f32_e32 v167, v167
	v_pk_fma_f32 v[180:181], v[178:179], v[180:181], s[6:7] op_sel_hi:[1,1,0]
	v_exp_f32_e32 v168, v168
	v_exp_f32_e32 v169, v169
	v_pk_fma_f32 v[180:181], v[178:179], v[180:181], s[8:9] op_sel_hi:[1,1,0]
	v_pk_mul_f32 v[166:167], v[166:167], v[170:171]
	v_pk_mul_f32 v[178:179], v[178:179], v[180:181]
	v_cmp_gt_f32_e64 s[2:3], 0, v139
	v_pk_mul_f32 v[174:175], v[174:175], v[178:179]
	v_pk_mul_f32 v[162:163], v[168:169], v[162:163]
	v_pk_mul_f32 v[178:179], v[138:139], v[174:175]
	v_pk_fma_f32 v[174:175], v[138:139], v[174:175], v[138:139] neg_lo:[1,0,0] neg_hi:[1,0,0]
	v_pk_mul_f32 v[170:171], v[142:143], v[166:167]
	v_pk_fma_f32 v[166:167], v[142:143], v[166:167], v[142:143] neg_lo:[1,0,0] neg_hi:[1,0,0]
	v_cndmask_b32_e64 v180, v175, v179, s[2:3]
	v_cmp_gt_f32_e64 s[2:3], 0, v142
	v_pk_mul_f32 v[168:169], v[140:141], v[162:163]
	v_pk_fma_f32 v[162:163], v[140:141], v[162:163], v[140:141] neg_lo:[1,0,0] neg_hi:[1,0,0]
	v_cndmask_b32_e64 v183, v166, v170, s[2:3]
	v_cmp_gt_f32_e64 s[2:3], 0, v140
	v_pk_fma_f32 v[134:135], v[134:135], v[158:159], v[46:47] op_sel_hi:[1,0,1]
	v_pk_fma_f32 v[132:133], v[132:133], v[158:159], v[44:45] op_sel_hi:[1,0,1]
	v_cndmask_b32_e64 v182, v162, v168, s[2:3]
	v_cmp_gt_f32_e64 s[2:3], 0, v143
	v_pk_fma_f32 v[130:131], v[130:131], v[158:159], v[42:43] op_sel_hi:[1,0,1]
	v_pk_mul_f32 v[176:177], v[136:137], v[136:137]
	v_cndmask_b32_e64 v143, v167, v171, s[2:3]
	v_cmp_gt_f32_e64 s[2:3], 0, v141
	v_and_b32_e32 v193, 0x7fffffff, v131
	v_and_b32_e32 v192, 0x7fffffff, v130
	v_cndmask_b32_e64 v142, v163, v169, s[2:3]
	v_pk_add_f32 v[140:141], v[182:183], v[142:143]
	v_pk_fma_f32 v[168:169], v[128:129], v[158:159], v[40:41] op_sel_hi:[1,0,1]
	v_pk_add_f32 v[162:163], v[140:141], v[140:141] op_sel:[0,1] op_sel_hi:[1,0]
	v_pk_mul_f32 v[140:141], v[142:143], v[142:143]
	v_pk_mul_f32 v[170:171], v[132:133], v[132:133]
	v_pk_fma_f32 v[140:141], v[182:183], v[182:183], v[140:141]
	v_pk_fma_f32 v[192:193], v[192:193], s[4:5], 1.0 op_sel_hi:[1,0,0]
	v_pk_add_f32 v[166:167], v[140:141], v[140:141] op_sel_hi:[0,1]
	v_cvt_pk_bf16_f32 v140, v182, v142
	v_cvt_pk_bf16_f32 v141, v183, v143
	v_and_b32_e32 v183, 0x7fffffff, v135
	v_and_b32_e32 v182, 0x7fffffff, v134
	v_pk_fma_f32 v[182:183], v[182:183], s[4:5], 1.0 op_sel_hi:[1,0,0]
	v_and_b32_e32 v143, 0x7fffffff, v133
	v_rcp_f32_e32 v182, v182
	v_rcp_f32_e32 v183, v183
	v_and_b32_e32 v142, 0x7fffffff, v132
	v_pk_fma_f32 v[142:143], v[142:143], s[4:5], 1.0 op_sel_hi:[1,0,0]
	v_pk_mul_f32 v[170:171], v[170:171], s[12:13] op_sel_hi:[1,0]
	v_pk_fma_f32 v[186:187], v[182:183], s[0:1], v[164:165] op_sel_hi:[1,0,0]
	v_rcp_f32_e32 v142, v142
	v_pk_fma_f32 v[186:187], v[182:183], v[186:187], s[10:11] op_sel_hi:[1,1,0]
	v_rcp_f32_e32 v143, v143
	v_pk_fma_f32 v[186:187], v[182:183], v[186:187], s[6:7] op_sel_hi:[1,1,0]
	v_rcp_f32_e32 v192, v192
	v_pk_fma_f32 v[186:187], v[182:183], v[186:187], s[8:9] op_sel_hi:[1,1,0]
	v_pk_fma_f32 v[128:129], v[142:143], s[0:1], v[164:165] op_sel_hi:[1,0,0]
	v_pk_mul_f32 v[182:183], v[182:183], v[186:187]
	v_and_b32_e32 v187, 0x7fffffff, v169
	v_and_b32_e32 v186, 0x7fffffff, v168
	v_pk_fma_f32 v[186:187], v[186:187], s[4:5], 1.0 op_sel_hi:[1,0,0]
	v_pk_fma_f32 v[128:129], v[142:143], v[128:129], s[10:11] op_sel_hi:[1,1,0]
	v_rcp_f32_e32 v186, v186
	v_rcp_f32_e32 v187, v187
	v_pk_fma_f32 v[128:129], v[142:143], v[128:129], s[6:7] op_sel_hi:[1,1,0]
	v_rcp_f32_e32 v193, v193
	v_pk_fma_f32 v[128:129], v[142:143], v[128:129], s[8:9] op_sel_hi:[1,1,0]
	v_pk_fma_f32 v[188:189], v[186:187], s[0:1], v[164:165] op_sel_hi:[1,0,0]
	v_pk_mul_f32 v[128:129], v[142:143], v[128:129]
	v_pk_fma_f32 v[188:189], v[186:187], v[188:189], s[10:11] op_sel_hi:[1,1,0]
	v_pk_mul_f32 v[142:143], v[134:135], v[134:135]
	v_exp_f32_e32 v170, v170
	v_exp_f32_e32 v171, v171
	v_pk_fma_f32 v[188:189], v[186:187], v[188:189], s[6:7] op_sel_hi:[1,1,0]
	v_pk_mul_f32 v[142:143], v[142:143], s[12:13] op_sel_hi:[1,0]
	v_pk_fma_f32 v[188:189], v[186:187], v[188:189], s[8:9] op_sel_hi:[1,1,0]
	v_exp_f32_e32 v142, v142
	v_exp_f32_e32 v143, v143
	v_pk_mul_f32 v[186:187], v[186:187], v[188:189]
	v_pk_mul_f32 v[188:189], v[130:131], v[130:131]
	v_pk_fma_f32 v[164:165], v[192:193], s[0:1], v[164:165] op_sel_hi:[1,0,0]
	v_pk_mul_f32 v[188:189], v[188:189], s[12:13] op_sel_hi:[1,0]
	v_pk_mul_f32 v[128:129], v[170:171], v[128:129]
	v_pk_fma_f32 v[164:165], v[192:193], v[164:165], s[10:11] op_sel_hi:[1,1,0]
	v_exp_f32_e32 v188, v188
	v_exp_f32_e32 v189, v189
	v_pk_mul_f32 v[176:177], v[176:177], s[12:13] op_sel_hi:[1,0]
	v_pk_mul_f32 v[170:171], v[132:133], v[128:129]
	v_pk_fma_f32 v[128:129], v[132:133], v[128:129], v[132:133] neg_lo:[1,0,0] neg_hi:[1,0,0]
	v_pk_mul_f32 v[190:191], v[168:169], v[168:169]
	v_pk_fma_f32 v[164:165], v[192:193], v[164:165], s[6:7] op_sel_hi:[1,1,0]
	v_cmp_gt_f32_e64 s[2:3], 0, v133
	v_exp_f32_e32 v176, v176
	v_exp_f32_e32 v177, v177
	v_pk_mul_f32 v[142:143], v[142:143], v[182:183]
	v_pk_mul_f32 v[190:191], v[190:191], s[12:13] op_sel_hi:[1,0]
	v_pk_fma_f32 v[164:165], v[192:193], v[164:165], s[8:9] op_sel_hi:[1,1,0]
	v_cndmask_b32_e64 v133, v129, v171, s[2:3]
	v_cmp_gt_f32_e64 s[2:3], 0, v132
	v_pk_mul_f32 v[182:183], v[134:135], v[142:143]
	v_pk_fma_f32 v[142:143], v[134:135], v[142:143], v[134:135] neg_lo:[1,0,0] neg_hi:[1,0,0]
	v_exp_f32_e32 v190, v190
	v_exp_f32_e32 v191, v191
	v_pk_mul_f32 v[164:165], v[192:193], v[164:165]
	v_cndmask_b32_e64 v132, v128, v170, s[2:3]
	v_cmp_gt_f32_e64 s[2:3], 0, v135
	v_pk_mul_f32 v[164:165], v[188:189], v[164:165]
	v_pk_mul_f32 v[172:173], v[176:177], v[172:173]
	v_cndmask_b32_e64 v183, v143, v183, s[2:3]
	v_cmp_gt_f32_e64 s[2:3], 0, v134
	v_pk_mul_f32 v[188:189], v[130:131], v[164:165]
	v_pk_fma_f32 v[164:165], v[130:131], v[164:165], v[130:131] neg_lo:[1,0,0] neg_hi:[1,0,0]
	v_cndmask_b32_e64 v182, v142, v182, s[2:3]
	v_cmp_gt_f32_e64 s[2:3], 0, v131
	v_mul_f32_e32 v128, v132, v132
	v_pk_mul_f32 v[176:177], v[136:137], v[172:173]
	v_cndmask_b32_e64 v131, v165, v189, s[2:3]
	v_cmp_gt_f32_e64 s[2:3], 0, v130
	v_pk_fma_f32 v[172:173], v[136:137], v[172:173], v[136:137] neg_lo:[1,0,0] neg_hi:[1,0,0]
	v_pk_mul_f32 v[186:187], v[190:191], v[186:187]
	v_pk_fma_f32 v[170:171], v[132:133], v[132:133], v[128:129] op_sel_hi:[1,1,0]
	v_mov_b32_e32 v128, v132
	v_mov_b32_e32 v129, v182
	v_mov_b32_e32 v134, v133
	v_mov_b32_e32 v135, v183
	v_cndmask_b32_e64 v130, v164, v188, s[2:3]
	v_cmp_gt_f32_e64 s[2:3], 0, v136
	v_pk_mul_f32 v[190:191], v[168:169], v[186:187]
	v_pk_fma_f32 v[186:187], v[168:169], v[186:187], v[168:169] neg_lo:[1,0,0] neg_hi:[1,0,0]
	v_pk_add_f32 v[134:135], v[128:129], v[134:135]
	v_mul_f32_e32 v128, v182, v182
	v_cndmask_b32_e64 v164, v172, v176, s[2:3]
	v_cmp_gt_f32_e64 s[2:3], 0, v168
	v_cmp_eq_u32_e32 vcc, 0, v153
	v_ashrrev_i32_e32 v153, 31, v152
	v_pk_fma_f32 v[192:193], v[182:183], v[182:183], v[128:129] op_sel_hi:[1,1,0]
	v_mul_f32_e32 v128, v130, v130
	v_cndmask_b32_e64 v165, v186, v190, s[2:3]
	v_cmp_gt_f32_e64 s[2:3], 0, v137
	v_lshlrev_b64 v[160:161], 13, v[152:153]
	v_pk_fma_f32 v[128:129], v[130:131], v[130:131], v[128:129] op_sel_hi:[1,1,0]
	v_cndmask_b32_e64 v136, v173, v177, s[2:3]
	v_cmp_gt_f32_e64 s[2:3], 0, v138
	v_lshl_add_u64 v[160:161], s[28:29], 0, v[160:161]
	v_mov_b32_e32 v142, v164
	v_mov_b32_e32 v143, v136
	v_mul_f32_e32 v128, v164, v164
	v_cndmask_b32_e64 v139, v174, v178, s[2:3]
	v_cmp_gt_f32_e64 s[2:3], 0, v169
	v_lshl_add_u64 v[160:161], v[148:149], 1, v[160:161]
	v_pk_fma_f32 v[172:173], v[142:143], v[142:143], v[128:129] op_sel_hi:[1,1,0]
	v_cvt_pk_bf16_f32 v142, v164, v136
	v_mov_b32_e32 v138, v165
	v_cndmask_b32_e64 v168, v187, v191, s[2:3]
	v_mov_b32_e32 v169, v139
	v_cvt_pk_bf16_f32 v143, v139, v180
	v_mul_f32_e32 v163, v180, v180
	global_store_dwordx4 v[160:161], v[140:143], off
	v_pk_add_f32 v[134:135], v[134:135], v[134:135] op_sel:[0,1] op_sel_hi:[1,0]
	v_mov_b32_e32 v172, v130
	v_pk_add_f32 v[140:141], v[138:139], v[168:169]
	v_pk_mul_f32 v[142:143], v[138:139], v[168:169]
	v_mov_b32_e32 v135, v163
	v_mov_b32_e32 v141, v143
	v_mov_b32_e32 v166, v131
	v_mov_b32_e32 v137, v165
	v_pk_add_f32 v[134:135], v[140:141], v[134:135]
	v_pk_add_f32 v[140:141], v[172:173], v[166:167]
	v_mov_b32_e32 v170, v139
	v_pk_add_f32 v[134:135], v[134:135], v[140:141]
	v_pk_add_f32 v[140:141], v[164:165], v[136:137]
	v_pk_mul_f32 v[136:137], v[164:165], v[136:137]
	v_mov_b32_e32 v181, v193
	v_mov_b32_e32 v141, v137
	v_pk_mul_f32 v[136:137], v[168:169], v[168:169]
	v_pk_add_f32 v[138:139], v[170:171], v[180:181]
	v_mov_b32_e32 v163, v136
	v_pk_add_f32 v[136:137], v[140:141], v[162:163]
	v_mov_b32_e32 v128, 0
	v_pk_add_f32 v[136:137], v[136:137], v[138:139]
	s_cmp_gt_i32 s13, 7
	v_pk_add_f32 v[136:137], v[136:137], v[128:129]
	v_mbcnt_lo_u32_b32 v129, -1, 0
	v_mbcnt_hi_u32_b32 v129, -1, v129
	v_pk_add_f32 v[140:141], v[134:135], v[136:137]
	v_and_b32_e32 v135, 64, v129
	v_xor_b32_e32 v134, 16, v129
	v_add_u32_e32 v135, 64, v135
	v_cmp_lt_i32_e64 s[2:3], v134, v135
	v_cvt_pk_bf16_f32 v136, v132, v133
	v_xor_b32_e32 v132, 32, v129
	v_cvt_pk_bf16_f32 v137, v182, v183
	v_cvt_pk_bf16_f32 v138, v165, v168
	v_cvt_pk_bf16_f32 v139, v130, v131
	s_nop 0
	v_cndmask_b32_e64 v134, v129, v134, s[2:3]
	v_lshlrev_b32_e32 v134, 2, v134
	v_mov_b32_e32 v142, v140
	v_mov_b32_e32 v143, v141
	s_nop 1
	v_permlane16_swap_b32_e32 v142, v140
	v_permlane16_swap_b32_e32 v143, v141
	v_cmp_lt_i32_e64 s[2:3], v132, v135
	global_store_dwordx4 v[160:161], v[136:139], off offset:256
	s_waitcnt lgkmcnt(0)
	v_pk_add_f32 v[130:131], v[140:141], v[142:143]
	v_cndmask_b32_e64 v129, v129, v132, s[2:3]
	v_lshlrev_b32_e32 v135, 2, v129
	v_mov_b32_e32 v132, v130
	v_mov_b32_e32 v133, v131
	s_nop 1
	v_permlane32_swap_b32_e32 v132, v130
	v_permlane32_swap_b32_e32 v133, v131
	s_cselect_b64 s[2:3], -1, 0
	s_and_b64 s[2:3], s[2:3], vcc
	s_and_saveexec_b64 s[16:17], s[2:3]
	s_cbranch_execz .LBB0_351
	s_lshl_b32 s1, s13, 3
	s_waitcnt lgkmcnt(0)
	v_pk_add_f32 v[130:131], v[130:131], v[132:133]
	v_lshlrev_b64 v[132:133], 8, v[152:153]
	s_add_i32 s18, s1, s72
	v_lshl_add_u64 v[132:133], s[26:27], 0, v[132:133]
	s_ashr_i32 s19, s18, 31
	v_lshl_add_u64 v[132:133], s[18:19], 2, v[132:133]
	global_store_dwordx2 v[132:133], v[130:131], off
.LBB0_351:
	s_or_b64 exec, exec, s[16:17]
	v_mov_b32_e32 v136, v159
	v_pk_fma_f32 v[126:127], v[126:127], v[136:137], v[54:55] op_sel_hi:[1,0,1]
	v_mov_b64_e32 v[140:141], s[14:15]
	v_and_b32_e32 v161, 0x7fffffff, v127
	v_and_b32_e32 v160, 0x7fffffff, v126
	v_pk_fma_f32 v[160:161], v[160:161], s[4:5], 1.0 op_sel_hi:[1,0,0]
	v_pk_fma_f32 v[120:121], v[120:121], v[136:137], v[48:49] op_sel_hi:[1,0,1]
	v_rcp_f32_e32 v160, v160
	v_rcp_f32_e32 v161, v161
	v_pk_fma_f32 v[124:125], v[124:125], v[136:137], v[52:53] op_sel_hi:[1,0,1]
	v_pk_fma_f32 v[122:123], v[122:123], v[136:137], v[50:51] op_sel_hi:[1,0,1]
	v_and_b32_e32 v139, 0x7fffffff, v125
	v_pk_fma_f32 v[162:163], v[160:161], s[0:1], v[140:141] op_sel_hi:[1,0,0]
	v_and_b32_e32 v138, 0x7fffffff, v124
	v_pk_fma_f32 v[162:163], v[160:161], v[162:163], s[10:11] op_sel_hi:[1,1,0]
	v_pk_fma_f32 v[138:139], v[138:139], s[4:5], 1.0 op_sel_hi:[1,0,0]
	v_pk_fma_f32 v[162:163], v[160:161], v[162:163], s[6:7] op_sel_hi:[1,1,0]
	v_rcp_f32_e32 v138, v138
	v_pk_fma_f32 v[162:163], v[160:161], v[162:163], s[8:9] op_sel_hi:[1,1,0]
	v_rcp_f32_e32 v139, v139
	v_pk_mul_f32 v[160:161], v[160:161], v[162:163]
	v_and_b32_e32 v163, 0x7fffffff, v121
	v_and_b32_e32 v162, 0x7fffffff, v120
	v_pk_fma_f32 v[162:163], v[162:163], s[4:5], 1.0 op_sel_hi:[1,0,0]
	v_and_b32_e32 v169, 0x7fffffff, v123
	v_rcp_f32_e32 v162, v162
	v_rcp_f32_e32 v163, v163
	v_and_b32_e32 v168, 0x7fffffff, v122
	v_pk_fma_f32 v[168:169], v[168:169], s[4:5], 1.0 op_sel_hi:[1,0,0]
	v_pk_fma_f32 v[142:143], v[138:139], s[0:1], v[140:141] op_sel_hi:[1,0,0]
	v_pk_fma_f32 v[164:165], v[162:163], s[0:1], v[140:141] op_sel_hi:[1,0,0]
	v_rcp_f32_e32 v168, v168
	v_pk_fma_f32 v[164:165], v[162:163], v[164:165], s[10:11] op_sel_hi:[1,1,0]
	v_rcp_f32_e32 v169, v169
	v_pk_fma_f32 v[142:143], v[138:139], v[142:143], s[10:11] op_sel_hi:[1,1,0]
	v_pk_fma_f32 v[164:165], v[162:163], v[164:165], s[6:7] op_sel_hi:[1,1,0]
	v_pk_fma_f32 v[142:143], v[138:139], v[142:143], s[6:7] op_sel_hi:[1,1,0]
	v_pk_fma_f32 v[164:165], v[162:163], v[164:165], s[8:9] op_sel_hi:[1,1,0]
	v_pk_fma_f32 v[142:143], v[138:139], v[142:143], s[8:9] op_sel_hi:[1,1,0]
	v_pk_mul_f32 v[162:163], v[162:163], v[164:165]
	v_pk_mul_f32 v[164:165], v[122:123], v[122:123]
	v_pk_mul_f32 v[138:139], v[138:139], v[142:143]
	v_pk_mul_f32 v[142:143], v[126:127], v[126:127]
	v_pk_fma_f32 v[170:171], v[168:169], s[0:1], v[140:141] op_sel_hi:[1,0,0]
	v_pk_mul_f32 v[164:165], v[164:165], s[12:13] op_sel_hi:[1,0]
	v_pk_mul_f32 v[158:159], v[124:125], v[124:125]
	v_pk_mul_f32 v[142:143], v[142:143], s[12:13] op_sel_hi:[1,0]
	v_pk_fma_f32 v[170:171], v[168:169], v[170:171], s[10:11] op_sel_hi:[1,1,0]
	v_exp_f32_e32 v164, v164
	v_exp_f32_e32 v165, v165
	v_pk_mul_f32 v[158:159], v[158:159], s[12:13] op_sel_hi:[1,0]
	v_exp_f32_e32 v142, v142
	v_exp_f32_e32 v143, v143
	v_pk_fma_f32 v[170:171], v[168:169], v[170:171], s[6:7] op_sel_hi:[1,1,0]
	v_exp_f32_e32 v158, v158
	v_exp_f32_e32 v159, v159
	v_pk_fma_f32 v[170:171], v[168:169], v[170:171], s[8:9] op_sel_hi:[1,1,0]
	v_pk_mul_f32 v[142:143], v[142:143], v[160:161]
	v_pk_mul_f32 v[168:169], v[168:169], v[170:171]
	v_cmp_gt_f32_e32 vcc, 0, v123
	v_pk_mul_f32 v[164:165], v[164:165], v[168:169]
	v_pk_mul_f32 v[138:139], v[158:159], v[138:139]
	v_pk_mul_f32 v[168:169], v[122:123], v[164:165]
	v_pk_fma_f32 v[164:165], v[122:123], v[164:165], v[122:123] neg_lo:[1,0,0] neg_hi:[1,0,0]
	v_pk_mul_f32 v[160:161], v[126:127], v[142:143]
	v_pk_fma_f32 v[142:143], v[126:127], v[142:143], v[126:127] neg_lo:[1,0,0] neg_hi:[1,0,0]
	v_cndmask_b32_e32 v170, v165, v169, vcc
	v_cmp_gt_f32_e32 vcc, 0, v126
	v_pk_mul_f32 v[158:159], v[124:125], v[138:139]
	v_pk_fma_f32 v[138:139], v[124:125], v[138:139], v[124:125] neg_lo:[1,0,0] neg_hi:[1,0,0]
	v_cndmask_b32_e32 v173, v142, v160, vcc
	v_cmp_gt_f32_e32 vcc, 0, v124
	v_pk_fma_f32 v[118:119], v[118:119], v[136:137], v[46:47] op_sel_hi:[1,0,1]
	v_pk_fma_f32 v[116:117], v[116:117], v[136:137], v[44:45] op_sel_hi:[1,0,1]
	v_cndmask_b32_e32 v172, v138, v158, vcc
	v_cmp_gt_f32_e32 vcc, 0, v127
	v_and_b32_e32 v160, 0x7fffffff, v118
	v_pk_fma_f32 v[112:113], v[112:113], v[136:137], v[40:41] op_sel_hi:[1,0,1]
	v_cndmask_b32_e32 v127, v143, v161, vcc
	v_and_b32_e32 v161, 0x7fffffff, v119
	v_cmp_gt_f32_e32 vcc, 0, v125
	v_pk_fma_f32 v[160:161], v[160:161], s[4:5], 1.0 op_sel_hi:[1,0,0]
	v_pk_fma_f32 v[114:115], v[114:115], v[136:137], v[42:43] op_sel_hi:[1,0,1]
	v_cndmask_b32_e32 v126, v139, v159, vcc
	v_rcp_f32_e32 v160, v160
	v_rcp_f32_e32 v161, v161
	v_pk_add_f32 v[124:125], v[172:173], v[126:127]
	v_and_b32_e32 v179, 0x7fffffff, v115
	v_pk_add_f32 v[138:139], v[124:125], v[124:125] op_sel:[0,1] op_sel_hi:[1,0]
	v_pk_mul_f32 v[124:125], v[126:127], v[126:127]
	v_and_b32_e32 v178, 0x7fffffff, v114
	v_pk_fma_f32 v[124:125], v[172:173], v[172:173], v[124:125]
	v_pk_mul_f32 v[158:159], v[116:117], v[116:117]
	v_pk_add_f32 v[142:143], v[124:125], v[124:125] op_sel_hi:[0,1]
	v_cvt_pk_bf16_f32 v124, v172, v126
	v_cvt_pk_bf16_f32 v125, v173, v127
	v_pk_fma_f32 v[172:173], v[160:161], s[0:1], v[140:141] op_sel_hi:[1,0,0]
	v_and_b32_e32 v127, 0x7fffffff, v117
	v_pk_fma_f32 v[172:173], v[160:161], v[172:173], s[10:11] op_sel_hi:[1,1,0]
	v_and_b32_e32 v126, 0x7fffffff, v116
	v_pk_fma_f32 v[172:173], v[160:161], v[172:173], s[6:7] op_sel_hi:[1,1,0]
	v_pk_fma_f32 v[126:127], v[126:127], s[4:5], 1.0 op_sel_hi:[1,0,0]
	v_pk_fma_f32 v[172:173], v[160:161], v[172:173], s[8:9] op_sel_hi:[1,1,0]
	v_rcp_f32_e32 v126, v126
	v_rcp_f32_e32 v127, v127
	v_pk_mul_f32 v[160:161], v[160:161], v[172:173]
	v_and_b32_e32 v173, 0x7fffffff, v113
	v_and_b32_e32 v172, 0x7fffffff, v112
	v_pk_fma_f32 v[172:173], v[172:173], s[4:5], 1.0 op_sel_hi:[1,0,0]
	v_pk_fma_f32 v[136:137], v[126:127], s[0:1], v[140:141] op_sel_hi:[1,0,0]
	v_rcp_f32_e32 v172, v172
	v_rcp_f32_e32 v173, v173
	v_pk_fma_f32 v[136:137], v[126:127], v[136:137], s[10:11] op_sel_hi:[1,1,0]
	v_pk_fma_f32 v[178:179], v[178:179], s[4:5], 1.0 op_sel_hi:[1,0,0]
	v_pk_fma_f32 v[136:137], v[126:127], v[136:137], s[6:7] op_sel_hi:[1,1,0]
	v_pk_fma_f32 v[174:175], v[172:173], s[0:1], v[140:141] op_sel_hi:[1,0,0]
	v_pk_fma_f32 v[136:137], v[126:127], v[136:137], s[8:9] op_sel_hi:[1,1,0]
	v_pk_mul_f32 v[158:159], v[158:159], s[12:13] op_sel_hi:[1,0]
	v_pk_fma_f32 v[174:175], v[172:173], v[174:175], s[10:11] op_sel_hi:[1,1,0]
	v_rcp_f32_e32 v178, v178
	v_rcp_f32_e32 v179, v179
	v_pk_mul_f32 v[126:127], v[126:127], v[136:137]
	v_pk_mul_f32 v[136:137], v[118:119], v[118:119]
	v_exp_f32_e32 v158, v158
	v_exp_f32_e32 v159, v159
	v_pk_fma_f32 v[174:175], v[172:173], v[174:175], s[6:7] op_sel_hi:[1,1,0]
	v_pk_mul_f32 v[136:137], v[136:137], s[12:13] op_sel_hi:[1,0]
	v_pk_fma_f32 v[174:175], v[172:173], v[174:175], s[8:9] op_sel_hi:[1,1,0]
	v_exp_f32_e32 v136, v136
	v_exp_f32_e32 v137, v137
	v_pk_mul_f32 v[172:173], v[172:173], v[174:175]
	v_pk_mul_f32 v[174:175], v[114:115], v[114:115]
	v_pk_fma_f32 v[140:141], v[178:179], s[0:1], v[140:141] op_sel_hi:[1,0,0]
	v_pk_mul_f32 v[174:175], v[174:175], s[12:13] op_sel_hi:[1,0]
	v_pk_mul_f32 v[166:167], v[120:121], v[120:121]
	v_pk_mul_f32 v[126:127], v[158:159], v[126:127]
	v_pk_fma_f32 v[140:141], v[178:179], v[140:141], s[10:11] op_sel_hi:[1,1,0]
	v_exp_f32_e32 v174, v174
	v_exp_f32_e32 v175, v175
	v_pk_mul_f32 v[166:167], v[166:167], s[12:13] op_sel_hi:[1,0]
	v_pk_mul_f32 v[158:159], v[116:117], v[126:127]
	v_pk_fma_f32 v[126:127], v[116:117], v[126:127], v[116:117] neg_lo:[1,0,0] neg_hi:[1,0,0]
	v_pk_mul_f32 v[176:177], v[112:113], v[112:113]
	v_pk_fma_f32 v[140:141], v[178:179], v[140:141], s[6:7] op_sel_hi:[1,1,0]
	v_cmp_gt_f32_e32 vcc, 0, v117
	v_exp_f32_e32 v166, v166
	v_exp_f32_e32 v167, v167
	v_pk_mul_f32 v[136:137], v[136:137], v[160:161]
	v_pk_mul_f32 v[176:177], v[176:177], s[12:13] op_sel_hi:[1,0]
	v_pk_fma_f32 v[140:141], v[178:179], v[140:141], s[8:9] op_sel_hi:[1,1,0]
	v_cndmask_b32_e32 v117, v127, v159, vcc
	v_cmp_gt_f32_e32 vcc, 0, v116
	v_pk_mul_f32 v[160:161], v[118:119], v[136:137]
	v_pk_fma_f32 v[136:137], v[118:119], v[136:137], v[118:119] neg_lo:[1,0,0] neg_hi:[1,0,0]
	v_exp_f32_e32 v176, v176
	v_exp_f32_e32 v177, v177
	v_pk_mul_f32 v[140:141], v[178:179], v[140:141]
	v_cndmask_b32_e32 v116, v126, v158, vcc
	v_cmp_gt_f32_e32 vcc, 0, v119
	v_pk_mul_f32 v[140:141], v[174:175], v[140:141]
	v_pk_mul_f32 v[162:163], v[166:167], v[162:163]
	v_cndmask_b32_e32 v119, v137, v161, vcc
	v_cmp_gt_f32_e32 vcc, 0, v118
	v_pk_mul_f32 v[174:175], v[114:115], v[140:141]
	v_pk_fma_f32 v[140:141], v[114:115], v[140:141], v[114:115] neg_lo:[1,0,0] neg_hi:[1,0,0]
	v_cndmask_b32_e32 v118, v136, v160, vcc
	v_cmp_gt_f32_e32 vcc, 0, v115
	v_pk_mul_f32 v[166:167], v[120:121], v[162:163]
	v_pk_fma_f32 v[162:163], v[120:121], v[162:163], v[120:121] neg_lo:[1,0,0] neg_hi:[1,0,0]
	v_cndmask_b32_e32 v141, v141, v175, vcc
	v_cmp_gt_f32_e32 vcc, 0, v114
	v_pk_mul_f32 v[172:173], v[176:177], v[172:173]
	v_mov_b32_e32 v136, v116
	v_cndmask_b32_e32 v140, v140, v174, vcc
	v_cmp_gt_f32_e32 vcc, 0, v120
	v_pk_mul_f32 v[176:177], v[112:113], v[172:173]
	v_pk_fma_f32 v[172:173], v[112:113], v[172:173], v[112:113] neg_lo:[1,0,0] neg_hi:[1,0,0]
	v_cndmask_b32_e32 v160, v162, v166, vcc
	v_cmp_gt_f32_e32 vcc, 0, v112
	v_mov_b32_e32 v137, v118
	v_mov_b32_e32 v158, v117
	v_cndmask_b32_e32 v161, v172, v176, vcc
	v_cmp_gt_f32_e32 vcc, 0, v121
	v_mov_b32_e32 v159, v119
	v_pk_add_f32 v[136:137], v[136:137], v[158:159]
	v_cndmask_b32_e32 v120, v163, v167, vcc
	v_cmp_gt_f32_e32 vcc, 0, v122
	v_mov_b32_e32 v162, v160
	v_mov_b32_e32 v163, v120
	v_cndmask_b32_e32 v123, v164, v168, vcc
	v_cmp_gt_f32_e32 vcc, 0, v113
	v_mul_f32_e32 v112, v160, v160
	v_mov_b32_e32 v122, v161
	v_cndmask_b32_e32 v164, v173, v177, vcc
	v_mov_b32_e32 v165, v123
	v_mul_f32_e32 v129, v170, v170
	v_pk_fma_f32 v[162:163], v[162:163], v[162:163], v[112:113] op_sel_hi:[1,1,0]
	v_pk_add_f32 v[112:113], v[122:123], v[164:165]
	v_pk_mul_f32 v[166:167], v[122:123], v[164:165]
	v_pk_add_f32 v[136:137], v[136:137], v[136:137] op_sel:[0,1] op_sel_hi:[1,0]
	v_mul_f32_e32 v126, v116, v116
	v_mov_b32_e32 v113, v167
	v_mov_b32_e32 v137, v129
	v_mov_b32_e32 v162, v140
	v_mov_b32_e32 v142, v141
	v_pk_fma_f32 v[126:127], v[116:117], v[116:117], v[126:127] op_sel_hi:[1,1,0]
	v_mov_b32_e32 v121, v161
	v_pk_add_f32 v[112:113], v[112:113], v[136:137]
	v_pk_add_f32 v[136:137], v[162:163], v[142:143]
	v_mul_f32_e32 v126, v118, v118
	v_pk_add_f32 v[112:113], v[112:113], v[136:137]
	v_pk_add_f32 v[136:137], v[160:161], v[120:121]
	v_pk_mul_f32 v[142:143], v[160:161], v[120:121]
	v_pk_fma_f32 v[158:159], v[118:119], v[118:119], v[126:127] op_sel_hi:[1,1,0]
	v_mov_b32_e32 v137, v143
	v_pk_mul_f32 v[142:143], v[164:165], v[164:165]
	v_mul_f32_e32 v114, v140, v140
	v_mov_b32_e32 v126, v123
	v_mov_b32_e32 v171, v159
	v_mov_b32_e32 v139, v142
	v_pk_fma_f32 v[114:115], v[140:141], v[140:141], v[114:115] op_sel_hi:[1,1,0]
	v_pk_add_f32 v[126:127], v[126:127], v[170:171]
	v_pk_add_f32 v[136:137], v[136:137], v[138:139]
	v_mov_b32_e32 v129, v115
	v_pk_add_f32 v[126:127], v[136:137], v[126:127]
	v_add_u32_e32 v130, 16, v152
	v_pk_add_f32 v[114:115], v[126:127], v[128:129]
	v_ashrrev_i32_e32 v131, 31, v130
	v_pk_add_f32 v[112:113], v[112:113], v[114:115]
	v_mov_b32_e32 v114, v112
	v_mov_b32_e32 v115, v113
	s_nop 1
	v_permlane16_swap_b32_e32 v114, v112
	v_permlane16_swap_b32_e32 v115, v113
	s_waitcnt lgkmcnt(2)
	v_lshlrev_b64 v[132:133], 13, v[130:131]
	v_lshl_add_u64 v[132:133], s[28:29], 0, v[132:133]
	v_lshl_add_u64 v[132:133], v[148:149], 1, v[132:133]
	v_cvt_pk_bf16_f32 v126, v160, v120
	s_waitcnt lgkmcnt(0)
	v_pk_add_f32 v[112:113], v[112:113], v[114:115]
	v_mov_b32_e32 v114, v112
	v_mov_b32_e32 v115, v113
	s_nop 1
	v_permlane32_swap_b32_e32 v114, v112
	v_permlane32_swap_b32_e32 v115, v113
	v_cvt_pk_bf16_f32 v127, v123, v170
	global_store_dwordx4 v[132:133], v[124:127], off
	v_cvt_pk_bf16_f32 v116, v116, v117
	v_cvt_pk_bf16_f32 v117, v118, v119
	v_cvt_pk_bf16_f32 v118, v161, v164
	v_cvt_pk_bf16_f32 v119, v140, v141
	global_store_dwordx4 v[132:133], v[116:119], off offset:256
	s_and_saveexec_b64 s[0:1], s[2:3]
	s_cbranch_execz .LBB0_353
	s_lshl_b32 s4, s13, 3
	s_waitcnt lgkmcnt(0)
	v_pk_add_f32 v[112:113], v[112:113], v[114:115]
	v_lshlrev_b64 v[114:115], 8, v[130:131]
	s_add_i32 s4, s4, s72
	v_lshl_add_u64 v[114:115], s[26:27], 0, v[114:115]
	s_ashr_i32 s5, s4, 31
	v_lshl_add_u64 v[114:115], s[4:5], 2, v[114:115]
	global_store_dwordx2 v[114:115], v[112:113], off
.LBB0_353:
	s_or_b64 exec, exec, s[0:1]
	v_pk_fma_f32 v[116:117], v[108:109], v[156:157], v[52:53] op_sel_hi:[1,0,1]
	s_mov_b32 s4, 0x3e6d3388
	v_and_b32_e32 v109, 0x7fffffff, v117
	v_and_b32_e32 v108, 0x7fffffff, v116
	v_pk_fma_f32 v[108:109], v[108:109], s[4:5], 1.0 op_sel_hi:[1,0,0]
	v_pk_fma_f32 v[110:111], v[110:111], v[156:157], v[54:55] op_sel_hi:[1,0,1]
	v_rcp_f32_e32 v108, v108
	v_rcp_f32_e32 v109, v109
	s_mov_b32 s0, 0x3f07dc22
	v_mov_b64_e32 v[118:119], s[14:15]
	v_pk_mul_f32 v[122:123], v[116:117], v[116:117]
	v_pk_fma_f32 v[120:121], v[108:109], s[0:1], v[118:119] op_sel_hi:[1,0,0]
	v_pk_mul_f32 v[122:123], v[122:123], s[12:13] op_sel_hi:[1,0]
	v_and_b32_e32 v125, 0x7fffffff, v111
	v_and_b32_e32 v124, 0x7fffffff, v110
	v_pk_fma_f32 v[120:121], v[108:109], v[120:121], s[10:11] op_sel_hi:[1,1,0]
	v_exp_f32_e32 v122, v122
	v_exp_f32_e32 v123, v123
	v_pk_fma_f32 v[124:125], v[124:125], s[4:5], 1.0 op_sel_hi:[1,0,0]
	v_pk_fma_f32 v[120:121], v[108:109], v[120:121], s[6:7] op_sel_hi:[1,1,0]
	v_rcp_f32_e32 v124, v124
	v_rcp_f32_e32 v125, v125
	v_pk_fma_f32 v[120:121], v[108:109], v[120:121], s[8:9] op_sel_hi:[1,1,0]
	v_pk_fma_f32 v[104:105], v[104:105], v[156:157], v[48:49] op_sel_hi:[1,0,1]
	v_pk_mul_f32 v[108:109], v[108:109], v[120:121]
	v_pk_mul_f32 v[120:121], v[110:111], v[110:111]
	v_pk_mul_f32 v[108:109], v[122:123], v[108:109]
	v_pk_mul_f32 v[120:121], v[120:121], s[12:13] op_sel_hi:[1,0]
	v_pk_mul_f32 v[122:123], v[116:117], v[108:109]
	v_pk_fma_f32 v[126:127], v[116:117], v[108:109], v[116:117] neg_lo:[1,0,0] neg_hi:[1,0,0]
	v_pk_fma_f32 v[108:109], v[124:125], s[0:1], v[118:119] op_sel_hi:[1,0,0]
	v_exp_f32_e32 v120, v120
	v_pk_fma_f32 v[108:109], v[124:125], v[108:109], s[10:11] op_sel_hi:[1,1,0]
	v_exp_f32_e32 v121, v121
	v_pk_fma_f32 v[108:109], v[124:125], v[108:109], s[6:7] op_sel_hi:[1,1,0]
	v_pk_fma_f32 v[106:107], v[106:107], v[156:157], v[50:51] op_sel_hi:[1,0,1]
	v_pk_fma_f32 v[108:109], v[124:125], v[108:109], s[8:9] op_sel_hi:[1,1,0]
	v_pk_mul_f32 v[130:131], v[104:105], v[104:105]
	v_pk_mul_f32 v[108:109], v[124:125], v[108:109]
	v_and_b32_e32 v125, 0x7fffffff, v105
	v_and_b32_e32 v124, 0x7fffffff, v104
	v_pk_fma_f32 v[124:125], v[124:125], s[4:5], 1.0 op_sel_hi:[1,0,0]
	v_pk_mul_f32 v[108:109], v[120:121], v[108:109]
	v_rcp_f32_e32 v124, v124
	v_rcp_f32_e32 v125, v125
	v_pk_mul_f32 v[120:121], v[110:111], v[108:109]
	v_pk_fma_f32 v[128:129], v[110:111], v[108:109], v[110:111] neg_lo:[1,0,0] neg_hi:[1,0,0]
	v_pk_mul_f32 v[130:131], v[130:131], s[12:13] op_sel_hi:[1,0]
	v_pk_fma_f32 v[108:109], v[124:125], s[0:1], v[118:119] op_sel_hi:[1,0,0]
	v_and_b32_e32 v133, 0x7fffffff, v107
	v_and_b32_e32 v132, 0x7fffffff, v106
	v_pk_fma_f32 v[108:109], v[124:125], v[108:109], s[10:11] op_sel_hi:[1,1,0]
	v_exp_f32_e32 v130, v130
	v_exp_f32_e32 v131, v131
	v_pk_fma_f32 v[132:133], v[132:133], s[4:5], 1.0 op_sel_hi:[1,0,0]
	v_pk_fma_f32 v[108:109], v[124:125], v[108:109], s[6:7] op_sel_hi:[1,1,0]
	v_rcp_f32_e32 v132, v132
	v_rcp_f32_e32 v133, v133
	v_pk_fma_f32 v[108:109], v[124:125], v[108:109], s[8:9] op_sel_hi:[1,1,0]
	v_cmp_gt_f32_e32 vcc, 0, v107
	v_pk_mul_f32 v[108:109], v[124:125], v[108:109]
	v_pk_mul_f32 v[124:125], v[106:107], v[106:107]
	v_pk_mul_f32 v[108:109], v[130:131], v[108:109]
	v_pk_mul_f32 v[124:125], v[124:125], s[12:13] op_sel_hi:[1,0]
	v_pk_mul_f32 v[130:131], v[104:105], v[108:109]
	v_pk_fma_f32 v[136:137], v[104:105], v[108:109], v[104:105] neg_lo:[1,0,0] neg_hi:[1,0,0]
	v_pk_fma_f32 v[108:109], v[132:133], s[0:1], v[118:119] op_sel_hi:[1,0,0]
	v_exp_f32_e32 v124, v124
	v_pk_fma_f32 v[108:109], v[132:133], v[108:109], s[10:11] op_sel_hi:[1,1,0]
	v_exp_f32_e32 v125, v125
	v_pk_fma_f32 v[108:109], v[132:133], v[108:109], s[6:7] op_sel_hi:[1,1,0]
	v_pk_fma_f32 v[102:103], v[102:103], v[156:157], v[46:47] op_sel_hi:[1,0,1]
	v_pk_fma_f32 v[108:109], v[132:133], v[108:109], s[8:9] op_sel_hi:[1,1,0]
	v_pk_fma_f32 v[100:101], v[100:101], v[156:157], v[44:45] op_sel_hi:[1,0,1]
	v_pk_mul_f32 v[108:109], v[132:133], v[108:109]
	v_pk_fma_f32 v[98:99], v[98:99], v[156:157], v[42:43] op_sel_hi:[1,0,1]
	v_pk_mul_f32 v[108:109], v[124:125], v[108:109]
	v_and_b32_e32 v161, 0x7fffffff, v99
	v_pk_mul_f32 v[124:125], v[106:107], v[108:109]
	v_pk_fma_f32 v[132:133], v[106:107], v[108:109], v[106:107] neg_lo:[1,0,0] neg_hi:[1,0,0]
	v_and_b32_e32 v160, 0x7fffffff, v98
	v_cndmask_b32_e32 v108, v133, v125, vcc
	v_cmp_gt_f32_e32 vcc, 0, v110
	v_pk_fma_f32 v[160:161], v[160:161], s[4:5], 1.0 op_sel_hi:[1,0,0]
	v_mul_f32_e32 v109, v108, v108
	v_cndmask_b32_e32 v139, v128, v120, vcc
	v_cmp_gt_f32_e32 vcc, 0, v116
	v_rcp_f32_e32 v160, v160
	v_rcp_f32_e32 v161, v161
	v_cndmask_b32_e32 v138, v126, v122, vcc
	v_cmp_gt_f32_e32 vcc, 0, v111
	v_add_u32_e32 v112, 32, v152
	v_ashrrev_i32_e32 v113, 31, v112
	v_cndmask_b32_e32 v111, v129, v121, vcc
	v_cmp_gt_f32_e32 vcc, 0, v117
	v_pk_mul_f32 v[128:129], v[100:101], v[100:101]
	s_waitcnt lgkmcnt(0)
	v_lshlrev_b64 v[114:115], 13, v[112:113]
	v_cndmask_b32_e32 v110, v127, v123, vcc
	v_pk_add_f32 v[116:117], v[138:139], v[110:111]
	v_pk_fma_f32 v[126:127], v[96:97], v[156:157], v[40:41] op_sel_hi:[1,0,1]
	v_pk_add_f32 v[120:121], v[116:117], v[116:117] op_sel:[0,1] op_sel_hi:[1,0]
	v_pk_mul_f32 v[116:117], v[110:111], v[110:111]
	v_pk_mul_f32 v[128:129], v[128:129], s[12:13] op_sel_hi:[1,0]
	v_pk_fma_f32 v[116:117], v[138:139], v[138:139], v[116:117]
	v_exp_f32_e32 v128, v128
	v_pk_add_f32 v[122:123], v[116:117], v[116:117] op_sel_hi:[0,1]
	v_cvt_pk_bf16_f32 v116, v138, v110
	v_cvt_pk_bf16_f32 v117, v139, v111
	v_and_b32_e32 v139, 0x7fffffff, v103
	v_and_b32_e32 v138, 0x7fffffff, v102
	v_pk_fma_f32 v[138:139], v[138:139], s[4:5], 1.0 op_sel_hi:[1,0,0]
	v_and_b32_e32 v111, 0x7fffffff, v101
	v_rcp_f32_e32 v138, v138
	v_rcp_f32_e32 v139, v139
	v_and_b32_e32 v110, 0x7fffffff, v100
	v_pk_fma_f32 v[110:111], v[110:111], s[4:5], 1.0 op_sel_hi:[1,0,0]
	v_exp_f32_e32 v129, v129
	v_pk_fma_f32 v[140:141], v[138:139], s[0:1], v[118:119] op_sel_hi:[1,0,0]
	v_rcp_f32_e32 v110, v110
	v_pk_fma_f32 v[140:141], v[138:139], v[140:141], s[10:11] op_sel_hi:[1,1,0]
	v_rcp_f32_e32 v111, v111
	v_pk_fma_f32 v[140:141], v[138:139], v[140:141], s[6:7] op_sel_hi:[1,1,0]
	v_pk_mul_f32 v[158:159], v[126:127], v[126:127]
	v_pk_fma_f32 v[140:141], v[138:139], v[140:141], s[8:9] op_sel_hi:[1,1,0]
	v_pk_fma_f32 v[96:97], v[110:111], s[0:1], v[118:119] op_sel_hi:[1,0,0]
	v_pk_mul_f32 v[138:139], v[138:139], v[140:141]
	v_and_b32_e32 v141, 0x7fffffff, v127
	v_and_b32_e32 v140, 0x7fffffff, v126
	v_pk_fma_f32 v[140:141], v[140:141], s[4:5], 1.0 op_sel_hi:[1,0,0]
	v_pk_fma_f32 v[96:97], v[110:111], v[96:97], s[10:11] op_sel_hi:[1,1,0]
	v_rcp_f32_e32 v140, v140
	v_rcp_f32_e32 v141, v141
	v_pk_fma_f32 v[96:97], v[110:111], v[96:97], s[6:7] op_sel_hi:[1,1,0]
	v_cmp_gt_f32_e32 vcc, 0, v101
	v_pk_fma_f32 v[96:97], v[110:111], v[96:97], s[8:9] op_sel_hi:[1,1,0]
	v_pk_fma_f32 v[142:143], v[140:141], s[0:1], v[118:119] op_sel_hi:[1,0,0]
	v_pk_mul_f32 v[96:97], v[110:111], v[96:97]
	v_pk_fma_f32 v[142:143], v[140:141], v[142:143], s[10:11] op_sel_hi:[1,1,0]
	v_pk_mul_f32 v[110:111], v[102:103], v[102:103]
	v_pk_fma_f32 v[142:143], v[140:141], v[142:143], s[6:7] op_sel_hi:[1,1,0]
	v_pk_mul_f32 v[110:111], v[110:111], s[12:13] op_sel_hi:[1,0]
	v_pk_fma_f32 v[142:143], v[140:141], v[142:143], s[8:9] op_sel_hi:[1,1,0]
	v_exp_f32_e32 v110, v110
	v_exp_f32_e32 v111, v111
	v_pk_mul_f32 v[140:141], v[140:141], v[142:143]
	v_pk_mul_f32 v[142:143], v[98:99], v[98:99]
	v_pk_fma_f32 v[118:119], v[160:161], s[0:1], v[118:119] op_sel_hi:[1,0,0]
	v_pk_mul_f32 v[142:143], v[142:143], s[12:13] op_sel_hi:[1,0]
	v_pk_mul_f32 v[96:97], v[128:129], v[96:97]
	v_pk_fma_f32 v[118:119], v[160:161], v[118:119], s[10:11] op_sel_hi:[1,1,0]
	v_exp_f32_e32 v142, v142
	v_exp_f32_e32 v143, v143
	v_pk_mul_f32 v[128:129], v[100:101], v[96:97]
	v_pk_fma_f32 v[96:97], v[100:101], v[96:97], v[100:101] neg_lo:[1,0,0] neg_hi:[1,0,0]
	v_pk_fma_f32 v[118:119], v[160:161], v[118:119], s[6:7] op_sel_hi:[1,1,0]
	v_pk_mul_f32 v[110:111], v[110:111], v[138:139]
	v_pk_mul_f32 v[158:159], v[158:159], s[12:13] op_sel_hi:[1,0]
	v_pk_fma_f32 v[118:119], v[160:161], v[118:119], s[8:9] op_sel_hi:[1,1,0]
	v_cndmask_b32_e32 v101, v97, v129, vcc
	v_cmp_gt_f32_e32 vcc, 0, v100
	v_pk_mul_f32 v[138:139], v[102:103], v[110:111]
	v_pk_fma_f32 v[110:111], v[102:103], v[110:111], v[102:103] neg_lo:[1,0,0] neg_hi:[1,0,0]
	v_exp_f32_e32 v158, v158
	v_exp_f32_e32 v159, v159
	v_pk_mul_f32 v[118:119], v[160:161], v[118:119]
	v_cndmask_b32_e32 v100, v96, v128, vcc
	v_cmp_gt_f32_e32 vcc, 0, v103
	v_pk_mul_f32 v[118:119], v[142:143], v[118:119]
	v_pk_mul_f32 v[140:141], v[158:159], v[140:141]
	v_cndmask_b32_e32 v111, v111, v139, vcc
	v_cmp_gt_f32_e32 vcc, 0, v102
	v_pk_mul_f32 v[142:143], v[98:99], v[118:119]
	v_pk_fma_f32 v[118:119], v[98:99], v[118:119], v[98:99] neg_lo:[1,0,0] neg_hi:[1,0,0]
	v_cndmask_b32_e32 v110, v110, v138, vcc
	v_cmp_gt_f32_e32 vcc, 0, v99
	v_mul_f32_e32 v96, v100, v100
	v_pk_mul_f32 v[158:159], v[126:127], v[140:141]
	v_cndmask_b32_e32 v143, v119, v143, vcc
	v_cmp_gt_f32_e32 vcc, 0, v98
	v_pk_fma_f32 v[140:141], v[126:127], v[140:141], v[126:127] neg_lo:[1,0,0] neg_hi:[1,0,0]
	v_pk_fma_f32 v[128:129], v[100:101], v[100:101], v[96:97] op_sel_hi:[1,1,0]
	v_cndmask_b32_e32 v142, v118, v142, vcc
	v_cmp_gt_f32_e32 vcc, 0, v104
	v_mov_b32_e32 v96, v100
	v_mov_b32_e32 v97, v110
	v_mov_b32_e32 v102, v101
	v_mov_b32_e32 v103, v111
	v_cndmask_b32_e32 v160, v136, v130, vcc
	v_cmp_gt_f32_e32 vcc, 0, v126
	v_pk_add_f32 v[102:103], v[96:97], v[102:103]
	v_mul_f32_e32 v96, v110, v110
	v_cndmask_b32_e32 v161, v140, v158, vcc
	v_cmp_gt_f32_e32 vcc, 0, v105
	v_pk_fma_f32 v[138:139], v[110:111], v[110:111], v[96:97] op_sel_hi:[1,1,0]
	v_mul_f32_e32 v96, v142, v142
	v_cndmask_b32_e32 v98, v137, v131, vcc
	v_cmp_gt_f32_e32 vcc, 0, v106
	v_pk_fma_f32 v[96:97], v[142:143], v[142:143], v[96:97] op_sel_hi:[1,1,0]
	v_mov_b32_e32 v104, v160
	v_cndmask_b32_e32 v107, v132, v124, vcc
	v_cmp_gt_f32_e32 vcc, 0, v127
	v_mov_b32_e32 v105, v98
	v_mul_f32_e32 v96, v160, v160
	v_mov_b32_e32 v106, v161
	v_cndmask_b32_e32 v124, v141, v159, vcc
	v_mov_b32_e32 v125, v107
	v_pk_fma_f32 v[104:105], v[104:105], v[104:105], v[96:97] op_sel_hi:[1,1,0]
	v_pk_add_f32 v[118:119], v[106:107], v[124:125]
	v_pk_mul_f32 v[126:127], v[106:107], v[124:125]
	v_pk_add_f32 v[102:103], v[102:103], v[102:103] op_sel:[0,1] op_sel_hi:[1,0]
	v_mov_b32_e32 v99, v161
	v_mov_b32_e32 v119, v127
	v_mov_b32_e32 v103, v109
	v_mov_b32_e32 v104, v142
	v_mov_b32_e32 v122, v143
	v_pk_add_f32 v[102:103], v[118:119], v[102:103]
	v_pk_add_f32 v[104:105], v[104:105], v[122:123]
	v_pk_add_f32 v[118:119], v[160:161], v[98:99]
	v_pk_mul_f32 v[122:123], v[160:161], v[98:99]
	v_mov_b32_e32 v128, v107
	v_mov_b32_e32 v119, v123
	v_pk_mul_f32 v[122:123], v[124:125], v[124:125]
	v_mov_b32_e32 v109, v139
	v_mov_b32_e32 v121, v122
	v_pk_add_f32 v[102:103], v[102:103], v[104:105]
	v_pk_add_f32 v[104:105], v[128:129], v[108:109]
	v_pk_add_f32 v[118:119], v[118:119], v[120:121]
	v_mov_b32_e32 v96, 0
	v_pk_add_f32 v[104:105], v[118:119], v[104:105]
	v_lshl_add_u64 v[114:115], s[28:29], 0, v[114:115]
	v_pk_add_f32 v[104:105], v[104:105], v[96:97]
	v_lshl_add_u64 v[114:115], v[148:149], 1, v[114:115]
	v_pk_add_f32 v[104:105], v[102:103], v[104:105]
	v_mov_b32_e32 v120, v104
	v_mov_b32_e32 v121, v105
	s_nop 1
	v_permlane16_swap_b32_e32 v120, v104
	v_permlane16_swap_b32_e32 v121, v105
	v_cvt_pk_bf16_f32 v118, v160, v98
	v_cvt_pk_bf16_f32 v119, v107, v108
	global_store_dwordx4 v[114:115], v[116:119], off
	v_cvt_pk_bf16_f32 v102, v100, v101
	s_waitcnt lgkmcnt(0)
	v_pk_add_f32 v[98:99], v[104:105], v[120:121]
	v_mov_b32_e32 v100, v98
	v_mov_b32_e32 v101, v99
	s_nop 1
	v_permlane32_swap_b32_e32 v100, v98
	v_permlane32_swap_b32_e32 v101, v99
	v_cvt_pk_bf16_f32 v103, v110, v111
	v_cvt_pk_bf16_f32 v104, v161, v124
	v_cvt_pk_bf16_f32 v105, v142, v143
	global_store_dwordx4 v[114:115], v[102:105], off offset:256
	s_and_saveexec_b64 s[16:17], s[2:3]
	s_cbranch_execz .LBB0_355
	s_lshl_b32 s1, s13, 3
	s_waitcnt lgkmcnt(0)
	v_pk_add_f32 v[98:99], v[98:99], v[100:101]
	v_lshlrev_b64 v[100:101], 8, v[112:113]
	s_add_i32 s18, s1, s72
	v_lshl_add_u64 v[100:101], s[26:27], 0, v[100:101]
	s_ashr_i32 s19, s18, 31
	v_lshl_add_u64 v[100:101], s[18:19], 2, v[100:101]
	global_store_dwordx2 v[100:101], v[98:99], off
.LBB0_355:
	s_or_b64 exec, exec, s[16:17]
	v_mov_b32_e32 v102, v157
	v_pk_fma_f32 v[94:95], v[94:95], v[102:103], v[54:55] op_sel_hi:[1,0,1]
	v_mov_b64_e32 v[106:107], s[14:15]
	v_and_b32_e32 v113, 0x7fffffff, v95
	v_and_b32_e32 v112, 0x7fffffff, v94
	v_pk_fma_f32 v[112:113], v[112:113], s[4:5], 1.0 op_sel_hi:[1,0,0]
	v_pk_fma_f32 v[88:89], v[88:89], v[102:103], v[48:49] op_sel_hi:[1,0,1]
	v_rcp_f32_e32 v112, v112
	v_rcp_f32_e32 v113, v113
	v_pk_fma_f32 v[92:93], v[92:93], v[102:103], v[52:53] op_sel_hi:[1,0,1]
	v_pk_fma_f32 v[90:91], v[90:91], v[102:103], v[50:51] op_sel_hi:[1,0,1]
	v_and_b32_e32 v105, 0x7fffffff, v93
	v_pk_fma_f32 v[114:115], v[112:113], s[0:1], v[106:107] op_sel_hi:[1,0,0]
	v_and_b32_e32 v104, 0x7fffffff, v92
	v_pk_fma_f32 v[114:115], v[112:113], v[114:115], s[10:11] op_sel_hi:[1,1,0]
	v_pk_fma_f32 v[104:105], v[104:105], s[4:5], 1.0 op_sel_hi:[1,0,0]
	v_pk_fma_f32 v[114:115], v[112:113], v[114:115], s[6:7] op_sel_hi:[1,1,0]
	v_rcp_f32_e32 v104, v104
	v_pk_fma_f32 v[114:115], v[112:113], v[114:115], s[8:9] op_sel_hi:[1,1,0]
	v_rcp_f32_e32 v105, v105
	v_pk_mul_f32 v[112:113], v[112:113], v[114:115]
	v_and_b32_e32 v115, 0x7fffffff, v89
	v_and_b32_e32 v114, 0x7fffffff, v88
	v_pk_fma_f32 v[114:115], v[114:115], s[4:5], 1.0 op_sel_hi:[1,0,0]
	v_and_b32_e32 v121, 0x7fffffff, v91
	v_rcp_f32_e32 v114, v114
	v_rcp_f32_e32 v115, v115
	v_and_b32_e32 v120, 0x7fffffff, v90
	v_pk_fma_f32 v[120:121], v[120:121], s[4:5], 1.0 op_sel_hi:[1,0,0]
	v_pk_fma_f32 v[108:109], v[104:105], s[0:1], v[106:107] op_sel_hi:[1,0,0]
	v_pk_fma_f32 v[116:117], v[114:115], s[0:1], v[106:107] op_sel_hi:[1,0,0]
	v_rcp_f32_e32 v120, v120
	v_pk_fma_f32 v[116:117], v[114:115], v[116:117], s[10:11] op_sel_hi:[1,1,0]
	v_rcp_f32_e32 v121, v121
	v_pk_fma_f32 v[108:109], v[104:105], v[108:109], s[10:11] op_sel_hi:[1,1,0]
	v_pk_fma_f32 v[116:117], v[114:115], v[116:117], s[6:7] op_sel_hi:[1,1,0]
	v_pk_fma_f32 v[108:109], v[104:105], v[108:109], s[6:7] op_sel_hi:[1,1,0]
	v_pk_fma_f32 v[116:117], v[114:115], v[116:117], s[8:9] op_sel_hi:[1,1,0]
	v_pk_fma_f32 v[108:109], v[104:105], v[108:109], s[8:9] op_sel_hi:[1,1,0]
	v_pk_mul_f32 v[114:115], v[114:115], v[116:117]
	v_pk_mul_f32 v[116:117], v[90:91], v[90:91]
	v_pk_mul_f32 v[104:105], v[104:105], v[108:109]
	v_pk_mul_f32 v[108:109], v[94:95], v[94:95]
	v_pk_fma_f32 v[122:123], v[120:121], s[0:1], v[106:107] op_sel_hi:[1,0,0]
	v_pk_mul_f32 v[116:117], v[116:117], s[12:13] op_sel_hi:[1,0]
	v_pk_mul_f32 v[110:111], v[92:93], v[92:93]
	v_pk_mul_f32 v[108:109], v[108:109], s[12:13] op_sel_hi:[1,0]
	v_pk_fma_f32 v[122:123], v[120:121], v[122:123], s[10:11] op_sel_hi:[1,1,0]
	v_exp_f32_e32 v116, v116
	v_exp_f32_e32 v117, v117
	v_pk_mul_f32 v[110:111], v[110:111], s[12:13] op_sel_hi:[1,0]
	v_exp_f32_e32 v108, v108
	v_exp_f32_e32 v109, v109
	v_pk_fma_f32 v[122:123], v[120:121], v[122:123], s[6:7] op_sel_hi:[1,1,0]
	v_exp_f32_e32 v110, v110
	v_exp_f32_e32 v111, v111
	v_pk_fma_f32 v[122:123], v[120:121], v[122:123], s[8:9] op_sel_hi:[1,1,0]
	v_pk_mul_f32 v[108:109], v[108:109], v[112:113]
	v_pk_mul_f32 v[120:121], v[120:121], v[122:123]
	v_cmp_gt_f32_e32 vcc, 0, v91
	v_pk_mul_f32 v[116:117], v[116:117], v[120:121]
	v_pk_mul_f32 v[104:105], v[110:111], v[104:105]
	v_pk_mul_f32 v[120:121], v[90:91], v[116:117]
	v_pk_fma_f32 v[116:117], v[90:91], v[116:117], v[90:91] neg_lo:[1,0,0] neg_hi:[1,0,0]
	v_pk_mul_f32 v[112:113], v[94:95], v[108:109]
	v_pk_fma_f32 v[108:109], v[94:95], v[108:109], v[94:95] neg_lo:[1,0,0] neg_hi:[1,0,0]
	v_cndmask_b32_e32 v122, v117, v121, vcc
	v_cmp_gt_f32_e32 vcc, 0, v94
	v_pk_mul_f32 v[110:111], v[92:93], v[104:105]
	v_pk_fma_f32 v[104:105], v[92:93], v[104:105], v[92:93] neg_lo:[1,0,0] neg_hi:[1,0,0]
	v_cndmask_b32_e32 v125, v108, v112, vcc
	v_cmp_gt_f32_e32 vcc, 0, v92
	v_pk_fma_f32 v[86:87], v[86:87], v[102:103], v[46:47] op_sel_hi:[1,0,1]
	v_pk_fma_f32 v[84:85], v[84:85], v[102:103], v[44:45] op_sel_hi:[1,0,1]
	v_cndmask_b32_e32 v124, v104, v110, vcc
	v_cmp_gt_f32_e32 vcc, 0, v95
	v_and_b32_e32 v112, 0x7fffffff, v86
	v_pk_fma_f32 v[80:81], v[80:81], v[102:103], v[40:41] op_sel_hi:[1,0,1]
	v_cndmask_b32_e32 v95, v109, v113, vcc
	v_and_b32_e32 v113, 0x7fffffff, v87
	v_cmp_gt_f32_e32 vcc, 0, v93
	v_pk_fma_f32 v[112:113], v[112:113], s[4:5], 1.0 op_sel_hi:[1,0,0]
	v_pk_fma_f32 v[82:83], v[82:83], v[102:103], v[42:43] op_sel_hi:[1,0,1]
	v_cndmask_b32_e32 v94, v105, v111, vcc
	v_rcp_f32_e32 v112, v112
	v_rcp_f32_e32 v113, v113
	v_pk_add_f32 v[92:93], v[124:125], v[94:95]
	v_and_b32_e32 v131, 0x7fffffff, v83
	v_pk_add_f32 v[104:105], v[92:93], v[92:93] op_sel:[0,1] op_sel_hi:[1,0]
	v_pk_mul_f32 v[92:93], v[94:95], v[94:95]
	v_and_b32_e32 v130, 0x7fffffff, v82
	v_pk_fma_f32 v[92:93], v[124:125], v[124:125], v[92:93]
	v_pk_mul_f32 v[110:111], v[84:85], v[84:85]
	v_pk_add_f32 v[108:109], v[92:93], v[92:93] op_sel_hi:[0,1]
	v_cvt_pk_bf16_f32 v92, v124, v94
	v_cvt_pk_bf16_f32 v93, v125, v95
	v_pk_fma_f32 v[124:125], v[112:113], s[0:1], v[106:107] op_sel_hi:[1,0,0]
	v_and_b32_e32 v95, 0x7fffffff, v85
	v_pk_fma_f32 v[124:125], v[112:113], v[124:125], s[10:11] op_sel_hi:[1,1,0]
	v_and_b32_e32 v94, 0x7fffffff, v84
	v_pk_fma_f32 v[124:125], v[112:113], v[124:125], s[6:7] op_sel_hi:[1,1,0]
	v_pk_fma_f32 v[94:95], v[94:95], s[4:5], 1.0 op_sel_hi:[1,0,0]
	v_pk_fma_f32 v[124:125], v[112:113], v[124:125], s[8:9] op_sel_hi:[1,1,0]
	v_rcp_f32_e32 v94, v94
	v_rcp_f32_e32 v95, v95
	v_pk_mul_f32 v[112:113], v[112:113], v[124:125]
	v_and_b32_e32 v125, 0x7fffffff, v81
	v_and_b32_e32 v124, 0x7fffffff, v80
	v_pk_fma_f32 v[124:125], v[124:125], s[4:5], 1.0 op_sel_hi:[1,0,0]
	v_pk_fma_f32 v[102:103], v[94:95], s[0:1], v[106:107] op_sel_hi:[1,0,0]
	v_rcp_f32_e32 v124, v124
	v_rcp_f32_e32 v125, v125
	v_pk_fma_f32 v[102:103], v[94:95], v[102:103], s[10:11] op_sel_hi:[1,1,0]
	v_pk_fma_f32 v[130:131], v[130:131], s[4:5], 1.0 op_sel_hi:[1,0,0]
	v_pk_fma_f32 v[102:103], v[94:95], v[102:103], s[6:7] op_sel_hi:[1,1,0]
	v_pk_fma_f32 v[126:127], v[124:125], s[0:1], v[106:107] op_sel_hi:[1,0,0]
	v_pk_fma_f32 v[102:103], v[94:95], v[102:103], s[8:9] op_sel_hi:[1,1,0]
	v_pk_mul_f32 v[110:111], v[110:111], s[12:13] op_sel_hi:[1,0]
	v_pk_fma_f32 v[126:127], v[124:125], v[126:127], s[10:11] op_sel_hi:[1,1,0]
	v_rcp_f32_e32 v130, v130
	v_rcp_f32_e32 v131, v131
	v_pk_mul_f32 v[94:95], v[94:95], v[102:103]
	v_pk_mul_f32 v[102:103], v[86:87], v[86:87]
	v_exp_f32_e32 v110, v110
	v_exp_f32_e32 v111, v111
	v_pk_fma_f32 v[126:127], v[124:125], v[126:127], s[6:7] op_sel_hi:[1,1,0]
	v_pk_mul_f32 v[102:103], v[102:103], s[12:13] op_sel_hi:[1,0]
	v_pk_fma_f32 v[126:127], v[124:125], v[126:127], s[8:9] op_sel_hi:[1,1,0]
	v_exp_f32_e32 v102, v102
	v_exp_f32_e32 v103, v103
	v_pk_mul_f32 v[124:125], v[124:125], v[126:127]
	v_pk_mul_f32 v[126:127], v[82:83], v[82:83]
	v_pk_fma_f32 v[106:107], v[130:131], s[0:1], v[106:107] op_sel_hi:[1,0,0]
	v_pk_mul_f32 v[126:127], v[126:127], s[12:13] op_sel_hi:[1,0]
	v_pk_mul_f32 v[118:119], v[88:89], v[88:89]
	v_pk_mul_f32 v[94:95], v[110:111], v[94:95]
	v_pk_fma_f32 v[106:107], v[130:131], v[106:107], s[10:11] op_sel_hi:[1,1,0]
	v_exp_f32_e32 v126, v126
	v_exp_f32_e32 v127, v127
	v_pk_mul_f32 v[118:119], v[118:119], s[12:13] op_sel_hi:[1,0]
	v_pk_mul_f32 v[110:111], v[84:85], v[94:95]
	v_pk_fma_f32 v[94:95], v[84:85], v[94:95], v[84:85] neg_lo:[1,0,0] neg_hi:[1,0,0]
	v_pk_mul_f32 v[128:129], v[80:81], v[80:81]
	v_pk_fma_f32 v[106:107], v[130:131], v[106:107], s[6:7] op_sel_hi:[1,1,0]
	v_cmp_gt_f32_e32 vcc, 0, v85
	v_exp_f32_e32 v118, v118
	v_exp_f32_e32 v119, v119
	v_pk_mul_f32 v[102:103], v[102:103], v[112:113]
	v_pk_mul_f32 v[128:129], v[128:129], s[12:13] op_sel_hi:[1,0]
	v_pk_fma_f32 v[106:107], v[130:131], v[106:107], s[8:9] op_sel_hi:[1,1,0]
	v_cndmask_b32_e32 v85, v95, v111, vcc
	v_cmp_gt_f32_e32 vcc, 0, v84
	v_pk_mul_f32 v[112:113], v[86:87], v[102:103]
	v_pk_fma_f32 v[102:103], v[86:87], v[102:103], v[86:87] neg_lo:[1,0,0] neg_hi:[1,0,0]
	v_exp_f32_e32 v128, v128
	v_exp_f32_e32 v129, v129
	v_pk_mul_f32 v[106:107], v[130:131], v[106:107]
	v_cndmask_b32_e32 v84, v94, v110, vcc
	v_cmp_gt_f32_e32 vcc, 0, v87
	v_pk_mul_f32 v[106:107], v[126:127], v[106:107]
	v_pk_mul_f32 v[114:115], v[118:119], v[114:115]
	v_cndmask_b32_e32 v87, v103, v113, vcc
	v_cmp_gt_f32_e32 vcc, 0, v86
	v_pk_mul_f32 v[126:127], v[82:83], v[106:107]
	v_pk_fma_f32 v[106:107], v[82:83], v[106:107], v[82:83] neg_lo:[1,0,0] neg_hi:[1,0,0]
	v_cndmask_b32_e32 v86, v102, v112, vcc
	v_cmp_gt_f32_e32 vcc, 0, v83
	v_pk_mul_f32 v[118:119], v[88:89], v[114:115]
	v_pk_fma_f32 v[114:115], v[88:89], v[114:115], v[88:89] neg_lo:[1,0,0] neg_hi:[1,0,0]
	v_cndmask_b32_e32 v107, v107, v127, vcc
	v_cmp_gt_f32_e32 vcc, 0, v82
	v_pk_mul_f32 v[124:125], v[128:129], v[124:125]
	v_mov_b32_e32 v102, v84
	v_cndmask_b32_e32 v106, v106, v126, vcc
	v_cmp_gt_f32_e32 vcc, 0, v88
	v_pk_mul_f32 v[128:129], v[80:81], v[124:125]
	v_pk_fma_f32 v[124:125], v[80:81], v[124:125], v[80:81] neg_lo:[1,0,0] neg_hi:[1,0,0]
	v_cndmask_b32_e32 v112, v114, v118, vcc
	v_cmp_gt_f32_e32 vcc, 0, v80
	v_mov_b32_e32 v103, v86
	v_mov_b32_e32 v110, v85
	v_cndmask_b32_e32 v113, v124, v128, vcc
	v_cmp_gt_f32_e32 vcc, 0, v89
	v_mov_b32_e32 v111, v87
	v_pk_add_f32 v[102:103], v[102:103], v[110:111]
	v_cndmask_b32_e32 v88, v115, v119, vcc
	v_cmp_gt_f32_e32 vcc, 0, v90
	v_mov_b32_e32 v114, v112
	v_mov_b32_e32 v115, v88
	v_cndmask_b32_e32 v91, v116, v120, vcc
	v_cmp_gt_f32_e32 vcc, 0, v81
	v_mul_f32_e32 v80, v112, v112
	v_mov_b32_e32 v90, v113
	v_cndmask_b32_e32 v116, v125, v129, vcc
	v_mov_b32_e32 v117, v91
	v_mul_f32_e32 v97, v122, v122
	v_pk_fma_f32 v[114:115], v[114:115], v[114:115], v[80:81] op_sel_hi:[1,1,0]
	v_pk_add_f32 v[80:81], v[90:91], v[116:117]
	v_pk_mul_f32 v[118:119], v[90:91], v[116:117]
	v_pk_add_f32 v[102:103], v[102:103], v[102:103] op_sel:[0,1] op_sel_hi:[1,0]
	v_mul_f32_e32 v94, v84, v84
	v_mov_b32_e32 v81, v119
	v_mov_b32_e32 v103, v97
	v_mov_b32_e32 v114, v106
	v_mov_b32_e32 v108, v107
	v_pk_fma_f32 v[94:95], v[84:85], v[84:85], v[94:95] op_sel_hi:[1,1,0]
	v_mov_b32_e32 v89, v113
	v_pk_add_f32 v[80:81], v[80:81], v[102:103]
	v_pk_add_f32 v[102:103], v[114:115], v[108:109]
	v_mul_f32_e32 v94, v86, v86
	v_pk_add_f32 v[80:81], v[80:81], v[102:103]
	v_pk_add_f32 v[102:103], v[112:113], v[88:89]
	v_pk_mul_f32 v[108:109], v[112:113], v[88:89]
	v_pk_fma_f32 v[110:111], v[86:87], v[86:87], v[94:95] op_sel_hi:[1,1,0]
	v_mov_b32_e32 v103, v109
	v_pk_mul_f32 v[108:109], v[116:117], v[116:117]
	v_mul_f32_e32 v82, v106, v106
	v_mov_b32_e32 v94, v91
	v_mov_b32_e32 v123, v111
	v_mov_b32_e32 v105, v108
	v_pk_fma_f32 v[82:83], v[106:107], v[106:107], v[82:83] op_sel_hi:[1,1,0]
	v_pk_add_f32 v[94:95], v[94:95], v[122:123]
	v_pk_add_f32 v[102:103], v[102:103], v[104:105]
	v_mov_b32_e32 v97, v83
	v_pk_add_f32 v[94:95], v[102:103], v[94:95]
	v_add_u32_e32 v98, 48, v152
	v_pk_add_f32 v[82:83], v[94:95], v[96:97]
	v_ashrrev_i32_e32 v99, 31, v98
	v_pk_add_f32 v[80:81], v[80:81], v[82:83]
	v_mov_b32_e32 v82, v80
	v_mov_b32_e32 v83, v81
	s_nop 1
	v_permlane16_swap_b32_e32 v82, v80
	v_permlane16_swap_b32_e32 v83, v81
	s_waitcnt lgkmcnt(2)
	v_lshlrev_b64 v[100:101], 13, v[98:99]
	v_lshl_add_u64 v[100:101], s[28:29], 0, v[100:101]
	v_lshl_add_u64 v[100:101], v[148:149], 1, v[100:101]
	v_cvt_pk_bf16_f32 v94, v112, v88
	s_waitcnt lgkmcnt(0)
	v_pk_add_f32 v[80:81], v[80:81], v[82:83]
	v_mov_b32_e32 v82, v80
	v_mov_b32_e32 v83, v81
	s_nop 1
	v_permlane32_swap_b32_e32 v82, v80
	v_permlane32_swap_b32_e32 v83, v81
	v_cvt_pk_bf16_f32 v95, v91, v122
	global_store_dwordx4 v[100:101], v[92:95], off
	v_cvt_pk_bf16_f32 v84, v84, v85
	v_cvt_pk_bf16_f32 v85, v86, v87
	v_cvt_pk_bf16_f32 v86, v113, v116
	v_cvt_pk_bf16_f32 v87, v106, v107
	global_store_dwordx4 v[100:101], v[84:87], off offset:256
	s_and_saveexec_b64 s[0:1], s[2:3]
	s_cbranch_execz .LBB0_357
	s_lshl_b32 s4, s13, 3
	s_waitcnt lgkmcnt(0)
	v_pk_add_f32 v[80:81], v[80:81], v[82:83]
	v_lshlrev_b64 v[82:83], 8, v[98:99]
	s_add_i32 s4, s4, s72
	v_lshl_add_u64 v[82:83], s[26:27], 0, v[82:83]
	s_ashr_i32 s5, s4, 31
	v_lshl_add_u64 v[82:83], s[4:5], 2, v[82:83]
	global_store_dwordx2 v[82:83], v[80:81], off
.LBB0_357:
	s_or_b64 exec, exec, s[0:1]
	v_pk_fma_f32 v[84:85], v[76:77], v[154:155], v[52:53] op_sel_hi:[1,0,1]
	s_mov_b32 s4, 0x3e6d3388
	v_and_b32_e32 v77, 0x7fffffff, v85
	v_and_b32_e32 v76, 0x7fffffff, v84
	v_pk_fma_f32 v[76:77], v[76:77], s[4:5], 1.0 op_sel_hi:[1,0,0]
	v_pk_fma_f32 v[78:79], v[78:79], v[154:155], v[54:55] op_sel_hi:[1,0,1]
	v_rcp_f32_e32 v76, v76
	v_rcp_f32_e32 v77, v77
	s_mov_b32 s0, 0x3f07dc22
	v_mov_b64_e32 v[86:87], s[14:15]
	v_pk_mul_f32 v[90:91], v[84:85], v[84:85]
	v_pk_fma_f32 v[88:89], v[76:77], s[0:1], v[86:87] op_sel_hi:[1,0,0]
	v_pk_mul_f32 v[90:91], v[90:91], s[12:13] op_sel_hi:[1,0]
	v_and_b32_e32 v93, 0x7fffffff, v79
	v_and_b32_e32 v92, 0x7fffffff, v78
	v_pk_fma_f32 v[88:89], v[76:77], v[88:89], s[10:11] op_sel_hi:[1,1,0]
	v_exp_f32_e32 v90, v90
	v_exp_f32_e32 v91, v91
	v_pk_fma_f32 v[92:93], v[92:93], s[4:5], 1.0 op_sel_hi:[1,0,0]
	v_pk_fma_f32 v[88:89], v[76:77], v[88:89], s[6:7] op_sel_hi:[1,1,0]
	v_rcp_f32_e32 v92, v92
	v_rcp_f32_e32 v93, v93
	v_pk_fma_f32 v[88:89], v[76:77], v[88:89], s[8:9] op_sel_hi:[1,1,0]
	v_pk_fma_f32 v[72:73], v[72:73], v[154:155], v[48:49] op_sel_hi:[1,0,1]
	v_pk_mul_f32 v[76:77], v[76:77], v[88:89]
	v_pk_mul_f32 v[88:89], v[78:79], v[78:79]
	v_pk_mul_f32 v[76:77], v[90:91], v[76:77]
	v_pk_mul_f32 v[88:89], v[88:89], s[12:13] op_sel_hi:[1,0]
	v_pk_mul_f32 v[90:91], v[84:85], v[76:77]
	v_pk_fma_f32 v[94:95], v[84:85], v[76:77], v[84:85] neg_lo:[1,0,0] neg_hi:[1,0,0]
	v_pk_fma_f32 v[76:77], v[92:93], s[0:1], v[86:87] op_sel_hi:[1,0,0]
	v_exp_f32_e32 v88, v88
	v_pk_fma_f32 v[76:77], v[92:93], v[76:77], s[10:11] op_sel_hi:[1,1,0]
	v_exp_f32_e32 v89, v89
	v_pk_fma_f32 v[76:77], v[92:93], v[76:77], s[6:7] op_sel_hi:[1,1,0]
	v_pk_fma_f32 v[74:75], v[74:75], v[154:155], v[50:51] op_sel_hi:[1,0,1]
	v_pk_fma_f32 v[76:77], v[92:93], v[76:77], s[8:9] op_sel_hi:[1,1,0]
	v_pk_mul_f32 v[98:99], v[72:73], v[72:73]
	v_pk_mul_f32 v[76:77], v[92:93], v[76:77]
	v_and_b32_e32 v93, 0x7fffffff, v73
	v_and_b32_e32 v92, 0x7fffffff, v72
	v_pk_fma_f32 v[92:93], v[92:93], s[4:5], 1.0 op_sel_hi:[1,0,0]
	v_pk_mul_f32 v[76:77], v[88:89], v[76:77]
	v_rcp_f32_e32 v92, v92
	v_rcp_f32_e32 v93, v93
	v_pk_mul_f32 v[88:89], v[78:79], v[76:77]
	v_pk_fma_f32 v[96:97], v[78:79], v[76:77], v[78:79] neg_lo:[1,0,0] neg_hi:[1,0,0]
	v_pk_mul_f32 v[98:99], v[98:99], s[12:13] op_sel_hi:[1,0]
	v_pk_fma_f32 v[76:77], v[92:93], s[0:1], v[86:87] op_sel_hi:[1,0,0]
	v_and_b32_e32 v101, 0x7fffffff, v75
	v_and_b32_e32 v100, 0x7fffffff, v74
	v_pk_fma_f32 v[76:77], v[92:93], v[76:77], s[10:11] op_sel_hi:[1,1,0]
	v_exp_f32_e32 v98, v98
	v_exp_f32_e32 v99, v99
	v_pk_fma_f32 v[100:101], v[100:101], s[4:5], 1.0 op_sel_hi:[1,0,0]
	v_pk_fma_f32 v[76:77], v[92:93], v[76:77], s[6:7] op_sel_hi:[1,1,0]
	v_rcp_f32_e32 v100, v100
	v_rcp_f32_e32 v101, v101
	v_pk_fma_f32 v[76:77], v[92:93], v[76:77], s[8:9] op_sel_hi:[1,1,0]
	v_cmp_gt_f32_e32 vcc, 0, v75
	v_pk_mul_f32 v[76:77], v[92:93], v[76:77]
	v_pk_mul_f32 v[92:93], v[74:75], v[74:75]
	v_pk_mul_f32 v[76:77], v[98:99], v[76:77]
	v_pk_mul_f32 v[92:93], v[92:93], s[12:13] op_sel_hi:[1,0]
	v_pk_mul_f32 v[98:99], v[72:73], v[76:77]
	v_pk_fma_f32 v[102:103], v[72:73], v[76:77], v[72:73] neg_lo:[1,0,0] neg_hi:[1,0,0]
	v_pk_fma_f32 v[76:77], v[100:101], s[0:1], v[86:87] op_sel_hi:[1,0,0]
	v_exp_f32_e32 v92, v92
	v_pk_fma_f32 v[76:77], v[100:101], v[76:77], s[10:11] op_sel_hi:[1,1,0]
	v_exp_f32_e32 v93, v93
	v_pk_fma_f32 v[76:77], v[100:101], v[76:77], s[6:7] op_sel_hi:[1,1,0]
	v_pk_fma_f32 v[70:71], v[70:71], v[154:155], v[46:47] op_sel_hi:[1,0,1]
	v_pk_fma_f32 v[76:77], v[100:101], v[76:77], s[8:9] op_sel_hi:[1,1,0]
	v_pk_fma_f32 v[68:69], v[68:69], v[154:155], v[44:45] op_sel_hi:[1,0,1]
	v_pk_mul_f32 v[76:77], v[100:101], v[76:77]
	v_pk_fma_f32 v[66:67], v[66:67], v[154:155], v[42:43] op_sel_hi:[1,0,1]
	v_pk_mul_f32 v[76:77], v[92:93], v[76:77]
	v_and_b32_e32 v113, 0x7fffffff, v67
	v_pk_mul_f32 v[92:93], v[74:75], v[76:77]
	v_pk_fma_f32 v[100:101], v[74:75], v[76:77], v[74:75] neg_lo:[1,0,0] neg_hi:[1,0,0]
	v_and_b32_e32 v112, 0x7fffffff, v66
	v_cndmask_b32_e32 v76, v101, v93, vcc
	v_cmp_gt_f32_e32 vcc, 0, v78
	v_pk_fma_f32 v[112:113], v[112:113], s[4:5], 1.0 op_sel_hi:[1,0,0]
	v_mul_f32_e32 v77, v76, v76
	v_cndmask_b32_e32 v105, v96, v88, vcc
	v_cmp_gt_f32_e32 vcc, 0, v84
	v_rcp_f32_e32 v112, v112
	v_rcp_f32_e32 v113, v113
	v_cndmask_b32_e32 v104, v94, v90, vcc
	v_cmp_gt_f32_e32 vcc, 0, v79
	v_add_u32_e32 v80, 0x80, v152
	v_ashrrev_i32_e32 v81, 31, v80
	v_cndmask_b32_e32 v79, v97, v89, vcc
	v_cmp_gt_f32_e32 vcc, 0, v85
	v_pk_mul_f32 v[96:97], v[68:69], v[68:69]
	s_waitcnt lgkmcnt(0)
	v_lshlrev_b64 v[82:83], 13, v[80:81]
	v_cndmask_b32_e32 v78, v95, v91, vcc
	v_pk_add_f32 v[84:85], v[104:105], v[78:79]
	v_pk_fma_f32 v[94:95], v[64:65], v[154:155], v[40:41] op_sel_hi:[1,0,1]
	v_pk_add_f32 v[88:89], v[84:85], v[84:85] op_sel:[0,1] op_sel_hi:[1,0]
	v_pk_mul_f32 v[84:85], v[78:79], v[78:79]
	v_pk_mul_f32 v[96:97], v[96:97], s[12:13] op_sel_hi:[1,0]
	v_pk_fma_f32 v[84:85], v[104:105], v[104:105], v[84:85]
	v_exp_f32_e32 v96, v96
	v_pk_add_f32 v[90:91], v[84:85], v[84:85] op_sel_hi:[0,1]
	v_cvt_pk_bf16_f32 v84, v104, v78
	v_cvt_pk_bf16_f32 v85, v105, v79
	v_and_b32_e32 v105, 0x7fffffff, v71
	v_and_b32_e32 v104, 0x7fffffff, v70
	v_pk_fma_f32 v[104:105], v[104:105], s[4:5], 1.0 op_sel_hi:[1,0,0]
	v_and_b32_e32 v79, 0x7fffffff, v69
	v_rcp_f32_e32 v104, v104
	v_rcp_f32_e32 v105, v105
	v_and_b32_e32 v78, 0x7fffffff, v68
	v_pk_fma_f32 v[78:79], v[78:79], s[4:5], 1.0 op_sel_hi:[1,0,0]
	v_exp_f32_e32 v97, v97
	v_pk_fma_f32 v[106:107], v[104:105], s[0:1], v[86:87] op_sel_hi:[1,0,0]
	v_rcp_f32_e32 v78, v78
	v_pk_fma_f32 v[106:107], v[104:105], v[106:107], s[10:11] op_sel_hi:[1,1,0]
	v_rcp_f32_e32 v79, v79
	v_pk_fma_f32 v[106:107], v[104:105], v[106:107], s[6:7] op_sel_hi:[1,1,0]
	v_pk_mul_f32 v[110:111], v[94:95], v[94:95]
	v_pk_fma_f32 v[106:107], v[104:105], v[106:107], s[8:9] op_sel_hi:[1,1,0]
	v_pk_fma_f32 v[64:65], v[78:79], s[0:1], v[86:87] op_sel_hi:[1,0,0]
	v_pk_mul_f32 v[104:105], v[104:105], v[106:107]
	v_and_b32_e32 v107, 0x7fffffff, v95
	v_and_b32_e32 v106, 0x7fffffff, v94
	v_pk_fma_f32 v[106:107], v[106:107], s[4:5], 1.0 op_sel_hi:[1,0,0]
	v_pk_fma_f32 v[64:65], v[78:79], v[64:65], s[10:11] op_sel_hi:[1,1,0]
	v_rcp_f32_e32 v106, v106
	v_rcp_f32_e32 v107, v107
	v_pk_fma_f32 v[64:65], v[78:79], v[64:65], s[6:7] op_sel_hi:[1,1,0]
	v_cmp_gt_f32_e32 vcc, 0, v69
	v_pk_fma_f32 v[64:65], v[78:79], v[64:65], s[8:9] op_sel_hi:[1,1,0]
	v_pk_fma_f32 v[108:109], v[106:107], s[0:1], v[86:87] op_sel_hi:[1,0,0]
	v_pk_mul_f32 v[64:65], v[78:79], v[64:65]
	v_pk_fma_f32 v[108:109], v[106:107], v[108:109], s[10:11] op_sel_hi:[1,1,0]
	v_pk_mul_f32 v[78:79], v[70:71], v[70:71]
	v_pk_fma_f32 v[108:109], v[106:107], v[108:109], s[6:7] op_sel_hi:[1,1,0]
	v_pk_mul_f32 v[78:79], v[78:79], s[12:13] op_sel_hi:[1,0]
	v_pk_fma_f32 v[108:109], v[106:107], v[108:109], s[8:9] op_sel_hi:[1,1,0]
	v_exp_f32_e32 v78, v78
	v_exp_f32_e32 v79, v79
	v_pk_mul_f32 v[106:107], v[106:107], v[108:109]
	v_pk_mul_f32 v[108:109], v[66:67], v[66:67]
	v_pk_fma_f32 v[86:87], v[112:113], s[0:1], v[86:87] op_sel_hi:[1,0,0]
	v_pk_mul_f32 v[108:109], v[108:109], s[12:13] op_sel_hi:[1,0]
	v_pk_mul_f32 v[64:65], v[96:97], v[64:65]
	v_pk_fma_f32 v[86:87], v[112:113], v[86:87], s[10:11] op_sel_hi:[1,1,0]
	v_exp_f32_e32 v108, v108
	v_exp_f32_e32 v109, v109
	v_pk_mul_f32 v[96:97], v[68:69], v[64:65]
	v_pk_fma_f32 v[64:65], v[68:69], v[64:65], v[68:69] neg_lo:[1,0,0] neg_hi:[1,0,0]
	v_pk_fma_f32 v[86:87], v[112:113], v[86:87], s[6:7] op_sel_hi:[1,1,0]
	v_pk_mul_f32 v[78:79], v[78:79], v[104:105]
	v_pk_mul_f32 v[110:111], v[110:111], s[12:13] op_sel_hi:[1,0]
	v_pk_fma_f32 v[86:87], v[112:113], v[86:87], s[8:9] op_sel_hi:[1,1,0]
	v_cndmask_b32_e32 v69, v65, v97, vcc
	v_cmp_gt_f32_e32 vcc, 0, v68
	v_pk_mul_f32 v[104:105], v[70:71], v[78:79]
	v_pk_fma_f32 v[78:79], v[70:71], v[78:79], v[70:71] neg_lo:[1,0,0] neg_hi:[1,0,0]
	v_exp_f32_e32 v110, v110
	v_exp_f32_e32 v111, v111
	v_pk_mul_f32 v[86:87], v[112:113], v[86:87]
	v_cndmask_b32_e32 v68, v64, v96, vcc
	v_cmp_gt_f32_e32 vcc, 0, v71
	v_pk_mul_f32 v[86:87], v[108:109], v[86:87]
	v_pk_mul_f32 v[106:107], v[110:111], v[106:107]
	v_cndmask_b32_e32 v79, v79, v105, vcc
	v_cmp_gt_f32_e32 vcc, 0, v70
	v_pk_mul_f32 v[108:109], v[66:67], v[86:87]
	v_pk_fma_f32 v[86:87], v[66:67], v[86:87], v[66:67] neg_lo:[1,0,0] neg_hi:[1,0,0]
	v_cndmask_b32_e32 v78, v78, v104, vcc
	v_cmp_gt_f32_e32 vcc, 0, v67
	v_mul_f32_e32 v64, v68, v68
	v_pk_mul_f32 v[110:111], v[94:95], v[106:107]
	v_cndmask_b32_e32 v109, v87, v109, vcc
	v_cmp_gt_f32_e32 vcc, 0, v66
	v_pk_fma_f32 v[106:107], v[94:95], v[106:107], v[94:95] neg_lo:[1,0,0] neg_hi:[1,0,0]
	v_pk_fma_f32 v[96:97], v[68:69], v[68:69], v[64:65] op_sel_hi:[1,1,0]
	v_cndmask_b32_e32 v108, v86, v108, vcc
	v_cmp_gt_f32_e32 vcc, 0, v72
	v_mov_b32_e32 v64, v68
	v_mov_b32_e32 v65, v78
	v_mov_b32_e32 v70, v69
	v_mov_b32_e32 v71, v79
	v_cndmask_b32_e32 v112, v102, v98, vcc
	v_cmp_gt_f32_e32 vcc, 0, v94
	v_pk_add_f32 v[70:71], v[64:65], v[70:71]
	v_mul_f32_e32 v64, v78, v78
	v_cndmask_b32_e32 v113, v106, v110, vcc
	v_cmp_gt_f32_e32 vcc, 0, v73
	v_pk_fma_f32 v[104:105], v[78:79], v[78:79], v[64:65] op_sel_hi:[1,1,0]
	v_mul_f32_e32 v64, v108, v108
	v_cndmask_b32_e32 v66, v103, v99, vcc
	v_cmp_gt_f32_e32 vcc, 0, v74
	v_pk_fma_f32 v[64:65], v[108:109], v[108:109], v[64:65] op_sel_hi:[1,1,0]
	v_mov_b32_e32 v72, v112
	v_cndmask_b32_e32 v75, v100, v92, vcc
	v_cmp_gt_f32_e32 vcc, 0, v95
	v_mov_b32_e32 v73, v66
	v_mul_f32_e32 v64, v112, v112
	v_mov_b32_e32 v74, v113
	v_cndmask_b32_e32 v92, v107, v111, vcc
	v_mov_b32_e32 v93, v75
	v_pk_fma_f32 v[72:73], v[72:73], v[72:73], v[64:65] op_sel_hi:[1,1,0]
	v_pk_add_f32 v[86:87], v[74:75], v[92:93]
	v_pk_mul_f32 v[94:95], v[74:75], v[92:93]
	v_pk_add_f32 v[70:71], v[70:71], v[70:71] op_sel:[0,1] op_sel_hi:[1,0]
	v_mov_b32_e32 v67, v113
	v_mov_b32_e32 v87, v95
	v_mov_b32_e32 v71, v77
	v_mov_b32_e32 v72, v108
	v_mov_b32_e32 v90, v109
	v_pk_add_f32 v[70:71], v[86:87], v[70:71]
	v_pk_add_f32 v[72:73], v[72:73], v[90:91]
	v_pk_add_f32 v[86:87], v[112:113], v[66:67]
	v_pk_mul_f32 v[90:91], v[112:113], v[66:67]
	v_mov_b32_e32 v96, v75
	v_mov_b32_e32 v87, v91
	v_pk_mul_f32 v[90:91], v[92:93], v[92:93]
	v_mov_b32_e32 v77, v105
	v_mov_b32_e32 v89, v90
	v_pk_add_f32 v[70:71], v[70:71], v[72:73]
	v_pk_add_f32 v[72:73], v[96:97], v[76:77]
	v_pk_add_f32 v[86:87], v[86:87], v[88:89]
	v_mov_b32_e32 v64, 0
	v_pk_add_f32 v[72:73], v[86:87], v[72:73]
	v_lshl_add_u64 v[82:83], s[28:29], 0, v[82:83]
	v_pk_add_f32 v[72:73], v[72:73], v[64:65]
	v_lshl_add_u64 v[82:83], v[148:149], 1, v[82:83]
	v_pk_add_f32 v[72:73], v[70:71], v[72:73]
	v_mov_b32_e32 v88, v72
	v_mov_b32_e32 v89, v73
	s_nop 1
	v_permlane16_swap_b32_e32 v88, v72
	v_permlane16_swap_b32_e32 v89, v73
	v_cvt_pk_bf16_f32 v86, v112, v66
	v_cvt_pk_bf16_f32 v87, v75, v76
	global_store_dwordx4 v[82:83], v[84:87], off
	v_cvt_pk_bf16_f32 v70, v68, v69
	s_waitcnt lgkmcnt(0)
	v_pk_add_f32 v[66:67], v[72:73], v[88:89]
	v_mov_b32_e32 v68, v66
	v_mov_b32_e32 v69, v67
	s_nop 1
	v_permlane32_swap_b32_e32 v68, v66
	v_permlane32_swap_b32_e32 v69, v67
	v_cvt_pk_bf16_f32 v71, v78, v79
	v_cvt_pk_bf16_f32 v72, v113, v92
	v_cvt_pk_bf16_f32 v73, v108, v109
	global_store_dwordx4 v[82:83], v[70:73], off offset:256
	s_and_saveexec_b64 s[16:17], s[2:3]
	s_cbranch_execz .LBB0_359
	s_lshl_b32 s1, s13, 3
	s_waitcnt lgkmcnt(0)
	v_pk_add_f32 v[66:67], v[66:67], v[68:69]
	v_lshlrev_b64 v[68:69], 8, v[80:81]
	s_add_i32 s18, s1, s72
	v_lshl_add_u64 v[68:69], s[26:27], 0, v[68:69]
	s_ashr_i32 s19, s18, 31
	v_lshl_add_u64 v[68:69], s[18:19], 2, v[68:69]
	global_store_dwordx2 v[68:69], v[66:67], off
.LBB0_359:
	s_or_b64 exec, exec, s[16:17]
	v_mov_b32_e32 v70, v155
	v_pk_fma_f32 v[62:63], v[62:63], v[70:71], v[54:55] op_sel_hi:[1,0,1]
	v_mov_b64_e32 v[74:75], s[14:15]
	v_and_b32_e32 v81, 0x7fffffff, v63
	v_and_b32_e32 v80, 0x7fffffff, v62
	v_pk_fma_f32 v[80:81], v[80:81], s[4:5], 1.0 op_sel_hi:[1,0,0]
	v_pk_fma_f32 v[56:57], v[56:57], v[70:71], v[48:49] op_sel_hi:[1,0,1]
	v_rcp_f32_e32 v80, v80
	v_rcp_f32_e32 v81, v81
	v_pk_fma_f32 v[60:61], v[60:61], v[70:71], v[52:53] op_sel_hi:[1,0,1]
	v_pk_fma_f32 v[58:59], v[58:59], v[70:71], v[50:51] op_sel_hi:[1,0,1]
	v_and_b32_e32 v73, 0x7fffffff, v61
	v_pk_fma_f32 v[82:83], v[80:81], s[0:1], v[74:75] op_sel_hi:[1,0,0]
	v_and_b32_e32 v72, 0x7fffffff, v60
	v_pk_fma_f32 v[82:83], v[80:81], v[82:83], s[10:11] op_sel_hi:[1,1,0]
	v_pk_fma_f32 v[72:73], v[72:73], s[4:5], 1.0 op_sel_hi:[1,0,0]
	v_pk_fma_f32 v[82:83], v[80:81], v[82:83], s[6:7] op_sel_hi:[1,1,0]
	v_rcp_f32_e32 v72, v72
	v_pk_fma_f32 v[82:83], v[80:81], v[82:83], s[8:9] op_sel_hi:[1,1,0]
	v_rcp_f32_e32 v73, v73
	v_pk_mul_f32 v[80:81], v[80:81], v[82:83]
	v_and_b32_e32 v83, 0x7fffffff, v57
	v_and_b32_e32 v82, 0x7fffffff, v56
	v_pk_fma_f32 v[82:83], v[82:83], s[4:5], 1.0 op_sel_hi:[1,0,0]
	v_and_b32_e32 v89, 0x7fffffff, v59
	v_rcp_f32_e32 v82, v82
	v_rcp_f32_e32 v83, v83
	v_and_b32_e32 v88, 0x7fffffff, v58
	v_pk_fma_f32 v[88:89], v[88:89], s[4:5], 1.0 op_sel_hi:[1,0,0]
	v_pk_fma_f32 v[76:77], v[72:73], s[0:1], v[74:75] op_sel_hi:[1,0,0]
	v_pk_fma_f32 v[84:85], v[82:83], s[0:1], v[74:75] op_sel_hi:[1,0,0]
	v_rcp_f32_e32 v88, v88
	v_pk_fma_f32 v[84:85], v[82:83], v[84:85], s[10:11] op_sel_hi:[1,1,0]
	v_rcp_f32_e32 v89, v89
	v_pk_fma_f32 v[76:77], v[72:73], v[76:77], s[10:11] op_sel_hi:[1,1,0]
	v_pk_fma_f32 v[84:85], v[82:83], v[84:85], s[6:7] op_sel_hi:[1,1,0]
	v_pk_fma_f32 v[76:77], v[72:73], v[76:77], s[6:7] op_sel_hi:[1,1,0]
	v_pk_fma_f32 v[84:85], v[82:83], v[84:85], s[8:9] op_sel_hi:[1,1,0]
	v_pk_fma_f32 v[76:77], v[72:73], v[76:77], s[8:9] op_sel_hi:[1,1,0]
	v_pk_mul_f32 v[82:83], v[82:83], v[84:85]
	v_pk_mul_f32 v[84:85], v[58:59], v[58:59]
	v_pk_mul_f32 v[72:73], v[72:73], v[76:77]
	v_pk_mul_f32 v[76:77], v[62:63], v[62:63]
	v_pk_fma_f32 v[90:91], v[88:89], s[0:1], v[74:75] op_sel_hi:[1,0,0]
	v_pk_mul_f32 v[84:85], v[84:85], s[12:13] op_sel_hi:[1,0]
	v_pk_mul_f32 v[78:79], v[60:61], v[60:61]
	v_pk_mul_f32 v[76:77], v[76:77], s[12:13] op_sel_hi:[1,0]
	v_pk_fma_f32 v[90:91], v[88:89], v[90:91], s[10:11] op_sel_hi:[1,1,0]
	v_exp_f32_e32 v84, v84
	v_exp_f32_e32 v85, v85
	v_pk_mul_f32 v[78:79], v[78:79], s[12:13] op_sel_hi:[1,0]
	v_exp_f32_e32 v76, v76
	v_exp_f32_e32 v77, v77
	v_pk_fma_f32 v[90:91], v[88:89], v[90:91], s[6:7] op_sel_hi:[1,1,0]
	v_exp_f32_e32 v78, v78
	v_exp_f32_e32 v79, v79
	v_pk_fma_f32 v[90:91], v[88:89], v[90:91], s[8:9] op_sel_hi:[1,1,0]
	v_pk_mul_f32 v[76:77], v[76:77], v[80:81]
	v_pk_mul_f32 v[88:89], v[88:89], v[90:91]
	v_cmp_gt_f32_e32 vcc, 0, v59
	v_pk_mul_f32 v[84:85], v[84:85], v[88:89]
	v_pk_mul_f32 v[72:73], v[78:79], v[72:73]
	v_pk_mul_f32 v[88:89], v[58:59], v[84:85]
	v_pk_fma_f32 v[84:85], v[58:59], v[84:85], v[58:59] neg_lo:[1,0,0] neg_hi:[1,0,0]
	v_pk_mul_f32 v[80:81], v[62:63], v[76:77]
	v_pk_fma_f32 v[76:77], v[62:63], v[76:77], v[62:63] neg_lo:[1,0,0] neg_hi:[1,0,0]
	v_cndmask_b32_e32 v90, v85, v89, vcc
	v_cmp_gt_f32_e32 vcc, 0, v62
	v_pk_mul_f32 v[78:79], v[60:61], v[72:73]
	v_pk_fma_f32 v[72:73], v[60:61], v[72:73], v[60:61] neg_lo:[1,0,0] neg_hi:[1,0,0]
	v_cndmask_b32_e32 v93, v76, v80, vcc
	v_cmp_gt_f32_e32 vcc, 0, v60
	v_pk_fma_f32 v[38:39], v[38:39], v[70:71], v[46:47] op_sel_hi:[1,0,1]
	v_pk_fma_f32 v[36:37], v[36:37], v[70:71], v[44:45] op_sel_hi:[1,0,1]
	v_cndmask_b32_e32 v92, v72, v78, vcc
	v_cmp_gt_f32_e32 vcc, 0, v63
	v_and_b32_e32 v80, 0x7fffffff, v38
	v_pk_fma_f32 v[32:33], v[32:33], v[70:71], v[40:41] op_sel_hi:[1,0,1]
	v_cndmask_b32_e32 v63, v77, v81, vcc
	v_and_b32_e32 v81, 0x7fffffff, v39
	v_cmp_gt_f32_e32 vcc, 0, v61
	v_pk_fma_f32 v[80:81], v[80:81], s[4:5], 1.0 op_sel_hi:[1,0,0]
	v_pk_fma_f32 v[34:35], v[34:35], v[70:71], v[42:43] op_sel_hi:[1,0,1]
	v_cndmask_b32_e32 v62, v73, v79, vcc
	v_rcp_f32_e32 v80, v80
	v_rcp_f32_e32 v81, v81
	v_pk_add_f32 v[60:61], v[92:93], v[62:63]
	v_and_b32_e32 v99, 0x7fffffff, v35
	v_pk_add_f32 v[72:73], v[60:61], v[60:61] op_sel:[0,1] op_sel_hi:[1,0]
	v_pk_mul_f32 v[60:61], v[62:63], v[62:63]
	v_and_b32_e32 v98, 0x7fffffff, v34
	v_pk_fma_f32 v[60:61], v[92:93], v[92:93], v[60:61]
	v_pk_mul_f32 v[78:79], v[36:37], v[36:37]
	v_pk_add_f32 v[76:77], v[60:61], v[60:61] op_sel_hi:[0,1]
	v_cvt_pk_bf16_f32 v60, v92, v62
	v_cvt_pk_bf16_f32 v61, v93, v63
	v_pk_fma_f32 v[92:93], v[80:81], s[0:1], v[74:75] op_sel_hi:[1,0,0]
	v_and_b32_e32 v63, 0x7fffffff, v37
	v_pk_fma_f32 v[92:93], v[80:81], v[92:93], s[10:11] op_sel_hi:[1,1,0]
	v_and_b32_e32 v62, 0x7fffffff, v36
	v_pk_fma_f32 v[92:93], v[80:81], v[92:93], s[6:7] op_sel_hi:[1,1,0]
	v_pk_fma_f32 v[62:63], v[62:63], s[4:5], 1.0 op_sel_hi:[1,0,0]
	v_pk_fma_f32 v[92:93], v[80:81], v[92:93], s[8:9] op_sel_hi:[1,1,0]
	v_rcp_f32_e32 v62, v62
	v_rcp_f32_e32 v63, v63
	v_pk_mul_f32 v[80:81], v[80:81], v[92:93]
	v_and_b32_e32 v93, 0x7fffffff, v33
	v_and_b32_e32 v92, 0x7fffffff, v32
	v_pk_fma_f32 v[92:93], v[92:93], s[4:5], 1.0 op_sel_hi:[1,0,0]
	v_pk_fma_f32 v[70:71], v[62:63], s[0:1], v[74:75] op_sel_hi:[1,0,0]
	v_rcp_f32_e32 v92, v92
	v_rcp_f32_e32 v93, v93
	v_pk_fma_f32 v[70:71], v[62:63], v[70:71], s[10:11] op_sel_hi:[1,1,0]
	v_pk_fma_f32 v[98:99], v[98:99], s[4:5], 1.0 op_sel_hi:[1,0,0]
	v_pk_fma_f32 v[70:71], v[62:63], v[70:71], s[6:7] op_sel_hi:[1,1,0]
	v_pk_fma_f32 v[94:95], v[92:93], s[0:1], v[74:75] op_sel_hi:[1,0,0]
	v_pk_fma_f32 v[70:71], v[62:63], v[70:71], s[8:9] op_sel_hi:[1,1,0]
	v_pk_mul_f32 v[78:79], v[78:79], s[12:13] op_sel_hi:[1,0]
	v_pk_fma_f32 v[94:95], v[92:93], v[94:95], s[10:11] op_sel_hi:[1,1,0]
	v_rcp_f32_e32 v98, v98
	v_rcp_f32_e32 v99, v99
	v_pk_mul_f32 v[62:63], v[62:63], v[70:71]
	v_pk_mul_f32 v[70:71], v[38:39], v[38:39]
	v_exp_f32_e32 v78, v78
	v_exp_f32_e32 v79, v79
	v_pk_fma_f32 v[94:95], v[92:93], v[94:95], s[6:7] op_sel_hi:[1,1,0]
	v_pk_mul_f32 v[70:71], v[70:71], s[12:13] op_sel_hi:[1,0]
	v_pk_fma_f32 v[94:95], v[92:93], v[94:95], s[8:9] op_sel_hi:[1,1,0]
	v_exp_f32_e32 v70, v70
	v_exp_f32_e32 v71, v71
	v_pk_mul_f32 v[92:93], v[92:93], v[94:95]
	v_pk_mul_f32 v[94:95], v[34:35], v[34:35]
	v_pk_fma_f32 v[74:75], v[98:99], s[0:1], v[74:75] op_sel_hi:[1,0,0]
	v_pk_mul_f32 v[94:95], v[94:95], s[12:13] op_sel_hi:[1,0]
	v_pk_mul_f32 v[86:87], v[56:57], v[56:57]
	v_pk_mul_f32 v[62:63], v[78:79], v[62:63]
	v_pk_fma_f32 v[74:75], v[98:99], v[74:75], s[10:11] op_sel_hi:[1,1,0]
	v_exp_f32_e32 v94, v94
	v_exp_f32_e32 v95, v95
	v_pk_mul_f32 v[86:87], v[86:87], s[12:13] op_sel_hi:[1,0]
	v_pk_mul_f32 v[78:79], v[36:37], v[62:63]
	v_pk_fma_f32 v[62:63], v[36:37], v[62:63], v[36:37] neg_lo:[1,0,0] neg_hi:[1,0,0]
	v_pk_mul_f32 v[96:97], v[32:33], v[32:33]
	v_pk_fma_f32 v[74:75], v[98:99], v[74:75], s[6:7] op_sel_hi:[1,1,0]
	v_cmp_gt_f32_e32 vcc, 0, v37
	v_exp_f32_e32 v86, v86
	v_exp_f32_e32 v87, v87
	v_pk_mul_f32 v[70:71], v[70:71], v[80:81]
	v_pk_mul_f32 v[96:97], v[96:97], s[12:13] op_sel_hi:[1,0]
	v_pk_fma_f32 v[74:75], v[98:99], v[74:75], s[8:9] op_sel_hi:[1,1,0]
	v_cndmask_b32_e32 v37, v63, v79, vcc
	v_cmp_gt_f32_e32 vcc, 0, v36
	v_pk_mul_f32 v[80:81], v[38:39], v[70:71]
	v_pk_fma_f32 v[70:71], v[38:39], v[70:71], v[38:39] neg_lo:[1,0,0] neg_hi:[1,0,0]
	v_exp_f32_e32 v96, v96
	v_exp_f32_e32 v97, v97
	v_pk_mul_f32 v[74:75], v[98:99], v[74:75]
	v_cndmask_b32_e32 v36, v62, v78, vcc
	v_cmp_gt_f32_e32 vcc, 0, v39
	v_pk_mul_f32 v[74:75], v[94:95], v[74:75]
	v_pk_mul_f32 v[82:83], v[86:87], v[82:83]
	v_cndmask_b32_e32 v39, v71, v81, vcc
	v_cmp_gt_f32_e32 vcc, 0, v38
	v_pk_mul_f32 v[94:95], v[34:35], v[74:75]
	v_pk_fma_f32 v[74:75], v[34:35], v[74:75], v[34:35] neg_lo:[1,0,0] neg_hi:[1,0,0]
	v_cndmask_b32_e32 v38, v70, v80, vcc
	v_cmp_gt_f32_e32 vcc, 0, v35
	v_pk_mul_f32 v[86:87], v[56:57], v[82:83]
	v_pk_fma_f32 v[82:83], v[56:57], v[82:83], v[56:57] neg_lo:[1,0,0] neg_hi:[1,0,0]
	v_cndmask_b32_e32 v75, v75, v95, vcc
	v_cmp_gt_f32_e32 vcc, 0, v34
	v_pk_mul_f32 v[92:93], v[96:97], v[92:93]
	v_mov_b32_e32 v70, v36
	v_cndmask_b32_e32 v74, v74, v94, vcc
	v_cmp_gt_f32_e32 vcc, 0, v56
	v_pk_mul_f32 v[96:97], v[32:33], v[92:93]
	v_pk_fma_f32 v[92:93], v[32:33], v[92:93], v[32:33] neg_lo:[1,0,0] neg_hi:[1,0,0]
	v_cndmask_b32_e32 v80, v82, v86, vcc
	v_cmp_gt_f32_e32 vcc, 0, v32
	v_mov_b32_e32 v71, v38
	v_mov_b32_e32 v78, v37
	v_cndmask_b32_e32 v81, v92, v96, vcc
	v_cmp_gt_f32_e32 vcc, 0, v57
	v_mov_b32_e32 v79, v39
	v_pk_add_f32 v[70:71], v[70:71], v[78:79]
	v_cndmask_b32_e32 v56, v83, v87, vcc
	v_cmp_gt_f32_e32 vcc, 0, v58
	v_mov_b32_e32 v82, v80
	v_mov_b32_e32 v83, v56
	v_cndmask_b32_e32 v59, v84, v88, vcc
	v_cmp_gt_f32_e32 vcc, 0, v33
	v_mul_f32_e32 v32, v80, v80
	v_mov_b32_e32 v58, v81
	v_cndmask_b32_e32 v84, v93, v97, vcc
	v_mov_b32_e32 v85, v59
	v_mul_f32_e32 v65, v90, v90
	v_pk_fma_f32 v[82:83], v[82:83], v[82:83], v[32:33] op_sel_hi:[1,1,0]
	v_pk_add_f32 v[32:33], v[58:59], v[84:85]
	v_pk_mul_f32 v[86:87], v[58:59], v[84:85]
	v_pk_add_f32 v[70:71], v[70:71], v[70:71] op_sel:[0,1] op_sel_hi:[1,0]
	v_mul_f32_e32 v62, v36, v36
	v_mov_b32_e32 v33, v87
	v_mov_b32_e32 v71, v65
	v_mov_b32_e32 v82, v74
	v_mov_b32_e32 v76, v75
	v_pk_fma_f32 v[62:63], v[36:37], v[36:37], v[62:63] op_sel_hi:[1,1,0]
	v_mov_b32_e32 v57, v81
	v_pk_add_f32 v[32:33], v[32:33], v[70:71]
	v_pk_add_f32 v[70:71], v[82:83], v[76:77]
	v_mul_f32_e32 v62, v38, v38
	v_pk_add_f32 v[32:33], v[32:33], v[70:71]
	v_pk_add_f32 v[70:71], v[80:81], v[56:57]
	v_pk_mul_f32 v[76:77], v[80:81], v[56:57]
	v_pk_fma_f32 v[78:79], v[38:39], v[38:39], v[62:63] op_sel_hi:[1,1,0]
	v_mov_b32_e32 v71, v77
	v_pk_mul_f32 v[76:77], v[84:85], v[84:85]
	v_mul_f32_e32 v34, v74, v74
	v_mov_b32_e32 v62, v59
	v_mov_b32_e32 v91, v79
	v_mov_b32_e32 v73, v76
	v_pk_fma_f32 v[34:35], v[74:75], v[74:75], v[34:35] op_sel_hi:[1,1,0]
	v_pk_add_f32 v[62:63], v[62:63], v[90:91]
	v_pk_add_f32 v[70:71], v[70:71], v[72:73]
	v_mov_b32_e32 v65, v35
	v_pk_add_f32 v[62:63], v[70:71], v[62:63]
	v_add_u32_e32 v66, 0x90, v152
	v_pk_add_f32 v[34:35], v[62:63], v[64:65]
	v_ashrrev_i32_e32 v67, 31, v66
	v_pk_add_f32 v[32:33], v[32:33], v[34:35]
	v_mov_b32_e32 v34, v32
	v_mov_b32_e32 v35, v33
	s_nop 1
	v_permlane16_swap_b32_e32 v34, v32
	v_permlane16_swap_b32_e32 v35, v33
	s_waitcnt lgkmcnt(2)
	v_lshlrev_b64 v[68:69], 13, v[66:67]
	v_lshl_add_u64 v[68:69], s[28:29], 0, v[68:69]
	v_lshl_add_u64 v[68:69], v[148:149], 1, v[68:69]
	v_cvt_pk_bf16_f32 v62, v80, v56
	s_waitcnt lgkmcnt(0)
	v_pk_add_f32 v[32:33], v[32:33], v[34:35]
	v_mov_b32_e32 v34, v32
	v_mov_b32_e32 v35, v33
	s_nop 1
	v_permlane32_swap_b32_e32 v34, v32
	v_permlane32_swap_b32_e32 v35, v33
	v_cvt_pk_bf16_f32 v63, v59, v90
	global_store_dwordx4 v[68:69], v[60:63], off
	v_cvt_pk_bf16_f32 v36, v36, v37
	v_cvt_pk_bf16_f32 v37, v38, v39
	v_cvt_pk_bf16_f32 v38, v81, v84
	v_cvt_pk_bf16_f32 v39, v74, v75
	global_store_dwordx4 v[68:69], v[36:39], off offset:256
	s_and_saveexec_b64 s[0:1], s[2:3]
	s_cbranch_execz .LBB0_361
	s_lshl_b32 s4, s13, 3
	s_waitcnt lgkmcnt(0)
	v_pk_add_f32 v[32:33], v[32:33], v[34:35]
	v_lshlrev_b64 v[34:35], 8, v[66:67]
	s_add_i32 s4, s4, s72
	v_lshl_add_u64 v[34:35], s[26:27], 0, v[34:35]
	s_ashr_i32 s5, s4, 31
	v_lshl_add_u64 v[34:35], s[4:5], 2, v[34:35]
	global_store_dwordx2 v[34:35], v[32:33], off
.LBB0_361:
	s_or_b64 exec, exec, s[0:1]
	v_pk_fma_f32 v[36:37], v[28:29], v[150:151], v[52:53] op_sel_hi:[1,0,1]
	s_mov_b32 s4, 0x3e6d3388
	v_and_b32_e32 v29, 0x7fffffff, v37
	v_and_b32_e32 v28, 0x7fffffff, v36
	v_pk_fma_f32 v[28:29], v[28:29], s[4:5], 1.0 op_sel_hi:[1,0,0]
	v_pk_fma_f32 v[30:31], v[30:31], v[150:151], v[54:55] op_sel_hi:[1,0,1]
	v_rcp_f32_e32 v28, v28
	v_rcp_f32_e32 v29, v29
	s_mov_b32 s0, 0x3f07dc22
	v_mov_b64_e32 v[38:39], s[14:15]
	v_pk_mul_f32 v[58:59], v[36:37], v[36:37]
	v_pk_fma_f32 v[56:57], v[28:29], s[0:1], v[38:39] op_sel_hi:[1,0,0]
	v_pk_mul_f32 v[58:59], v[58:59], s[12:13] op_sel_hi:[1,0]
	v_and_b32_e32 v61, 0x7fffffff, v31
	v_and_b32_e32 v60, 0x7fffffff, v30
	v_pk_fma_f32 v[56:57], v[28:29], v[56:57], s[10:11] op_sel_hi:[1,1,0]
	v_exp_f32_e32 v58, v58
	v_exp_f32_e32 v59, v59
	v_pk_fma_f32 v[60:61], v[60:61], s[4:5], 1.0 op_sel_hi:[1,0,0]
	v_pk_fma_f32 v[56:57], v[28:29], v[56:57], s[6:7] op_sel_hi:[1,1,0]
	v_rcp_f32_e32 v60, v60
	v_rcp_f32_e32 v61, v61
	v_pk_fma_f32 v[56:57], v[28:29], v[56:57], s[8:9] op_sel_hi:[1,1,0]
	v_pk_fma_f32 v[24:25], v[24:25], v[150:151], v[48:49] op_sel_hi:[1,0,1]
	v_pk_mul_f32 v[28:29], v[28:29], v[56:57]
	v_pk_mul_f32 v[56:57], v[30:31], v[30:31]
	v_pk_mul_f32 v[28:29], v[58:59], v[28:29]
	v_pk_mul_f32 v[56:57], v[56:57], s[12:13] op_sel_hi:[1,0]
	v_pk_mul_f32 v[58:59], v[36:37], v[28:29]
	v_pk_fma_f32 v[62:63], v[36:37], v[28:29], v[36:37] neg_lo:[1,0,0] neg_hi:[1,0,0]
	v_pk_fma_f32 v[28:29], v[60:61], s[0:1], v[38:39] op_sel_hi:[1,0,0]
	v_exp_f32_e32 v56, v56
	v_pk_fma_f32 v[28:29], v[60:61], v[28:29], s[10:11] op_sel_hi:[1,1,0]
	v_exp_f32_e32 v57, v57
	v_pk_fma_f32 v[28:29], v[60:61], v[28:29], s[6:7] op_sel_hi:[1,1,0]
	v_pk_fma_f32 v[26:27], v[26:27], v[150:151], v[50:51] op_sel_hi:[1,0,1]
	v_pk_fma_f32 v[28:29], v[60:61], v[28:29], s[8:9] op_sel_hi:[1,1,0]
	v_pk_mul_f32 v[66:67], v[24:25], v[24:25]
	v_pk_mul_f32 v[28:29], v[60:61], v[28:29]
	v_and_b32_e32 v61, 0x7fffffff, v25
	v_and_b32_e32 v60, 0x7fffffff, v24
	v_pk_fma_f32 v[60:61], v[60:61], s[4:5], 1.0 op_sel_hi:[1,0,0]
	v_pk_mul_f32 v[28:29], v[56:57], v[28:29]
	v_rcp_f32_e32 v60, v60
	v_rcp_f32_e32 v61, v61
	v_pk_mul_f32 v[56:57], v[30:31], v[28:29]
	v_pk_fma_f32 v[64:65], v[30:31], v[28:29], v[30:31] neg_lo:[1,0,0] neg_hi:[1,0,0]
	v_pk_mul_f32 v[66:67], v[66:67], s[12:13] op_sel_hi:[1,0]
	v_pk_fma_f32 v[28:29], v[60:61], s[0:1], v[38:39] op_sel_hi:[1,0,0]
	v_and_b32_e32 v69, 0x7fffffff, v27
	v_and_b32_e32 v68, 0x7fffffff, v26
	v_pk_fma_f32 v[28:29], v[60:61], v[28:29], s[10:11] op_sel_hi:[1,1,0]
	v_exp_f32_e32 v66, v66
	v_exp_f32_e32 v67, v67
	v_pk_fma_f32 v[68:69], v[68:69], s[4:5], 1.0 op_sel_hi:[1,0,0]
	v_pk_fma_f32 v[28:29], v[60:61], v[28:29], s[6:7] op_sel_hi:[1,1,0]
	v_rcp_f32_e32 v68, v68
	v_rcp_f32_e32 v69, v69
	v_pk_fma_f32 v[28:29], v[60:61], v[28:29], s[8:9] op_sel_hi:[1,1,0]
	v_cmp_gt_f32_e32 vcc, 0, v27
	v_pk_mul_f32 v[28:29], v[60:61], v[28:29]
	v_pk_mul_f32 v[60:61], v[26:27], v[26:27]
	v_pk_mul_f32 v[28:29], v[66:67], v[28:29]
	v_pk_mul_f32 v[60:61], v[60:61], s[12:13] op_sel_hi:[1,0]
	v_pk_mul_f32 v[66:67], v[24:25], v[28:29]
	v_pk_fma_f32 v[70:71], v[24:25], v[28:29], v[24:25] neg_lo:[1,0,0] neg_hi:[1,0,0]
	v_pk_fma_f32 v[28:29], v[68:69], s[0:1], v[38:39] op_sel_hi:[1,0,0]
	v_exp_f32_e32 v60, v60
	v_pk_fma_f32 v[28:29], v[68:69], v[28:29], s[10:11] op_sel_hi:[1,1,0]
	v_exp_f32_e32 v61, v61
	v_pk_fma_f32 v[28:29], v[68:69], v[28:29], s[6:7] op_sel_hi:[1,1,0]
	v_pk_fma_f32 v[22:23], v[22:23], v[150:151], v[46:47] op_sel_hi:[1,0,1]
	v_pk_fma_f32 v[28:29], v[68:69], v[28:29], s[8:9] op_sel_hi:[1,1,0]
	v_pk_fma_f32 v[20:21], v[20:21], v[150:151], v[44:45] op_sel_hi:[1,0,1]
	v_pk_mul_f32 v[28:29], v[68:69], v[28:29]
	v_pk_fma_f32 v[18:19], v[18:19], v[150:151], v[42:43] op_sel_hi:[1,0,1]
	v_pk_mul_f32 v[28:29], v[60:61], v[28:29]
	v_and_b32_e32 v81, 0x7fffffff, v19
	v_pk_mul_f32 v[60:61], v[26:27], v[28:29]
	v_pk_fma_f32 v[68:69], v[26:27], v[28:29], v[26:27] neg_lo:[1,0,0] neg_hi:[1,0,0]
	v_and_b32_e32 v80, 0x7fffffff, v18
	v_cndmask_b32_e32 v28, v69, v61, vcc
	v_cmp_gt_f32_e32 vcc, 0, v30
	v_pk_fma_f32 v[80:81], v[80:81], s[4:5], 1.0 op_sel_hi:[1,0,0]
	v_mul_f32_e32 v29, v28, v28
	v_cndmask_b32_e32 v73, v64, v56, vcc
	v_cmp_gt_f32_e32 vcc, 0, v36
	v_rcp_f32_e32 v80, v80
	v_rcp_f32_e32 v81, v81
	v_cndmask_b32_e32 v72, v62, v58, vcc
	v_cmp_gt_f32_e32 vcc, 0, v31
	v_add_u32_e32 v32, 0xa0, v152
	v_ashrrev_i32_e32 v33, 31, v32
	v_cndmask_b32_e32 v31, v65, v57, vcc
	v_cmp_gt_f32_e32 vcc, 0, v37
	v_pk_mul_f32 v[64:65], v[20:21], v[20:21]
	s_waitcnt lgkmcnt(0)
	v_lshlrev_b64 v[34:35], 13, v[32:33]
	v_cndmask_b32_e32 v30, v63, v59, vcc
	v_pk_add_f32 v[36:37], v[72:73], v[30:31]
	v_pk_fma_f32 v[62:63], v[16:17], v[150:151], v[40:41] op_sel_hi:[1,0,1]
	v_pk_add_f32 v[56:57], v[36:37], v[36:37] op_sel:[0,1] op_sel_hi:[1,0]
	v_pk_mul_f32 v[36:37], v[30:31], v[30:31]
	v_pk_mul_f32 v[64:65], v[64:65], s[12:13] op_sel_hi:[1,0]
	v_pk_fma_f32 v[36:37], v[72:73], v[72:73], v[36:37]
	v_exp_f32_e32 v64, v64
	v_pk_add_f32 v[58:59], v[36:37], v[36:37] op_sel_hi:[0,1]
	v_cvt_pk_bf16_f32 v36, v72, v30
	v_cvt_pk_bf16_f32 v37, v73, v31
	v_and_b32_e32 v73, 0x7fffffff, v23
	v_and_b32_e32 v72, 0x7fffffff, v22
	v_pk_fma_f32 v[72:73], v[72:73], s[4:5], 1.0 op_sel_hi:[1,0,0]
	v_and_b32_e32 v31, 0x7fffffff, v21
	v_rcp_f32_e32 v72, v72
	v_rcp_f32_e32 v73, v73
	v_and_b32_e32 v30, 0x7fffffff, v20
	v_pk_fma_f32 v[30:31], v[30:31], s[4:5], 1.0 op_sel_hi:[1,0,0]
	v_exp_f32_e32 v65, v65
	v_pk_fma_f32 v[74:75], v[72:73], s[0:1], v[38:39] op_sel_hi:[1,0,0]
	v_rcp_f32_e32 v30, v30
	v_pk_fma_f32 v[74:75], v[72:73], v[74:75], s[10:11] op_sel_hi:[1,1,0]
	v_rcp_f32_e32 v31, v31
	v_pk_fma_f32 v[74:75], v[72:73], v[74:75], s[6:7] op_sel_hi:[1,1,0]
	v_pk_mul_f32 v[78:79], v[62:63], v[62:63]
	v_pk_fma_f32 v[74:75], v[72:73], v[74:75], s[8:9] op_sel_hi:[1,1,0]
	v_pk_fma_f32 v[16:17], v[30:31], s[0:1], v[38:39] op_sel_hi:[1,0,0]
	v_pk_mul_f32 v[72:73], v[72:73], v[74:75]
	v_and_b32_e32 v75, 0x7fffffff, v63
	v_and_b32_e32 v74, 0x7fffffff, v62
	v_pk_fma_f32 v[74:75], v[74:75], s[4:5], 1.0 op_sel_hi:[1,0,0]
	v_pk_fma_f32 v[16:17], v[30:31], v[16:17], s[10:11] op_sel_hi:[1,1,0]
	v_rcp_f32_e32 v74, v74
	v_rcp_f32_e32 v75, v75
	v_pk_fma_f32 v[16:17], v[30:31], v[16:17], s[6:7] op_sel_hi:[1,1,0]
	v_cmp_gt_f32_e32 vcc, 0, v21
	v_pk_fma_f32 v[16:17], v[30:31], v[16:17], s[8:9] op_sel_hi:[1,1,0]
	v_pk_fma_f32 v[76:77], v[74:75], s[0:1], v[38:39] op_sel_hi:[1,0,0]
	v_pk_mul_f32 v[16:17], v[30:31], v[16:17]
	v_pk_fma_f32 v[76:77], v[74:75], v[76:77], s[10:11] op_sel_hi:[1,1,0]
	v_pk_mul_f32 v[30:31], v[22:23], v[22:23]
	v_pk_fma_f32 v[76:77], v[74:75], v[76:77], s[6:7] op_sel_hi:[1,1,0]
	v_pk_mul_f32 v[30:31], v[30:31], s[12:13] op_sel_hi:[1,0]
	v_pk_fma_f32 v[76:77], v[74:75], v[76:77], s[8:9] op_sel_hi:[1,1,0]
	v_exp_f32_e32 v30, v30
	v_exp_f32_e32 v31, v31
	v_pk_mul_f32 v[74:75], v[74:75], v[76:77]
	v_pk_mul_f32 v[76:77], v[18:19], v[18:19]
	v_pk_fma_f32 v[38:39], v[80:81], s[0:1], v[38:39] op_sel_hi:[1,0,0]
	v_pk_mul_f32 v[76:77], v[76:77], s[12:13] op_sel_hi:[1,0]
	v_pk_mul_f32 v[16:17], v[64:65], v[16:17]
	v_pk_fma_f32 v[38:39], v[80:81], v[38:39], s[10:11] op_sel_hi:[1,1,0]
	v_exp_f32_e32 v76, v76
	v_exp_f32_e32 v77, v77
	v_pk_mul_f32 v[64:65], v[20:21], v[16:17]
	v_pk_fma_f32 v[16:17], v[20:21], v[16:17], v[20:21] neg_lo:[1,0,0] neg_hi:[1,0,0]
	v_pk_fma_f32 v[38:39], v[80:81], v[38:39], s[6:7] op_sel_hi:[1,1,0]
	v_pk_mul_f32 v[30:31], v[30:31], v[72:73]
	v_pk_mul_f32 v[78:79], v[78:79], s[12:13] op_sel_hi:[1,0]
	v_pk_fma_f32 v[38:39], v[80:81], v[38:39], s[8:9] op_sel_hi:[1,1,0]
	v_cndmask_b32_e32 v21, v17, v65, vcc
	v_cmp_gt_f32_e32 vcc, 0, v20
	v_pk_mul_f32 v[72:73], v[22:23], v[30:31]
	v_pk_fma_f32 v[30:31], v[22:23], v[30:31], v[22:23] neg_lo:[1,0,0] neg_hi:[1,0,0]
	v_exp_f32_e32 v78, v78
	v_exp_f32_e32 v79, v79
	v_pk_mul_f32 v[38:39], v[80:81], v[38:39]
	v_cndmask_b32_e32 v20, v16, v64, vcc
	v_cmp_gt_f32_e32 vcc, 0, v23
	v_pk_mul_f32 v[38:39], v[76:77], v[38:39]
	v_pk_mul_f32 v[74:75], v[78:79], v[74:75]
	v_cndmask_b32_e32 v31, v31, v73, vcc
	v_cmp_gt_f32_e32 vcc, 0, v22
	v_pk_mul_f32 v[76:77], v[18:19], v[38:39]
	v_pk_fma_f32 v[38:39], v[18:19], v[38:39], v[18:19] neg_lo:[1,0,0] neg_hi:[1,0,0]
	v_cndmask_b32_e32 v30, v30, v72, vcc
	v_cmp_gt_f32_e32 vcc, 0, v19
	v_mul_f32_e32 v16, v20, v20
	v_pk_mul_f32 v[78:79], v[62:63], v[74:75]
	v_cndmask_b32_e32 v77, v39, v77, vcc
	v_cmp_gt_f32_e32 vcc, 0, v18
	v_pk_fma_f32 v[74:75], v[62:63], v[74:75], v[62:63] neg_lo:[1,0,0] neg_hi:[1,0,0]
	v_pk_fma_f32 v[64:65], v[20:21], v[20:21], v[16:17] op_sel_hi:[1,1,0]
	v_cndmask_b32_e32 v76, v38, v76, vcc
	v_cmp_gt_f32_e32 vcc, 0, v24
	v_mov_b32_e32 v16, v20
	v_mov_b32_e32 v17, v30
	v_mov_b32_e32 v22, v21
	v_mov_b32_e32 v23, v31
	v_cndmask_b32_e32 v80, v70, v66, vcc
	v_cmp_gt_f32_e32 vcc, 0, v62
	v_pk_add_f32 v[22:23], v[16:17], v[22:23]
	v_mul_f32_e32 v16, v30, v30
	v_cndmask_b32_e32 v81, v74, v78, vcc
	v_cmp_gt_f32_e32 vcc, 0, v25
	v_pk_fma_f32 v[72:73], v[30:31], v[30:31], v[16:17] op_sel_hi:[1,1,0]
	v_mul_f32_e32 v16, v76, v76
	v_cndmask_b32_e32 v18, v71, v67, vcc
	v_cmp_gt_f32_e32 vcc, 0, v26
	v_pk_fma_f32 v[16:17], v[76:77], v[76:77], v[16:17] op_sel_hi:[1,1,0]
	v_mov_b32_e32 v24, v80
	v_cndmask_b32_e32 v27, v68, v60, vcc
	v_cmp_gt_f32_e32 vcc, 0, v63
	v_mov_b32_e32 v25, v18
	v_mul_f32_e32 v16, v80, v80
	v_mov_b32_e32 v26, v81
	v_cndmask_b32_e32 v60, v75, v79, vcc
	v_mov_b32_e32 v61, v27
	v_pk_fma_f32 v[24:25], v[24:25], v[24:25], v[16:17] op_sel_hi:[1,1,0]
	v_pk_add_f32 v[38:39], v[26:27], v[60:61]
	v_pk_mul_f32 v[62:63], v[26:27], v[60:61]
	v_pk_add_f32 v[22:23], v[22:23], v[22:23] op_sel:[0,1] op_sel_hi:[1,0]
	v_mov_b32_e32 v19, v81
	v_mov_b32_e32 v39, v63
	v_mov_b32_e32 v23, v29
	v_mov_b32_e32 v24, v76
	v_mov_b32_e32 v58, v77
	v_pk_add_f32 v[22:23], v[38:39], v[22:23]
	v_pk_add_f32 v[24:25], v[24:25], v[58:59]
	v_pk_add_f32 v[38:39], v[80:81], v[18:19]
	v_pk_mul_f32 v[58:59], v[80:81], v[18:19]
	v_mov_b32_e32 v64, v27
	v_mov_b32_e32 v39, v59
	v_pk_mul_f32 v[58:59], v[60:61], v[60:61]
	v_mov_b32_e32 v29, v73
	v_mov_b32_e32 v57, v58
	v_pk_add_f32 v[22:23], v[22:23], v[24:25]
	v_pk_add_f32 v[24:25], v[64:65], v[28:29]
	v_pk_add_f32 v[38:39], v[38:39], v[56:57]
	v_mov_b32_e32 v16, 0
	v_pk_add_f32 v[24:25], v[38:39], v[24:25]
	v_lshl_add_u64 v[34:35], s[28:29], 0, v[34:35]
	v_pk_add_f32 v[24:25], v[24:25], v[16:17]
	v_lshl_add_u64 v[34:35], v[148:149], 1, v[34:35]
	v_pk_add_f32 v[24:25], v[22:23], v[24:25]
	v_mov_b32_e32 v56, v24
	v_mov_b32_e32 v57, v25
	s_nop 1
	v_permlane16_swap_b32_e32 v56, v24
	v_permlane16_swap_b32_e32 v57, v25
	v_cvt_pk_bf16_f32 v38, v80, v18
	v_cvt_pk_bf16_f32 v39, v27, v28
	global_store_dwordx4 v[34:35], v[36:39], off
	v_cvt_pk_bf16_f32 v22, v20, v21
	s_waitcnt lgkmcnt(0)
	v_pk_add_f32 v[18:19], v[24:25], v[56:57]
	v_mov_b32_e32 v20, v18
	v_mov_b32_e32 v21, v19
	s_nop 1
	v_permlane32_swap_b32_e32 v20, v18
	v_permlane32_swap_b32_e32 v21, v19
	v_cvt_pk_bf16_f32 v23, v30, v31
	v_cvt_pk_bf16_f32 v24, v81, v60
	v_cvt_pk_bf16_f32 v25, v76, v77
	global_store_dwordx4 v[34:35], v[22:25], off offset:256
	s_and_saveexec_b64 s[16:17], s[2:3]
	s_cbranch_execz .LBB0_363
	s_lshl_b32 s1, s13, 3
	s_waitcnt lgkmcnt(0)
	v_pk_add_f32 v[18:19], v[18:19], v[20:21]
	v_lshlrev_b64 v[20:21], 8, v[32:33]
	s_add_i32 s18, s1, s72
	v_lshl_add_u64 v[20:21], s[26:27], 0, v[20:21]
	s_ashr_i32 s19, s18, 31
	v_lshl_add_u64 v[20:21], s[18:19], 2, v[20:21]
	global_store_dwordx2 v[20:21], v[18:19], off
.LBB0_363:
	s_or_b64 exec, exec, s[16:17]
	v_mov_b32_e32 v22, v151
	v_pk_fma_f32 v[14:15], v[14:15], v[22:23], v[54:55] op_sel_hi:[1,0,1]
	v_mov_b64_e32 v[26:27], s[14:15]
	v_and_b32_e32 v33, 0x7fffffff, v15
	v_and_b32_e32 v32, 0x7fffffff, v14
	v_pk_fma_f32 v[32:33], v[32:33], s[4:5], 1.0 op_sel_hi:[1,0,0]
	v_pk_fma_f32 v[8:9], v[8:9], v[22:23], v[48:49] op_sel_hi:[1,0,1]
	v_rcp_f32_e32 v32, v32
	v_rcp_f32_e32 v33, v33
	v_pk_fma_f32 v[12:13], v[12:13], v[22:23], v[52:53] op_sel_hi:[1,0,1]
	v_pk_fma_f32 v[10:11], v[10:11], v[22:23], v[50:51] op_sel_hi:[1,0,1]
	v_and_b32_e32 v25, 0x7fffffff, v13
	v_pk_fma_f32 v[34:35], v[32:33], s[0:1], v[26:27] op_sel_hi:[1,0,0]
	v_and_b32_e32 v24, 0x7fffffff, v12
	v_pk_fma_f32 v[34:35], v[32:33], v[34:35], s[10:11] op_sel_hi:[1,1,0]
	v_pk_fma_f32 v[24:25], v[24:25], s[4:5], 1.0 op_sel_hi:[1,0,0]
	v_pk_fma_f32 v[34:35], v[32:33], v[34:35], s[6:7] op_sel_hi:[1,1,0]
	v_rcp_f32_e32 v24, v24
	v_pk_fma_f32 v[34:35], v[32:33], v[34:35], s[8:9] op_sel_hi:[1,1,0]
	v_rcp_f32_e32 v25, v25
	v_pk_mul_f32 v[32:33], v[32:33], v[34:35]
	v_and_b32_e32 v35, 0x7fffffff, v9
	v_and_b32_e32 v34, 0x7fffffff, v8
	v_pk_fma_f32 v[34:35], v[34:35], s[4:5], 1.0 op_sel_hi:[1,0,0]
	v_and_b32_e32 v49, 0x7fffffff, v11
	v_rcp_f32_e32 v34, v34
	v_rcp_f32_e32 v35, v35
	v_and_b32_e32 v48, 0x7fffffff, v10
	v_pk_fma_f32 v[48:49], v[48:49], s[4:5], 1.0 op_sel_hi:[1,0,0]
	v_pk_fma_f32 v[28:29], v[24:25], s[0:1], v[26:27] op_sel_hi:[1,0,0]
	v_pk_fma_f32 v[36:37], v[34:35], s[0:1], v[26:27] op_sel_hi:[1,0,0]
	v_rcp_f32_e32 v48, v48
	v_pk_fma_f32 v[36:37], v[34:35], v[36:37], s[10:11] op_sel_hi:[1,1,0]
	v_rcp_f32_e32 v49, v49
	v_pk_fma_f32 v[28:29], v[24:25], v[28:29], s[10:11] op_sel_hi:[1,1,0]
	v_pk_fma_f32 v[36:37], v[34:35], v[36:37], s[6:7] op_sel_hi:[1,1,0]
	v_pk_fma_f32 v[28:29], v[24:25], v[28:29], s[6:7] op_sel_hi:[1,1,0]
	v_pk_fma_f32 v[36:37], v[34:35], v[36:37], s[8:9] op_sel_hi:[1,1,0]
	v_pk_fma_f32 v[28:29], v[24:25], v[28:29], s[8:9] op_sel_hi:[1,1,0]
	v_pk_mul_f32 v[34:35], v[34:35], v[36:37]
	v_pk_mul_f32 v[36:37], v[10:11], v[10:11]
	v_pk_mul_f32 v[24:25], v[24:25], v[28:29]
	v_pk_mul_f32 v[28:29], v[14:15], v[14:15]
	v_pk_fma_f32 v[50:51], v[48:49], s[0:1], v[26:27] op_sel_hi:[1,0,0]
	v_pk_mul_f32 v[36:37], v[36:37], s[12:13] op_sel_hi:[1,0]
	v_pk_mul_f32 v[30:31], v[12:13], v[12:13]
	v_pk_mul_f32 v[28:29], v[28:29], s[12:13] op_sel_hi:[1,0]
	v_pk_fma_f32 v[50:51], v[48:49], v[50:51], s[10:11] op_sel_hi:[1,1,0]
	v_exp_f32_e32 v36, v36
	v_exp_f32_e32 v37, v37
	v_pk_mul_f32 v[30:31], v[30:31], s[12:13] op_sel_hi:[1,0]
	v_exp_f32_e32 v28, v28
	v_exp_f32_e32 v29, v29
	v_pk_fma_f32 v[50:51], v[48:49], v[50:51], s[6:7] op_sel_hi:[1,1,0]
	v_exp_f32_e32 v30, v30
	v_exp_f32_e32 v31, v31
	v_pk_fma_f32 v[50:51], v[48:49], v[50:51], s[8:9] op_sel_hi:[1,1,0]
	v_pk_mul_f32 v[28:29], v[28:29], v[32:33]
	v_pk_mul_f32 v[48:49], v[48:49], v[50:51]
	v_cmp_gt_f32_e32 vcc, 0, v11
	v_pk_mul_f32 v[36:37], v[36:37], v[48:49]
	v_pk_mul_f32 v[24:25], v[30:31], v[24:25]
	v_pk_mul_f32 v[48:49], v[10:11], v[36:37]
	v_pk_fma_f32 v[36:37], v[10:11], v[36:37], v[10:11] neg_lo:[1,0,0] neg_hi:[1,0,0]
	v_pk_mul_f32 v[32:33], v[14:15], v[28:29]
	v_pk_fma_f32 v[28:29], v[14:15], v[28:29], v[14:15] neg_lo:[1,0,0] neg_hi:[1,0,0]
	v_cndmask_b32_e32 v50, v37, v49, vcc
	v_cmp_gt_f32_e32 vcc, 0, v14
	v_pk_mul_f32 v[30:31], v[12:13], v[24:25]
	v_pk_fma_f32 v[24:25], v[12:13], v[24:25], v[12:13] neg_lo:[1,0,0] neg_hi:[1,0,0]
	v_cndmask_b32_e32 v53, v28, v32, vcc
	v_cmp_gt_f32_e32 vcc, 0, v12
	v_pk_fma_f32 v[6:7], v[6:7], v[22:23], v[46:47] op_sel_hi:[1,0,1]
	v_pk_fma_f32 v[0:1], v[0:1], v[22:23], v[40:41] op_sel_hi:[1,0,1]
	v_cndmask_b32_e32 v52, v24, v30, vcc
	v_cmp_gt_f32_e32 vcc, 0, v15
	v_and_b32_e32 v32, 0x7fffffff, v6
	v_pk_fma_f32 v[4:5], v[4:5], v[22:23], v[44:45] op_sel_hi:[1,0,1]
	v_cndmask_b32_e32 v15, v29, v33, vcc
	v_and_b32_e32 v33, 0x7fffffff, v7
	v_pk_fma_f32 v[32:33], v[32:33], s[4:5], 1.0 op_sel_hi:[1,0,0]
	v_cmp_gt_f32_e32 vcc, 0, v13
	v_rcp_f32_e32 v32, v32
	v_rcp_f32_e32 v33, v33
	v_cndmask_b32_e32 v14, v25, v31, vcc
	v_pk_add_f32 v[12:13], v[52:53], v[14:15]
	v_pk_fma_f32 v[2:3], v[2:3], v[22:23], v[42:43] op_sel_hi:[1,0,1]
	v_pk_add_f32 v[24:25], v[12:13], v[12:13] op_sel:[0,1] op_sel_hi:[1,0]
	v_pk_mul_f32 v[12:13], v[14:15], v[14:15]
	v_pk_fma_f32 v[40:41], v[32:33], s[0:1], v[26:27] op_sel_hi:[1,0,0]
	v_pk_fma_f32 v[12:13], v[52:53], v[52:53], v[12:13]
	v_pk_fma_f32 v[40:41], v[32:33], v[40:41], s[10:11] op_sel_hi:[1,1,0]
	v_pk_add_f32 v[28:29], v[12:13], v[12:13] op_sel_hi:[0,1]
	v_cvt_pk_bf16_f32 v12, v52, v14
	v_cvt_pk_bf16_f32 v13, v53, v15
	v_and_b32_e32 v15, 0x7fffffff, v5
	v_and_b32_e32 v14, 0x7fffffff, v4
	v_pk_fma_f32 v[40:41], v[32:33], v[40:41], s[6:7] op_sel_hi:[1,1,0]
	v_pk_fma_f32 v[14:15], v[14:15], s[4:5], 1.0 op_sel_hi:[1,0,0]
	v_pk_fma_f32 v[40:41], v[32:33], v[40:41], s[8:9] op_sel_hi:[1,1,0]
	v_rcp_f32_e32 v14, v14
	v_rcp_f32_e32 v15, v15
	v_pk_mul_f32 v[32:33], v[32:33], v[40:41]
	v_and_b32_e32 v41, 0x7fffffff, v1
	v_and_b32_e32 v40, 0x7fffffff, v0
	v_pk_fma_f32 v[40:41], v[40:41], s[4:5], 1.0 op_sel_hi:[1,0,0]
	v_pk_fma_f32 v[22:23], v[14:15], s[0:1], v[26:27] op_sel_hi:[1,0,0]
	v_rcp_f32_e32 v40, v40
	v_rcp_f32_e32 v41, v41
	v_pk_fma_f32 v[22:23], v[14:15], v[22:23], s[10:11] op_sel_hi:[1,1,0]
	v_and_b32_e32 v47, 0x7fffffff, v3
	v_and_b32_e32 v46, 0x7fffffff, v2
	v_pk_fma_f32 v[22:23], v[14:15], v[22:23], s[6:7] op_sel_hi:[1,1,0]
	v_pk_mul_f32 v[30:31], v[4:5], v[4:5]
	v_pk_fma_f32 v[42:43], v[40:41], s[0:1], v[26:27] op_sel_hi:[1,0,0]
	v_pk_fma_f32 v[46:47], v[46:47], s[4:5], 1.0 op_sel_hi:[1,0,0]
	v_pk_fma_f32 v[22:23], v[14:15], v[22:23], s[8:9] op_sel_hi:[1,1,0]
	v_pk_mul_f32 v[30:31], v[30:31], s[12:13] op_sel_hi:[1,0]
	v_pk_fma_f32 v[42:43], v[40:41], v[42:43], s[10:11] op_sel_hi:[1,1,0]
	v_rcp_f32_e32 v46, v46
	v_rcp_f32_e32 v47, v47
	v_pk_mul_f32 v[14:15], v[14:15], v[22:23]
	v_pk_mul_f32 v[22:23], v[6:7], v[6:7]
	v_exp_f32_e32 v30, v30
	v_exp_f32_e32 v31, v31
	v_pk_fma_f32 v[42:43], v[40:41], v[42:43], s[6:7] op_sel_hi:[1,1,0]
	v_pk_mul_f32 v[22:23], v[22:23], s[12:13] op_sel_hi:[1,0]
	v_pk_fma_f32 v[42:43], v[40:41], v[42:43], s[8:9] op_sel_hi:[1,1,0]
	v_exp_f32_e32 v22, v22
	v_exp_f32_e32 v23, v23
	v_pk_mul_f32 v[40:41], v[40:41], v[42:43]
	v_pk_mul_f32 v[42:43], v[2:3], v[2:3]
	v_pk_fma_f32 v[26:27], v[46:47], s[0:1], v[26:27] op_sel_hi:[1,0,0]
	v_pk_mul_f32 v[42:43], v[42:43], s[12:13] op_sel_hi:[1,0]
	v_pk_mul_f32 v[38:39], v[8:9], v[8:9]
	v_pk_mul_f32 v[14:15], v[30:31], v[14:15]
	v_pk_fma_f32 v[26:27], v[46:47], v[26:27], s[10:11] op_sel_hi:[1,1,0]
	v_exp_f32_e32 v42, v42
	v_exp_f32_e32 v43, v43
	v_pk_mul_f32 v[38:39], v[38:39], s[12:13] op_sel_hi:[1,0]
	v_pk_mul_f32 v[30:31], v[4:5], v[14:15]
	v_pk_fma_f32 v[14:15], v[4:5], v[14:15], v[4:5] neg_lo:[1,0,0] neg_hi:[1,0,0]
	v_pk_mul_f32 v[44:45], v[0:1], v[0:1]
	v_pk_fma_f32 v[26:27], v[46:47], v[26:27], s[6:7] op_sel_hi:[1,1,0]
	v_cmp_gt_f32_e32 vcc, 0, v5
	v_exp_f32_e32 v38, v38
	v_exp_f32_e32 v39, v39
	v_pk_mul_f32 v[22:23], v[22:23], v[32:33]
	v_pk_mul_f32 v[44:45], v[44:45], s[12:13] op_sel_hi:[1,0]
	v_pk_fma_f32 v[26:27], v[46:47], v[26:27], s[8:9] op_sel_hi:[1,1,0]
	v_cndmask_b32_e32 v5, v15, v31, vcc
	v_cmp_gt_f32_e32 vcc, 0, v4
	v_pk_mul_f32 v[32:33], v[6:7], v[22:23]
	v_pk_fma_f32 v[22:23], v[6:7], v[22:23], v[6:7] neg_lo:[1,0,0] neg_hi:[1,0,0]
	v_exp_f32_e32 v44, v44
	v_exp_f32_e32 v45, v45
	v_pk_mul_f32 v[26:27], v[46:47], v[26:27]
	v_cndmask_b32_e32 v4, v14, v30, vcc
	v_cmp_gt_f32_e32 vcc, 0, v7
	v_pk_mul_f32 v[26:27], v[42:43], v[26:27]
	v_pk_mul_f32 v[34:35], v[38:39], v[34:35]
	v_cndmask_b32_e32 v7, v23, v33, vcc
	v_cmp_gt_f32_e32 vcc, 0, v6
	v_pk_mul_f32 v[42:43], v[2:3], v[26:27]
	v_pk_fma_f32 v[26:27], v[2:3], v[26:27], v[2:3] neg_lo:[1,0,0] neg_hi:[1,0,0]
	v_cndmask_b32_e32 v6, v22, v32, vcc
	v_cmp_gt_f32_e32 vcc, 0, v3
	v_pk_mul_f32 v[38:39], v[8:9], v[34:35]
	v_pk_fma_f32 v[34:35], v[8:9], v[34:35], v[8:9] neg_lo:[1,0,0] neg_hi:[1,0,0]
	v_cndmask_b32_e32 v27, v27, v43, vcc
	v_cmp_gt_f32_e32 vcc, 0, v2
	v_pk_mul_f32 v[40:41], v[44:45], v[40:41]
	v_mov_b32_e32 v22, v4
	v_cndmask_b32_e32 v26, v26, v42, vcc
	v_cmp_gt_f32_e32 vcc, 0, v8
	v_pk_mul_f32 v[44:45], v[0:1], v[40:41]
	v_pk_fma_f32 v[40:41], v[0:1], v[40:41], v[0:1] neg_lo:[1,0,0] neg_hi:[1,0,0]
	v_cndmask_b32_e32 v32, v34, v38, vcc
	v_cmp_gt_f32_e32 vcc, 0, v0
	v_mov_b32_e32 v23, v6
	v_mov_b32_e32 v30, v5
	v_cndmask_b32_e32 v33, v40, v44, vcc
	v_cmp_gt_f32_e32 vcc, 0, v9
	v_mov_b32_e32 v31, v7
	v_pk_add_f32 v[22:23], v[22:23], v[30:31]
	v_cndmask_b32_e32 v8, v35, v39, vcc
	v_cmp_gt_f32_e32 vcc, 0, v10
	v_mov_b32_e32 v34, v32
	v_mov_b32_e32 v35, v8
	v_cndmask_b32_e32 v11, v36, v48, vcc
	v_cmp_gt_f32_e32 vcc, 0, v1
	v_mul_f32_e32 v0, v32, v32
	v_mov_b32_e32 v10, v33
	v_cndmask_b32_e32 v36, v41, v45, vcc
	v_mov_b32_e32 v37, v11
	v_mul_f32_e32 v17, v50, v50
	v_pk_fma_f32 v[34:35], v[34:35], v[34:35], v[0:1] op_sel_hi:[1,1,0]
	v_pk_add_f32 v[0:1], v[10:11], v[36:37]
	v_pk_mul_f32 v[38:39], v[10:11], v[36:37]
	v_pk_add_f32 v[22:23], v[22:23], v[22:23] op_sel:[0,1] op_sel_hi:[1,0]
	v_mul_f32_e32 v14, v4, v4
	v_mov_b32_e32 v1, v39
	v_mov_b32_e32 v23, v17
	v_mov_b32_e32 v34, v26
	v_mov_b32_e32 v28, v27
	v_pk_fma_f32 v[14:15], v[4:5], v[4:5], v[14:15] op_sel_hi:[1,1,0]
	v_mov_b32_e32 v9, v33
	v_pk_add_f32 v[0:1], v[0:1], v[22:23]
	v_pk_add_f32 v[22:23], v[34:35], v[28:29]
	v_mul_f32_e32 v14, v6, v6
	v_pk_add_f32 v[0:1], v[0:1], v[22:23]
	v_pk_add_f32 v[22:23], v[32:33], v[8:9]
	v_pk_mul_f32 v[28:29], v[32:33], v[8:9]
	v_pk_fma_f32 v[30:31], v[6:7], v[6:7], v[14:15] op_sel_hi:[1,1,0]
	v_mov_b32_e32 v23, v29
	v_pk_mul_f32 v[28:29], v[36:37], v[36:37]
	v_mul_f32_e32 v2, v26, v26
	v_mov_b32_e32 v14, v11
	v_mov_b32_e32 v51, v31
	v_mov_b32_e32 v25, v28
	v_pk_fma_f32 v[2:3], v[26:27], v[26:27], v[2:3] op_sel_hi:[1,1,0]
	v_pk_add_f32 v[14:15], v[14:15], v[50:51]
	v_pk_add_f32 v[22:23], v[22:23], v[24:25]
	v_mov_b32_e32 v17, v3
	v_pk_add_f32 v[14:15], v[22:23], v[14:15]
	v_add_u32_e32 v18, 0xb0, v152
	v_pk_add_f32 v[2:3], v[14:15], v[16:17]
	v_ashrrev_i32_e32 v19, 31, v18
	v_pk_add_f32 v[0:1], v[0:1], v[2:3]
	v_mov_b32_e32 v2, v0
	v_mov_b32_e32 v3, v1
	s_nop 1
	v_permlane16_swap_b32_e32 v2, v0
	v_permlane16_swap_b32_e32 v3, v1
	s_waitcnt lgkmcnt(2)
	v_lshlrev_b64 v[20:21], 13, v[18:19]
	v_lshl_add_u64 v[20:21], s[28:29], 0, v[20:21]
	v_lshl_add_u64 v[20:21], v[148:149], 1, v[20:21]
	v_cvt_pk_bf16_f32 v14, v32, v8
	s_waitcnt lgkmcnt(0)
	v_pk_add_f32 v[0:1], v[0:1], v[2:3]
	v_mov_b32_e32 v2, v0
	v_mov_b32_e32 v3, v1
	s_nop 1
	v_permlane32_swap_b32_e32 v2, v0
	v_permlane32_swap_b32_e32 v3, v1
	v_cvt_pk_bf16_f32 v15, v11, v50
	global_store_dwordx4 v[20:21], v[12:15], off
	v_cvt_pk_bf16_f32 v4, v4, v5
	v_cvt_pk_bf16_f32 v5, v6, v7
	v_cvt_pk_bf16_f32 v6, v33, v36
	v_cvt_pk_bf16_f32 v7, v26, v27
	global_store_dwordx4 v[20:21], v[4:7], off offset:256
	s_and_saveexec_b64 s[0:1], s[2:3]
	s_cbranch_execz .LBB0_365
	s_lshl_b32 s2, s13, 3
	s_waitcnt lgkmcnt(0)
	v_pk_add_f32 v[0:1], v[0:1], v[2:3]
	v_lshlrev_b64 v[2:3], 8, v[18:19]
	s_add_i32 s2, s2, s72
	v_lshl_add_u64 v[2:3], s[26:27], 0, v[2:3]
	s_ashr_i32 s3, s2, 31
	v_lshl_add_u64 v[2:3], s[2:3], 2, v[2:3]
	global_store_dwordx2 v[2:3], v[0:1], off
